# poolprep pool_rows rewritten: straight-line 4 variants with 8-row deep global-load ring (was 1 row in flight)
# baseline (speedup 1.0000x reference)
; template <int W>
; DI void pool_rows(const float* __restrict__ x, const float* smr, bf16_t* __restrict__ pb, int t0, int s0, int tid) {
;   const int tq0 = t0 - s0;
;   const float* xq = x + tid * 4;
;   f32x4 Sm = {0.f, 0.f, 0.f, 0.f};
; #pragma unroll
;   for (int i = 1; i < W; ++i) {
;     int t = t0 - i; if (t < tq0) t = tq0;
;     Sm += *(const f32x4*)(xq + (size_t)t * D) * smr[15 - i];
;   }
; #pragma unroll 8
;   for (int tl = 0; tl < 64; ++tl) {
;     const int t = t0 + tl, s = s0 + tl;
;     int to = t - W + 1; if (to < tq0) to = tq0;
;     const f32x4 hn = *(const f32x4*)(xq + (size_t)t * D) * smr[15 + tl];
;     const f32x4 ho = *(const f32x4*)(xq + (size_t)to * D) * smr[15 + tl - W + 1];
; DI void poolprep_phase(int vb, int nvb, const float* __restrict__ x, const float* __restrict__ ssq, bf16_t* __restrict__ pb, float* smf) {
;     ...
;     if (on && tid < 79) smf[tid] = (s0 + tid >= 15) ? rsqrtf(ssq[t0 - 15 + tid] * (1.f / D) + EPS) : 0.f;
;     __syncthreads();
;     if (on) {
;       if (wave == 0) pool_rows<2>(x, smf, pb, t0, s0, tid);
;       else if (wave == 1) pool_rows<4>(x, smf, pb, t0, s0, tid);
;       else if (wave == 2) pool_rows<8>(x, smf, pb, t0, s0, tid);
;       else pool_rows<16>(x, smf, pb, t0, s0, tid);
.LBB0_1475:
	s_or_b64 exec, exec, s[12:13]
	s_andn2_b64 vcc, exec, s[2:3]
	s_waitcnt lgkmcnt(0)
	s_barrier
	s_cbranch_vccnz .LBB0_1470
	v_and_b32_e32 v0, 63, v40
	v_readfirstlane_b32 s2, v14
	v_readfirstlane_b32 s3, v15
	v_readfirstlane_b32 s12, v16
	v_readfirstlane_b32 s13, v17
	v_readfirstlane_b32 s1, v41
	v_lshlrev_b32_e32 v222, 3, v0
	v_lshlrev_b32_e32 v0, 4, v0
	v_mov_b32_e32 v223, s93
	s_lshl_b32 s31, s92, 12
	s_add_u32 s2, s2, s31
	s_addc_u32 s3, s3, 0
	s_mul_i32 s31, s92, 0x880
	s_add_u32 s12, s12, s31
	s_addc_u32 s13, s13, 0
	s_and_b32 s58, s92, 0x3fc0
	ds_read_b128 v[108:111], v223
	ds_read_b128 v[112:115], v223 offset:16
	ds_read_b128 v[116:119], v223 offset:32
	ds_read_b128 v[120:123], v223 offset:48
	ds_read_b128 v[124:127], v223 offset:64
	ds_read_b128 v[128:131], v223 offset:80
	ds_read_b128 v[132:135], v223 offset:96
	ds_read_b128 v[136:139], v223 offset:112
	ds_read_b128 v[140:143], v223 offset:128
	ds_read_b128 v[144:147], v223 offset:144
	ds_read_b128 v[148:151], v223 offset:160
	ds_read_b128 v[152:155], v223 offset:176
	ds_read_b128 v[156:159], v223 offset:192
	ds_read_b128 v[160:163], v223 offset:208
	ds_read_b128 v[164:167], v223 offset:224
	ds_read_b128 v[168:171], v223 offset:240
	ds_read_b128 v[172:175], v223 offset:256
	ds_read_b128 v[176:179], v223 offset:272
	ds_read_b128 v[180:183], v223 offset:288
	ds_read_b128 v[184:187], v223 offset:304
	s_cmp_eq_u32 s1, 0
	s_cbranch_scc1 .Lpp_w2
	s_cmp_eq_u32 s1, 1
	s_cbranch_scc1 .Lpp_w4
	s_cmp_eq_u32 s1, 2
	s_cbranch_scc1 .Lpp_w8
	s_mov_b32 s59, 0x3d800000
	s_cmp_eq_u32 s58, 0
	s_cselect_b32 s31, 0, 0xfffff000
	s_cselect_b32 s32, 0, -1
	s_add_u32 s14, s2, s31
	s_addc_u32 s15, s3, s32
	global_load_dwordx4 v[188:191], v0, s[14:15]
	s_cmp_eq_u32 s58, 0
	s_cselect_b32 s31, 0, 0xffffe000
	s_cselect_b32 s32, 0, -1
	s_add_u32 s56, s2, s31
	s_addc_u32 s57, s3, s32
	global_load_dwordx4 v[192:195], v0, s[56:57]
	s_cmp_eq_u32 s58, 0
	s_cselect_b32 s31, 0, 0xffffd000
	s_cselect_b32 s32, 0, -1
	s_add_u32 s70, s2, s31
	s_addc_u32 s71, s3, s32
	global_load_dwordx4 v[196:199], v0, s[70:71]
	s_cmp_eq_u32 s58, 0
	s_cselect_b32 s31, 0, 0xffffc000
	s_cselect_b32 s32, 0, -1
	s_add_u32 s14, s2, s31
	s_addc_u32 s15, s3, s32
	global_load_dwordx4 v[200:203], v0, s[14:15]
	s_cmp_eq_u32 s58, 0
	s_cselect_b32 s31, 0, 0xffffb000
	s_cselect_b32 s32, 0, -1
	s_add_u32 s56, s2, s31
	s_addc_u32 s57, s3, s32
	global_load_dwordx4 v[204:207], v0, s[56:57]
	s_cmp_eq_u32 s58, 0
	s_cselect_b32 s31, 0, 0xffffa000
	s_cselect_b32 s32, 0, -1
	s_add_u32 s70, s2, s31
	s_addc_u32 s71, s3, s32
	global_load_dwordx4 v[224:227], v0, s[70:71]
	s_cmp_eq_u32 s58, 0
	s_cselect_b32 s31, 0, 0xffff9000
	s_cselect_b32 s32, 0, -1
	s_add_u32 s14, s2, s31
	s_addc_u32 s15, s3, s32
	global_load_dwordx4 v[228:231], v0, s[14:15]
	s_cmp_eq_u32 s58, 0
	s_cselect_b32 s31, 0, 0xffff8000
	s_cselect_b32 s32, 0, -1
	s_add_u32 s56, s2, s31
	s_addc_u32 s57, s3, s32
	global_load_dwordx4 v[232:235], v0, s[56:57]
	s_cmp_eq_u32 s58, 0
	s_cselect_b32 s31, 0, 0xffff7000
	s_cselect_b32 s32, 0, -1
	s_add_u32 s70, s2, s31
	s_addc_u32 s71, s3, s32
	global_load_dwordx4 v[236:239], v0, s[70:71]
	s_cmp_eq_u32 s58, 0
	s_cselect_b32 s31, 0, 0xffff6000
	s_cselect_b32 s32, 0, -1
	s_add_u32 s14, s2, s31
	s_addc_u32 s15, s3, s32
	global_load_dwordx4 v[240:243], v0, s[14:15]
	s_cmp_eq_u32 s58, 0
	s_cselect_b32 s31, 0, 0xffff5000
	s_cselect_b32 s32, 0, -1
	s_add_u32 s56, s2, s31
	s_addc_u32 s57, s3, s32
	global_load_dwordx4 v[244:247], v0, s[56:57]
	s_cmp_eq_u32 s58, 0
	s_cselect_b32 s31, 0, 0xffff4000
	s_cselect_b32 s32, 0, -1
	s_add_u32 s70, s2, s31
	s_addc_u32 s71, s3, s32
	global_load_dwordx4 v[248:251], v0, s[70:71]
	s_cmp_eq_u32 s58, 0
	s_cselect_b32 s31, 0, 0xffff3000
	s_cselect_b32 s32, 0, -1
	s_add_u32 s14, s2, s31
	s_addc_u32 s15, s3, s32
	global_load_dwordx4 v[4:7], v0, s[14:15]
	s_cmp_eq_u32 s58, 0
	s_cselect_b32 s31, 0, 0xffff2000
	s_cselect_b32 s32, 0, -1
	s_add_u32 s56, s2, s31
	s_addc_u32 s57, s3, s32
	global_load_dwordx4 v[8:11], v0, s[56:57]
	s_cmp_eq_u32 s58, 0
	s_cselect_b32 s31, 0, 0xffff1000
	s_cselect_b32 s32, 0, -1
	s_add_u32 s70, s2, s31
	s_addc_u32 s71, s3, s32
	global_load_dwordx4 v[24:27], v0, s[70:71]
	s_mov_b32 s14, s2
	s_mov_b32 s15, s3
	global_load_dwordx4 v[44:47], v0, s[14:15]
	s_cmp_eq_u32 s58, 0
	s_cselect_b32 s31, 0, 0xffff1000
	s_cselect_b32 s32, 0, -1
	s_add_u32 s56, s2, s31
	s_addc_u32 s57, s3, s32
	global_load_dwordx4 v[48:51], v0, s[56:57]
	s_add_u32 s70, s2, 0x1000
	s_addc_u32 s71, s3, 0
	global_load_dwordx4 v[52:55], v0, s[70:71]
	s_cmp_eq_u32 s58, 0
	s_cselect_b32 s31, 0, 0xffff2000
	s_cselect_b32 s32, 0, -1
	s_add_u32 s14, s2, s31
	s_addc_u32 s15, s3, s32
	global_load_dwordx4 v[56:59], v0, s[14:15]
	s_add_u32 s56, s2, 0x2000
	s_addc_u32 s57, s3, 0
	global_load_dwordx4 v[60:63], v0, s[56:57]
	s_cmp_eq_u32 s58, 0
	s_cselect_b32 s31, 0, 0xffff3000
	s_cselect_b32 s32, 0, -1
	s_add_u32 s70, s2, s31
	s_addc_u32 s71, s3, s32
	global_load_dwordx4 v[64:67], v0, s[70:71]
	s_add_u32 s14, s2, 0x3000
	s_addc_u32 s15, s3, 0
	global_load_dwordx4 v[68:71], v0, s[14:15]
	s_cmp_eq_u32 s58, 0
	s_cselect_b32 s31, 0, 0xffff4000
	s_cselect_b32 s32, 0, -1
	s_add_u32 s56, s2, s31
	s_addc_u32 s57, s3, s32
	global_load_dwordx4 v[72:75], v0, s[56:57]
	s_add_u32 s70, s2, 0x4000
	s_addc_u32 s71, s3, 0
	global_load_dwordx4 v[76:79], v0, s[70:71]
	s_cmp_eq_u32 s58, 0
	s_cselect_b32 s31, 0, 0xffff5000
	s_cselect_b32 s32, 0, -1
	s_add_u32 s14, s2, s31
	s_addc_u32 s15, s3, s32
	global_load_dwordx4 v[80:83], v0, s[14:15]
	s_add_u32 s56, s2, 0x5000
	s_addc_u32 s57, s3, 0
	global_load_dwordx4 v[84:87], v0, s[56:57]
	s_cmp_eq_u32 s58, 0
	s_cselect_b32 s31, 0, 0xffff6000
	s_cselect_b32 s32, 0, -1
	s_add_u32 s70, s2, s31
	s_addc_u32 s71, s3, s32
	global_load_dwordx4 v[88:91], v0, s[70:71]
	s_add_u32 s14, s2, 0x6000
	s_addc_u32 s15, s3, 0
	global_load_dwordx4 v[92:95], v0, s[14:15]
	s_cmp_eq_u32 s58, 0
	s_cselect_b32 s31, 0, 0xffff7000
	s_cselect_b32 s32, 0, -1
	s_add_u32 s56, s2, s31
	s_addc_u32 s57, s3, s32
	global_load_dwordx4 v[96:99], v0, s[56:57]
	s_add_u32 s70, s2, 0x7000
	s_addc_u32 s71, s3, 0
	global_load_dwordx4 v[100:103], v0, s[70:71]
	s_cmp_eq_u32 s58, 0
	s_cselect_b32 s31, 0, 0xffff8000
	s_cselect_b32 s32, 0, -1
	s_add_u32 s14, s2, s31
	s_addc_u32 s15, s3, s32
	global_load_dwordx4 v[104:107], v0, s[14:15]
	s_waitcnt lgkmcnt(0)
; DI unsigned pack_bf16(float lo, float hi) { f32x2 v = {lo, hi}; bf16v2 b = __builtin_convertvector(v, bf16v2); return __builtin_bit_cast(unsigned, b); }
; template <int W>
; DI void pool_rows(const float* __restrict__ x, const float* smr, bf16_t* __restrict__ pb, int t0, int s0, int tid) {
;     ...
;   for (int i = 1; i < W; ++i) {
;     int t = t0 - i; if (t < tq0) t = tq0;
;     Sm += *(const f32x4*)(xq + (size_t)t * D) * smr[15 - i];
;   }
; #pragma unroll 8
;   for (int tl = 0; tl < 64; ++tl) {
;     const int t = t0 + tl, s = s0 + tl;
;     int to = t - W + 1; if (to < tq0) to = tq0;
;     const f32x4 hn = *(const f32x4*)(xq + (size_t)t * D) * smr[15 + tl];
;     const f32x4 ho = *(const f32x4*)(xq + (size_t)to * D) * smr[15 + tl - W + 1];
;     const int cnt = (s + 1 < W) ? (s + 1) : W;
;     const float ic = 1.f / (float)cnt;
;     Sm += hn;
;     const f32x4 p = Sm * ic - hn;
;     Sm -= ho;
;     u32x2 o; o.x = pack_bf16(p.x, p.y); o.y = pack_bf16(p.z, p.w);
;     *(u32x2*)(pb + (size_t)t * LDH + tid * 4) = o;
	s_waitcnt vmcnt(16)
	v_mul_f32_e32 v36, v188, v122
	v_mul_f32_e32 v37, v189, v122
	v_mul_f32_e32 v38, v190, v122
	v_mul_f32_e32 v39, v191, v122
	v_fmac_f32_e32 v36, v192, v121
	v_fmac_f32_e32 v37, v193, v121
	v_fmac_f32_e32 v38, v194, v121
	v_fmac_f32_e32 v39, v195, v121
	v_fmac_f32_e32 v36, v196, v120
	v_fmac_f32_e32 v37, v197, v120
	v_fmac_f32_e32 v38, v198, v120
	v_fmac_f32_e32 v39, v199, v120
	v_fmac_f32_e32 v36, v200, v119
	v_fmac_f32_e32 v37, v201, v119
	v_fmac_f32_e32 v38, v202, v119
	v_fmac_f32_e32 v39, v203, v119
	v_fmac_f32_e32 v36, v204, v118
	v_fmac_f32_e32 v37, v205, v118
	v_fmac_f32_e32 v38, v206, v118
	v_fmac_f32_e32 v39, v207, v118
	v_fmac_f32_e32 v36, v224, v117
	v_fmac_f32_e32 v37, v225, v117
	v_fmac_f32_e32 v38, v226, v117
	v_fmac_f32_e32 v39, v227, v117
	v_fmac_f32_e32 v36, v228, v116
	v_fmac_f32_e32 v37, v229, v116
	v_fmac_f32_e32 v38, v230, v116
	v_fmac_f32_e32 v39, v231, v116
	v_fmac_f32_e32 v36, v232, v115
	v_fmac_f32_e32 v37, v233, v115
	v_fmac_f32_e32 v38, v234, v115
	v_fmac_f32_e32 v39, v235, v115
	v_fmac_f32_e32 v36, v236, v114
	v_fmac_f32_e32 v37, v237, v114
	v_fmac_f32_e32 v38, v238, v114
	v_fmac_f32_e32 v39, v239, v114
	v_fmac_f32_e32 v36, v240, v113
	v_fmac_f32_e32 v37, v241, v113
	v_fmac_f32_e32 v38, v242, v113
	v_fmac_f32_e32 v39, v243, v113
	v_fmac_f32_e32 v36, v244, v112
	v_fmac_f32_e32 v37, v245, v112
	v_fmac_f32_e32 v38, v246, v112
	v_fmac_f32_e32 v39, v247, v112
	v_fmac_f32_e32 v36, v248, v111
	v_fmac_f32_e32 v37, v249, v111
	v_fmac_f32_e32 v38, v250, v111
	v_fmac_f32_e32 v39, v251, v111
	v_fmac_f32_e32 v36, v4, v110
	v_fmac_f32_e32 v37, v5, v110
	v_fmac_f32_e32 v38, v6, v110
	v_fmac_f32_e32 v39, v7, v110
	v_fmac_f32_e32 v36, v8, v109
	v_fmac_f32_e32 v37, v9, v109
	v_fmac_f32_e32 v38, v10, v109
	v_fmac_f32_e32 v39, v11, v109
	v_fmac_f32_e32 v36, v24, v108
	v_fmac_f32_e32 v37, v25, v108
	v_fmac_f32_e32 v38, v26, v108
	v_fmac_f32_e32 v39, v27, v108
	s_mov_b32 s32, 0x3f800000
	s_cmp_eq_u32 s58, 0
	s_cselect_b32 s32, s32, s59
	s_add_u32 s54, s12, 0x0
	s_addc_u32 s55, s13, 0
	s_waitcnt vmcnt(15)
	v_mul_f32_e32 v212, v44, v123
	v_mul_f32_e32 v213, v45, v123
	v_mul_f32_e32 v214, v46, v123
	v_mul_f32_e32 v215, v47, v123
	v_fmac_f32_e32 v36, v44, v123
	v_fmac_f32_e32 v37, v45, v123
	v_fmac_f32_e32 v38, v46, v123
	v_fmac_f32_e32 v39, v47, v123
	v_fma_f32 v12, v36, s32, -v212
	v_fma_f32 v13, v37, s32, -v213
	v_fma_f32 v22, v38, s32, -v214
	v_fma_f32 v23, v39, s32, -v215
	s_waitcnt vmcnt(14)
	v_fma_f32 v36, -v48, v108, v36
	v_fma_f32 v37, -v49, v108, v37
	v_fma_f32 v38, -v50, v108, v38
	v_fma_f32 v39, -v51, v108, v39
	v_cvt_pk_bf16_f32 v2, v12, v13
	v_cvt_pk_bf16_f32 v3, v22, v23
	global_store_dwordx2 v222, v[2:3], s[54:55]
	s_add_u32 s56, s2, 0x8000
	s_addc_u32 s57, s3, 0
	global_load_dwordx4 v[44:47], v0, s[56:57]
	s_cmp_eq_u32 s58, 0
	s_cselect_b32 s31, 0, 0xffff9000
	s_cselect_b32 s32, 0, -1
	s_add_u32 s70, s2, s31
	s_addc_u32 s71, s3, s32
	global_load_dwordx4 v[48:51], v0, s[70:71]
	s_mov_b32 s32, 0x3f000000
	s_cmp_eq_u32 s58, 0
	s_cselect_b32 s32, s32, s59
	s_add_u32 s74, s12, 0x880
	s_addc_u32 s75, s13, 0
	s_waitcnt vmcnt(16)
	v_mul_f32_e32 v212, v52, v124
	v_mul_f32_e32 v213, v53, v124
	v_mul_f32_e32 v214, v54, v124
	v_mul_f32_e32 v215, v55, v124
	v_fmac_f32_e32 v36, v52, v124
	v_fmac_f32_e32 v37, v53, v124
	v_fmac_f32_e32 v38, v54, v124
	v_fmac_f32_e32 v39, v55, v124
	v_fma_f32 v12, v36, s32, -v212
	v_fma_f32 v13, v37, s32, -v213
	v_fma_f32 v22, v38, s32, -v214
	v_fma_f32 v23, v39, s32, -v215
	s_waitcnt vmcnt(15)
	v_fma_f32 v36, -v56, v109, v36
	v_fma_f32 v37, -v57, v109, v37
	v_fma_f32 v38, -v58, v109, v38
	v_fma_f32 v39, -v59, v109, v39
	v_cvt_pk_bf16_f32 v208, v12, v13
	v_cvt_pk_bf16_f32 v209, v22, v23
	global_store_dwordx2 v222, v[208:209], s[74:75]
	s_add_u32 s14, s2, 0x9000
	s_addc_u32 s15, s3, 0
	global_load_dwordx4 v[52:55], v0, s[14:15]
	s_cmp_eq_u32 s58, 0
	s_cselect_b32 s31, 0, 0xffffa000
	s_cselect_b32 s32, 0, -1
	s_add_u32 s56, s2, s31
	s_addc_u32 s57, s3, s32
	global_load_dwordx4 v[56:59], v0, s[56:57]
	s_mov_b32 s32, 0x3eaaaaab
	s_cmp_eq_u32 s58, 0
	s_cselect_b32 s32, s32, s59
	s_add_u32 s54, s12, 0x1100
	s_addc_u32 s55, s13, 0
	s_waitcnt vmcnt(17)
	v_mul_f32_e32 v212, v60, v125
	v_mul_f32_e32 v213, v61, v125
	v_mul_f32_e32 v214, v62, v125
	v_mul_f32_e32 v215, v63, v125
	v_fmac_f32_e32 v36, v60, v125
	v_fmac_f32_e32 v37, v61, v125
	v_fmac_f32_e32 v38, v62, v125
	v_fmac_f32_e32 v39, v63, v125
	v_fma_f32 v12, v36, s32, -v212
	v_fma_f32 v13, v37, s32, -v213
	v_fma_f32 v22, v38, s32, -v214
	v_fma_f32 v23, v39, s32, -v215
	s_waitcnt vmcnt(16)
	v_fma_f32 v36, -v64, v110, v36
	v_fma_f32 v37, -v65, v110, v37
	v_fma_f32 v38, -v66, v110, v38
	v_fma_f32 v39, -v67, v110, v39
	v_cvt_pk_bf16_f32 v2, v12, v13
	v_cvt_pk_bf16_f32 v3, v22, v23
	global_store_dwordx2 v222, v[2:3], s[54:55]
	s_add_u32 s70, s2, 0xa000
	s_addc_u32 s71, s3, 0
	global_load_dwordx4 v[60:63], v0, s[70:71]
	s_cmp_eq_u32 s58, 0
	s_cselect_b32 s31, 0, 0xffffb000
	s_cselect_b32 s32, 0, -1
	s_add_u32 s14, s2, s31
	s_addc_u32 s15, s3, s32
	global_load_dwordx4 v[64:67], v0, s[14:15]
	s_mov_b32 s32, 0x3e800000
	s_cmp_eq_u32 s58, 0
	s_cselect_b32 s32, s32, s59
	s_add_u32 s74, s12, 0x1980
	s_addc_u32 s75, s13, 0
	s_waitcnt vmcnt(18)
	v_mul_f32_e32 v212, v68, v126
	v_mul_f32_e32 v213, v69, v126
	v_mul_f32_e32 v214, v70, v126
	v_mul_f32_e32 v215, v71, v126
	v_fmac_f32_e32 v36, v68, v126
	v_fmac_f32_e32 v37, v69, v126
	v_fmac_f32_e32 v38, v70, v126
	v_fmac_f32_e32 v39, v71, v126
	v_fma_f32 v12, v36, s32, -v212
	v_fma_f32 v13, v37, s32, -v213
	v_fma_f32 v22, v38, s32, -v214
	v_fma_f32 v23, v39, s32, -v215
	s_waitcnt vmcnt(17)
; DI unsigned pack_bf16(float lo, float hi) { f32x2 v = {lo, hi}; bf16v2 b = __builtin_convertvector(v, bf16v2); return __builtin_bit_cast(unsigned, b); }
; template <int W>
; DI void pool_rows(const float* __restrict__ x, const float* smr, bf16_t* __restrict__ pb, int t0, int s0, int tid) {
;     ...
; #pragma unroll 8
;   for (int tl = 0; tl < 64; ++tl) {
;     const int t = t0 + tl, s = s0 + tl;
;     int to = t - W + 1; if (to < tq0) to = tq0;
;     const f32x4 hn = *(const f32x4*)(xq + (size_t)t * D) * smr[15 + tl];
;     const f32x4 ho = *(const f32x4*)(xq + (size_t)to * D) * smr[15 + tl - W + 1];
;     const int cnt = (s + 1 < W) ? (s + 1) : W;
;     const float ic = 1.f / (float)cnt;
;     Sm += hn;
;     const f32x4 p = Sm * ic - hn;
;     Sm -= ho;
;     u32x2 o; o.x = pack_bf16(p.x, p.y); o.y = pack_bf16(p.z, p.w);
;     *(u32x2*)(pb + (size_t)t * LDH + tid * 4) = o;
;   }
	v_fma_f32 v36, -v72, v111, v36
	v_fma_f32 v37, -v73, v111, v37
	v_fma_f32 v38, -v74, v111, v38
	v_fma_f32 v39, -v75, v111, v39
	v_cvt_pk_bf16_f32 v208, v12, v13
	v_cvt_pk_bf16_f32 v209, v22, v23
	global_store_dwordx2 v222, v[208:209], s[74:75]
	s_add_u32 s56, s2, 0xb000
	s_addc_u32 s57, s3, 0
	global_load_dwordx4 v[68:71], v0, s[56:57]
	s_cmp_eq_u32 s58, 0
	s_cselect_b32 s31, 0, 0xffffc000
	s_cselect_b32 s32, 0, -1
	s_add_u32 s70, s2, s31
	s_addc_u32 s71, s3, s32
	global_load_dwordx4 v[72:75], v0, s[70:71]
	s_mov_b32 s32, 0x3e4ccccd
	s_cmp_eq_u32 s58, 0
	s_cselect_b32 s32, s32, s59
	s_add_u32 s54, s12, 0x2200
	s_addc_u32 s55, s13, 0
	s_waitcnt vmcnt(19)
	v_mul_f32_e32 v212, v76, v127
	v_mul_f32_e32 v213, v77, v127
	v_mul_f32_e32 v214, v78, v127
	v_mul_f32_e32 v215, v79, v127
	v_fmac_f32_e32 v36, v76, v127
	v_fmac_f32_e32 v37, v77, v127
	v_fmac_f32_e32 v38, v78, v127
	v_fmac_f32_e32 v39, v79, v127
	v_fma_f32 v12, v36, s32, -v212
	v_fma_f32 v13, v37, s32, -v213
	v_fma_f32 v22, v38, s32, -v214
	v_fma_f32 v23, v39, s32, -v215
	s_waitcnt vmcnt(18)
	v_fma_f32 v36, -v80, v112, v36
	v_fma_f32 v37, -v81, v112, v37
	v_fma_f32 v38, -v82, v112, v38
	v_fma_f32 v39, -v83, v112, v39
	v_cvt_pk_bf16_f32 v2, v12, v13
	v_cvt_pk_bf16_f32 v3, v22, v23
	global_store_dwordx2 v222, v[2:3], s[54:55]
	s_add_u32 s14, s2, 0xc000
	s_addc_u32 s15, s3, 0
	global_load_dwordx4 v[76:79], v0, s[14:15]
	s_cmp_eq_u32 s58, 0
	s_cselect_b32 s31, 0, 0xffffd000
	s_cselect_b32 s32, 0, -1
	s_add_u32 s56, s2, s31
	s_addc_u32 s57, s3, s32
	global_load_dwordx4 v[80:83], v0, s[56:57]
	s_mov_b32 s32, 0x3e2aaaab
	s_cmp_eq_u32 s58, 0
	s_cselect_b32 s32, s32, s59
	s_add_u32 s74, s12, 0x2a80
	s_addc_u32 s75, s13, 0
	s_waitcnt vmcnt(20)
	v_mul_f32_e32 v212, v84, v128
	v_mul_f32_e32 v213, v85, v128
	v_mul_f32_e32 v214, v86, v128
	v_mul_f32_e32 v215, v87, v128
	v_fmac_f32_e32 v36, v84, v128
	v_fmac_f32_e32 v37, v85, v128
	v_fmac_f32_e32 v38, v86, v128
	v_fmac_f32_e32 v39, v87, v128
	v_fma_f32 v12, v36, s32, -v212
	v_fma_f32 v13, v37, s32, -v213
	v_fma_f32 v22, v38, s32, -v214
	v_fma_f32 v23, v39, s32, -v215
	s_waitcnt vmcnt(19)
	v_fma_f32 v36, -v88, v113, v36
	v_fma_f32 v37, -v89, v113, v37
	v_fma_f32 v38, -v90, v113, v38
	v_fma_f32 v39, -v91, v113, v39
	v_cvt_pk_bf16_f32 v208, v12, v13
	v_cvt_pk_bf16_f32 v209, v22, v23
	global_store_dwordx2 v222, v[208:209], s[74:75]
	s_add_u32 s70, s2, 0xd000
	s_addc_u32 s71, s3, 0
	global_load_dwordx4 v[84:87], v0, s[70:71]
	s_cmp_eq_u32 s58, 0
	s_cselect_b32 s31, 0, 0xffffe000
	s_cselect_b32 s32, 0, -1
	s_add_u32 s14, s2, s31
	s_addc_u32 s15, s3, s32
	global_load_dwordx4 v[88:91], v0, s[14:15]
	s_mov_b32 s32, 0x3e124925
	s_cmp_eq_u32 s58, 0
	s_cselect_b32 s32, s32, s59
	s_add_u32 s54, s12, 0x3300
	s_addc_u32 s55, s13, 0
	s_waitcnt vmcnt(21)
	v_mul_f32_e32 v212, v92, v129
	v_mul_f32_e32 v213, v93, v129
	v_mul_f32_e32 v214, v94, v129
	v_mul_f32_e32 v215, v95, v129
	v_fmac_f32_e32 v36, v92, v129
	v_fmac_f32_e32 v37, v93, v129
	v_fmac_f32_e32 v38, v94, v129
	v_fmac_f32_e32 v39, v95, v129
	v_fma_f32 v12, v36, s32, -v212
	v_fma_f32 v13, v37, s32, -v213
	v_fma_f32 v22, v38, s32, -v214
	v_fma_f32 v23, v39, s32, -v215
	s_waitcnt vmcnt(20)
	v_fma_f32 v36, -v96, v114, v36
	v_fma_f32 v37, -v97, v114, v37
	v_fma_f32 v38, -v98, v114, v38
	v_fma_f32 v39, -v99, v114, v39
	v_cvt_pk_bf16_f32 v2, v12, v13
	v_cvt_pk_bf16_f32 v3, v22, v23
	global_store_dwordx2 v222, v[2:3], s[54:55]
	s_add_u32 s56, s2, 0xe000
	s_addc_u32 s57, s3, 0
	global_load_dwordx4 v[92:95], v0, s[56:57]
	s_cmp_eq_u32 s58, 0
	s_cselect_b32 s31, 0, 0xfffff000
	s_cselect_b32 s32, 0, -1
	s_add_u32 s70, s2, s31
	s_addc_u32 s71, s3, s32
	global_load_dwordx4 v[96:99], v0, s[70:71]
	s_mov_b32 s32, 0x3e000000
	s_cmp_eq_u32 s58, 0
	s_cselect_b32 s32, s32, s59
	s_add_u32 s74, s12, 0x3b80
	s_addc_u32 s75, s13, 0
	s_waitcnt vmcnt(22)
	v_mul_f32_e32 v212, v100, v130
	v_mul_f32_e32 v213, v101, v130
	v_mul_f32_e32 v214, v102, v130
	v_mul_f32_e32 v215, v103, v130
	v_fmac_f32_e32 v36, v100, v130
	v_fmac_f32_e32 v37, v101, v130
	v_fmac_f32_e32 v38, v102, v130
	v_fmac_f32_e32 v39, v103, v130
	v_fma_f32 v12, v36, s32, -v212
	v_fma_f32 v13, v37, s32, -v213
	v_fma_f32 v22, v38, s32, -v214
	v_fma_f32 v23, v39, s32, -v215
	s_waitcnt vmcnt(21)
	v_fma_f32 v36, -v104, v115, v36
	v_fma_f32 v37, -v105, v115, v37
	v_fma_f32 v38, -v106, v115, v38
	v_fma_f32 v39, -v107, v115, v39
	v_cvt_pk_bf16_f32 v208, v12, v13
	v_cvt_pk_bf16_f32 v209, v22, v23
	global_store_dwordx2 v222, v[208:209], s[74:75]
	s_add_u32 s14, s2, 0xf000
	s_addc_u32 s15, s3, 0
	global_load_dwordx4 v[100:103], v0, s[14:15]
	s_mov_b32 s56, s2
	s_mov_b32 s57, s3
	global_load_dwordx4 v[104:107], v0, s[56:57]
	s_mov_b32 s32, 0x3de38e39
	s_cmp_eq_u32 s58, 0
	s_cselect_b32 s32, s32, s59
	s_add_u32 s54, s12, 0x4400
	s_addc_u32 s55, s13, 0
	s_waitcnt vmcnt(22)
	v_mul_f32_e32 v212, v44, v131
	v_mul_f32_e32 v213, v45, v131
	v_mul_f32_e32 v214, v46, v131
	v_mul_f32_e32 v215, v47, v131
	v_fmac_f32_e32 v36, v44, v131
	v_fmac_f32_e32 v37, v45, v131
	v_fmac_f32_e32 v38, v46, v131
	v_fmac_f32_e32 v39, v47, v131
	v_fma_f32 v12, v36, s32, -v212
	v_fma_f32 v13, v37, s32, -v213
	v_fma_f32 v22, v38, s32, -v214
	v_fma_f32 v23, v39, s32, -v215
	s_waitcnt vmcnt(21)
	v_fma_f32 v36, -v48, v116, v36
	v_fma_f32 v37, -v49, v116, v37
	v_fma_f32 v38, -v50, v116, v38
	v_fma_f32 v39, -v51, v116, v39
	v_cvt_pk_bf16_f32 v2, v12, v13
	v_cvt_pk_bf16_f32 v3, v22, v23
	global_store_dwordx2 v222, v[2:3], s[54:55]
	s_add_u32 s70, s2, 0x10000
	s_addc_u32 s71, s3, 0
	global_load_dwordx4 v[44:47], v0, s[70:71]
	s_add_u32 s14, s2, 0x1000
	s_addc_u32 s15, s3, 0
	global_load_dwordx4 v[48:51], v0, s[14:15]
	s_mov_b32 s32, 0x3dcccccd
	s_cmp_eq_u32 s58, 0
	s_cselect_b32 s32, s32, s59
	s_add_u32 s74, s12, 0x4c80
	s_addc_u32 s75, s13, 0
	s_waitcnt vmcnt(22)
; DI unsigned pack_bf16(float lo, float hi) { f32x2 v = {lo, hi}; bf16v2 b = __builtin_convertvector(v, bf16v2); return __builtin_bit_cast(unsigned, b); }
; template <int W>
; DI void pool_rows(const float* __restrict__ x, const float* smr, bf16_t* __restrict__ pb, int t0, int s0, int tid) {
;     ...
; #pragma unroll 8
;   for (int tl = 0; tl < 64; ++tl) {
;     const int t = t0 + tl, s = s0 + tl;
;     int to = t - W + 1; if (to < tq0) to = tq0;
;     const f32x4 hn = *(const f32x4*)(xq + (size_t)t * D) * smr[15 + tl];
;     const f32x4 ho = *(const f32x4*)(xq + (size_t)to * D) * smr[15 + tl - W + 1];
;     const int cnt = (s + 1 < W) ? (s + 1) : W;
;     const float ic = 1.f / (float)cnt;
;     Sm += hn;
;     const f32x4 p = Sm * ic - hn;
;     Sm -= ho;
;     u32x2 o; o.x = pack_bf16(p.x, p.y); o.y = pack_bf16(p.z, p.w);
;     *(u32x2*)(pb + (size_t)t * LDH + tid * 4) = o;
;   }
	v_mul_f32_e32 v212, v52, v132
	v_mul_f32_e32 v213, v53, v132
	v_mul_f32_e32 v214, v54, v132
	v_mul_f32_e32 v215, v55, v132
	v_fmac_f32_e32 v36, v52, v132
	v_fmac_f32_e32 v37, v53, v132
	v_fmac_f32_e32 v38, v54, v132
	v_fmac_f32_e32 v39, v55, v132
	v_fma_f32 v12, v36, s32, -v212
	v_fma_f32 v13, v37, s32, -v213
	v_fma_f32 v22, v38, s32, -v214
	v_fma_f32 v23, v39, s32, -v215
	s_waitcnt vmcnt(21)
	v_fma_f32 v36, -v56, v117, v36
	v_fma_f32 v37, -v57, v117, v37
	v_fma_f32 v38, -v58, v117, v38
	v_fma_f32 v39, -v59, v117, v39
	v_cvt_pk_bf16_f32 v208, v12, v13
	v_cvt_pk_bf16_f32 v209, v22, v23
	global_store_dwordx2 v222, v[208:209], s[74:75]
	s_add_u32 s56, s2, 0x11000
	s_addc_u32 s57, s3, 0
	global_load_dwordx4 v[52:55], v0, s[56:57]
	s_add_u32 s70, s2, 0x2000
	s_addc_u32 s71, s3, 0
	global_load_dwordx4 v[56:59], v0, s[70:71]
	s_mov_b32 s32, 0x3dba2e8c
	s_cmp_eq_u32 s58, 0
	s_cselect_b32 s32, s32, s59
	s_add_u32 s54, s12, 0x5500
	s_addc_u32 s55, s13, 0
	s_waitcnt vmcnt(22)
	v_mul_f32_e32 v212, v60, v133
	v_mul_f32_e32 v213, v61, v133
	v_mul_f32_e32 v214, v62, v133
	v_mul_f32_e32 v215, v63, v133
	v_fmac_f32_e32 v36, v60, v133
	v_fmac_f32_e32 v37, v61, v133
	v_fmac_f32_e32 v38, v62, v133
	v_fmac_f32_e32 v39, v63, v133
	v_fma_f32 v12, v36, s32, -v212
	v_fma_f32 v13, v37, s32, -v213
	v_fma_f32 v22, v38, s32, -v214
	v_fma_f32 v23, v39, s32, -v215
	s_waitcnt vmcnt(21)
	v_fma_f32 v36, -v64, v118, v36
	v_fma_f32 v37, -v65, v118, v37
	v_fma_f32 v38, -v66, v118, v38
	v_fma_f32 v39, -v67, v118, v39
	v_cvt_pk_bf16_f32 v2, v12, v13
	v_cvt_pk_bf16_f32 v3, v22, v23
	global_store_dwordx2 v222, v[2:3], s[54:55]
	s_add_u32 s14, s2, 0x12000
	s_addc_u32 s15, s3, 0
	global_load_dwordx4 v[60:63], v0, s[14:15]
	s_add_u32 s56, s2, 0x3000
	s_addc_u32 s57, s3, 0
	global_load_dwordx4 v[64:67], v0, s[56:57]
	s_mov_b32 s32, 0x3daaaaab
	s_cmp_eq_u32 s58, 0
	s_cselect_b32 s32, s32, s59
	s_add_u32 s74, s12, 0x5d80
	s_addc_u32 s75, s13, 0
	s_waitcnt vmcnt(22)
	v_mul_f32_e32 v212, v68, v134
	v_mul_f32_e32 v213, v69, v134
	v_mul_f32_e32 v214, v70, v134
	v_mul_f32_e32 v215, v71, v134
	v_fmac_f32_e32 v36, v68, v134
	v_fmac_f32_e32 v37, v69, v134
	v_fmac_f32_e32 v38, v70, v134
	v_fmac_f32_e32 v39, v71, v134
	v_fma_f32 v12, v36, s32, -v212
	v_fma_f32 v13, v37, s32, -v213
	v_fma_f32 v22, v38, s32, -v214
	v_fma_f32 v23, v39, s32, -v215
	s_waitcnt vmcnt(21)
	v_fma_f32 v36, -v72, v119, v36
	v_fma_f32 v37, -v73, v119, v37
	v_fma_f32 v38, -v74, v119, v38
	v_fma_f32 v39, -v75, v119, v39
	v_cvt_pk_bf16_f32 v208, v12, v13
	v_cvt_pk_bf16_f32 v209, v22, v23
	global_store_dwordx2 v222, v[208:209], s[74:75]
	s_add_u32 s70, s2, 0x13000
	s_addc_u32 s71, s3, 0
	global_load_dwordx4 v[68:71], v0, s[70:71]
	s_add_u32 s14, s2, 0x4000
	s_addc_u32 s15, s3, 0
	global_load_dwordx4 v[72:75], v0, s[14:15]
	s_mov_b32 s32, 0x3d9d89d9
	s_cmp_eq_u32 s58, 0
	s_cselect_b32 s32, s32, s59
	s_add_u32 s54, s12, 0x6600
	s_addc_u32 s55, s13, 0
	s_waitcnt vmcnt(22)
	v_mul_f32_e32 v212, v76, v135
	v_mul_f32_e32 v213, v77, v135
	v_mul_f32_e32 v214, v78, v135
	v_mul_f32_e32 v215, v79, v135
	v_fmac_f32_e32 v36, v76, v135
	v_fmac_f32_e32 v37, v77, v135
	v_fmac_f32_e32 v38, v78, v135
	v_fmac_f32_e32 v39, v79, v135
	v_fma_f32 v12, v36, s32, -v212
	v_fma_f32 v13, v37, s32, -v213
	v_fma_f32 v22, v38, s32, -v214
	v_fma_f32 v23, v39, s32, -v215
	s_waitcnt vmcnt(21)
	v_fma_f32 v36, -v80, v120, v36
	v_fma_f32 v37, -v81, v120, v37
	v_fma_f32 v38, -v82, v120, v38
	v_fma_f32 v39, -v83, v120, v39
	v_cvt_pk_bf16_f32 v2, v12, v13
	v_cvt_pk_bf16_f32 v3, v22, v23
	global_store_dwordx2 v222, v[2:3], s[54:55]
	s_add_u32 s56, s2, 0x14000
	s_addc_u32 s57, s3, 0
	global_load_dwordx4 v[76:79], v0, s[56:57]
	s_add_u32 s70, s2, 0x5000
	s_addc_u32 s71, s3, 0
	global_load_dwordx4 v[80:83], v0, s[70:71]
	s_mov_b32 s32, 0x3d924925
	s_cmp_eq_u32 s58, 0
	s_cselect_b32 s32, s32, s59
	s_add_u32 s74, s12, 0x6e80
	s_addc_u32 s75, s13, 0
	s_waitcnt vmcnt(22)
	v_mul_f32_e32 v212, v84, v136
	v_mul_f32_e32 v213, v85, v136
	v_mul_f32_e32 v214, v86, v136
	v_mul_f32_e32 v215, v87, v136
	v_fmac_f32_e32 v36, v84, v136
	v_fmac_f32_e32 v37, v85, v136
	v_fmac_f32_e32 v38, v86, v136
	v_fmac_f32_e32 v39, v87, v136
	v_fma_f32 v12, v36, s32, -v212
	v_fma_f32 v13, v37, s32, -v213
	v_fma_f32 v22, v38, s32, -v214
	v_fma_f32 v23, v39, s32, -v215
	s_waitcnt vmcnt(21)
	v_fma_f32 v36, -v88, v121, v36
	v_fma_f32 v37, -v89, v121, v37
	v_fma_f32 v38, -v90, v121, v38
	v_fma_f32 v39, -v91, v121, v39
	v_cvt_pk_bf16_f32 v208, v12, v13
	v_cvt_pk_bf16_f32 v209, v22, v23
	global_store_dwordx2 v222, v[208:209], s[74:75]
	s_add_u32 s14, s2, 0x15000
	s_addc_u32 s15, s3, 0
	global_load_dwordx4 v[84:87], v0, s[14:15]
	s_add_u32 s56, s2, 0x6000
	s_addc_u32 s57, s3, 0
	global_load_dwordx4 v[88:91], v0, s[56:57]
	s_mov_b32 s32, 0x3d888889
	s_cmp_eq_u32 s58, 0
	s_cselect_b32 s32, s32, s59
	s_add_u32 s54, s12, 0x7700
	s_addc_u32 s55, s13, 0
	s_waitcnt vmcnt(22)
	v_mul_f32_e32 v212, v92, v137
	v_mul_f32_e32 v213, v93, v137
	v_mul_f32_e32 v214, v94, v137
	v_mul_f32_e32 v215, v95, v137
	v_fmac_f32_e32 v36, v92, v137
	v_fmac_f32_e32 v37, v93, v137
	v_fmac_f32_e32 v38, v94, v137
	v_fmac_f32_e32 v39, v95, v137
	v_fma_f32 v12, v36, s32, -v212
	v_fma_f32 v13, v37, s32, -v213
	v_fma_f32 v22, v38, s32, -v214
	v_fma_f32 v23, v39, s32, -v215
	s_waitcnt vmcnt(21)
	v_fma_f32 v36, -v96, v122, v36
	v_fma_f32 v37, -v97, v122, v37
	v_fma_f32 v38, -v98, v122, v38
	v_fma_f32 v39, -v99, v122, v39
	v_cvt_pk_bf16_f32 v2, v12, v13
	v_cvt_pk_bf16_f32 v3, v22, v23
	global_store_dwordx2 v222, v[2:3], s[54:55]
	s_add_u32 s70, s2, 0x16000
	s_addc_u32 s71, s3, 0
	global_load_dwordx4 v[92:95], v0, s[70:71]
	s_add_u32 s14, s2, 0x7000
	s_addc_u32 s15, s3, 0
	global_load_dwordx4 v[96:99], v0, s[14:15]
	s_add_u32 s74, s12, 0x7f80
	s_addc_u32 s75, s13, 0
	s_waitcnt vmcnt(22)
; DI unsigned pack_bf16(float lo, float hi) { f32x2 v = {lo, hi}; bf16v2 b = __builtin_convertvector(v, bf16v2); return __builtin_bit_cast(unsigned, b); }
; template <int W>
; DI void pool_rows(const float* __restrict__ x, const float* smr, bf16_t* __restrict__ pb, int t0, int s0, int tid) {
;     ...
; #pragma unroll 8
;   for (int tl = 0; tl < 64; ++tl) {
;     const int t = t0 + tl, s = s0 + tl;
;     int to = t - W + 1; if (to < tq0) to = tq0;
;     const f32x4 hn = *(const f32x4*)(xq + (size_t)t * D) * smr[15 + tl];
;     const f32x4 ho = *(const f32x4*)(xq + (size_t)to * D) * smr[15 + tl - W + 1];
;     const int cnt = (s + 1 < W) ? (s + 1) : W;
;     const float ic = 1.f / (float)cnt;
;     Sm += hn;
;     const f32x4 p = Sm * ic - hn;
;     Sm -= ho;
;     u32x2 o; o.x = pack_bf16(p.x, p.y); o.y = pack_bf16(p.z, p.w);
;     *(u32x2*)(pb + (size_t)t * LDH + tid * 4) = o;
;   }
	v_mul_f32_e32 v212, v100, v138
	v_mul_f32_e32 v213, v101, v138
	v_mul_f32_e32 v214, v102, v138
	v_mul_f32_e32 v215, v103, v138
	v_fmac_f32_e32 v36, v100, v138
	v_fmac_f32_e32 v37, v101, v138
	v_fmac_f32_e32 v38, v102, v138
	v_fmac_f32_e32 v39, v103, v138
	v_fma_f32 v12, v36, s59, -v212
	v_fma_f32 v13, v37, s59, -v213
	v_fma_f32 v22, v38, s59, -v214
	v_fma_f32 v23, v39, s59, -v215
	s_waitcnt vmcnt(21)
	v_fma_f32 v36, -v104, v123, v36
	v_fma_f32 v37, -v105, v123, v37
	v_fma_f32 v38, -v106, v123, v38
	v_fma_f32 v39, -v107, v123, v39
	v_cvt_pk_bf16_f32 v208, v12, v13
	v_cvt_pk_bf16_f32 v209, v22, v23
	global_store_dwordx2 v222, v[208:209], s[74:75]
	s_add_u32 s56, s2, 0x17000
	s_addc_u32 s57, s3, 0
	global_load_dwordx4 v[100:103], v0, s[56:57]
	s_add_u32 s70, s2, 0x8000
	s_addc_u32 s71, s3, 0
	global_load_dwordx4 v[104:107], v0, s[70:71]
	s_add_u32 s54, s12, 0x8800
	s_addc_u32 s55, s13, 0
	s_waitcnt vmcnt(22)
	v_mul_f32_e32 v212, v44, v139
	v_mul_f32_e32 v213, v45, v139
	v_mul_f32_e32 v214, v46, v139
	v_mul_f32_e32 v215, v47, v139
	v_fmac_f32_e32 v36, v44, v139
	v_fmac_f32_e32 v37, v45, v139
	v_fmac_f32_e32 v38, v46, v139
	v_fmac_f32_e32 v39, v47, v139
	v_fma_f32 v12, v36, s59, -v212
	v_fma_f32 v13, v37, s59, -v213
	v_fma_f32 v22, v38, s59, -v214
	v_fma_f32 v23, v39, s59, -v215
	s_waitcnt vmcnt(21)
	v_fma_f32 v36, -v48, v124, v36
	v_fma_f32 v37, -v49, v124, v37
	v_fma_f32 v38, -v50, v124, v38
	v_fma_f32 v39, -v51, v124, v39
	v_cvt_pk_bf16_f32 v2, v12, v13
	v_cvt_pk_bf16_f32 v3, v22, v23
	global_store_dwordx2 v222, v[2:3], s[54:55]
	s_add_u32 s14, s2, 0x18000
	s_addc_u32 s15, s3, 0
	global_load_dwordx4 v[44:47], v0, s[14:15]
	s_add_u32 s56, s2, 0x9000
	s_addc_u32 s57, s3, 0
	global_load_dwordx4 v[48:51], v0, s[56:57]
	s_add_u32 s74, s12, 0x9080
	s_addc_u32 s75, s13, 0
	s_waitcnt vmcnt(22)
	v_mul_f32_e32 v212, v52, v140
	v_mul_f32_e32 v213, v53, v140
	v_mul_f32_e32 v214, v54, v140
	v_mul_f32_e32 v215, v55, v140
	v_fmac_f32_e32 v36, v52, v140
	v_fmac_f32_e32 v37, v53, v140
	v_fmac_f32_e32 v38, v54, v140
	v_fmac_f32_e32 v39, v55, v140
	v_fma_f32 v12, v36, s59, -v212
	v_fma_f32 v13, v37, s59, -v213
	v_fma_f32 v22, v38, s59, -v214
	v_fma_f32 v23, v39, s59, -v215
	s_waitcnt vmcnt(21)
	v_fma_f32 v36, -v56, v125, v36
	v_fma_f32 v37, -v57, v125, v37
	v_fma_f32 v38, -v58, v125, v38
	v_fma_f32 v39, -v59, v125, v39
	v_cvt_pk_bf16_f32 v208, v12, v13
	v_cvt_pk_bf16_f32 v209, v22, v23
	global_store_dwordx2 v222, v[208:209], s[74:75]
	s_add_u32 s70, s2, 0x19000
	s_addc_u32 s71, s3, 0
	global_load_dwordx4 v[52:55], v0, s[70:71]
	s_add_u32 s14, s2, 0xa000
	s_addc_u32 s15, s3, 0
	global_load_dwordx4 v[56:59], v0, s[14:15]
	s_add_u32 s54, s12, 0x9900
	s_addc_u32 s55, s13, 0
	s_waitcnt vmcnt(22)
	v_mul_f32_e32 v212, v60, v141
	v_mul_f32_e32 v213, v61, v141
	v_mul_f32_e32 v214, v62, v141
	v_mul_f32_e32 v215, v63, v141
	v_fmac_f32_e32 v36, v60, v141
	v_fmac_f32_e32 v37, v61, v141
	v_fmac_f32_e32 v38, v62, v141
	v_fmac_f32_e32 v39, v63, v141
	v_fma_f32 v12, v36, s59, -v212
	v_fma_f32 v13, v37, s59, -v213
	v_fma_f32 v22, v38, s59, -v214
	v_fma_f32 v23, v39, s59, -v215
	s_waitcnt vmcnt(21)
	v_fma_f32 v36, -v64, v126, v36
	v_fma_f32 v37, -v65, v126, v37
	v_fma_f32 v38, -v66, v126, v38
	v_fma_f32 v39, -v67, v126, v39
	v_cvt_pk_bf16_f32 v2, v12, v13
	v_cvt_pk_bf16_f32 v3, v22, v23
	global_store_dwordx2 v222, v[2:3], s[54:55]
	s_add_u32 s56, s2, 0x1a000
	s_addc_u32 s57, s3, 0
	global_load_dwordx4 v[60:63], v0, s[56:57]
	s_add_u32 s70, s2, 0xb000
	s_addc_u32 s71, s3, 0
	global_load_dwordx4 v[64:67], v0, s[70:71]
	s_add_u32 s74, s12, 0xa180
	s_addc_u32 s75, s13, 0
	s_waitcnt vmcnt(22)
	v_mul_f32_e32 v212, v68, v142
	v_mul_f32_e32 v213, v69, v142
	v_mul_f32_e32 v214, v70, v142
	v_mul_f32_e32 v215, v71, v142
	v_fmac_f32_e32 v36, v68, v142
	v_fmac_f32_e32 v37, v69, v142
	v_fmac_f32_e32 v38, v70, v142
	v_fmac_f32_e32 v39, v71, v142
	v_fma_f32 v12, v36, s59, -v212
	v_fma_f32 v13, v37, s59, -v213
	v_fma_f32 v22, v38, s59, -v214
	v_fma_f32 v23, v39, s59, -v215
	s_waitcnt vmcnt(21)
	v_fma_f32 v36, -v72, v127, v36
	v_fma_f32 v37, -v73, v127, v37
	v_fma_f32 v38, -v74, v127, v38
	v_fma_f32 v39, -v75, v127, v39
	v_cvt_pk_bf16_f32 v208, v12, v13
	v_cvt_pk_bf16_f32 v209, v22, v23
	global_store_dwordx2 v222, v[208:209], s[74:75]
	s_add_u32 s14, s2, 0x1b000
	s_addc_u32 s15, s3, 0
	global_load_dwordx4 v[68:71], v0, s[14:15]
	s_add_u32 s56, s2, 0xc000
	s_addc_u32 s57, s3, 0
	global_load_dwordx4 v[72:75], v0, s[56:57]
	s_add_u32 s54, s12, 0xaa00
	s_addc_u32 s55, s13, 0
	s_waitcnt vmcnt(22)
	v_mul_f32_e32 v212, v76, v143
	v_mul_f32_e32 v213, v77, v143
	v_mul_f32_e32 v214, v78, v143
	v_mul_f32_e32 v215, v79, v143
	v_fmac_f32_e32 v36, v76, v143
	v_fmac_f32_e32 v37, v77, v143
	v_fmac_f32_e32 v38, v78, v143
	v_fmac_f32_e32 v39, v79, v143
	v_fma_f32 v12, v36, s59, -v212
	v_fma_f32 v13, v37, s59, -v213
	v_fma_f32 v22, v38, s59, -v214
	v_fma_f32 v23, v39, s59, -v215
	s_waitcnt vmcnt(21)
	v_fma_f32 v36, -v80, v128, v36
	v_fma_f32 v37, -v81, v128, v37
	v_fma_f32 v38, -v82, v128, v38
	v_fma_f32 v39, -v83, v128, v39
	v_cvt_pk_bf16_f32 v2, v12, v13
	v_cvt_pk_bf16_f32 v3, v22, v23
	global_store_dwordx2 v222, v[2:3], s[54:55]
	s_add_u32 s70, s2, 0x1c000
	s_addc_u32 s71, s3, 0
	global_load_dwordx4 v[76:79], v0, s[70:71]
	s_add_u32 s14, s2, 0xd000
	s_addc_u32 s15, s3, 0
	global_load_dwordx4 v[80:83], v0, s[14:15]
	s_add_u32 s74, s12, 0xb280
	s_addc_u32 s75, s13, 0
	s_waitcnt vmcnt(22)
	v_mul_f32_e32 v212, v84, v144
	v_mul_f32_e32 v213, v85, v144
	v_mul_f32_e32 v214, v86, v144
	v_mul_f32_e32 v215, v87, v144
	v_fmac_f32_e32 v36, v84, v144
	v_fmac_f32_e32 v37, v85, v144
	v_fmac_f32_e32 v38, v86, v144
	v_fmac_f32_e32 v39, v87, v144
	v_fma_f32 v12, v36, s59, -v212
	v_fma_f32 v13, v37, s59, -v213
	v_fma_f32 v22, v38, s59, -v214
	v_fma_f32 v23, v39, s59, -v215
	s_waitcnt vmcnt(21)
; DI unsigned pack_bf16(float lo, float hi) { f32x2 v = {lo, hi}; bf16v2 b = __builtin_convertvector(v, bf16v2); return __builtin_bit_cast(unsigned, b); }
; template <int W>
; DI void pool_rows(const float* __restrict__ x, const float* smr, bf16_t* __restrict__ pb, int t0, int s0, int tid) {
;     ...
; #pragma unroll 8
;   for (int tl = 0; tl < 64; ++tl) {
;     const int t = t0 + tl, s = s0 + tl;
;     int to = t - W + 1; if (to < tq0) to = tq0;
;     const f32x4 hn = *(const f32x4*)(xq + (size_t)t * D) * smr[15 + tl];
;     const f32x4 ho = *(const f32x4*)(xq + (size_t)to * D) * smr[15 + tl - W + 1];
;     const int cnt = (s + 1 < W) ? (s + 1) : W;
;     const float ic = 1.f / (float)cnt;
;     Sm += hn;
;     const f32x4 p = Sm * ic - hn;
;     Sm -= ho;
;     u32x2 o; o.x = pack_bf16(p.x, p.y); o.y = pack_bf16(p.z, p.w);
;     *(u32x2*)(pb + (size_t)t * LDH + tid * 4) = o;
;   }
	v_fma_f32 v36, -v88, v129, v36
	v_fma_f32 v37, -v89, v129, v37
	v_fma_f32 v38, -v90, v129, v38
	v_fma_f32 v39, -v91, v129, v39
	v_cvt_pk_bf16_f32 v208, v12, v13
	v_cvt_pk_bf16_f32 v209, v22, v23
	global_store_dwordx2 v222, v[208:209], s[74:75]
	s_add_u32 s56, s2, 0x1d000
	s_addc_u32 s57, s3, 0
	global_load_dwordx4 v[84:87], v0, s[56:57]
	s_add_u32 s70, s2, 0xe000
	s_addc_u32 s71, s3, 0
	global_load_dwordx4 v[88:91], v0, s[70:71]
	s_add_u32 s54, s12, 0xbb00
	s_addc_u32 s55, s13, 0
	s_waitcnt vmcnt(22)
	v_mul_f32_e32 v212, v92, v145
	v_mul_f32_e32 v213, v93, v145
	v_mul_f32_e32 v214, v94, v145
	v_mul_f32_e32 v215, v95, v145
	v_fmac_f32_e32 v36, v92, v145
	v_fmac_f32_e32 v37, v93, v145
	v_fmac_f32_e32 v38, v94, v145
	v_fmac_f32_e32 v39, v95, v145
	v_fma_f32 v12, v36, s59, -v212
	v_fma_f32 v13, v37, s59, -v213
	v_fma_f32 v22, v38, s59, -v214
	v_fma_f32 v23, v39, s59, -v215
	s_waitcnt vmcnt(21)
	v_fma_f32 v36, -v96, v130, v36
	v_fma_f32 v37, -v97, v130, v37
	v_fma_f32 v38, -v98, v130, v38
	v_fma_f32 v39, -v99, v130, v39
	v_cvt_pk_bf16_f32 v2, v12, v13
	v_cvt_pk_bf16_f32 v3, v22, v23
	global_store_dwordx2 v222, v[2:3], s[54:55]
	s_add_u32 s14, s2, 0x1e000
	s_addc_u32 s15, s3, 0
	global_load_dwordx4 v[92:95], v0, s[14:15]
	s_add_u32 s56, s2, 0xf000
	s_addc_u32 s57, s3, 0
	global_load_dwordx4 v[96:99], v0, s[56:57]
	s_add_u32 s74, s12, 0xc380
	s_addc_u32 s75, s13, 0
	s_waitcnt vmcnt(22)
	v_mul_f32_e32 v212, v100, v146
	v_mul_f32_e32 v213, v101, v146
	v_mul_f32_e32 v214, v102, v146
	v_mul_f32_e32 v215, v103, v146
	v_fmac_f32_e32 v36, v100, v146
	v_fmac_f32_e32 v37, v101, v146
	v_fmac_f32_e32 v38, v102, v146
	v_fmac_f32_e32 v39, v103, v146
	v_fma_f32 v12, v36, s59, -v212
	v_fma_f32 v13, v37, s59, -v213
	v_fma_f32 v22, v38, s59, -v214
	v_fma_f32 v23, v39, s59, -v215
	s_waitcnt vmcnt(21)
	v_fma_f32 v36, -v104, v131, v36
	v_fma_f32 v37, -v105, v131, v37
	v_fma_f32 v38, -v106, v131, v38
	v_fma_f32 v39, -v107, v131, v39
	v_cvt_pk_bf16_f32 v208, v12, v13
	v_cvt_pk_bf16_f32 v209, v22, v23
	global_store_dwordx2 v222, v[208:209], s[74:75]
	s_add_u32 s70, s2, 0x1f000
	s_addc_u32 s71, s3, 0
	global_load_dwordx4 v[100:103], v0, s[70:71]
	s_add_u32 s14, s2, 0x10000
	s_addc_u32 s15, s3, 0
	global_load_dwordx4 v[104:107], v0, s[14:15]
	s_add_u32 s54, s12, 0xcc00
	s_addc_u32 s55, s13, 0
	s_waitcnt vmcnt(22)
	v_mul_f32_e32 v212, v44, v147
	v_mul_f32_e32 v213, v45, v147
	v_mul_f32_e32 v214, v46, v147
	v_mul_f32_e32 v215, v47, v147
	v_fmac_f32_e32 v36, v44, v147
	v_fmac_f32_e32 v37, v45, v147
	v_fmac_f32_e32 v38, v46, v147
	v_fmac_f32_e32 v39, v47, v147
	v_fma_f32 v12, v36, s59, -v212
	v_fma_f32 v13, v37, s59, -v213
	v_fma_f32 v22, v38, s59, -v214
	v_fma_f32 v23, v39, s59, -v215
	s_waitcnt vmcnt(21)
	v_fma_f32 v36, -v48, v132, v36
	v_fma_f32 v37, -v49, v132, v37
	v_fma_f32 v38, -v50, v132, v38
	v_fma_f32 v39, -v51, v132, v39
	v_cvt_pk_bf16_f32 v2, v12, v13
	v_cvt_pk_bf16_f32 v3, v22, v23
	global_store_dwordx2 v222, v[2:3], s[54:55]
	s_add_u32 s56, s2, 0x20000
	s_addc_u32 s57, s3, 0
	global_load_dwordx4 v[44:47], v0, s[56:57]
	s_add_u32 s70, s2, 0x11000
	s_addc_u32 s71, s3, 0
	global_load_dwordx4 v[48:51], v0, s[70:71]
	s_add_u32 s74, s12, 0xd480
	s_addc_u32 s75, s13, 0
	s_waitcnt vmcnt(22)
	v_mul_f32_e32 v212, v52, v148
	v_mul_f32_e32 v213, v53, v148
	v_mul_f32_e32 v214, v54, v148
	v_mul_f32_e32 v215, v55, v148
	v_fmac_f32_e32 v36, v52, v148
	v_fmac_f32_e32 v37, v53, v148
	v_fmac_f32_e32 v38, v54, v148
	v_fmac_f32_e32 v39, v55, v148
	v_fma_f32 v12, v36, s59, -v212
	v_fma_f32 v13, v37, s59, -v213
	v_fma_f32 v22, v38, s59, -v214
	v_fma_f32 v23, v39, s59, -v215
	s_waitcnt vmcnt(21)
	v_fma_f32 v36, -v56, v133, v36
	v_fma_f32 v37, -v57, v133, v37
	v_fma_f32 v38, -v58, v133, v38
	v_fma_f32 v39, -v59, v133, v39
	v_cvt_pk_bf16_f32 v208, v12, v13
	v_cvt_pk_bf16_f32 v209, v22, v23
	global_store_dwordx2 v222, v[208:209], s[74:75]
	s_add_u32 s14, s2, 0x21000
	s_addc_u32 s15, s3, 0
	global_load_dwordx4 v[52:55], v0, s[14:15]
	s_add_u32 s56, s2, 0x12000
	s_addc_u32 s57, s3, 0
	global_load_dwordx4 v[56:59], v0, s[56:57]
	s_add_u32 s54, s12, 0xdd00
	s_addc_u32 s55, s13, 0
	s_waitcnt vmcnt(22)
	v_mul_f32_e32 v212, v60, v149
	v_mul_f32_e32 v213, v61, v149
	v_mul_f32_e32 v214, v62, v149
	v_mul_f32_e32 v215, v63, v149
	v_fmac_f32_e32 v36, v60, v149
	v_fmac_f32_e32 v37, v61, v149
	v_fmac_f32_e32 v38, v62, v149
	v_fmac_f32_e32 v39, v63, v149
	v_fma_f32 v12, v36, s59, -v212
	v_fma_f32 v13, v37, s59, -v213
	v_fma_f32 v22, v38, s59, -v214
	v_fma_f32 v23, v39, s59, -v215
	s_waitcnt vmcnt(21)
	v_fma_f32 v36, -v64, v134, v36
	v_fma_f32 v37, -v65, v134, v37
	v_fma_f32 v38, -v66, v134, v38
	v_fma_f32 v39, -v67, v134, v39
	v_cvt_pk_bf16_f32 v2, v12, v13
	v_cvt_pk_bf16_f32 v3, v22, v23
	global_store_dwordx2 v222, v[2:3], s[54:55]
	s_add_u32 s70, s2, 0x22000
	s_addc_u32 s71, s3, 0
	global_load_dwordx4 v[60:63], v0, s[70:71]
	s_add_u32 s14, s2, 0x13000
	s_addc_u32 s15, s3, 0
	global_load_dwordx4 v[64:67], v0, s[14:15]
	s_add_u32 s74, s12, 0xe580
	s_addc_u32 s75, s13, 0
	s_waitcnt vmcnt(22)
	v_mul_f32_e32 v212, v68, v150
	v_mul_f32_e32 v213, v69, v150
	v_mul_f32_e32 v214, v70, v150
	v_mul_f32_e32 v215, v71, v150
	v_fmac_f32_e32 v36, v68, v150
	v_fmac_f32_e32 v37, v69, v150
	v_fmac_f32_e32 v38, v70, v150
	v_fmac_f32_e32 v39, v71, v150
	v_fma_f32 v12, v36, s59, -v212
	v_fma_f32 v13, v37, s59, -v213
	v_fma_f32 v22, v38, s59, -v214
	v_fma_f32 v23, v39, s59, -v215
	s_waitcnt vmcnt(21)
; DI unsigned pack_bf16(float lo, float hi) { f32x2 v = {lo, hi}; bf16v2 b = __builtin_convertvector(v, bf16v2); return __builtin_bit_cast(unsigned, b); }
; template <int W>
; DI void pool_rows(const float* __restrict__ x, const float* smr, bf16_t* __restrict__ pb, int t0, int s0, int tid) {
;     ...
; #pragma unroll 8
;   for (int tl = 0; tl < 64; ++tl) {
;     const int t = t0 + tl, s = s0 + tl;
;     int to = t - W + 1; if (to < tq0) to = tq0;
;     const f32x4 hn = *(const f32x4*)(xq + (size_t)t * D) * smr[15 + tl];
;     const f32x4 ho = *(const f32x4*)(xq + (size_t)to * D) * smr[15 + tl - W + 1];
;     const int cnt = (s + 1 < W) ? (s + 1) : W;
;     const float ic = 1.f / (float)cnt;
;     Sm += hn;
;     const f32x4 p = Sm * ic - hn;
;     Sm -= ho;
;     u32x2 o; o.x = pack_bf16(p.x, p.y); o.y = pack_bf16(p.z, p.w);
;     *(u32x2*)(pb + (size_t)t * LDH + tid * 4) = o;
;   }
	v_fma_f32 v36, -v72, v135, v36
	v_fma_f32 v37, -v73, v135, v37
	v_fma_f32 v38, -v74, v135, v38
	v_fma_f32 v39, -v75, v135, v39
	v_cvt_pk_bf16_f32 v208, v12, v13
	v_cvt_pk_bf16_f32 v209, v22, v23
	global_store_dwordx2 v222, v[208:209], s[74:75]
	s_add_u32 s56, s2, 0x23000
	s_addc_u32 s57, s3, 0
	global_load_dwordx4 v[68:71], v0, s[56:57]
	s_add_u32 s70, s2, 0x14000
	s_addc_u32 s71, s3, 0
	global_load_dwordx4 v[72:75], v0, s[70:71]
	s_add_u32 s54, s12, 0xee00
	s_addc_u32 s55, s13, 0
	s_waitcnt vmcnt(22)
	v_mul_f32_e32 v212, v76, v151
	v_mul_f32_e32 v213, v77, v151
	v_mul_f32_e32 v214, v78, v151
	v_mul_f32_e32 v215, v79, v151
	v_fmac_f32_e32 v36, v76, v151
	v_fmac_f32_e32 v37, v77, v151
	v_fmac_f32_e32 v38, v78, v151
	v_fmac_f32_e32 v39, v79, v151
	v_fma_f32 v12, v36, s59, -v212
	v_fma_f32 v13, v37, s59, -v213
	v_fma_f32 v22, v38, s59, -v214
	v_fma_f32 v23, v39, s59, -v215
	s_waitcnt vmcnt(21)
	v_fma_f32 v36, -v80, v136, v36
	v_fma_f32 v37, -v81, v136, v37
	v_fma_f32 v38, -v82, v136, v38
	v_fma_f32 v39, -v83, v136, v39
	v_cvt_pk_bf16_f32 v2, v12, v13
	v_cvt_pk_bf16_f32 v3, v22, v23
	global_store_dwordx2 v222, v[2:3], s[54:55]
	s_add_u32 s14, s2, 0x24000
	s_addc_u32 s15, s3, 0
	global_load_dwordx4 v[76:79], v0, s[14:15]
	s_add_u32 s56, s2, 0x15000
	s_addc_u32 s57, s3, 0
	global_load_dwordx4 v[80:83], v0, s[56:57]
	s_add_u32 s74, s12, 0xf680
	s_addc_u32 s75, s13, 0
	s_waitcnt vmcnt(22)
	v_mul_f32_e32 v212, v84, v152
	v_mul_f32_e32 v213, v85, v152
	v_mul_f32_e32 v214, v86, v152
	v_mul_f32_e32 v215, v87, v152
	v_fmac_f32_e32 v36, v84, v152
	v_fmac_f32_e32 v37, v85, v152
	v_fmac_f32_e32 v38, v86, v152
	v_fmac_f32_e32 v39, v87, v152
	v_fma_f32 v12, v36, s59, -v212
	v_fma_f32 v13, v37, s59, -v213
	v_fma_f32 v22, v38, s59, -v214
	v_fma_f32 v23, v39, s59, -v215
	s_waitcnt vmcnt(21)
	v_fma_f32 v36, -v88, v137, v36
	v_fma_f32 v37, -v89, v137, v37
	v_fma_f32 v38, -v90, v137, v38
	v_fma_f32 v39, -v91, v137, v39
	v_cvt_pk_bf16_f32 v208, v12, v13
	v_cvt_pk_bf16_f32 v209, v22, v23
	global_store_dwordx2 v222, v[208:209], s[74:75]
	s_add_u32 s70, s2, 0x25000
	s_addc_u32 s71, s3, 0
	global_load_dwordx4 v[84:87], v0, s[70:71]
	s_add_u32 s14, s2, 0x16000
	s_addc_u32 s15, s3, 0
	global_load_dwordx4 v[88:91], v0, s[14:15]
	s_add_u32 s54, s12, 0xff00
	s_addc_u32 s55, s13, 0
	s_waitcnt vmcnt(22)
	v_mul_f32_e32 v212, v92, v153
	v_mul_f32_e32 v213, v93, v153
	v_mul_f32_e32 v214, v94, v153
	v_mul_f32_e32 v215, v95, v153
	v_fmac_f32_e32 v36, v92, v153
	v_fmac_f32_e32 v37, v93, v153
	v_fmac_f32_e32 v38, v94, v153
	v_fmac_f32_e32 v39, v95, v153
	v_fma_f32 v12, v36, s59, -v212
	v_fma_f32 v13, v37, s59, -v213
	v_fma_f32 v22, v38, s59, -v214
	v_fma_f32 v23, v39, s59, -v215
	s_waitcnt vmcnt(21)
	v_fma_f32 v36, -v96, v138, v36
	v_fma_f32 v37, -v97, v138, v37
	v_fma_f32 v38, -v98, v138, v38
	v_fma_f32 v39, -v99, v138, v39
	v_cvt_pk_bf16_f32 v2, v12, v13
	v_cvt_pk_bf16_f32 v3, v22, v23
	global_store_dwordx2 v222, v[2:3], s[54:55]
	s_add_u32 s56, s2, 0x26000
	s_addc_u32 s57, s3, 0
	global_load_dwordx4 v[92:95], v0, s[56:57]
	s_add_u32 s70, s2, 0x17000
	s_addc_u32 s71, s3, 0
	global_load_dwordx4 v[96:99], v0, s[70:71]
	s_add_u32 s74, s12, 0x10780
	s_addc_u32 s75, s13, 0
	s_waitcnt vmcnt(22)
	v_mul_f32_e32 v212, v100, v154
	v_mul_f32_e32 v213, v101, v154
	v_mul_f32_e32 v214, v102, v154
	v_mul_f32_e32 v215, v103, v154
	v_fmac_f32_e32 v36, v100, v154
	v_fmac_f32_e32 v37, v101, v154
	v_fmac_f32_e32 v38, v102, v154
	v_fmac_f32_e32 v39, v103, v154
	v_fma_f32 v12, v36, s59, -v212
	v_fma_f32 v13, v37, s59, -v213
	v_fma_f32 v22, v38, s59, -v214
	v_fma_f32 v23, v39, s59, -v215
	s_waitcnt vmcnt(21)
	v_fma_f32 v36, -v104, v139, v36
	v_fma_f32 v37, -v105, v139, v37
	v_fma_f32 v38, -v106, v139, v38
	v_fma_f32 v39, -v107, v139, v39
	v_cvt_pk_bf16_f32 v208, v12, v13
	v_cvt_pk_bf16_f32 v209, v22, v23
	global_store_dwordx2 v222, v[208:209], s[74:75]
	s_add_u32 s14, s2, 0x27000
	s_addc_u32 s15, s3, 0
	global_load_dwordx4 v[100:103], v0, s[14:15]
	s_add_u32 s56, s2, 0x18000
	s_addc_u32 s57, s3, 0
	global_load_dwordx4 v[104:107], v0, s[56:57]
	s_add_u32 s54, s12, 0x11000
	s_addc_u32 s55, s13, 0
	s_waitcnt vmcnt(22)
	v_mul_f32_e32 v212, v44, v155
	v_mul_f32_e32 v213, v45, v155
	v_mul_f32_e32 v214, v46, v155
	v_mul_f32_e32 v215, v47, v155
	v_fmac_f32_e32 v36, v44, v155
	v_fmac_f32_e32 v37, v45, v155
	v_fmac_f32_e32 v38, v46, v155
	v_fmac_f32_e32 v39, v47, v155
	v_fma_f32 v12, v36, s59, -v212
	v_fma_f32 v13, v37, s59, -v213
	v_fma_f32 v22, v38, s59, -v214
	v_fma_f32 v23, v39, s59, -v215
	s_waitcnt vmcnt(21)
	v_fma_f32 v36, -v48, v140, v36
	v_fma_f32 v37, -v49, v140, v37
	v_fma_f32 v38, -v50, v140, v38
	v_fma_f32 v39, -v51, v140, v39
	v_cvt_pk_bf16_f32 v2, v12, v13
	v_cvt_pk_bf16_f32 v3, v22, v23
	global_store_dwordx2 v222, v[2:3], s[54:55]
	s_add_u32 s70, s2, 0x28000
	s_addc_u32 s71, s3, 0
	global_load_dwordx4 v[44:47], v0, s[70:71]
	s_add_u32 s14, s2, 0x19000
	s_addc_u32 s15, s3, 0
	global_load_dwordx4 v[48:51], v0, s[14:15]
	s_add_u32 s74, s12, 0x11880
	s_addc_u32 s75, s13, 0
	s_waitcnt vmcnt(22)
	v_mul_f32_e32 v212, v52, v156
	v_mul_f32_e32 v213, v53, v156
	v_mul_f32_e32 v214, v54, v156
	v_mul_f32_e32 v215, v55, v156
	v_fmac_f32_e32 v36, v52, v156
	v_fmac_f32_e32 v37, v53, v156
	v_fmac_f32_e32 v38, v54, v156
	v_fmac_f32_e32 v39, v55, v156
	v_fma_f32 v12, v36, s59, -v212
	v_fma_f32 v13, v37, s59, -v213
	v_fma_f32 v22, v38, s59, -v214
	v_fma_f32 v23, v39, s59, -v215
	s_waitcnt vmcnt(21)
; DI unsigned pack_bf16(float lo, float hi) { f32x2 v = {lo, hi}; bf16v2 b = __builtin_convertvector(v, bf16v2); return __builtin_bit_cast(unsigned, b); }
; template <int W>
; DI void pool_rows(const float* __restrict__ x, const float* smr, bf16_t* __restrict__ pb, int t0, int s0, int tid) {
;     ...
; #pragma unroll 8
;   for (int tl = 0; tl < 64; ++tl) {
;     const int t = t0 + tl, s = s0 + tl;
;     int to = t - W + 1; if (to < tq0) to = tq0;
;     const f32x4 hn = *(const f32x4*)(xq + (size_t)t * D) * smr[15 + tl];
;     const f32x4 ho = *(const f32x4*)(xq + (size_t)to * D) * smr[15 + tl - W + 1];
;     const int cnt = (s + 1 < W) ? (s + 1) : W;
;     const float ic = 1.f / (float)cnt;
;     Sm += hn;
;     const f32x4 p = Sm * ic - hn;
;     Sm -= ho;
;     u32x2 o; o.x = pack_bf16(p.x, p.y); o.y = pack_bf16(p.z, p.w);
;     *(u32x2*)(pb + (size_t)t * LDH + tid * 4) = o;
;   }
	v_fma_f32 v36, -v56, v141, v36
	v_fma_f32 v37, -v57, v141, v37
	v_fma_f32 v38, -v58, v141, v38
	v_fma_f32 v39, -v59, v141, v39
	v_cvt_pk_bf16_f32 v208, v12, v13
	v_cvt_pk_bf16_f32 v209, v22, v23
	global_store_dwordx2 v222, v[208:209], s[74:75]
	s_add_u32 s56, s2, 0x29000
	s_addc_u32 s57, s3, 0
	global_load_dwordx4 v[52:55], v0, s[56:57]
	s_add_u32 s70, s2, 0x1a000
	s_addc_u32 s71, s3, 0
	global_load_dwordx4 v[56:59], v0, s[70:71]
	s_add_u32 s54, s12, 0x12100
	s_addc_u32 s55, s13, 0
	s_waitcnt vmcnt(22)
	v_mul_f32_e32 v212, v60, v157
	v_mul_f32_e32 v213, v61, v157
	v_mul_f32_e32 v214, v62, v157
	v_mul_f32_e32 v215, v63, v157
	v_fmac_f32_e32 v36, v60, v157
	v_fmac_f32_e32 v37, v61, v157
	v_fmac_f32_e32 v38, v62, v157
	v_fmac_f32_e32 v39, v63, v157
	v_fma_f32 v12, v36, s59, -v212
	v_fma_f32 v13, v37, s59, -v213
	v_fma_f32 v22, v38, s59, -v214
	v_fma_f32 v23, v39, s59, -v215
	s_waitcnt vmcnt(21)
	v_fma_f32 v36, -v64, v142, v36
	v_fma_f32 v37, -v65, v142, v37
	v_fma_f32 v38, -v66, v142, v38
	v_fma_f32 v39, -v67, v142, v39
	v_cvt_pk_bf16_f32 v2, v12, v13
	v_cvt_pk_bf16_f32 v3, v22, v23
	global_store_dwordx2 v222, v[2:3], s[54:55]
	s_add_u32 s14, s2, 0x2a000
	s_addc_u32 s15, s3, 0
	global_load_dwordx4 v[60:63], v0, s[14:15]
	s_add_u32 s56, s2, 0x1b000
	s_addc_u32 s57, s3, 0
	global_load_dwordx4 v[64:67], v0, s[56:57]
	s_add_u32 s74, s12, 0x12980
	s_addc_u32 s75, s13, 0
	s_waitcnt vmcnt(22)
	v_mul_f32_e32 v212, v68, v158
	v_mul_f32_e32 v213, v69, v158
	v_mul_f32_e32 v214, v70, v158
	v_mul_f32_e32 v215, v71, v158
	v_fmac_f32_e32 v36, v68, v158
	v_fmac_f32_e32 v37, v69, v158
	v_fmac_f32_e32 v38, v70, v158
	v_fmac_f32_e32 v39, v71, v158
	v_fma_f32 v12, v36, s59, -v212
	v_fma_f32 v13, v37, s59, -v213
	v_fma_f32 v22, v38, s59, -v214
	v_fma_f32 v23, v39, s59, -v215
	s_waitcnt vmcnt(21)
	v_fma_f32 v36, -v72, v143, v36
	v_fma_f32 v37, -v73, v143, v37
	v_fma_f32 v38, -v74, v143, v38
	v_fma_f32 v39, -v75, v143, v39
	v_cvt_pk_bf16_f32 v208, v12, v13
	v_cvt_pk_bf16_f32 v209, v22, v23
	global_store_dwordx2 v222, v[208:209], s[74:75]
	s_add_u32 s70, s2, 0x2b000
	s_addc_u32 s71, s3, 0
	global_load_dwordx4 v[68:71], v0, s[70:71]
	s_add_u32 s14, s2, 0x1c000
	s_addc_u32 s15, s3, 0
	global_load_dwordx4 v[72:75], v0, s[14:15]
	s_add_u32 s54, s12, 0x13200
	s_addc_u32 s55, s13, 0
	s_waitcnt vmcnt(22)
	v_mul_f32_e32 v212, v76, v159
	v_mul_f32_e32 v213, v77, v159
	v_mul_f32_e32 v214, v78, v159
	v_mul_f32_e32 v215, v79, v159
	v_fmac_f32_e32 v36, v76, v159
	v_fmac_f32_e32 v37, v77, v159
	v_fmac_f32_e32 v38, v78, v159
	v_fmac_f32_e32 v39, v79, v159
	v_fma_f32 v12, v36, s59, -v212
	v_fma_f32 v13, v37, s59, -v213
	v_fma_f32 v22, v38, s59, -v214
	v_fma_f32 v23, v39, s59, -v215
	s_waitcnt vmcnt(21)
	v_fma_f32 v36, -v80, v144, v36
	v_fma_f32 v37, -v81, v144, v37
	v_fma_f32 v38, -v82, v144, v38
	v_fma_f32 v39, -v83, v144, v39
	v_cvt_pk_bf16_f32 v2, v12, v13
	v_cvt_pk_bf16_f32 v3, v22, v23
	global_store_dwordx2 v222, v[2:3], s[54:55]
	s_add_u32 s56, s2, 0x2c000
	s_addc_u32 s57, s3, 0
	global_load_dwordx4 v[76:79], v0, s[56:57]
	s_add_u32 s70, s2, 0x1d000
	s_addc_u32 s71, s3, 0
	global_load_dwordx4 v[80:83], v0, s[70:71]
	s_add_u32 s74, s12, 0x13a80
	s_addc_u32 s75, s13, 0
	s_waitcnt vmcnt(22)
	v_mul_f32_e32 v212, v84, v160
	v_mul_f32_e32 v213, v85, v160
	v_mul_f32_e32 v214, v86, v160
	v_mul_f32_e32 v215, v87, v160
	v_fmac_f32_e32 v36, v84, v160
	v_fmac_f32_e32 v37, v85, v160
	v_fmac_f32_e32 v38, v86, v160
	v_fmac_f32_e32 v39, v87, v160
	v_fma_f32 v12, v36, s59, -v212
	v_fma_f32 v13, v37, s59, -v213
	v_fma_f32 v22, v38, s59, -v214
	v_fma_f32 v23, v39, s59, -v215
	s_waitcnt vmcnt(21)
	v_fma_f32 v36, -v88, v145, v36
	v_fma_f32 v37, -v89, v145, v37
	v_fma_f32 v38, -v90, v145, v38
	v_fma_f32 v39, -v91, v145, v39
	v_cvt_pk_bf16_f32 v208, v12, v13
	v_cvt_pk_bf16_f32 v209, v22, v23
	global_store_dwordx2 v222, v[208:209], s[74:75]
	s_add_u32 s14, s2, 0x2d000
	s_addc_u32 s15, s3, 0
	global_load_dwordx4 v[84:87], v0, s[14:15]
	s_add_u32 s56, s2, 0x1e000
	s_addc_u32 s57, s3, 0
	global_load_dwordx4 v[88:91], v0, s[56:57]
	s_add_u32 s54, s12, 0x14300
	s_addc_u32 s55, s13, 0
	s_waitcnt vmcnt(22)
	v_mul_f32_e32 v212, v92, v161
	v_mul_f32_e32 v213, v93, v161
	v_mul_f32_e32 v214, v94, v161
	v_mul_f32_e32 v215, v95, v161
	v_fmac_f32_e32 v36, v92, v161
	v_fmac_f32_e32 v37, v93, v161
	v_fmac_f32_e32 v38, v94, v161
	v_fmac_f32_e32 v39, v95, v161
	v_fma_f32 v12, v36, s59, -v212
	v_fma_f32 v13, v37, s59, -v213
	v_fma_f32 v22, v38, s59, -v214
	v_fma_f32 v23, v39, s59, -v215
	s_waitcnt vmcnt(21)
	v_fma_f32 v36, -v96, v146, v36
	v_fma_f32 v37, -v97, v146, v37
	v_fma_f32 v38, -v98, v146, v38
	v_fma_f32 v39, -v99, v146, v39
	v_cvt_pk_bf16_f32 v2, v12, v13
	v_cvt_pk_bf16_f32 v3, v22, v23
	global_store_dwordx2 v222, v[2:3], s[54:55]
	s_add_u32 s70, s2, 0x2e000
	s_addc_u32 s71, s3, 0
	global_load_dwordx4 v[92:95], v0, s[70:71]
	s_add_u32 s14, s2, 0x1f000
	s_addc_u32 s15, s3, 0
	global_load_dwordx4 v[96:99], v0, s[14:15]
	s_add_u32 s74, s12, 0x14b80
	s_addc_u32 s75, s13, 0
	s_waitcnt vmcnt(22)
	v_mul_f32_e32 v212, v100, v162
	v_mul_f32_e32 v213, v101, v162
	v_mul_f32_e32 v214, v102, v162
	v_mul_f32_e32 v215, v103, v162
	v_fmac_f32_e32 v36, v100, v162
	v_fmac_f32_e32 v37, v101, v162
	v_fmac_f32_e32 v38, v102, v162
	v_fmac_f32_e32 v39, v103, v162
	v_fma_f32 v12, v36, s59, -v212
	v_fma_f32 v13, v37, s59, -v213
	v_fma_f32 v22, v38, s59, -v214
	v_fma_f32 v23, v39, s59, -v215
	s_waitcnt vmcnt(21)
; DI unsigned pack_bf16(float lo, float hi) { f32x2 v = {lo, hi}; bf16v2 b = __builtin_convertvector(v, bf16v2); return __builtin_bit_cast(unsigned, b); }
; template <int W>
; DI void pool_rows(const float* __restrict__ x, const float* smr, bf16_t* __restrict__ pb, int t0, int s0, int tid) {
;     ...
; #pragma unroll 8
;   for (int tl = 0; tl < 64; ++tl) {
;     const int t = t0 + tl, s = s0 + tl;
;     int to = t - W + 1; if (to < tq0) to = tq0;
;     const f32x4 hn = *(const f32x4*)(xq + (size_t)t * D) * smr[15 + tl];
;     const f32x4 ho = *(const f32x4*)(xq + (size_t)to * D) * smr[15 + tl - W + 1];
;     const int cnt = (s + 1 < W) ? (s + 1) : W;
;     const float ic = 1.f / (float)cnt;
;     Sm += hn;
;     const f32x4 p = Sm * ic - hn;
;     Sm -= ho;
;     u32x2 o; o.x = pack_bf16(p.x, p.y); o.y = pack_bf16(p.z, p.w);
;     *(u32x2*)(pb + (size_t)t * LDH + tid * 4) = o;
;   }
	v_fma_f32 v36, -v104, v147, v36
	v_fma_f32 v37, -v105, v147, v37
	v_fma_f32 v38, -v106, v147, v38
	v_fma_f32 v39, -v107, v147, v39
	v_cvt_pk_bf16_f32 v208, v12, v13
	v_cvt_pk_bf16_f32 v209, v22, v23
	global_store_dwordx2 v222, v[208:209], s[74:75]
	s_add_u32 s56, s2, 0x2f000
	s_addc_u32 s57, s3, 0
	global_load_dwordx4 v[100:103], v0, s[56:57]
	s_add_u32 s70, s2, 0x20000
	s_addc_u32 s71, s3, 0
	global_load_dwordx4 v[104:107], v0, s[70:71]
	s_add_u32 s54, s12, 0x15400
	s_addc_u32 s55, s13, 0
	s_waitcnt vmcnt(22)
	v_mul_f32_e32 v212, v44, v163
	v_mul_f32_e32 v213, v45, v163
	v_mul_f32_e32 v214, v46, v163
	v_mul_f32_e32 v215, v47, v163
	v_fmac_f32_e32 v36, v44, v163
	v_fmac_f32_e32 v37, v45, v163
	v_fmac_f32_e32 v38, v46, v163
	v_fmac_f32_e32 v39, v47, v163
	v_fma_f32 v12, v36, s59, -v212
	v_fma_f32 v13, v37, s59, -v213
	v_fma_f32 v22, v38, s59, -v214
	v_fma_f32 v23, v39, s59, -v215
	s_waitcnt vmcnt(21)
	v_fma_f32 v36, -v48, v148, v36
	v_fma_f32 v37, -v49, v148, v37
	v_fma_f32 v38, -v50, v148, v38
	v_fma_f32 v39, -v51, v148, v39
	v_cvt_pk_bf16_f32 v2, v12, v13
	v_cvt_pk_bf16_f32 v3, v22, v23
	global_store_dwordx2 v222, v[2:3], s[54:55]
	s_add_u32 s14, s2, 0x30000
	s_addc_u32 s15, s3, 0
	global_load_dwordx4 v[44:47], v0, s[14:15]
	s_add_u32 s56, s2, 0x21000
	s_addc_u32 s57, s3, 0
	global_load_dwordx4 v[48:51], v0, s[56:57]
	s_add_u32 s74, s12, 0x15c80
	s_addc_u32 s75, s13, 0
	s_waitcnt vmcnt(22)
	v_mul_f32_e32 v212, v52, v164
	v_mul_f32_e32 v213, v53, v164
	v_mul_f32_e32 v214, v54, v164
	v_mul_f32_e32 v215, v55, v164
	v_fmac_f32_e32 v36, v52, v164
	v_fmac_f32_e32 v37, v53, v164
	v_fmac_f32_e32 v38, v54, v164
	v_fmac_f32_e32 v39, v55, v164
	v_fma_f32 v12, v36, s59, -v212
	v_fma_f32 v13, v37, s59, -v213
	v_fma_f32 v22, v38, s59, -v214
	v_fma_f32 v23, v39, s59, -v215
	s_waitcnt vmcnt(21)
	v_fma_f32 v36, -v56, v149, v36
	v_fma_f32 v37, -v57, v149, v37
	v_fma_f32 v38, -v58, v149, v38
	v_fma_f32 v39, -v59, v149, v39
	v_cvt_pk_bf16_f32 v208, v12, v13
	v_cvt_pk_bf16_f32 v209, v22, v23
	global_store_dwordx2 v222, v[208:209], s[74:75]
	s_add_u32 s70, s2, 0x31000
	s_addc_u32 s71, s3, 0
	global_load_dwordx4 v[52:55], v0, s[70:71]
	s_add_u32 s14, s2, 0x22000
	s_addc_u32 s15, s3, 0
	global_load_dwordx4 v[56:59], v0, s[14:15]
	s_add_u32 s54, s12, 0x16500
	s_addc_u32 s55, s13, 0
	s_waitcnt vmcnt(22)
	v_mul_f32_e32 v212, v60, v165
	v_mul_f32_e32 v213, v61, v165
	v_mul_f32_e32 v214, v62, v165
	v_mul_f32_e32 v215, v63, v165
	v_fmac_f32_e32 v36, v60, v165
	v_fmac_f32_e32 v37, v61, v165
	v_fmac_f32_e32 v38, v62, v165
	v_fmac_f32_e32 v39, v63, v165
	v_fma_f32 v12, v36, s59, -v212
	v_fma_f32 v13, v37, s59, -v213
	v_fma_f32 v22, v38, s59, -v214
	v_fma_f32 v23, v39, s59, -v215
	s_waitcnt vmcnt(21)
	v_fma_f32 v36, -v64, v150, v36
	v_fma_f32 v37, -v65, v150, v37
	v_fma_f32 v38, -v66, v150, v38
	v_fma_f32 v39, -v67, v150, v39
	v_cvt_pk_bf16_f32 v2, v12, v13
	v_cvt_pk_bf16_f32 v3, v22, v23
	global_store_dwordx2 v222, v[2:3], s[54:55]
	s_add_u32 s56, s2, 0x32000
	s_addc_u32 s57, s3, 0
	global_load_dwordx4 v[60:63], v0, s[56:57]
	s_add_u32 s70, s2, 0x23000
	s_addc_u32 s71, s3, 0
	global_load_dwordx4 v[64:67], v0, s[70:71]
	s_add_u32 s74, s12, 0x16d80
	s_addc_u32 s75, s13, 0
	s_waitcnt vmcnt(22)
	v_mul_f32_e32 v212, v68, v166
	v_mul_f32_e32 v213, v69, v166
	v_mul_f32_e32 v214, v70, v166
	v_mul_f32_e32 v215, v71, v166
	v_fmac_f32_e32 v36, v68, v166
	v_fmac_f32_e32 v37, v69, v166
	v_fmac_f32_e32 v38, v70, v166
	v_fmac_f32_e32 v39, v71, v166
	v_fma_f32 v12, v36, s59, -v212
	v_fma_f32 v13, v37, s59, -v213
	v_fma_f32 v22, v38, s59, -v214
	v_fma_f32 v23, v39, s59, -v215
	s_waitcnt vmcnt(21)
	v_fma_f32 v36, -v72, v151, v36
	v_fma_f32 v37, -v73, v151, v37
	v_fma_f32 v38, -v74, v151, v38
	v_fma_f32 v39, -v75, v151, v39
	v_cvt_pk_bf16_f32 v208, v12, v13
	v_cvt_pk_bf16_f32 v209, v22, v23
	global_store_dwordx2 v222, v[208:209], s[74:75]
	s_add_u32 s14, s2, 0x33000
	s_addc_u32 s15, s3, 0
	global_load_dwordx4 v[68:71], v0, s[14:15]
	s_add_u32 s56, s2, 0x24000
	s_addc_u32 s57, s3, 0
	global_load_dwordx4 v[72:75], v0, s[56:57]
	s_add_u32 s54, s12, 0x17600
	s_addc_u32 s55, s13, 0
	s_waitcnt vmcnt(22)
	v_mul_f32_e32 v212, v76, v167
	v_mul_f32_e32 v213, v77, v167
	v_mul_f32_e32 v214, v78, v167
	v_mul_f32_e32 v215, v79, v167
	v_fmac_f32_e32 v36, v76, v167
	v_fmac_f32_e32 v37, v77, v167
	v_fmac_f32_e32 v38, v78, v167
	v_fmac_f32_e32 v39, v79, v167
	v_fma_f32 v12, v36, s59, -v212
	v_fma_f32 v13, v37, s59, -v213
	v_fma_f32 v22, v38, s59, -v214
	v_fma_f32 v23, v39, s59, -v215
	s_waitcnt vmcnt(21)
	v_fma_f32 v36, -v80, v152, v36
	v_fma_f32 v37, -v81, v152, v37
	v_fma_f32 v38, -v82, v152, v38
	v_fma_f32 v39, -v83, v152, v39
	v_cvt_pk_bf16_f32 v2, v12, v13
	v_cvt_pk_bf16_f32 v3, v22, v23
	global_store_dwordx2 v222, v[2:3], s[54:55]
	s_add_u32 s70, s2, 0x34000
	s_addc_u32 s71, s3, 0
	global_load_dwordx4 v[76:79], v0, s[70:71]
	s_add_u32 s14, s2, 0x25000
	s_addc_u32 s15, s3, 0
	global_load_dwordx4 v[80:83], v0, s[14:15]
	s_add_u32 s74, s12, 0x17e80
	s_addc_u32 s75, s13, 0
	s_waitcnt vmcnt(22)
	v_mul_f32_e32 v212, v84, v168
	v_mul_f32_e32 v213, v85, v168
	v_mul_f32_e32 v214, v86, v168
	v_mul_f32_e32 v215, v87, v168
	v_fmac_f32_e32 v36, v84, v168
	v_fmac_f32_e32 v37, v85, v168
	v_fmac_f32_e32 v38, v86, v168
	v_fmac_f32_e32 v39, v87, v168
	v_fma_f32 v12, v36, s59, -v212
	v_fma_f32 v13, v37, s59, -v213
	v_fma_f32 v22, v38, s59, -v214
	v_fma_f32 v23, v39, s59, -v215
	s_waitcnt vmcnt(21)
; DI unsigned pack_bf16(float lo, float hi) { f32x2 v = {lo, hi}; bf16v2 b = __builtin_convertvector(v, bf16v2); return __builtin_bit_cast(unsigned, b); }
; template <int W>
; DI void pool_rows(const float* __restrict__ x, const float* smr, bf16_t* __restrict__ pb, int t0, int s0, int tid) {
;     ...
; #pragma unroll 8
;   for (int tl = 0; tl < 64; ++tl) {
;     const int t = t0 + tl, s = s0 + tl;
;     int to = t - W + 1; if (to < tq0) to = tq0;
;     const f32x4 hn = *(const f32x4*)(xq + (size_t)t * D) * smr[15 + tl];
;     const f32x4 ho = *(const f32x4*)(xq + (size_t)to * D) * smr[15 + tl - W + 1];
;     const int cnt = (s + 1 < W) ? (s + 1) : W;
;     const float ic = 1.f / (float)cnt;
;     Sm += hn;
;     const f32x4 p = Sm * ic - hn;
;     Sm -= ho;
;     u32x2 o; o.x = pack_bf16(p.x, p.y); o.y = pack_bf16(p.z, p.w);
;     *(u32x2*)(pb + (size_t)t * LDH + tid * 4) = o;
;   }
	v_fma_f32 v36, -v88, v153, v36
	v_fma_f32 v37, -v89, v153, v37
	v_fma_f32 v38, -v90, v153, v38
	v_fma_f32 v39, -v91, v153, v39
	v_cvt_pk_bf16_f32 v208, v12, v13
	v_cvt_pk_bf16_f32 v209, v22, v23
	global_store_dwordx2 v222, v[208:209], s[74:75]
	s_add_u32 s56, s2, 0x35000
	s_addc_u32 s57, s3, 0
	global_load_dwordx4 v[84:87], v0, s[56:57]
	s_add_u32 s70, s2, 0x26000
	s_addc_u32 s71, s3, 0
	global_load_dwordx4 v[88:91], v0, s[70:71]
	s_add_u32 s54, s12, 0x18700
	s_addc_u32 s55, s13, 0
	s_waitcnt vmcnt(22)
	v_mul_f32_e32 v212, v92, v169
	v_mul_f32_e32 v213, v93, v169
	v_mul_f32_e32 v214, v94, v169
	v_mul_f32_e32 v215, v95, v169
	v_fmac_f32_e32 v36, v92, v169
	v_fmac_f32_e32 v37, v93, v169
	v_fmac_f32_e32 v38, v94, v169
	v_fmac_f32_e32 v39, v95, v169
	v_fma_f32 v12, v36, s59, -v212
	v_fma_f32 v13, v37, s59, -v213
	v_fma_f32 v22, v38, s59, -v214
	v_fma_f32 v23, v39, s59, -v215
	s_waitcnt vmcnt(21)
	v_fma_f32 v36, -v96, v154, v36
	v_fma_f32 v37, -v97, v154, v37
	v_fma_f32 v38, -v98, v154, v38
	v_fma_f32 v39, -v99, v154, v39
	v_cvt_pk_bf16_f32 v2, v12, v13
	v_cvt_pk_bf16_f32 v3, v22, v23
	global_store_dwordx2 v222, v[2:3], s[54:55]
	s_add_u32 s14, s2, 0x36000
	s_addc_u32 s15, s3, 0
	global_load_dwordx4 v[92:95], v0, s[14:15]
	s_add_u32 s56, s2, 0x27000
	s_addc_u32 s57, s3, 0
	global_load_dwordx4 v[96:99], v0, s[56:57]
	s_add_u32 s74, s12, 0x18f80
	s_addc_u32 s75, s13, 0
	s_waitcnt vmcnt(22)
	v_mul_f32_e32 v212, v100, v170
	v_mul_f32_e32 v213, v101, v170
	v_mul_f32_e32 v214, v102, v170
	v_mul_f32_e32 v215, v103, v170
	v_fmac_f32_e32 v36, v100, v170
	v_fmac_f32_e32 v37, v101, v170
	v_fmac_f32_e32 v38, v102, v170
	v_fmac_f32_e32 v39, v103, v170
	v_fma_f32 v12, v36, s59, -v212
	v_fma_f32 v13, v37, s59, -v213
	v_fma_f32 v22, v38, s59, -v214
	v_fma_f32 v23, v39, s59, -v215
	s_waitcnt vmcnt(21)
	v_fma_f32 v36, -v104, v155, v36
	v_fma_f32 v37, -v105, v155, v37
	v_fma_f32 v38, -v106, v155, v38
	v_fma_f32 v39, -v107, v155, v39
	v_cvt_pk_bf16_f32 v208, v12, v13
	v_cvt_pk_bf16_f32 v209, v22, v23
	global_store_dwordx2 v222, v[208:209], s[74:75]
	s_add_u32 s70, s2, 0x37000
	s_addc_u32 s71, s3, 0
	global_load_dwordx4 v[100:103], v0, s[70:71]
	s_add_u32 s14, s2, 0x28000
	s_addc_u32 s15, s3, 0
	global_load_dwordx4 v[104:107], v0, s[14:15]
	s_add_u32 s54, s12, 0x19800
	s_addc_u32 s55, s13, 0
	s_waitcnt vmcnt(22)
	v_mul_f32_e32 v212, v44, v171
	v_mul_f32_e32 v213, v45, v171
	v_mul_f32_e32 v214, v46, v171
	v_mul_f32_e32 v215, v47, v171
	v_fmac_f32_e32 v36, v44, v171
	v_fmac_f32_e32 v37, v45, v171
	v_fmac_f32_e32 v38, v46, v171
	v_fmac_f32_e32 v39, v47, v171
	v_fma_f32 v12, v36, s59, -v212
	v_fma_f32 v13, v37, s59, -v213
	v_fma_f32 v22, v38, s59, -v214
	v_fma_f32 v23, v39, s59, -v215
	s_waitcnt vmcnt(21)
	v_fma_f32 v36, -v48, v156, v36
	v_fma_f32 v37, -v49, v156, v37
	v_fma_f32 v38, -v50, v156, v38
	v_fma_f32 v39, -v51, v156, v39
	v_cvt_pk_bf16_f32 v2, v12, v13
	v_cvt_pk_bf16_f32 v3, v22, v23
	global_store_dwordx2 v222, v[2:3], s[54:55]
	s_add_u32 s56, s2, 0x38000
	s_addc_u32 s57, s3, 0
	global_load_dwordx4 v[44:47], v0, s[56:57]
	s_add_u32 s70, s2, 0x29000
	s_addc_u32 s71, s3, 0
	global_load_dwordx4 v[48:51], v0, s[70:71]
	s_add_u32 s74, s12, 0x1a080
	s_addc_u32 s75, s13, 0
	s_waitcnt vmcnt(22)
	v_mul_f32_e32 v212, v52, v172
	v_mul_f32_e32 v213, v53, v172
	v_mul_f32_e32 v214, v54, v172
	v_mul_f32_e32 v215, v55, v172
	v_fmac_f32_e32 v36, v52, v172
	v_fmac_f32_e32 v37, v53, v172
	v_fmac_f32_e32 v38, v54, v172
	v_fmac_f32_e32 v39, v55, v172
	v_fma_f32 v12, v36, s59, -v212
	v_fma_f32 v13, v37, s59, -v213
	v_fma_f32 v22, v38, s59, -v214
	v_fma_f32 v23, v39, s59, -v215
	s_waitcnt vmcnt(21)
	v_fma_f32 v36, -v56, v157, v36
	v_fma_f32 v37, -v57, v157, v37
	v_fma_f32 v38, -v58, v157, v38
	v_fma_f32 v39, -v59, v157, v39
	v_cvt_pk_bf16_f32 v208, v12, v13
	v_cvt_pk_bf16_f32 v209, v22, v23
	global_store_dwordx2 v222, v[208:209], s[74:75]
	s_add_u32 s14, s2, 0x39000
	s_addc_u32 s15, s3, 0
	global_load_dwordx4 v[52:55], v0, s[14:15]
	s_add_u32 s56, s2, 0x2a000
	s_addc_u32 s57, s3, 0
	global_load_dwordx4 v[56:59], v0, s[56:57]
	s_add_u32 s54, s12, 0x1a900
	s_addc_u32 s55, s13, 0
	s_waitcnt vmcnt(22)
	v_mul_f32_e32 v212, v60, v173
	v_mul_f32_e32 v213, v61, v173
	v_mul_f32_e32 v214, v62, v173
	v_mul_f32_e32 v215, v63, v173
	v_fmac_f32_e32 v36, v60, v173
	v_fmac_f32_e32 v37, v61, v173
	v_fmac_f32_e32 v38, v62, v173
	v_fmac_f32_e32 v39, v63, v173
	v_fma_f32 v12, v36, s59, -v212
	v_fma_f32 v13, v37, s59, -v213
	v_fma_f32 v22, v38, s59, -v214
	v_fma_f32 v23, v39, s59, -v215
	s_waitcnt vmcnt(21)
	v_fma_f32 v36, -v64, v158, v36
	v_fma_f32 v37, -v65, v158, v37
	v_fma_f32 v38, -v66, v158, v38
	v_fma_f32 v39, -v67, v158, v39
	v_cvt_pk_bf16_f32 v2, v12, v13
	v_cvt_pk_bf16_f32 v3, v22, v23
	global_store_dwordx2 v222, v[2:3], s[54:55]
	s_add_u32 s70, s2, 0x3a000
	s_addc_u32 s71, s3, 0
	global_load_dwordx4 v[60:63], v0, s[70:71]
	s_add_u32 s14, s2, 0x2b000
	s_addc_u32 s15, s3, 0
	global_load_dwordx4 v[64:67], v0, s[14:15]
	s_add_u32 s74, s12, 0x1b180
	s_addc_u32 s75, s13, 0
	s_waitcnt vmcnt(22)
	v_mul_f32_e32 v212, v68, v174
	v_mul_f32_e32 v213, v69, v174
	v_mul_f32_e32 v214, v70, v174
	v_mul_f32_e32 v215, v71, v174
	v_fmac_f32_e32 v36, v68, v174
	v_fmac_f32_e32 v37, v69, v174
	v_fmac_f32_e32 v38, v70, v174
	v_fmac_f32_e32 v39, v71, v174
	v_fma_f32 v12, v36, s59, -v212
	v_fma_f32 v13, v37, s59, -v213
	v_fma_f32 v22, v38, s59, -v214
	v_fma_f32 v23, v39, s59, -v215
	s_waitcnt vmcnt(21)
; DI unsigned pack_bf16(float lo, float hi) { f32x2 v = {lo, hi}; bf16v2 b = __builtin_convertvector(v, bf16v2); return __builtin_bit_cast(unsigned, b); }
; template <int W>
; DI void pool_rows(const float* __restrict__ x, const float* smr, bf16_t* __restrict__ pb, int t0, int s0, int tid) {
;     ...
; #pragma unroll 8
;   for (int tl = 0; tl < 64; ++tl) {
;     const int t = t0 + tl, s = s0 + tl;
;     int to = t - W + 1; if (to < tq0) to = tq0;
;     const f32x4 hn = *(const f32x4*)(xq + (size_t)t * D) * smr[15 + tl];
;     const f32x4 ho = *(const f32x4*)(xq + (size_t)to * D) * smr[15 + tl - W + 1];
;     const int cnt = (s + 1 < W) ? (s + 1) : W;
;     const float ic = 1.f / (float)cnt;
;     Sm += hn;
;     const f32x4 p = Sm * ic - hn;
;     Sm -= ho;
;     u32x2 o; o.x = pack_bf16(p.x, p.y); o.y = pack_bf16(p.z, p.w);
;     *(u32x2*)(pb + (size_t)t * LDH + tid * 4) = o;
;   }
	v_fma_f32 v36, -v72, v159, v36
	v_fma_f32 v37, -v73, v159, v37
	v_fma_f32 v38, -v74, v159, v38
	v_fma_f32 v39, -v75, v159, v39
	v_cvt_pk_bf16_f32 v208, v12, v13
	v_cvt_pk_bf16_f32 v209, v22, v23
	global_store_dwordx2 v222, v[208:209], s[74:75]
	s_add_u32 s56, s2, 0x3b000
	s_addc_u32 s57, s3, 0
	global_load_dwordx4 v[68:71], v0, s[56:57]
	s_add_u32 s70, s2, 0x2c000
	s_addc_u32 s71, s3, 0
	global_load_dwordx4 v[72:75], v0, s[70:71]
	s_add_u32 s54, s12, 0x1ba00
	s_addc_u32 s55, s13, 0
	s_waitcnt vmcnt(22)
	v_mul_f32_e32 v212, v76, v175
	v_mul_f32_e32 v213, v77, v175
	v_mul_f32_e32 v214, v78, v175
	v_mul_f32_e32 v215, v79, v175
	v_fmac_f32_e32 v36, v76, v175
	v_fmac_f32_e32 v37, v77, v175
	v_fmac_f32_e32 v38, v78, v175
	v_fmac_f32_e32 v39, v79, v175
	v_fma_f32 v12, v36, s59, -v212
	v_fma_f32 v13, v37, s59, -v213
	v_fma_f32 v22, v38, s59, -v214
	v_fma_f32 v23, v39, s59, -v215
	s_waitcnt vmcnt(21)
	v_fma_f32 v36, -v80, v160, v36
	v_fma_f32 v37, -v81, v160, v37
	v_fma_f32 v38, -v82, v160, v38
	v_fma_f32 v39, -v83, v160, v39
	v_cvt_pk_bf16_f32 v2, v12, v13
	v_cvt_pk_bf16_f32 v3, v22, v23
	global_store_dwordx2 v222, v[2:3], s[54:55]
	s_add_u32 s14, s2, 0x3c000
	s_addc_u32 s15, s3, 0
	global_load_dwordx4 v[76:79], v0, s[14:15]
	s_add_u32 s56, s2, 0x2d000
	s_addc_u32 s57, s3, 0
	global_load_dwordx4 v[80:83], v0, s[56:57]
	s_add_u32 s74, s12, 0x1c280
	s_addc_u32 s75, s13, 0
	s_waitcnt vmcnt(22)
	v_mul_f32_e32 v212, v84, v176
	v_mul_f32_e32 v213, v85, v176
	v_mul_f32_e32 v214, v86, v176
	v_mul_f32_e32 v215, v87, v176
	v_fmac_f32_e32 v36, v84, v176
	v_fmac_f32_e32 v37, v85, v176
	v_fmac_f32_e32 v38, v86, v176
	v_fmac_f32_e32 v39, v87, v176
	v_fma_f32 v12, v36, s59, -v212
	v_fma_f32 v13, v37, s59, -v213
	v_fma_f32 v22, v38, s59, -v214
	v_fma_f32 v23, v39, s59, -v215
	s_waitcnt vmcnt(21)
	v_fma_f32 v36, -v88, v161, v36
	v_fma_f32 v37, -v89, v161, v37
	v_fma_f32 v38, -v90, v161, v38
	v_fma_f32 v39, -v91, v161, v39
	v_cvt_pk_bf16_f32 v208, v12, v13
	v_cvt_pk_bf16_f32 v209, v22, v23
	global_store_dwordx2 v222, v[208:209], s[74:75]
	s_add_u32 s70, s2, 0x3d000
	s_addc_u32 s71, s3, 0
	global_load_dwordx4 v[84:87], v0, s[70:71]
	s_add_u32 s14, s2, 0x2e000
	s_addc_u32 s15, s3, 0
	global_load_dwordx4 v[88:91], v0, s[14:15]
	s_add_u32 s54, s12, 0x1cb00
	s_addc_u32 s55, s13, 0
	s_waitcnt vmcnt(22)
	v_mul_f32_e32 v212, v92, v177
	v_mul_f32_e32 v213, v93, v177
	v_mul_f32_e32 v214, v94, v177
	v_mul_f32_e32 v215, v95, v177
	v_fmac_f32_e32 v36, v92, v177
	v_fmac_f32_e32 v37, v93, v177
	v_fmac_f32_e32 v38, v94, v177
	v_fmac_f32_e32 v39, v95, v177
	v_fma_f32 v12, v36, s59, -v212
	v_fma_f32 v13, v37, s59, -v213
	v_fma_f32 v22, v38, s59, -v214
	v_fma_f32 v23, v39, s59, -v215
	s_waitcnt vmcnt(21)
	v_fma_f32 v36, -v96, v162, v36
	v_fma_f32 v37, -v97, v162, v37
	v_fma_f32 v38, -v98, v162, v38
	v_fma_f32 v39, -v99, v162, v39
	v_cvt_pk_bf16_f32 v2, v12, v13
	v_cvt_pk_bf16_f32 v3, v22, v23
	global_store_dwordx2 v222, v[2:3], s[54:55]
	s_add_u32 s56, s2, 0x3e000
	s_addc_u32 s57, s3, 0
	global_load_dwordx4 v[92:95], v0, s[56:57]
	s_add_u32 s70, s2, 0x2f000
	s_addc_u32 s71, s3, 0
	global_load_dwordx4 v[96:99], v0, s[70:71]
	s_add_u32 s74, s12, 0x1d380
	s_addc_u32 s75, s13, 0
	s_waitcnt vmcnt(22)
	v_mul_f32_e32 v212, v100, v178
	v_mul_f32_e32 v213, v101, v178
	v_mul_f32_e32 v214, v102, v178
	v_mul_f32_e32 v215, v103, v178
	v_fmac_f32_e32 v36, v100, v178
	v_fmac_f32_e32 v37, v101, v178
	v_fmac_f32_e32 v38, v102, v178
	v_fmac_f32_e32 v39, v103, v178
	v_fma_f32 v12, v36, s59, -v212
	v_fma_f32 v13, v37, s59, -v213
	v_fma_f32 v22, v38, s59, -v214
	v_fma_f32 v23, v39, s59, -v215
	s_waitcnt vmcnt(21)
	v_fma_f32 v36, -v104, v163, v36
	v_fma_f32 v37, -v105, v163, v37
	v_fma_f32 v38, -v106, v163, v38
	v_fma_f32 v39, -v107, v163, v39
	v_cvt_pk_bf16_f32 v208, v12, v13
	v_cvt_pk_bf16_f32 v209, v22, v23
	global_store_dwordx2 v222, v[208:209], s[74:75]
	s_add_u32 s14, s2, 0x3f000
	s_addc_u32 s15, s3, 0
	global_load_dwordx4 v[100:103], v0, s[14:15]
	s_add_u32 s56, s2, 0x30000
	s_addc_u32 s57, s3, 0
	global_load_dwordx4 v[104:107], v0, s[56:57]
	s_add_u32 s54, s12, 0x1dc00
	s_addc_u32 s55, s13, 0
	s_waitcnt vmcnt(22)
	v_mul_f32_e32 v212, v44, v179
	v_mul_f32_e32 v213, v45, v179
	v_mul_f32_e32 v214, v46, v179
	v_mul_f32_e32 v215, v47, v179
	v_fmac_f32_e32 v36, v44, v179
	v_fmac_f32_e32 v37, v45, v179
	v_fmac_f32_e32 v38, v46, v179
	v_fmac_f32_e32 v39, v47, v179
	v_fma_f32 v12, v36, s59, -v212
	v_fma_f32 v13, v37, s59, -v213
	v_fma_f32 v22, v38, s59, -v214
	v_fma_f32 v23, v39, s59, -v215
	s_waitcnt vmcnt(21)
	v_fma_f32 v36, -v48, v164, v36
	v_fma_f32 v37, -v49, v164, v37
	v_fma_f32 v38, -v50, v164, v38
	v_fma_f32 v39, -v51, v164, v39
	v_cvt_pk_bf16_f32 v2, v12, v13
	v_cvt_pk_bf16_f32 v3, v22, v23
	global_store_dwordx2 v222, v[2:3], s[54:55]
	s_add_u32 s74, s12, 0x1e480
	s_addc_u32 s75, s13, 0
	s_waitcnt vmcnt(20)
	v_mul_f32_e32 v212, v52, v180
	v_mul_f32_e32 v213, v53, v180
	v_mul_f32_e32 v214, v54, v180
	v_mul_f32_e32 v215, v55, v180
	v_fmac_f32_e32 v36, v52, v180
	v_fmac_f32_e32 v37, v53, v180
	v_fmac_f32_e32 v38, v54, v180
	v_fmac_f32_e32 v39, v55, v180
	v_fma_f32 v12, v36, s59, -v212
	v_fma_f32 v13, v37, s59, -v213
	v_fma_f32 v22, v38, s59, -v214
	v_fma_f32 v23, v39, s59, -v215
	s_waitcnt vmcnt(19)
	v_fma_f32 v36, -v56, v165, v36
	v_fma_f32 v37, -v57, v165, v37
	v_fma_f32 v38, -v58, v165, v38
	v_fma_f32 v39, -v59, v165, v39
	v_cvt_pk_bf16_f32 v208, v12, v13
	v_cvt_pk_bf16_f32 v209, v22, v23
	global_store_dwordx2 v222, v[208:209], s[74:75]
	s_add_u32 s54, s12, 0x1ed00
	s_addc_u32 s55, s13, 0
	s_waitcnt vmcnt(18)
; DI unsigned pack_bf16(float lo, float hi) { f32x2 v = {lo, hi}; bf16v2 b = __builtin_convertvector(v, bf16v2); return __builtin_bit_cast(unsigned, b); }
; template <int W>
; DI void pool_rows(const float* __restrict__ x, const float* smr, bf16_t* __restrict__ pb, int t0, int s0, int tid) {
;   const int tq0 = t0 - s0;
;   const float* xq = x + tid * 4;
;   f32x4 Sm = {0.f, 0.f, 0.f, 0.f};
; #pragma unroll
;   for (int i = 1; i < W; ++i) {
;     int t = t0 - i; if (t < tq0) t = tq0;
;     Sm += *(const f32x4*)(xq + (size_t)t * D) * smr[15 - i];
;   }
;     ...
;   for (int tl = 0; tl < 64; ++tl) {
;     const int t = t0 + tl, s = s0 + tl;
;     int to = t - W + 1; if (to < tq0) to = tq0;
;     const f32x4 hn = *(const f32x4*)(xq + (size_t)t * D) * smr[15 + tl];
;     const f32x4 ho = *(const f32x4*)(xq + (size_t)to * D) * smr[15 + tl - W + 1];
;     const int cnt = (s + 1 < W) ? (s + 1) : W;
;     const float ic = 1.f / (float)cnt;
;     Sm += hn;
;     const f32x4 p = Sm * ic - hn;
;     Sm -= ho;
;     u32x2 o; o.x = pack_bf16(p.x, p.y); o.y = pack_bf16(p.z, p.w);
;     *(u32x2*)(pb + (size_t)t * LDH + tid * 4) = o;
;   }
; DI void poolprep_phase(int vb, int nvb, const float* __restrict__ x, const float* __restrict__ ssq, bf16_t* __restrict__ pb, float* smf) {
;     ...
;       if (wave == 0) pool_rows<2>(x, smf, pb, t0, s0, tid);
;       else if (wave == 1) pool_rows<4>(x, smf, pb, t0, s0, tid);
;       else if (wave == 2) pool_rows<8>(x, smf, pb, t0, s0, tid);
;       else pool_rows<16>(x, smf, pb, t0, s0, tid);
	v_mul_f32_e32 v212, v60, v181
	v_mul_f32_e32 v213, v61, v181
	v_mul_f32_e32 v214, v62, v181
	v_mul_f32_e32 v215, v63, v181
	v_fmac_f32_e32 v36, v60, v181
	v_fmac_f32_e32 v37, v61, v181
	v_fmac_f32_e32 v38, v62, v181
	v_fmac_f32_e32 v39, v63, v181
	v_fma_f32 v12, v36, s59, -v212
	v_fma_f32 v13, v37, s59, -v213
	v_fma_f32 v22, v38, s59, -v214
	v_fma_f32 v23, v39, s59, -v215
	s_waitcnt vmcnt(17)
	v_fma_f32 v36, -v64, v166, v36
	v_fma_f32 v37, -v65, v166, v37
	v_fma_f32 v38, -v66, v166, v38
	v_fma_f32 v39, -v67, v166, v39
	v_cvt_pk_bf16_f32 v2, v12, v13
	v_cvt_pk_bf16_f32 v3, v22, v23
	global_store_dwordx2 v222, v[2:3], s[54:55]
	s_add_u32 s74, s12, 0x1f580
	s_addc_u32 s75, s13, 0
	s_waitcnt vmcnt(16)
	v_mul_f32_e32 v212, v68, v182
	v_mul_f32_e32 v213, v69, v182
	v_mul_f32_e32 v214, v70, v182
	v_mul_f32_e32 v215, v71, v182
	v_fmac_f32_e32 v36, v68, v182
	v_fmac_f32_e32 v37, v69, v182
	v_fmac_f32_e32 v38, v70, v182
	v_fmac_f32_e32 v39, v71, v182
	v_fma_f32 v12, v36, s59, -v212
	v_fma_f32 v13, v37, s59, -v213
	v_fma_f32 v22, v38, s59, -v214
	v_fma_f32 v23, v39, s59, -v215
	s_waitcnt vmcnt(15)
	v_fma_f32 v36, -v72, v167, v36
	v_fma_f32 v37, -v73, v167, v37
	v_fma_f32 v38, -v74, v167, v38
	v_fma_f32 v39, -v75, v167, v39
	v_cvt_pk_bf16_f32 v208, v12, v13
	v_cvt_pk_bf16_f32 v209, v22, v23
	global_store_dwordx2 v222, v[208:209], s[74:75]
	s_add_u32 s54, s12, 0x1fe00
	s_addc_u32 s55, s13, 0
	s_waitcnt vmcnt(14)
	v_mul_f32_e32 v212, v76, v183
	v_mul_f32_e32 v213, v77, v183
	v_mul_f32_e32 v214, v78, v183
	v_mul_f32_e32 v215, v79, v183
	v_fmac_f32_e32 v36, v76, v183
	v_fmac_f32_e32 v37, v77, v183
	v_fmac_f32_e32 v38, v78, v183
	v_fmac_f32_e32 v39, v79, v183
	v_fma_f32 v12, v36, s59, -v212
	v_fma_f32 v13, v37, s59, -v213
	v_fma_f32 v22, v38, s59, -v214
	v_fma_f32 v23, v39, s59, -v215
	s_waitcnt vmcnt(13)
	v_fma_f32 v36, -v80, v168, v36
	v_fma_f32 v37, -v81, v168, v37
	v_fma_f32 v38, -v82, v168, v38
	v_fma_f32 v39, -v83, v168, v39
	v_cvt_pk_bf16_f32 v2, v12, v13
	v_cvt_pk_bf16_f32 v3, v22, v23
	global_store_dwordx2 v222, v[2:3], s[54:55]
	s_add_u32 s74, s12, 0x20680
	s_addc_u32 s75, s13, 0
	s_waitcnt vmcnt(12)
	v_mul_f32_e32 v212, v84, v184
	v_mul_f32_e32 v213, v85, v184
	v_mul_f32_e32 v214, v86, v184
	v_mul_f32_e32 v215, v87, v184
	v_fmac_f32_e32 v36, v84, v184
	v_fmac_f32_e32 v37, v85, v184
	v_fmac_f32_e32 v38, v86, v184
	v_fmac_f32_e32 v39, v87, v184
	v_fma_f32 v12, v36, s59, -v212
	v_fma_f32 v13, v37, s59, -v213
	v_fma_f32 v22, v38, s59, -v214
	v_fma_f32 v23, v39, s59, -v215
	s_waitcnt vmcnt(11)
	v_fma_f32 v36, -v88, v169, v36
	v_fma_f32 v37, -v89, v169, v37
	v_fma_f32 v38, -v90, v169, v38
	v_fma_f32 v39, -v91, v169, v39
	v_cvt_pk_bf16_f32 v208, v12, v13
	v_cvt_pk_bf16_f32 v209, v22, v23
	global_store_dwordx2 v222, v[208:209], s[74:75]
	s_add_u32 s54, s12, 0x20f00
	s_addc_u32 s55, s13, 0
	s_waitcnt vmcnt(10)
	v_mul_f32_e32 v212, v92, v185
	v_mul_f32_e32 v213, v93, v185
	v_mul_f32_e32 v214, v94, v185
	v_mul_f32_e32 v215, v95, v185
	v_fmac_f32_e32 v36, v92, v185
	v_fmac_f32_e32 v37, v93, v185
	v_fmac_f32_e32 v38, v94, v185
	v_fmac_f32_e32 v39, v95, v185
	v_fma_f32 v12, v36, s59, -v212
	v_fma_f32 v13, v37, s59, -v213
	v_fma_f32 v22, v38, s59, -v214
	v_fma_f32 v23, v39, s59, -v215
	s_waitcnt vmcnt(9)
	v_fma_f32 v36, -v96, v170, v36
	v_fma_f32 v37, -v97, v170, v37
	v_fma_f32 v38, -v98, v170, v38
	v_fma_f32 v39, -v99, v170, v39
	v_cvt_pk_bf16_f32 v2, v12, v13
	v_cvt_pk_bf16_f32 v3, v22, v23
	global_store_dwordx2 v222, v[2:3], s[54:55]
	s_add_u32 s74, s12, 0x21780
	s_addc_u32 s75, s13, 0
	s_waitcnt vmcnt(8)
	v_mul_f32_e32 v212, v100, v186
	v_mul_f32_e32 v213, v101, v186
	v_mul_f32_e32 v214, v102, v186
	v_mul_f32_e32 v215, v103, v186
	v_fmac_f32_e32 v36, v100, v186
	v_fmac_f32_e32 v37, v101, v186
	v_fmac_f32_e32 v38, v102, v186
	v_fmac_f32_e32 v39, v103, v186
	v_fma_f32 v12, v36, s59, -v212
	v_fma_f32 v13, v37, s59, -v213
	v_fma_f32 v22, v38, s59, -v214
	v_fma_f32 v23, v39, s59, -v215
	s_waitcnt vmcnt(7)
	v_fma_f32 v36, -v104, v171, v36
	v_fma_f32 v37, -v105, v171, v37
	v_fma_f32 v38, -v106, v171, v38
	v_fma_f32 v39, -v107, v171, v39
	v_cvt_pk_bf16_f32 v208, v12, v13
	v_cvt_pk_bf16_f32 v209, v22, v23
	global_store_dwordx2 v222, v[208:209], s[74:75]
	s_branch .Lpp_done
.Lpp_w2:
	s_mov_b32 s59, 0x3f000000
	s_cmp_eq_u32 s58, 0
	s_cselect_b32 s31, 0, 0xfffff000
	s_cselect_b32 s32, 0, -1
	s_add_u32 s14, s2, s31
	s_addc_u32 s15, s3, s32
	global_load_dwordx4 v[188:191], v0, s[14:15]
	s_mov_b32 s56, s2
	s_mov_b32 s57, s3
	global_load_dwordx4 v[44:47], v0, s[56:57]
	s_cmp_eq_u32 s58, 0
	s_cselect_b32 s31, 0, 0xfffff000
	s_cselect_b32 s32, 0, -1
	s_add_u32 s70, s2, s31
	s_addc_u32 s71, s3, s32
	global_load_dwordx4 v[48:51], v0, s[70:71]
	s_add_u32 s14, s2, 0x1000
	s_addc_u32 s15, s3, 0
	global_load_dwordx4 v[52:55], v0, s[14:15]
	s_mov_b32 s56, s2
	s_mov_b32 s57, s3
	global_load_dwordx4 v[56:59], v0, s[56:57]
	s_add_u32 s70, s2, 0x2000
	s_addc_u32 s71, s3, 0
	global_load_dwordx4 v[60:63], v0, s[70:71]
	s_add_u32 s14, s2, 0x1000
	s_addc_u32 s15, s3, 0
	global_load_dwordx4 v[64:67], v0, s[14:15]
	s_add_u32 s56, s2, 0x3000
	s_addc_u32 s57, s3, 0
	global_load_dwordx4 v[68:71], v0, s[56:57]
	s_add_u32 s70, s2, 0x2000
	s_addc_u32 s71, s3, 0
	global_load_dwordx4 v[72:75], v0, s[70:71]
	s_add_u32 s14, s2, 0x4000
	s_addc_u32 s15, s3, 0
	global_load_dwordx4 v[76:79], v0, s[14:15]
	s_add_u32 s56, s2, 0x3000
	s_addc_u32 s57, s3, 0
	global_load_dwordx4 v[80:83], v0, s[56:57]
	s_add_u32 s70, s2, 0x5000
	s_addc_u32 s71, s3, 0
	global_load_dwordx4 v[84:87], v0, s[70:71]
	s_add_u32 s14, s2, 0x4000
	s_addc_u32 s15, s3, 0
	global_load_dwordx4 v[88:91], v0, s[14:15]
	s_add_u32 s56, s2, 0x6000
	s_addc_u32 s57, s3, 0
	global_load_dwordx4 v[92:95], v0, s[56:57]
	s_add_u32 s70, s2, 0x5000
	s_addc_u32 s71, s3, 0
	global_load_dwordx4 v[96:99], v0, s[70:71]
	s_add_u32 s14, s2, 0x7000
	s_addc_u32 s15, s3, 0
	global_load_dwordx4 v[100:103], v0, s[14:15]
	s_add_u32 s56, s2, 0x6000
	s_addc_u32 s57, s3, 0
	global_load_dwordx4 v[104:107], v0, s[56:57]
	s_waitcnt lgkmcnt(0)
; DI unsigned pack_bf16(float lo, float hi) { f32x2 v = {lo, hi}; bf16v2 b = __builtin_convertvector(v, bf16v2); return __builtin_bit_cast(unsigned, b); }
; template <int W>
; DI void pool_rows(const float* __restrict__ x, const float* smr, bf16_t* __restrict__ pb, int t0, int s0, int tid) {
;     ...
;   f32x4 Sm = {0.f, 0.f, 0.f, 0.f};
; #pragma unroll
;   for (int i = 1; i < W; ++i) {
;     int t = t0 - i; if (t < tq0) t = tq0;
;     Sm += *(const f32x4*)(xq + (size_t)t * D) * smr[15 - i];
;   }
; #pragma unroll 8
;   for (int tl = 0; tl < 64; ++tl) {
;     const int t = t0 + tl, s = s0 + tl;
;     int to = t - W + 1; if (to < tq0) to = tq0;
;     const f32x4 hn = *(const f32x4*)(xq + (size_t)t * D) * smr[15 + tl];
;     const f32x4 ho = *(const f32x4*)(xq + (size_t)to * D) * smr[15 + tl - W + 1];
;     const int cnt = (s + 1 < W) ? (s + 1) : W;
;     const float ic = 1.f / (float)cnt;
;     Sm += hn;
;     const f32x4 p = Sm * ic - hn;
;     Sm -= ho;
;     u32x2 o; o.x = pack_bf16(p.x, p.y); o.y = pack_bf16(p.z, p.w);
;     *(u32x2*)(pb + (size_t)t * LDH + tid * 4) = o;
;   }
	s_waitcnt vmcnt(16)
	v_mul_f32_e32 v36, v188, v122
	v_mul_f32_e32 v37, v189, v122
	v_mul_f32_e32 v38, v190, v122
	v_mul_f32_e32 v39, v191, v122
	s_mov_b32 s32, 0x3f800000
	s_cmp_eq_u32 s58, 0
	s_cselect_b32 s32, s32, s59
	s_add_u32 s54, s12, 0x0
	s_addc_u32 s55, s13, 0
	s_waitcnt vmcnt(15)
	v_mul_f32_e32 v212, v44, v123
	v_mul_f32_e32 v213, v45, v123
	v_mul_f32_e32 v214, v46, v123
	v_mul_f32_e32 v215, v47, v123
	v_fmac_f32_e32 v36, v44, v123
	v_fmac_f32_e32 v37, v45, v123
	v_fmac_f32_e32 v38, v46, v123
	v_fmac_f32_e32 v39, v47, v123
	v_fma_f32 v12, v36, s32, -v212
	v_fma_f32 v13, v37, s32, -v213
	v_fma_f32 v22, v38, s32, -v214
	v_fma_f32 v23, v39, s32, -v215
	s_waitcnt vmcnt(14)
	v_fma_f32 v36, -v48, v122, v36
	v_fma_f32 v37, -v49, v122, v37
	v_fma_f32 v38, -v50, v122, v38
	v_fma_f32 v39, -v51, v122, v39
	v_cvt_pk_bf16_f32 v2, v12, v13
	v_cvt_pk_bf16_f32 v3, v22, v23
	global_store_dwordx2 v222, v[2:3], s[54:55]
	s_add_u32 s70, s2, 0x8000
	s_addc_u32 s71, s3, 0
	global_load_dwordx4 v[44:47], v0, s[70:71]
	s_add_u32 s14, s2, 0x7000
	s_addc_u32 s15, s3, 0
	global_load_dwordx4 v[48:51], v0, s[14:15]
	s_add_u32 s74, s12, 0x880
	s_addc_u32 s75, s13, 0
	s_waitcnt vmcnt(16)
	v_mul_f32_e32 v212, v52, v124
	v_mul_f32_e32 v213, v53, v124
	v_mul_f32_e32 v214, v54, v124
	v_mul_f32_e32 v215, v55, v124
	v_fmac_f32_e32 v36, v52, v124
	v_fmac_f32_e32 v37, v53, v124
	v_fmac_f32_e32 v38, v54, v124
	v_fmac_f32_e32 v39, v55, v124
	v_fma_f32 v12, v36, s59, -v212
	v_fma_f32 v13, v37, s59, -v213
	v_fma_f32 v22, v38, s59, -v214
	v_fma_f32 v23, v39, s59, -v215
	s_waitcnt vmcnt(15)
	v_fma_f32 v36, -v56, v123, v36
	v_fma_f32 v37, -v57, v123, v37
	v_fma_f32 v38, -v58, v123, v38
	v_fma_f32 v39, -v59, v123, v39
	v_cvt_pk_bf16_f32 v208, v12, v13
	v_cvt_pk_bf16_f32 v209, v22, v23
	global_store_dwordx2 v222, v[208:209], s[74:75]
	s_add_u32 s56, s2, 0x9000
	s_addc_u32 s57, s3, 0
	global_load_dwordx4 v[52:55], v0, s[56:57]
	s_add_u32 s70, s2, 0x8000
	s_addc_u32 s71, s3, 0
	global_load_dwordx4 v[56:59], v0, s[70:71]
	s_add_u32 s54, s12, 0x1100
	s_addc_u32 s55, s13, 0
	s_waitcnt vmcnt(17)
	v_mul_f32_e32 v212, v60, v125
	v_mul_f32_e32 v213, v61, v125
	v_mul_f32_e32 v214, v62, v125
	v_mul_f32_e32 v215, v63, v125
	v_fmac_f32_e32 v36, v60, v125
	v_fmac_f32_e32 v37, v61, v125
	v_fmac_f32_e32 v38, v62, v125
	v_fmac_f32_e32 v39, v63, v125
	v_fma_f32 v12, v36, s59, -v212
	v_fma_f32 v13, v37, s59, -v213
	v_fma_f32 v22, v38, s59, -v214
	v_fma_f32 v23, v39, s59, -v215
	s_waitcnt vmcnt(16)
	v_fma_f32 v36, -v64, v124, v36
	v_fma_f32 v37, -v65, v124, v37
	v_fma_f32 v38, -v66, v124, v38
	v_fma_f32 v39, -v67, v124, v39
	v_cvt_pk_bf16_f32 v2, v12, v13
	v_cvt_pk_bf16_f32 v3, v22, v23
	global_store_dwordx2 v222, v[2:3], s[54:55]
	s_add_u32 s14, s2, 0xa000
	s_addc_u32 s15, s3, 0
	global_load_dwordx4 v[60:63], v0, s[14:15]
	s_add_u32 s56, s2, 0x9000
	s_addc_u32 s57, s3, 0
	global_load_dwordx4 v[64:67], v0, s[56:57]
	s_add_u32 s74, s12, 0x1980
	s_addc_u32 s75, s13, 0
	s_waitcnt vmcnt(18)
	v_mul_f32_e32 v212, v68, v126
	v_mul_f32_e32 v213, v69, v126
	v_mul_f32_e32 v214, v70, v126
	v_mul_f32_e32 v215, v71, v126
	v_fmac_f32_e32 v36, v68, v126
	v_fmac_f32_e32 v37, v69, v126
	v_fmac_f32_e32 v38, v70, v126
	v_fmac_f32_e32 v39, v71, v126
	v_fma_f32 v12, v36, s59, -v212
	v_fma_f32 v13, v37, s59, -v213
	v_fma_f32 v22, v38, s59, -v214
	v_fma_f32 v23, v39, s59, -v215
	s_waitcnt vmcnt(17)
	v_fma_f32 v36, -v72, v125, v36
	v_fma_f32 v37, -v73, v125, v37
	v_fma_f32 v38, -v74, v125, v38
	v_fma_f32 v39, -v75, v125, v39
	v_cvt_pk_bf16_f32 v208, v12, v13
	v_cvt_pk_bf16_f32 v209, v22, v23
	global_store_dwordx2 v222, v[208:209], s[74:75]
	s_add_u32 s70, s2, 0xb000
	s_addc_u32 s71, s3, 0
	global_load_dwordx4 v[68:71], v0, s[70:71]
	s_add_u32 s14, s2, 0xa000
	s_addc_u32 s15, s3, 0
	global_load_dwordx4 v[72:75], v0, s[14:15]
	s_add_u32 s54, s12, 0x2200
	s_addc_u32 s55, s13, 0
	s_waitcnt vmcnt(19)
	v_mul_f32_e32 v212, v76, v127
	v_mul_f32_e32 v213, v77, v127
	v_mul_f32_e32 v214, v78, v127
	v_mul_f32_e32 v215, v79, v127
	v_fmac_f32_e32 v36, v76, v127
	v_fmac_f32_e32 v37, v77, v127
	v_fmac_f32_e32 v38, v78, v127
	v_fmac_f32_e32 v39, v79, v127
	v_fma_f32 v12, v36, s59, -v212
	v_fma_f32 v13, v37, s59, -v213
	v_fma_f32 v22, v38, s59, -v214
	v_fma_f32 v23, v39, s59, -v215
	s_waitcnt vmcnt(18)
	v_fma_f32 v36, -v80, v126, v36
	v_fma_f32 v37, -v81, v126, v37
	v_fma_f32 v38, -v82, v126, v38
	v_fma_f32 v39, -v83, v126, v39
	v_cvt_pk_bf16_f32 v2, v12, v13
	v_cvt_pk_bf16_f32 v3, v22, v23
	global_store_dwordx2 v222, v[2:3], s[54:55]
	s_add_u32 s56, s2, 0xc000
	s_addc_u32 s57, s3, 0
	global_load_dwordx4 v[76:79], v0, s[56:57]
	s_add_u32 s70, s2, 0xb000
	s_addc_u32 s71, s3, 0
	global_load_dwordx4 v[80:83], v0, s[70:71]
	s_add_u32 s74, s12, 0x2a80
	s_addc_u32 s75, s13, 0
	s_waitcnt vmcnt(20)
	v_mul_f32_e32 v212, v84, v128
	v_mul_f32_e32 v213, v85, v128
	v_mul_f32_e32 v214, v86, v128
	v_mul_f32_e32 v215, v87, v128
	v_fmac_f32_e32 v36, v84, v128
	v_fmac_f32_e32 v37, v85, v128
	v_fmac_f32_e32 v38, v86, v128
	v_fmac_f32_e32 v39, v87, v128
	v_fma_f32 v12, v36, s59, -v212
	v_fma_f32 v13, v37, s59, -v213
	v_fma_f32 v22, v38, s59, -v214
	v_fma_f32 v23, v39, s59, -v215
	s_waitcnt vmcnt(19)
	v_fma_f32 v36, -v88, v127, v36
	v_fma_f32 v37, -v89, v127, v37
	v_fma_f32 v38, -v90, v127, v38
	v_fma_f32 v39, -v91, v127, v39
	v_cvt_pk_bf16_f32 v208, v12, v13
	v_cvt_pk_bf16_f32 v209, v22, v23
	global_store_dwordx2 v222, v[208:209], s[74:75]
	s_add_u32 s14, s2, 0xd000
	s_addc_u32 s15, s3, 0
	global_load_dwordx4 v[84:87], v0, s[14:15]
	s_add_u32 s56, s2, 0xc000
	s_addc_u32 s57, s3, 0
	global_load_dwordx4 v[88:91], v0, s[56:57]
	s_add_u32 s54, s12, 0x3300
	s_addc_u32 s55, s13, 0
	s_waitcnt vmcnt(21)
; DI unsigned pack_bf16(float lo, float hi) { f32x2 v = {lo, hi}; bf16v2 b = __builtin_convertvector(v, bf16v2); return __builtin_bit_cast(unsigned, b); }
; template <int W>
; DI void pool_rows(const float* __restrict__ x, const float* smr, bf16_t* __restrict__ pb, int t0, int s0, int tid) {
;     ...
; #pragma unroll 8
;   for (int tl = 0; tl < 64; ++tl) {
;     const int t = t0 + tl, s = s0 + tl;
;     int to = t - W + 1; if (to < tq0) to = tq0;
;     const f32x4 hn = *(const f32x4*)(xq + (size_t)t * D) * smr[15 + tl];
;     const f32x4 ho = *(const f32x4*)(xq + (size_t)to * D) * smr[15 + tl - W + 1];
;     const int cnt = (s + 1 < W) ? (s + 1) : W;
;     const float ic = 1.f / (float)cnt;
;     Sm += hn;
;     const f32x4 p = Sm * ic - hn;
;     Sm -= ho;
;     u32x2 o; o.x = pack_bf16(p.x, p.y); o.y = pack_bf16(p.z, p.w);
;     *(u32x2*)(pb + (size_t)t * LDH + tid * 4) = o;
;   }
	v_mul_f32_e32 v212, v92, v129
	v_mul_f32_e32 v213, v93, v129
	v_mul_f32_e32 v214, v94, v129
	v_mul_f32_e32 v215, v95, v129
	v_fmac_f32_e32 v36, v92, v129
	v_fmac_f32_e32 v37, v93, v129
	v_fmac_f32_e32 v38, v94, v129
	v_fmac_f32_e32 v39, v95, v129
	v_fma_f32 v12, v36, s59, -v212
	v_fma_f32 v13, v37, s59, -v213
	v_fma_f32 v22, v38, s59, -v214
	v_fma_f32 v23, v39, s59, -v215
	s_waitcnt vmcnt(20)
	v_fma_f32 v36, -v96, v128, v36
	v_fma_f32 v37, -v97, v128, v37
	v_fma_f32 v38, -v98, v128, v38
	v_fma_f32 v39, -v99, v128, v39
	v_cvt_pk_bf16_f32 v2, v12, v13
	v_cvt_pk_bf16_f32 v3, v22, v23
	global_store_dwordx2 v222, v[2:3], s[54:55]
	s_add_u32 s70, s2, 0xe000
	s_addc_u32 s71, s3, 0
	global_load_dwordx4 v[92:95], v0, s[70:71]
	s_add_u32 s14, s2, 0xd000
	s_addc_u32 s15, s3, 0
	global_load_dwordx4 v[96:99], v0, s[14:15]
	s_add_u32 s74, s12, 0x3b80
	s_addc_u32 s75, s13, 0
	s_waitcnt vmcnt(22)
	v_mul_f32_e32 v212, v100, v130
	v_mul_f32_e32 v213, v101, v130
	v_mul_f32_e32 v214, v102, v130
	v_mul_f32_e32 v215, v103, v130
	v_fmac_f32_e32 v36, v100, v130
	v_fmac_f32_e32 v37, v101, v130
	v_fmac_f32_e32 v38, v102, v130
	v_fmac_f32_e32 v39, v103, v130
	v_fma_f32 v12, v36, s59, -v212
	v_fma_f32 v13, v37, s59, -v213
	v_fma_f32 v22, v38, s59, -v214
	v_fma_f32 v23, v39, s59, -v215
	s_waitcnt vmcnt(21)
	v_fma_f32 v36, -v104, v129, v36
	v_fma_f32 v37, -v105, v129, v37
	v_fma_f32 v38, -v106, v129, v38
	v_fma_f32 v39, -v107, v129, v39
	v_cvt_pk_bf16_f32 v208, v12, v13
	v_cvt_pk_bf16_f32 v209, v22, v23
	global_store_dwordx2 v222, v[208:209], s[74:75]
	s_add_u32 s56, s2, 0xf000
	s_addc_u32 s57, s3, 0
	global_load_dwordx4 v[100:103], v0, s[56:57]
	s_add_u32 s70, s2, 0xe000
	s_addc_u32 s71, s3, 0
	global_load_dwordx4 v[104:107], v0, s[70:71]
	s_add_u32 s54, s12, 0x4400
	s_addc_u32 s55, s13, 0
	s_waitcnt vmcnt(22)
	v_mul_f32_e32 v212, v44, v131
	v_mul_f32_e32 v213, v45, v131
	v_mul_f32_e32 v214, v46, v131
	v_mul_f32_e32 v215, v47, v131
	v_fmac_f32_e32 v36, v44, v131
	v_fmac_f32_e32 v37, v45, v131
	v_fmac_f32_e32 v38, v46, v131
	v_fmac_f32_e32 v39, v47, v131
	v_fma_f32 v12, v36, s59, -v212
	v_fma_f32 v13, v37, s59, -v213
	v_fma_f32 v22, v38, s59, -v214
	v_fma_f32 v23, v39, s59, -v215
	s_waitcnt vmcnt(21)
	v_fma_f32 v36, -v48, v130, v36
	v_fma_f32 v37, -v49, v130, v37
	v_fma_f32 v38, -v50, v130, v38
	v_fma_f32 v39, -v51, v130, v39
	v_cvt_pk_bf16_f32 v2, v12, v13
	v_cvt_pk_bf16_f32 v3, v22, v23
	global_store_dwordx2 v222, v[2:3], s[54:55]
	s_add_u32 s14, s2, 0x10000
	s_addc_u32 s15, s3, 0
	global_load_dwordx4 v[44:47], v0, s[14:15]
	s_add_u32 s56, s2, 0xf000
	s_addc_u32 s57, s3, 0
	global_load_dwordx4 v[48:51], v0, s[56:57]
	s_add_u32 s74, s12, 0x4c80
	s_addc_u32 s75, s13, 0
	s_waitcnt vmcnt(22)
	v_mul_f32_e32 v212, v52, v132
	v_mul_f32_e32 v213, v53, v132
	v_mul_f32_e32 v214, v54, v132
	v_mul_f32_e32 v215, v55, v132
	v_fmac_f32_e32 v36, v52, v132
	v_fmac_f32_e32 v37, v53, v132
	v_fmac_f32_e32 v38, v54, v132
	v_fmac_f32_e32 v39, v55, v132
	v_fma_f32 v12, v36, s59, -v212
	v_fma_f32 v13, v37, s59, -v213
	v_fma_f32 v22, v38, s59, -v214
	v_fma_f32 v23, v39, s59, -v215
	s_waitcnt vmcnt(21)
	v_fma_f32 v36, -v56, v131, v36
	v_fma_f32 v37, -v57, v131, v37
	v_fma_f32 v38, -v58, v131, v38
	v_fma_f32 v39, -v59, v131, v39
	v_cvt_pk_bf16_f32 v208, v12, v13
	v_cvt_pk_bf16_f32 v209, v22, v23
	global_store_dwordx2 v222, v[208:209], s[74:75]
	s_add_u32 s70, s2, 0x11000
	s_addc_u32 s71, s3, 0
	global_load_dwordx4 v[52:55], v0, s[70:71]
	s_add_u32 s14, s2, 0x10000
	s_addc_u32 s15, s3, 0
	global_load_dwordx4 v[56:59], v0, s[14:15]
	s_add_u32 s54, s12, 0x5500
	s_addc_u32 s55, s13, 0
	s_waitcnt vmcnt(22)
	v_mul_f32_e32 v212, v60, v133
	v_mul_f32_e32 v213, v61, v133
	v_mul_f32_e32 v214, v62, v133
	v_mul_f32_e32 v215, v63, v133
	v_fmac_f32_e32 v36, v60, v133
	v_fmac_f32_e32 v37, v61, v133
	v_fmac_f32_e32 v38, v62, v133
	v_fmac_f32_e32 v39, v63, v133
	v_fma_f32 v12, v36, s59, -v212
	v_fma_f32 v13, v37, s59, -v213
	v_fma_f32 v22, v38, s59, -v214
	v_fma_f32 v23, v39, s59, -v215
	s_waitcnt vmcnt(21)
	v_fma_f32 v36, -v64, v132, v36
	v_fma_f32 v37, -v65, v132, v37
	v_fma_f32 v38, -v66, v132, v38
	v_fma_f32 v39, -v67, v132, v39
	v_cvt_pk_bf16_f32 v2, v12, v13
	v_cvt_pk_bf16_f32 v3, v22, v23
	global_store_dwordx2 v222, v[2:3], s[54:55]
	s_add_u32 s56, s2, 0x12000
	s_addc_u32 s57, s3, 0
	global_load_dwordx4 v[60:63], v0, s[56:57]
	s_add_u32 s70, s2, 0x11000
	s_addc_u32 s71, s3, 0
	global_load_dwordx4 v[64:67], v0, s[70:71]
	s_add_u32 s74, s12, 0x5d80
	s_addc_u32 s75, s13, 0
	s_waitcnt vmcnt(22)
	v_mul_f32_e32 v212, v68, v134
	v_mul_f32_e32 v213, v69, v134
	v_mul_f32_e32 v214, v70, v134
	v_mul_f32_e32 v215, v71, v134
	v_fmac_f32_e32 v36, v68, v134
	v_fmac_f32_e32 v37, v69, v134
	v_fmac_f32_e32 v38, v70, v134
	v_fmac_f32_e32 v39, v71, v134
	v_fma_f32 v12, v36, s59, -v212
	v_fma_f32 v13, v37, s59, -v213
	v_fma_f32 v22, v38, s59, -v214
	v_fma_f32 v23, v39, s59, -v215
	s_waitcnt vmcnt(21)
	v_fma_f32 v36, -v72, v133, v36
	v_fma_f32 v37, -v73, v133, v37
	v_fma_f32 v38, -v74, v133, v38
	v_fma_f32 v39, -v75, v133, v39
	v_cvt_pk_bf16_f32 v208, v12, v13
	v_cvt_pk_bf16_f32 v209, v22, v23
	global_store_dwordx2 v222, v[208:209], s[74:75]
	s_add_u32 s14, s2, 0x13000
	s_addc_u32 s15, s3, 0
	global_load_dwordx4 v[68:71], v0, s[14:15]
	s_add_u32 s56, s2, 0x12000
	s_addc_u32 s57, s3, 0
	global_load_dwordx4 v[72:75], v0, s[56:57]
	s_add_u32 s54, s12, 0x6600
	s_addc_u32 s55, s13, 0
	s_waitcnt vmcnt(22)
	v_mul_f32_e32 v212, v76, v135
	v_mul_f32_e32 v213, v77, v135
	v_mul_f32_e32 v214, v78, v135
	v_mul_f32_e32 v215, v79, v135
	v_fmac_f32_e32 v36, v76, v135
	v_fmac_f32_e32 v37, v77, v135
	v_fmac_f32_e32 v38, v78, v135
	v_fmac_f32_e32 v39, v79, v135
	v_fma_f32 v12, v36, s59, -v212
	v_fma_f32 v13, v37, s59, -v213
	v_fma_f32 v22, v38, s59, -v214
	v_fma_f32 v23, v39, s59, -v215
	s_waitcnt vmcnt(21)
; DI unsigned pack_bf16(float lo, float hi) { f32x2 v = {lo, hi}; bf16v2 b = __builtin_convertvector(v, bf16v2); return __builtin_bit_cast(unsigned, b); }
; template <int W>
; DI void pool_rows(const float* __restrict__ x, const float* smr, bf16_t* __restrict__ pb, int t0, int s0, int tid) {
;     ...
; #pragma unroll 8
;   for (int tl = 0; tl < 64; ++tl) {
;     const int t = t0 + tl, s = s0 + tl;
;     int to = t - W + 1; if (to < tq0) to = tq0;
;     const f32x4 hn = *(const f32x4*)(xq + (size_t)t * D) * smr[15 + tl];
;     const f32x4 ho = *(const f32x4*)(xq + (size_t)to * D) * smr[15 + tl - W + 1];
;     const int cnt = (s + 1 < W) ? (s + 1) : W;
;     const float ic = 1.f / (float)cnt;
;     Sm += hn;
;     const f32x4 p = Sm * ic - hn;
;     Sm -= ho;
;     u32x2 o; o.x = pack_bf16(p.x, p.y); o.y = pack_bf16(p.z, p.w);
;     *(u32x2*)(pb + (size_t)t * LDH + tid * 4) = o;
;   }
	v_fma_f32 v36, -v80, v134, v36
	v_fma_f32 v37, -v81, v134, v37
	v_fma_f32 v38, -v82, v134, v38
	v_fma_f32 v39, -v83, v134, v39
	v_cvt_pk_bf16_f32 v2, v12, v13
	v_cvt_pk_bf16_f32 v3, v22, v23
	global_store_dwordx2 v222, v[2:3], s[54:55]
	s_add_u32 s70, s2, 0x14000
	s_addc_u32 s71, s3, 0
	global_load_dwordx4 v[76:79], v0, s[70:71]
	s_add_u32 s14, s2, 0x13000
	s_addc_u32 s15, s3, 0
	global_load_dwordx4 v[80:83], v0, s[14:15]
	s_add_u32 s74, s12, 0x6e80
	s_addc_u32 s75, s13, 0
	s_waitcnt vmcnt(22)
	v_mul_f32_e32 v212, v84, v136
	v_mul_f32_e32 v213, v85, v136
	v_mul_f32_e32 v214, v86, v136
	v_mul_f32_e32 v215, v87, v136
	v_fmac_f32_e32 v36, v84, v136
	v_fmac_f32_e32 v37, v85, v136
	v_fmac_f32_e32 v38, v86, v136
	v_fmac_f32_e32 v39, v87, v136
	v_fma_f32 v12, v36, s59, -v212
	v_fma_f32 v13, v37, s59, -v213
	v_fma_f32 v22, v38, s59, -v214
	v_fma_f32 v23, v39, s59, -v215
	s_waitcnt vmcnt(21)
	v_fma_f32 v36, -v88, v135, v36
	v_fma_f32 v37, -v89, v135, v37
	v_fma_f32 v38, -v90, v135, v38
	v_fma_f32 v39, -v91, v135, v39
	v_cvt_pk_bf16_f32 v208, v12, v13
	v_cvt_pk_bf16_f32 v209, v22, v23
	global_store_dwordx2 v222, v[208:209], s[74:75]
	s_add_u32 s56, s2, 0x15000
	s_addc_u32 s57, s3, 0
	global_load_dwordx4 v[84:87], v0, s[56:57]
	s_add_u32 s70, s2, 0x14000
	s_addc_u32 s71, s3, 0
	global_load_dwordx4 v[88:91], v0, s[70:71]
	s_add_u32 s54, s12, 0x7700
	s_addc_u32 s55, s13, 0
	s_waitcnt vmcnt(22)
	v_mul_f32_e32 v212, v92, v137
	v_mul_f32_e32 v213, v93, v137
	v_mul_f32_e32 v214, v94, v137
	v_mul_f32_e32 v215, v95, v137
	v_fmac_f32_e32 v36, v92, v137
	v_fmac_f32_e32 v37, v93, v137
	v_fmac_f32_e32 v38, v94, v137
	v_fmac_f32_e32 v39, v95, v137
	v_fma_f32 v12, v36, s59, -v212
	v_fma_f32 v13, v37, s59, -v213
	v_fma_f32 v22, v38, s59, -v214
	v_fma_f32 v23, v39, s59, -v215
	s_waitcnt vmcnt(21)
	v_fma_f32 v36, -v96, v136, v36
	v_fma_f32 v37, -v97, v136, v37
	v_fma_f32 v38, -v98, v136, v38
	v_fma_f32 v39, -v99, v136, v39
	v_cvt_pk_bf16_f32 v2, v12, v13
	v_cvt_pk_bf16_f32 v3, v22, v23
	global_store_dwordx2 v222, v[2:3], s[54:55]
	s_add_u32 s14, s2, 0x16000
	s_addc_u32 s15, s3, 0
	global_load_dwordx4 v[92:95], v0, s[14:15]
	s_add_u32 s56, s2, 0x15000
	s_addc_u32 s57, s3, 0
	global_load_dwordx4 v[96:99], v0, s[56:57]
	s_add_u32 s74, s12, 0x7f80
	s_addc_u32 s75, s13, 0
	s_waitcnt vmcnt(22)
	v_mul_f32_e32 v212, v100, v138
	v_mul_f32_e32 v213, v101, v138
	v_mul_f32_e32 v214, v102, v138
	v_mul_f32_e32 v215, v103, v138
	v_fmac_f32_e32 v36, v100, v138
	v_fmac_f32_e32 v37, v101, v138
	v_fmac_f32_e32 v38, v102, v138
	v_fmac_f32_e32 v39, v103, v138
	v_fma_f32 v12, v36, s59, -v212
	v_fma_f32 v13, v37, s59, -v213
	v_fma_f32 v22, v38, s59, -v214
	v_fma_f32 v23, v39, s59, -v215
	s_waitcnt vmcnt(21)
	v_fma_f32 v36, -v104, v137, v36
	v_fma_f32 v37, -v105, v137, v37
	v_fma_f32 v38, -v106, v137, v38
	v_fma_f32 v39, -v107, v137, v39
	v_cvt_pk_bf16_f32 v208, v12, v13
	v_cvt_pk_bf16_f32 v209, v22, v23
	global_store_dwordx2 v222, v[208:209], s[74:75]
	s_add_u32 s70, s2, 0x17000
	s_addc_u32 s71, s3, 0
	global_load_dwordx4 v[100:103], v0, s[70:71]
	s_add_u32 s14, s2, 0x16000
	s_addc_u32 s15, s3, 0
	global_load_dwordx4 v[104:107], v0, s[14:15]
	s_add_u32 s54, s12, 0x8800
	s_addc_u32 s55, s13, 0
	s_waitcnt vmcnt(22)
	v_mul_f32_e32 v212, v44, v139
	v_mul_f32_e32 v213, v45, v139
	v_mul_f32_e32 v214, v46, v139
	v_mul_f32_e32 v215, v47, v139
	v_fmac_f32_e32 v36, v44, v139
	v_fmac_f32_e32 v37, v45, v139
	v_fmac_f32_e32 v38, v46, v139
	v_fmac_f32_e32 v39, v47, v139
	v_fma_f32 v12, v36, s59, -v212
	v_fma_f32 v13, v37, s59, -v213
	v_fma_f32 v22, v38, s59, -v214
	v_fma_f32 v23, v39, s59, -v215
	s_waitcnt vmcnt(21)
	v_fma_f32 v36, -v48, v138, v36
	v_fma_f32 v37, -v49, v138, v37
	v_fma_f32 v38, -v50, v138, v38
	v_fma_f32 v39, -v51, v138, v39
	v_cvt_pk_bf16_f32 v2, v12, v13
	v_cvt_pk_bf16_f32 v3, v22, v23
	global_store_dwordx2 v222, v[2:3], s[54:55]
	s_add_u32 s56, s2, 0x18000
	s_addc_u32 s57, s3, 0
	global_load_dwordx4 v[44:47], v0, s[56:57]
	s_add_u32 s70, s2, 0x17000
	s_addc_u32 s71, s3, 0
	global_load_dwordx4 v[48:51], v0, s[70:71]
	s_add_u32 s74, s12, 0x9080
	s_addc_u32 s75, s13, 0
	s_waitcnt vmcnt(22)
	v_mul_f32_e32 v212, v52, v140
	v_mul_f32_e32 v213, v53, v140
	v_mul_f32_e32 v214, v54, v140
	v_mul_f32_e32 v215, v55, v140
	v_fmac_f32_e32 v36, v52, v140
	v_fmac_f32_e32 v37, v53, v140
	v_fmac_f32_e32 v38, v54, v140
	v_fmac_f32_e32 v39, v55, v140
	v_fma_f32 v12, v36, s59, -v212
	v_fma_f32 v13, v37, s59, -v213
	v_fma_f32 v22, v38, s59, -v214
	v_fma_f32 v23, v39, s59, -v215
	s_waitcnt vmcnt(21)
	v_fma_f32 v36, -v56, v139, v36
	v_fma_f32 v37, -v57, v139, v37
	v_fma_f32 v38, -v58, v139, v38
	v_fma_f32 v39, -v59, v139, v39
	v_cvt_pk_bf16_f32 v208, v12, v13
	v_cvt_pk_bf16_f32 v209, v22, v23
	global_store_dwordx2 v222, v[208:209], s[74:75]
	s_add_u32 s14, s2, 0x19000
	s_addc_u32 s15, s3, 0
	global_load_dwordx4 v[52:55], v0, s[14:15]
	s_add_u32 s56, s2, 0x18000
	s_addc_u32 s57, s3, 0
	global_load_dwordx4 v[56:59], v0, s[56:57]
	s_add_u32 s54, s12, 0x9900
	s_addc_u32 s55, s13, 0
	s_waitcnt vmcnt(22)
	v_mul_f32_e32 v212, v60, v141
	v_mul_f32_e32 v213, v61, v141
	v_mul_f32_e32 v214, v62, v141
	v_mul_f32_e32 v215, v63, v141
	v_fmac_f32_e32 v36, v60, v141
	v_fmac_f32_e32 v37, v61, v141
	v_fmac_f32_e32 v38, v62, v141
	v_fmac_f32_e32 v39, v63, v141
	v_fma_f32 v12, v36, s59, -v212
	v_fma_f32 v13, v37, s59, -v213
	v_fma_f32 v22, v38, s59, -v214
	v_fma_f32 v23, v39, s59, -v215
	s_waitcnt vmcnt(21)
; DI unsigned pack_bf16(float lo, float hi) { f32x2 v = {lo, hi}; bf16v2 b = __builtin_convertvector(v, bf16v2); return __builtin_bit_cast(unsigned, b); }
; template <int W>
; DI void pool_rows(const float* __restrict__ x, const float* smr, bf16_t* __restrict__ pb, int t0, int s0, int tid) {
;     ...
; #pragma unroll 8
;   for (int tl = 0; tl < 64; ++tl) {
;     const int t = t0 + tl, s = s0 + tl;
;     int to = t - W + 1; if (to < tq0) to = tq0;
;     const f32x4 hn = *(const f32x4*)(xq + (size_t)t * D) * smr[15 + tl];
;     const f32x4 ho = *(const f32x4*)(xq + (size_t)to * D) * smr[15 + tl - W + 1];
;     const int cnt = (s + 1 < W) ? (s + 1) : W;
;     const float ic = 1.f / (float)cnt;
;     Sm += hn;
;     const f32x4 p = Sm * ic - hn;
;     Sm -= ho;
;     u32x2 o; o.x = pack_bf16(p.x, p.y); o.y = pack_bf16(p.z, p.w);
;     *(u32x2*)(pb + (size_t)t * LDH + tid * 4) = o;
;   }
	v_fma_f32 v36, -v64, v140, v36
	v_fma_f32 v37, -v65, v140, v37
	v_fma_f32 v38, -v66, v140, v38
	v_fma_f32 v39, -v67, v140, v39
	v_cvt_pk_bf16_f32 v2, v12, v13
	v_cvt_pk_bf16_f32 v3, v22, v23
	global_store_dwordx2 v222, v[2:3], s[54:55]
	s_add_u32 s70, s2, 0x1a000
	s_addc_u32 s71, s3, 0
	global_load_dwordx4 v[60:63], v0, s[70:71]
	s_add_u32 s14, s2, 0x19000
	s_addc_u32 s15, s3, 0
	global_load_dwordx4 v[64:67], v0, s[14:15]
	s_add_u32 s74, s12, 0xa180
	s_addc_u32 s75, s13, 0
	s_waitcnt vmcnt(22)
	v_mul_f32_e32 v212, v68, v142
	v_mul_f32_e32 v213, v69, v142
	v_mul_f32_e32 v214, v70, v142
	v_mul_f32_e32 v215, v71, v142
	v_fmac_f32_e32 v36, v68, v142
	v_fmac_f32_e32 v37, v69, v142
	v_fmac_f32_e32 v38, v70, v142
	v_fmac_f32_e32 v39, v71, v142
	v_fma_f32 v12, v36, s59, -v212
	v_fma_f32 v13, v37, s59, -v213
	v_fma_f32 v22, v38, s59, -v214
	v_fma_f32 v23, v39, s59, -v215
	s_waitcnt vmcnt(21)
	v_fma_f32 v36, -v72, v141, v36
	v_fma_f32 v37, -v73, v141, v37
	v_fma_f32 v38, -v74, v141, v38
	v_fma_f32 v39, -v75, v141, v39
	v_cvt_pk_bf16_f32 v208, v12, v13
	v_cvt_pk_bf16_f32 v209, v22, v23
	global_store_dwordx2 v222, v[208:209], s[74:75]
	s_add_u32 s56, s2, 0x1b000
	s_addc_u32 s57, s3, 0
	global_load_dwordx4 v[68:71], v0, s[56:57]
	s_add_u32 s70, s2, 0x1a000
	s_addc_u32 s71, s3, 0
	global_load_dwordx4 v[72:75], v0, s[70:71]
	s_add_u32 s54, s12, 0xaa00
	s_addc_u32 s55, s13, 0
	s_waitcnt vmcnt(22)
	v_mul_f32_e32 v212, v76, v143
	v_mul_f32_e32 v213, v77, v143
	v_mul_f32_e32 v214, v78, v143
	v_mul_f32_e32 v215, v79, v143
	v_fmac_f32_e32 v36, v76, v143
	v_fmac_f32_e32 v37, v77, v143
	v_fmac_f32_e32 v38, v78, v143
	v_fmac_f32_e32 v39, v79, v143
	v_fma_f32 v12, v36, s59, -v212
	v_fma_f32 v13, v37, s59, -v213
	v_fma_f32 v22, v38, s59, -v214
	v_fma_f32 v23, v39, s59, -v215
	s_waitcnt vmcnt(21)
	v_fma_f32 v36, -v80, v142, v36
	v_fma_f32 v37, -v81, v142, v37
	v_fma_f32 v38, -v82, v142, v38
	v_fma_f32 v39, -v83, v142, v39
	v_cvt_pk_bf16_f32 v2, v12, v13
	v_cvt_pk_bf16_f32 v3, v22, v23
	global_store_dwordx2 v222, v[2:3], s[54:55]
	s_add_u32 s14, s2, 0x1c000
	s_addc_u32 s15, s3, 0
	global_load_dwordx4 v[76:79], v0, s[14:15]
	s_add_u32 s56, s2, 0x1b000
	s_addc_u32 s57, s3, 0
	global_load_dwordx4 v[80:83], v0, s[56:57]
	s_add_u32 s74, s12, 0xb280
	s_addc_u32 s75, s13, 0
	s_waitcnt vmcnt(22)
	v_mul_f32_e32 v212, v84, v144
	v_mul_f32_e32 v213, v85, v144
	v_mul_f32_e32 v214, v86, v144
	v_mul_f32_e32 v215, v87, v144
	v_fmac_f32_e32 v36, v84, v144
	v_fmac_f32_e32 v37, v85, v144
	v_fmac_f32_e32 v38, v86, v144
	v_fmac_f32_e32 v39, v87, v144
	v_fma_f32 v12, v36, s59, -v212
	v_fma_f32 v13, v37, s59, -v213
	v_fma_f32 v22, v38, s59, -v214
	v_fma_f32 v23, v39, s59, -v215
	s_waitcnt vmcnt(21)
	v_fma_f32 v36, -v88, v143, v36
	v_fma_f32 v37, -v89, v143, v37
	v_fma_f32 v38, -v90, v143, v38
	v_fma_f32 v39, -v91, v143, v39
	v_cvt_pk_bf16_f32 v208, v12, v13
	v_cvt_pk_bf16_f32 v209, v22, v23
	global_store_dwordx2 v222, v[208:209], s[74:75]
	s_add_u32 s70, s2, 0x1d000
	s_addc_u32 s71, s3, 0
	global_load_dwordx4 v[84:87], v0, s[70:71]
	s_add_u32 s14, s2, 0x1c000
	s_addc_u32 s15, s3, 0
	global_load_dwordx4 v[88:91], v0, s[14:15]
	s_add_u32 s54, s12, 0xbb00
	s_addc_u32 s55, s13, 0
	s_waitcnt vmcnt(22)
	v_mul_f32_e32 v212, v92, v145
	v_mul_f32_e32 v213, v93, v145
	v_mul_f32_e32 v214, v94, v145
	v_mul_f32_e32 v215, v95, v145
	v_fmac_f32_e32 v36, v92, v145
	v_fmac_f32_e32 v37, v93, v145
	v_fmac_f32_e32 v38, v94, v145
	v_fmac_f32_e32 v39, v95, v145
	v_fma_f32 v12, v36, s59, -v212
	v_fma_f32 v13, v37, s59, -v213
	v_fma_f32 v22, v38, s59, -v214
	v_fma_f32 v23, v39, s59, -v215
	s_waitcnt vmcnt(21)
	v_fma_f32 v36, -v96, v144, v36
	v_fma_f32 v37, -v97, v144, v37
	v_fma_f32 v38, -v98, v144, v38
	v_fma_f32 v39, -v99, v144, v39
	v_cvt_pk_bf16_f32 v2, v12, v13
	v_cvt_pk_bf16_f32 v3, v22, v23
	global_store_dwordx2 v222, v[2:3], s[54:55]
	s_add_u32 s56, s2, 0x1e000
	s_addc_u32 s57, s3, 0
	global_load_dwordx4 v[92:95], v0, s[56:57]
	s_add_u32 s70, s2, 0x1d000
	s_addc_u32 s71, s3, 0
	global_load_dwordx4 v[96:99], v0, s[70:71]
	s_add_u32 s74, s12, 0xc380
	s_addc_u32 s75, s13, 0
	s_waitcnt vmcnt(22)
	v_mul_f32_e32 v212, v100, v146
	v_mul_f32_e32 v213, v101, v146
	v_mul_f32_e32 v214, v102, v146
	v_mul_f32_e32 v215, v103, v146
	v_fmac_f32_e32 v36, v100, v146
	v_fmac_f32_e32 v37, v101, v146
	v_fmac_f32_e32 v38, v102, v146
	v_fmac_f32_e32 v39, v103, v146
	v_fma_f32 v12, v36, s59, -v212
	v_fma_f32 v13, v37, s59, -v213
	v_fma_f32 v22, v38, s59, -v214
	v_fma_f32 v23, v39, s59, -v215
	s_waitcnt vmcnt(21)
	v_fma_f32 v36, -v104, v145, v36
	v_fma_f32 v37, -v105, v145, v37
	v_fma_f32 v38, -v106, v145, v38
	v_fma_f32 v39, -v107, v145, v39
	v_cvt_pk_bf16_f32 v208, v12, v13
	v_cvt_pk_bf16_f32 v209, v22, v23
	global_store_dwordx2 v222, v[208:209], s[74:75]
	s_add_u32 s14, s2, 0x1f000
	s_addc_u32 s15, s3, 0
	global_load_dwordx4 v[100:103], v0, s[14:15]
	s_add_u32 s56, s2, 0x1e000
	s_addc_u32 s57, s3, 0
	global_load_dwordx4 v[104:107], v0, s[56:57]
	s_add_u32 s54, s12, 0xcc00
	s_addc_u32 s55, s13, 0
	s_waitcnt vmcnt(22)
	v_mul_f32_e32 v212, v44, v147
	v_mul_f32_e32 v213, v45, v147
	v_mul_f32_e32 v214, v46, v147
	v_mul_f32_e32 v215, v47, v147
	v_fmac_f32_e32 v36, v44, v147
	v_fmac_f32_e32 v37, v45, v147
	v_fmac_f32_e32 v38, v46, v147
	v_fmac_f32_e32 v39, v47, v147
	v_fma_f32 v12, v36, s59, -v212
	v_fma_f32 v13, v37, s59, -v213
	v_fma_f32 v22, v38, s59, -v214
	v_fma_f32 v23, v39, s59, -v215
	s_waitcnt vmcnt(21)
; DI unsigned pack_bf16(float lo, float hi) { f32x2 v = {lo, hi}; bf16v2 b = __builtin_convertvector(v, bf16v2); return __builtin_bit_cast(unsigned, b); }
; template <int W>
; DI void pool_rows(const float* __restrict__ x, const float* smr, bf16_t* __restrict__ pb, int t0, int s0, int tid) {
;     ...
; #pragma unroll 8
;   for (int tl = 0; tl < 64; ++tl) {
;     const int t = t0 + tl, s = s0 + tl;
;     int to = t - W + 1; if (to < tq0) to = tq0;
;     const f32x4 hn = *(const f32x4*)(xq + (size_t)t * D) * smr[15 + tl];
;     const f32x4 ho = *(const f32x4*)(xq + (size_t)to * D) * smr[15 + tl - W + 1];
;     const int cnt = (s + 1 < W) ? (s + 1) : W;
;     const float ic = 1.f / (float)cnt;
;     Sm += hn;
;     const f32x4 p = Sm * ic - hn;
;     Sm -= ho;
;     u32x2 o; o.x = pack_bf16(p.x, p.y); o.y = pack_bf16(p.z, p.w);
;     *(u32x2*)(pb + (size_t)t * LDH + tid * 4) = o;
;   }
	v_fma_f32 v36, -v48, v146, v36
	v_fma_f32 v37, -v49, v146, v37
	v_fma_f32 v38, -v50, v146, v38
	v_fma_f32 v39, -v51, v146, v39
	v_cvt_pk_bf16_f32 v2, v12, v13
	v_cvt_pk_bf16_f32 v3, v22, v23
	global_store_dwordx2 v222, v[2:3], s[54:55]
	s_add_u32 s70, s2, 0x20000
	s_addc_u32 s71, s3, 0
	global_load_dwordx4 v[44:47], v0, s[70:71]
	s_add_u32 s14, s2, 0x1f000
	s_addc_u32 s15, s3, 0
	global_load_dwordx4 v[48:51], v0, s[14:15]
	s_add_u32 s74, s12, 0xd480
	s_addc_u32 s75, s13, 0
	s_waitcnt vmcnt(22)
	v_mul_f32_e32 v212, v52, v148
	v_mul_f32_e32 v213, v53, v148
	v_mul_f32_e32 v214, v54, v148
	v_mul_f32_e32 v215, v55, v148
	v_fmac_f32_e32 v36, v52, v148
	v_fmac_f32_e32 v37, v53, v148
	v_fmac_f32_e32 v38, v54, v148
	v_fmac_f32_e32 v39, v55, v148
	v_fma_f32 v12, v36, s59, -v212
	v_fma_f32 v13, v37, s59, -v213
	v_fma_f32 v22, v38, s59, -v214
	v_fma_f32 v23, v39, s59, -v215
	s_waitcnt vmcnt(21)
	v_fma_f32 v36, -v56, v147, v36
	v_fma_f32 v37, -v57, v147, v37
	v_fma_f32 v38, -v58, v147, v38
	v_fma_f32 v39, -v59, v147, v39
	v_cvt_pk_bf16_f32 v208, v12, v13
	v_cvt_pk_bf16_f32 v209, v22, v23
	global_store_dwordx2 v222, v[208:209], s[74:75]
	s_add_u32 s56, s2, 0x21000
	s_addc_u32 s57, s3, 0
	global_load_dwordx4 v[52:55], v0, s[56:57]
	s_add_u32 s70, s2, 0x20000
	s_addc_u32 s71, s3, 0
	global_load_dwordx4 v[56:59], v0, s[70:71]
	s_add_u32 s54, s12, 0xdd00
	s_addc_u32 s55, s13, 0
	s_waitcnt vmcnt(22)
	v_mul_f32_e32 v212, v60, v149
	v_mul_f32_e32 v213, v61, v149
	v_mul_f32_e32 v214, v62, v149
	v_mul_f32_e32 v215, v63, v149
	v_fmac_f32_e32 v36, v60, v149
	v_fmac_f32_e32 v37, v61, v149
	v_fmac_f32_e32 v38, v62, v149
	v_fmac_f32_e32 v39, v63, v149
	v_fma_f32 v12, v36, s59, -v212
	v_fma_f32 v13, v37, s59, -v213
	v_fma_f32 v22, v38, s59, -v214
	v_fma_f32 v23, v39, s59, -v215
	s_waitcnt vmcnt(21)
	v_fma_f32 v36, -v64, v148, v36
	v_fma_f32 v37, -v65, v148, v37
	v_fma_f32 v38, -v66, v148, v38
	v_fma_f32 v39, -v67, v148, v39
	v_cvt_pk_bf16_f32 v2, v12, v13
	v_cvt_pk_bf16_f32 v3, v22, v23
	global_store_dwordx2 v222, v[2:3], s[54:55]
	s_add_u32 s14, s2, 0x22000
	s_addc_u32 s15, s3, 0
	global_load_dwordx4 v[60:63], v0, s[14:15]
	s_add_u32 s56, s2, 0x21000
	s_addc_u32 s57, s3, 0
	global_load_dwordx4 v[64:67], v0, s[56:57]
	s_add_u32 s74, s12, 0xe580
	s_addc_u32 s75, s13, 0
	s_waitcnt vmcnt(22)
	v_mul_f32_e32 v212, v68, v150
	v_mul_f32_e32 v213, v69, v150
	v_mul_f32_e32 v214, v70, v150
	v_mul_f32_e32 v215, v71, v150
	v_fmac_f32_e32 v36, v68, v150
	v_fmac_f32_e32 v37, v69, v150
	v_fmac_f32_e32 v38, v70, v150
	v_fmac_f32_e32 v39, v71, v150
	v_fma_f32 v12, v36, s59, -v212
	v_fma_f32 v13, v37, s59, -v213
	v_fma_f32 v22, v38, s59, -v214
	v_fma_f32 v23, v39, s59, -v215
	s_waitcnt vmcnt(21)
	v_fma_f32 v36, -v72, v149, v36
	v_fma_f32 v37, -v73, v149, v37
	v_fma_f32 v38, -v74, v149, v38
	v_fma_f32 v39, -v75, v149, v39
	v_cvt_pk_bf16_f32 v208, v12, v13
	v_cvt_pk_bf16_f32 v209, v22, v23
	global_store_dwordx2 v222, v[208:209], s[74:75]
	s_add_u32 s70, s2, 0x23000
	s_addc_u32 s71, s3, 0
	global_load_dwordx4 v[68:71], v0, s[70:71]
	s_add_u32 s14, s2, 0x22000
	s_addc_u32 s15, s3, 0
	global_load_dwordx4 v[72:75], v0, s[14:15]
	s_add_u32 s54, s12, 0xee00
	s_addc_u32 s55, s13, 0
	s_waitcnt vmcnt(22)
	v_mul_f32_e32 v212, v76, v151
	v_mul_f32_e32 v213, v77, v151
	v_mul_f32_e32 v214, v78, v151
	v_mul_f32_e32 v215, v79, v151
	v_fmac_f32_e32 v36, v76, v151
	v_fmac_f32_e32 v37, v77, v151
	v_fmac_f32_e32 v38, v78, v151
	v_fmac_f32_e32 v39, v79, v151
	v_fma_f32 v12, v36, s59, -v212
	v_fma_f32 v13, v37, s59, -v213
	v_fma_f32 v22, v38, s59, -v214
	v_fma_f32 v23, v39, s59, -v215
	s_waitcnt vmcnt(21)
	v_fma_f32 v36, -v80, v150, v36
	v_fma_f32 v37, -v81, v150, v37
	v_fma_f32 v38, -v82, v150, v38
	v_fma_f32 v39, -v83, v150, v39
	v_cvt_pk_bf16_f32 v2, v12, v13
	v_cvt_pk_bf16_f32 v3, v22, v23
	global_store_dwordx2 v222, v[2:3], s[54:55]
	s_add_u32 s56, s2, 0x24000
	s_addc_u32 s57, s3, 0
	global_load_dwordx4 v[76:79], v0, s[56:57]
	s_add_u32 s70, s2, 0x23000
	s_addc_u32 s71, s3, 0
	global_load_dwordx4 v[80:83], v0, s[70:71]
	s_add_u32 s74, s12, 0xf680
	s_addc_u32 s75, s13, 0
	s_waitcnt vmcnt(22)
	v_mul_f32_e32 v212, v84, v152
	v_mul_f32_e32 v213, v85, v152
	v_mul_f32_e32 v214, v86, v152
	v_mul_f32_e32 v215, v87, v152
	v_fmac_f32_e32 v36, v84, v152
	v_fmac_f32_e32 v37, v85, v152
	v_fmac_f32_e32 v38, v86, v152
	v_fmac_f32_e32 v39, v87, v152
	v_fma_f32 v12, v36, s59, -v212
	v_fma_f32 v13, v37, s59, -v213
	v_fma_f32 v22, v38, s59, -v214
	v_fma_f32 v23, v39, s59, -v215
	s_waitcnt vmcnt(21)
	v_fma_f32 v36, -v88, v151, v36
	v_fma_f32 v37, -v89, v151, v37
	v_fma_f32 v38, -v90, v151, v38
	v_fma_f32 v39, -v91, v151, v39
	v_cvt_pk_bf16_f32 v208, v12, v13
	v_cvt_pk_bf16_f32 v209, v22, v23
	global_store_dwordx2 v222, v[208:209], s[74:75]
	s_add_u32 s14, s2, 0x25000
	s_addc_u32 s15, s3, 0
	global_load_dwordx4 v[84:87], v0, s[14:15]
	s_add_u32 s56, s2, 0x24000
	s_addc_u32 s57, s3, 0
	global_load_dwordx4 v[88:91], v0, s[56:57]
	s_add_u32 s54, s12, 0xff00
	s_addc_u32 s55, s13, 0
	s_waitcnt vmcnt(22)
	v_mul_f32_e32 v212, v92, v153
	v_mul_f32_e32 v213, v93, v153
	v_mul_f32_e32 v214, v94, v153
	v_mul_f32_e32 v215, v95, v153
	v_fmac_f32_e32 v36, v92, v153
	v_fmac_f32_e32 v37, v93, v153
	v_fmac_f32_e32 v38, v94, v153
	v_fmac_f32_e32 v39, v95, v153
	v_fma_f32 v12, v36, s59, -v212
	v_fma_f32 v13, v37, s59, -v213
	v_fma_f32 v22, v38, s59, -v214
	v_fma_f32 v23, v39, s59, -v215
	s_waitcnt vmcnt(21)
; DI unsigned pack_bf16(float lo, float hi) { f32x2 v = {lo, hi}; bf16v2 b = __builtin_convertvector(v, bf16v2); return __builtin_bit_cast(unsigned, b); }
; template <int W>
; DI void pool_rows(const float* __restrict__ x, const float* smr, bf16_t* __restrict__ pb, int t0, int s0, int tid) {
;     ...
; #pragma unroll 8
;   for (int tl = 0; tl < 64; ++tl) {
;     const int t = t0 + tl, s = s0 + tl;
;     int to = t - W + 1; if (to < tq0) to = tq0;
;     const f32x4 hn = *(const f32x4*)(xq + (size_t)t * D) * smr[15 + tl];
;     const f32x4 ho = *(const f32x4*)(xq + (size_t)to * D) * smr[15 + tl - W + 1];
;     const int cnt = (s + 1 < W) ? (s + 1) : W;
;     const float ic = 1.f / (float)cnt;
;     Sm += hn;
;     const f32x4 p = Sm * ic - hn;
;     Sm -= ho;
;     u32x2 o; o.x = pack_bf16(p.x, p.y); o.y = pack_bf16(p.z, p.w);
;     *(u32x2*)(pb + (size_t)t * LDH + tid * 4) = o;
;   }
	v_fma_f32 v36, -v96, v152, v36
	v_fma_f32 v37, -v97, v152, v37
	v_fma_f32 v38, -v98, v152, v38
	v_fma_f32 v39, -v99, v152, v39
	v_cvt_pk_bf16_f32 v2, v12, v13
	v_cvt_pk_bf16_f32 v3, v22, v23
	global_store_dwordx2 v222, v[2:3], s[54:55]
	s_add_u32 s70, s2, 0x26000
	s_addc_u32 s71, s3, 0
	global_load_dwordx4 v[92:95], v0, s[70:71]
	s_add_u32 s14, s2, 0x25000
	s_addc_u32 s15, s3, 0
	global_load_dwordx4 v[96:99], v0, s[14:15]
	s_add_u32 s74, s12, 0x10780
	s_addc_u32 s75, s13, 0
	s_waitcnt vmcnt(22)
	v_mul_f32_e32 v212, v100, v154
	v_mul_f32_e32 v213, v101, v154
	v_mul_f32_e32 v214, v102, v154
	v_mul_f32_e32 v215, v103, v154
	v_fmac_f32_e32 v36, v100, v154
	v_fmac_f32_e32 v37, v101, v154
	v_fmac_f32_e32 v38, v102, v154
	v_fmac_f32_e32 v39, v103, v154
	v_fma_f32 v12, v36, s59, -v212
	v_fma_f32 v13, v37, s59, -v213
	v_fma_f32 v22, v38, s59, -v214
	v_fma_f32 v23, v39, s59, -v215
	s_waitcnt vmcnt(21)
	v_fma_f32 v36, -v104, v153, v36
	v_fma_f32 v37, -v105, v153, v37
	v_fma_f32 v38, -v106, v153, v38
	v_fma_f32 v39, -v107, v153, v39
	v_cvt_pk_bf16_f32 v208, v12, v13
	v_cvt_pk_bf16_f32 v209, v22, v23
	global_store_dwordx2 v222, v[208:209], s[74:75]
	s_add_u32 s56, s2, 0x27000
	s_addc_u32 s57, s3, 0
	global_load_dwordx4 v[100:103], v0, s[56:57]
	s_add_u32 s70, s2, 0x26000
	s_addc_u32 s71, s3, 0
	global_load_dwordx4 v[104:107], v0, s[70:71]
	s_add_u32 s54, s12, 0x11000
	s_addc_u32 s55, s13, 0
	s_waitcnt vmcnt(22)
	v_mul_f32_e32 v212, v44, v155
	v_mul_f32_e32 v213, v45, v155
	v_mul_f32_e32 v214, v46, v155
	v_mul_f32_e32 v215, v47, v155
	v_fmac_f32_e32 v36, v44, v155
	v_fmac_f32_e32 v37, v45, v155
	v_fmac_f32_e32 v38, v46, v155
	v_fmac_f32_e32 v39, v47, v155
	v_fma_f32 v12, v36, s59, -v212
	v_fma_f32 v13, v37, s59, -v213
	v_fma_f32 v22, v38, s59, -v214
	v_fma_f32 v23, v39, s59, -v215
	s_waitcnt vmcnt(21)
	v_fma_f32 v36, -v48, v154, v36
	v_fma_f32 v37, -v49, v154, v37
	v_fma_f32 v38, -v50, v154, v38
	v_fma_f32 v39, -v51, v154, v39
	v_cvt_pk_bf16_f32 v2, v12, v13
	v_cvt_pk_bf16_f32 v3, v22, v23
	global_store_dwordx2 v222, v[2:3], s[54:55]
	s_add_u32 s14, s2, 0x28000
	s_addc_u32 s15, s3, 0
	global_load_dwordx4 v[44:47], v0, s[14:15]
	s_add_u32 s56, s2, 0x27000
	s_addc_u32 s57, s3, 0
	global_load_dwordx4 v[48:51], v0, s[56:57]
	s_add_u32 s74, s12, 0x11880
	s_addc_u32 s75, s13, 0
	s_waitcnt vmcnt(22)
	v_mul_f32_e32 v212, v52, v156
	v_mul_f32_e32 v213, v53, v156
	v_mul_f32_e32 v214, v54, v156
	v_mul_f32_e32 v215, v55, v156
	v_fmac_f32_e32 v36, v52, v156
	v_fmac_f32_e32 v37, v53, v156
	v_fmac_f32_e32 v38, v54, v156
	v_fmac_f32_e32 v39, v55, v156
	v_fma_f32 v12, v36, s59, -v212
	v_fma_f32 v13, v37, s59, -v213
	v_fma_f32 v22, v38, s59, -v214
	v_fma_f32 v23, v39, s59, -v215
	s_waitcnt vmcnt(21)
	v_fma_f32 v36, -v56, v155, v36
	v_fma_f32 v37, -v57, v155, v37
	v_fma_f32 v38, -v58, v155, v38
	v_fma_f32 v39, -v59, v155, v39
	v_cvt_pk_bf16_f32 v208, v12, v13
	v_cvt_pk_bf16_f32 v209, v22, v23
	global_store_dwordx2 v222, v[208:209], s[74:75]
	s_add_u32 s70, s2, 0x29000
	s_addc_u32 s71, s3, 0
	global_load_dwordx4 v[52:55], v0, s[70:71]
	s_add_u32 s14, s2, 0x28000
	s_addc_u32 s15, s3, 0
	global_load_dwordx4 v[56:59], v0, s[14:15]
	s_add_u32 s54, s12, 0x12100
	s_addc_u32 s55, s13, 0
	s_waitcnt vmcnt(22)
	v_mul_f32_e32 v212, v60, v157
	v_mul_f32_e32 v213, v61, v157
	v_mul_f32_e32 v214, v62, v157
	v_mul_f32_e32 v215, v63, v157
	v_fmac_f32_e32 v36, v60, v157
	v_fmac_f32_e32 v37, v61, v157
	v_fmac_f32_e32 v38, v62, v157
	v_fmac_f32_e32 v39, v63, v157
	v_fma_f32 v12, v36, s59, -v212
	v_fma_f32 v13, v37, s59, -v213
	v_fma_f32 v22, v38, s59, -v214
	v_fma_f32 v23, v39, s59, -v215
	s_waitcnt vmcnt(21)
	v_fma_f32 v36, -v64, v156, v36
	v_fma_f32 v37, -v65, v156, v37
	v_fma_f32 v38, -v66, v156, v38
	v_fma_f32 v39, -v67, v156, v39
	v_cvt_pk_bf16_f32 v2, v12, v13
	v_cvt_pk_bf16_f32 v3, v22, v23
	global_store_dwordx2 v222, v[2:3], s[54:55]
	s_add_u32 s56, s2, 0x2a000
	s_addc_u32 s57, s3, 0
	global_load_dwordx4 v[60:63], v0, s[56:57]
	s_add_u32 s70, s2, 0x29000
	s_addc_u32 s71, s3, 0
	global_load_dwordx4 v[64:67], v0, s[70:71]
	s_add_u32 s74, s12, 0x12980
	s_addc_u32 s75, s13, 0
	s_waitcnt vmcnt(22)
	v_mul_f32_e32 v212, v68, v158
	v_mul_f32_e32 v213, v69, v158
	v_mul_f32_e32 v214, v70, v158
	v_mul_f32_e32 v215, v71, v158
	v_fmac_f32_e32 v36, v68, v158
	v_fmac_f32_e32 v37, v69, v158
	v_fmac_f32_e32 v38, v70, v158
	v_fmac_f32_e32 v39, v71, v158
	v_fma_f32 v12, v36, s59, -v212
	v_fma_f32 v13, v37, s59, -v213
	v_fma_f32 v22, v38, s59, -v214
	v_fma_f32 v23, v39, s59, -v215
	s_waitcnt vmcnt(21)
	v_fma_f32 v36, -v72, v157, v36
	v_fma_f32 v37, -v73, v157, v37
	v_fma_f32 v38, -v74, v157, v38
	v_fma_f32 v39, -v75, v157, v39
	v_cvt_pk_bf16_f32 v208, v12, v13
	v_cvt_pk_bf16_f32 v209, v22, v23
	global_store_dwordx2 v222, v[208:209], s[74:75]
	s_add_u32 s14, s2, 0x2b000
	s_addc_u32 s15, s3, 0
	global_load_dwordx4 v[68:71], v0, s[14:15]
	s_add_u32 s56, s2, 0x2a000
	s_addc_u32 s57, s3, 0
	global_load_dwordx4 v[72:75], v0, s[56:57]
	s_add_u32 s54, s12, 0x13200
	s_addc_u32 s55, s13, 0
	s_waitcnt vmcnt(22)
	v_mul_f32_e32 v212, v76, v159
	v_mul_f32_e32 v213, v77, v159
	v_mul_f32_e32 v214, v78, v159
	v_mul_f32_e32 v215, v79, v159
	v_fmac_f32_e32 v36, v76, v159
	v_fmac_f32_e32 v37, v77, v159
	v_fmac_f32_e32 v38, v78, v159
	v_fmac_f32_e32 v39, v79, v159
	v_fma_f32 v12, v36, s59, -v212
	v_fma_f32 v13, v37, s59, -v213
	v_fma_f32 v22, v38, s59, -v214
	v_fma_f32 v23, v39, s59, -v215
	s_waitcnt vmcnt(21)
; DI unsigned pack_bf16(float lo, float hi) { f32x2 v = {lo, hi}; bf16v2 b = __builtin_convertvector(v, bf16v2); return __builtin_bit_cast(unsigned, b); }
; template <int W>
; DI void pool_rows(const float* __restrict__ x, const float* smr, bf16_t* __restrict__ pb, int t0, int s0, int tid) {
;     ...
; #pragma unroll 8
;   for (int tl = 0; tl < 64; ++tl) {
;     const int t = t0 + tl, s = s0 + tl;
;     int to = t - W + 1; if (to < tq0) to = tq0;
;     const f32x4 hn = *(const f32x4*)(xq + (size_t)t * D) * smr[15 + tl];
;     const f32x4 ho = *(const f32x4*)(xq + (size_t)to * D) * smr[15 + tl - W + 1];
;     const int cnt = (s + 1 < W) ? (s + 1) : W;
;     const float ic = 1.f / (float)cnt;
;     Sm += hn;
;     const f32x4 p = Sm * ic - hn;
;     Sm -= ho;
;     u32x2 o; o.x = pack_bf16(p.x, p.y); o.y = pack_bf16(p.z, p.w);
;     *(u32x2*)(pb + (size_t)t * LDH + tid * 4) = o;
;   }
	v_fma_f32 v36, -v80, v158, v36
	v_fma_f32 v37, -v81, v158, v37
	v_fma_f32 v38, -v82, v158, v38
	v_fma_f32 v39, -v83, v158, v39
	v_cvt_pk_bf16_f32 v2, v12, v13
	v_cvt_pk_bf16_f32 v3, v22, v23
	global_store_dwordx2 v222, v[2:3], s[54:55]
	s_add_u32 s70, s2, 0x2c000
	s_addc_u32 s71, s3, 0
	global_load_dwordx4 v[76:79], v0, s[70:71]
	s_add_u32 s14, s2, 0x2b000
	s_addc_u32 s15, s3, 0
	global_load_dwordx4 v[80:83], v0, s[14:15]
	s_add_u32 s74, s12, 0x13a80
	s_addc_u32 s75, s13, 0
	s_waitcnt vmcnt(22)
	v_mul_f32_e32 v212, v84, v160
	v_mul_f32_e32 v213, v85, v160
	v_mul_f32_e32 v214, v86, v160
	v_mul_f32_e32 v215, v87, v160
	v_fmac_f32_e32 v36, v84, v160
	v_fmac_f32_e32 v37, v85, v160
	v_fmac_f32_e32 v38, v86, v160
	v_fmac_f32_e32 v39, v87, v160
	v_fma_f32 v12, v36, s59, -v212
	v_fma_f32 v13, v37, s59, -v213
	v_fma_f32 v22, v38, s59, -v214
	v_fma_f32 v23, v39, s59, -v215
	s_waitcnt vmcnt(21)
	v_fma_f32 v36, -v88, v159, v36
	v_fma_f32 v37, -v89, v159, v37
	v_fma_f32 v38, -v90, v159, v38
	v_fma_f32 v39, -v91, v159, v39
	v_cvt_pk_bf16_f32 v208, v12, v13
	v_cvt_pk_bf16_f32 v209, v22, v23
	global_store_dwordx2 v222, v[208:209], s[74:75]
	s_add_u32 s56, s2, 0x2d000
	s_addc_u32 s57, s3, 0
	global_load_dwordx4 v[84:87], v0, s[56:57]
	s_add_u32 s70, s2, 0x2c000
	s_addc_u32 s71, s3, 0
	global_load_dwordx4 v[88:91], v0, s[70:71]
	s_add_u32 s54, s12, 0x14300
	s_addc_u32 s55, s13, 0
	s_waitcnt vmcnt(22)
	v_mul_f32_e32 v212, v92, v161
	v_mul_f32_e32 v213, v93, v161
	v_mul_f32_e32 v214, v94, v161
	v_mul_f32_e32 v215, v95, v161
	v_fmac_f32_e32 v36, v92, v161
	v_fmac_f32_e32 v37, v93, v161
	v_fmac_f32_e32 v38, v94, v161
	v_fmac_f32_e32 v39, v95, v161
	v_fma_f32 v12, v36, s59, -v212
	v_fma_f32 v13, v37, s59, -v213
	v_fma_f32 v22, v38, s59, -v214
	v_fma_f32 v23, v39, s59, -v215
	s_waitcnt vmcnt(21)
	v_fma_f32 v36, -v96, v160, v36
	v_fma_f32 v37, -v97, v160, v37
	v_fma_f32 v38, -v98, v160, v38
	v_fma_f32 v39, -v99, v160, v39
	v_cvt_pk_bf16_f32 v2, v12, v13
	v_cvt_pk_bf16_f32 v3, v22, v23
	global_store_dwordx2 v222, v[2:3], s[54:55]
	s_add_u32 s14, s2, 0x2e000
	s_addc_u32 s15, s3, 0
	global_load_dwordx4 v[92:95], v0, s[14:15]
	s_add_u32 s56, s2, 0x2d000
	s_addc_u32 s57, s3, 0
	global_load_dwordx4 v[96:99], v0, s[56:57]
	s_add_u32 s74, s12, 0x14b80
	s_addc_u32 s75, s13, 0
	s_waitcnt vmcnt(22)
	v_mul_f32_e32 v212, v100, v162
	v_mul_f32_e32 v213, v101, v162
	v_mul_f32_e32 v214, v102, v162
	v_mul_f32_e32 v215, v103, v162
	v_fmac_f32_e32 v36, v100, v162
	v_fmac_f32_e32 v37, v101, v162
	v_fmac_f32_e32 v38, v102, v162
	v_fmac_f32_e32 v39, v103, v162
	v_fma_f32 v12, v36, s59, -v212
	v_fma_f32 v13, v37, s59, -v213
	v_fma_f32 v22, v38, s59, -v214
	v_fma_f32 v23, v39, s59, -v215
	s_waitcnt vmcnt(21)
	v_fma_f32 v36, -v104, v161, v36
	v_fma_f32 v37, -v105, v161, v37
	v_fma_f32 v38, -v106, v161, v38
	v_fma_f32 v39, -v107, v161, v39
	v_cvt_pk_bf16_f32 v208, v12, v13
	v_cvt_pk_bf16_f32 v209, v22, v23
	global_store_dwordx2 v222, v[208:209], s[74:75]
	s_add_u32 s70, s2, 0x2f000
	s_addc_u32 s71, s3, 0
	global_load_dwordx4 v[100:103], v0, s[70:71]
	s_add_u32 s14, s2, 0x2e000
	s_addc_u32 s15, s3, 0
	global_load_dwordx4 v[104:107], v0, s[14:15]
	s_add_u32 s54, s12, 0x15400
	s_addc_u32 s55, s13, 0
	s_waitcnt vmcnt(22)
	v_mul_f32_e32 v212, v44, v163
	v_mul_f32_e32 v213, v45, v163
	v_mul_f32_e32 v214, v46, v163
	v_mul_f32_e32 v215, v47, v163
	v_fmac_f32_e32 v36, v44, v163
	v_fmac_f32_e32 v37, v45, v163
	v_fmac_f32_e32 v38, v46, v163
	v_fmac_f32_e32 v39, v47, v163
	v_fma_f32 v12, v36, s59, -v212
	v_fma_f32 v13, v37, s59, -v213
	v_fma_f32 v22, v38, s59, -v214
	v_fma_f32 v23, v39, s59, -v215
	s_waitcnt vmcnt(21)
	v_fma_f32 v36, -v48, v162, v36
	v_fma_f32 v37, -v49, v162, v37
	v_fma_f32 v38, -v50, v162, v38
	v_fma_f32 v39, -v51, v162, v39
	v_cvt_pk_bf16_f32 v2, v12, v13
	v_cvt_pk_bf16_f32 v3, v22, v23
	global_store_dwordx2 v222, v[2:3], s[54:55]
	s_add_u32 s56, s2, 0x30000
	s_addc_u32 s57, s3, 0
	global_load_dwordx4 v[44:47], v0, s[56:57]
	s_add_u32 s70, s2, 0x2f000
	s_addc_u32 s71, s3, 0
	global_load_dwordx4 v[48:51], v0, s[70:71]
	s_add_u32 s74, s12, 0x15c80
	s_addc_u32 s75, s13, 0
	s_waitcnt vmcnt(22)
	v_mul_f32_e32 v212, v52, v164
	v_mul_f32_e32 v213, v53, v164
	v_mul_f32_e32 v214, v54, v164
	v_mul_f32_e32 v215, v55, v164
	v_fmac_f32_e32 v36, v52, v164
	v_fmac_f32_e32 v37, v53, v164
	v_fmac_f32_e32 v38, v54, v164
	v_fmac_f32_e32 v39, v55, v164
	v_fma_f32 v12, v36, s59, -v212
	v_fma_f32 v13, v37, s59, -v213
	v_fma_f32 v22, v38, s59, -v214
	v_fma_f32 v23, v39, s59, -v215
	s_waitcnt vmcnt(21)
	v_fma_f32 v36, -v56, v163, v36
	v_fma_f32 v37, -v57, v163, v37
	v_fma_f32 v38, -v58, v163, v38
	v_fma_f32 v39, -v59, v163, v39
	v_cvt_pk_bf16_f32 v208, v12, v13
	v_cvt_pk_bf16_f32 v209, v22, v23
	global_store_dwordx2 v222, v[208:209], s[74:75]
	s_add_u32 s14, s2, 0x31000
	s_addc_u32 s15, s3, 0
	global_load_dwordx4 v[52:55], v0, s[14:15]
	s_add_u32 s56, s2, 0x30000
	s_addc_u32 s57, s3, 0
	global_load_dwordx4 v[56:59], v0, s[56:57]
	s_add_u32 s54, s12, 0x16500
	s_addc_u32 s55, s13, 0
	s_waitcnt vmcnt(22)
	v_mul_f32_e32 v212, v60, v165
	v_mul_f32_e32 v213, v61, v165
	v_mul_f32_e32 v214, v62, v165
	v_mul_f32_e32 v215, v63, v165
	v_fmac_f32_e32 v36, v60, v165
	v_fmac_f32_e32 v37, v61, v165
	v_fmac_f32_e32 v38, v62, v165
	v_fmac_f32_e32 v39, v63, v165
	v_fma_f32 v12, v36, s59, -v212
	v_fma_f32 v13, v37, s59, -v213
	v_fma_f32 v22, v38, s59, -v214
	v_fma_f32 v23, v39, s59, -v215
	s_waitcnt vmcnt(21)
; DI unsigned pack_bf16(float lo, float hi) { f32x2 v = {lo, hi}; bf16v2 b = __builtin_convertvector(v, bf16v2); return __builtin_bit_cast(unsigned, b); }
; template <int W>
; DI void pool_rows(const float* __restrict__ x, const float* smr, bf16_t* __restrict__ pb, int t0, int s0, int tid) {
;     ...
; #pragma unroll 8
;   for (int tl = 0; tl < 64; ++tl) {
;     const int t = t0 + tl, s = s0 + tl;
;     int to = t - W + 1; if (to < tq0) to = tq0;
;     const f32x4 hn = *(const f32x4*)(xq + (size_t)t * D) * smr[15 + tl];
;     const f32x4 ho = *(const f32x4*)(xq + (size_t)to * D) * smr[15 + tl - W + 1];
;     const int cnt = (s + 1 < W) ? (s + 1) : W;
;     const float ic = 1.f / (float)cnt;
;     Sm += hn;
;     const f32x4 p = Sm * ic - hn;
;     Sm -= ho;
;     u32x2 o; o.x = pack_bf16(p.x, p.y); o.y = pack_bf16(p.z, p.w);
;     *(u32x2*)(pb + (size_t)t * LDH + tid * 4) = o;
;   }
	v_fma_f32 v36, -v64, v164, v36
	v_fma_f32 v37, -v65, v164, v37
	v_fma_f32 v38, -v66, v164, v38
	v_fma_f32 v39, -v67, v164, v39
	v_cvt_pk_bf16_f32 v2, v12, v13
	v_cvt_pk_bf16_f32 v3, v22, v23
	global_store_dwordx2 v222, v[2:3], s[54:55]
	s_add_u32 s70, s2, 0x32000
	s_addc_u32 s71, s3, 0
	global_load_dwordx4 v[60:63], v0, s[70:71]
	s_add_u32 s14, s2, 0x31000
	s_addc_u32 s15, s3, 0
	global_load_dwordx4 v[64:67], v0, s[14:15]
	s_add_u32 s74, s12, 0x16d80
	s_addc_u32 s75, s13, 0
	s_waitcnt vmcnt(22)
	v_mul_f32_e32 v212, v68, v166
	v_mul_f32_e32 v213, v69, v166
	v_mul_f32_e32 v214, v70, v166
	v_mul_f32_e32 v215, v71, v166
	v_fmac_f32_e32 v36, v68, v166
	v_fmac_f32_e32 v37, v69, v166
	v_fmac_f32_e32 v38, v70, v166
	v_fmac_f32_e32 v39, v71, v166
	v_fma_f32 v12, v36, s59, -v212
	v_fma_f32 v13, v37, s59, -v213
	v_fma_f32 v22, v38, s59, -v214
	v_fma_f32 v23, v39, s59, -v215
	s_waitcnt vmcnt(21)
	v_fma_f32 v36, -v72, v165, v36
	v_fma_f32 v37, -v73, v165, v37
	v_fma_f32 v38, -v74, v165, v38
	v_fma_f32 v39, -v75, v165, v39
	v_cvt_pk_bf16_f32 v208, v12, v13
	v_cvt_pk_bf16_f32 v209, v22, v23
	global_store_dwordx2 v222, v[208:209], s[74:75]
	s_add_u32 s56, s2, 0x33000
	s_addc_u32 s57, s3, 0
	global_load_dwordx4 v[68:71], v0, s[56:57]
	s_add_u32 s70, s2, 0x32000
	s_addc_u32 s71, s3, 0
	global_load_dwordx4 v[72:75], v0, s[70:71]
	s_add_u32 s54, s12, 0x17600
	s_addc_u32 s55, s13, 0
	s_waitcnt vmcnt(22)
	v_mul_f32_e32 v212, v76, v167
	v_mul_f32_e32 v213, v77, v167
	v_mul_f32_e32 v214, v78, v167
	v_mul_f32_e32 v215, v79, v167
	v_fmac_f32_e32 v36, v76, v167
	v_fmac_f32_e32 v37, v77, v167
	v_fmac_f32_e32 v38, v78, v167
	v_fmac_f32_e32 v39, v79, v167
	v_fma_f32 v12, v36, s59, -v212
	v_fma_f32 v13, v37, s59, -v213
	v_fma_f32 v22, v38, s59, -v214
	v_fma_f32 v23, v39, s59, -v215
	s_waitcnt vmcnt(21)
	v_fma_f32 v36, -v80, v166, v36
	v_fma_f32 v37, -v81, v166, v37
	v_fma_f32 v38, -v82, v166, v38
	v_fma_f32 v39, -v83, v166, v39
	v_cvt_pk_bf16_f32 v2, v12, v13
	v_cvt_pk_bf16_f32 v3, v22, v23
	global_store_dwordx2 v222, v[2:3], s[54:55]
	s_add_u32 s14, s2, 0x34000
	s_addc_u32 s15, s3, 0
	global_load_dwordx4 v[76:79], v0, s[14:15]
	s_add_u32 s56, s2, 0x33000
	s_addc_u32 s57, s3, 0
	global_load_dwordx4 v[80:83], v0, s[56:57]
	s_add_u32 s74, s12, 0x17e80
	s_addc_u32 s75, s13, 0
	s_waitcnt vmcnt(22)
	v_mul_f32_e32 v212, v84, v168
	v_mul_f32_e32 v213, v85, v168
	v_mul_f32_e32 v214, v86, v168
	v_mul_f32_e32 v215, v87, v168
	v_fmac_f32_e32 v36, v84, v168
	v_fmac_f32_e32 v37, v85, v168
	v_fmac_f32_e32 v38, v86, v168
	v_fmac_f32_e32 v39, v87, v168
	v_fma_f32 v12, v36, s59, -v212
	v_fma_f32 v13, v37, s59, -v213
	v_fma_f32 v22, v38, s59, -v214
	v_fma_f32 v23, v39, s59, -v215
	s_waitcnt vmcnt(21)
	v_fma_f32 v36, -v88, v167, v36
	v_fma_f32 v37, -v89, v167, v37
	v_fma_f32 v38, -v90, v167, v38
	v_fma_f32 v39, -v91, v167, v39
	v_cvt_pk_bf16_f32 v208, v12, v13
	v_cvt_pk_bf16_f32 v209, v22, v23
	global_store_dwordx2 v222, v[208:209], s[74:75]
	s_add_u32 s70, s2, 0x35000
	s_addc_u32 s71, s3, 0
	global_load_dwordx4 v[84:87], v0, s[70:71]
	s_add_u32 s14, s2, 0x34000
	s_addc_u32 s15, s3, 0
	global_load_dwordx4 v[88:91], v0, s[14:15]
	s_add_u32 s54, s12, 0x18700
	s_addc_u32 s55, s13, 0
	s_waitcnt vmcnt(22)
	v_mul_f32_e32 v212, v92, v169
	v_mul_f32_e32 v213, v93, v169
	v_mul_f32_e32 v214, v94, v169
	v_mul_f32_e32 v215, v95, v169
	v_fmac_f32_e32 v36, v92, v169
	v_fmac_f32_e32 v37, v93, v169
	v_fmac_f32_e32 v38, v94, v169
	v_fmac_f32_e32 v39, v95, v169
	v_fma_f32 v12, v36, s59, -v212
	v_fma_f32 v13, v37, s59, -v213
	v_fma_f32 v22, v38, s59, -v214
	v_fma_f32 v23, v39, s59, -v215
	s_waitcnt vmcnt(21)
	v_fma_f32 v36, -v96, v168, v36
	v_fma_f32 v37, -v97, v168, v37
	v_fma_f32 v38, -v98, v168, v38
	v_fma_f32 v39, -v99, v168, v39
	v_cvt_pk_bf16_f32 v2, v12, v13
	v_cvt_pk_bf16_f32 v3, v22, v23
	global_store_dwordx2 v222, v[2:3], s[54:55]
	s_add_u32 s56, s2, 0x36000
	s_addc_u32 s57, s3, 0
	global_load_dwordx4 v[92:95], v0, s[56:57]
	s_add_u32 s70, s2, 0x35000
	s_addc_u32 s71, s3, 0
	global_load_dwordx4 v[96:99], v0, s[70:71]
	s_add_u32 s74, s12, 0x18f80
	s_addc_u32 s75, s13, 0
	s_waitcnt vmcnt(22)
	v_mul_f32_e32 v212, v100, v170
	v_mul_f32_e32 v213, v101, v170
	v_mul_f32_e32 v214, v102, v170
	v_mul_f32_e32 v215, v103, v170
	v_fmac_f32_e32 v36, v100, v170
	v_fmac_f32_e32 v37, v101, v170
	v_fmac_f32_e32 v38, v102, v170
	v_fmac_f32_e32 v39, v103, v170
	v_fma_f32 v12, v36, s59, -v212
	v_fma_f32 v13, v37, s59, -v213
	v_fma_f32 v22, v38, s59, -v214
	v_fma_f32 v23, v39, s59, -v215
	s_waitcnt vmcnt(21)
	v_fma_f32 v36, -v104, v169, v36
	v_fma_f32 v37, -v105, v169, v37
	v_fma_f32 v38, -v106, v169, v38
	v_fma_f32 v39, -v107, v169, v39
	v_cvt_pk_bf16_f32 v208, v12, v13
	v_cvt_pk_bf16_f32 v209, v22, v23
	global_store_dwordx2 v222, v[208:209], s[74:75]
	s_add_u32 s14, s2, 0x37000
	s_addc_u32 s15, s3, 0
	global_load_dwordx4 v[100:103], v0, s[14:15]
	s_add_u32 s56, s2, 0x36000
	s_addc_u32 s57, s3, 0
	global_load_dwordx4 v[104:107], v0, s[56:57]
	s_add_u32 s54, s12, 0x19800
	s_addc_u32 s55, s13, 0
	s_waitcnt vmcnt(22)
	v_mul_f32_e32 v212, v44, v171
	v_mul_f32_e32 v213, v45, v171
	v_mul_f32_e32 v214, v46, v171
	v_mul_f32_e32 v215, v47, v171
	v_fmac_f32_e32 v36, v44, v171
	v_fmac_f32_e32 v37, v45, v171
	v_fmac_f32_e32 v38, v46, v171
	v_fmac_f32_e32 v39, v47, v171
	v_fma_f32 v12, v36, s59, -v212
	v_fma_f32 v13, v37, s59, -v213
	v_fma_f32 v22, v38, s59, -v214
	v_fma_f32 v23, v39, s59, -v215
	s_waitcnt vmcnt(21)
; DI unsigned pack_bf16(float lo, float hi) { f32x2 v = {lo, hi}; bf16v2 b = __builtin_convertvector(v, bf16v2); return __builtin_bit_cast(unsigned, b); }
; template <int W>
; DI void pool_rows(const float* __restrict__ x, const float* smr, bf16_t* __restrict__ pb, int t0, int s0, int tid) {
;     ...
; #pragma unroll 8
;   for (int tl = 0; tl < 64; ++tl) {
;     const int t = t0 + tl, s = s0 + tl;
;     int to = t - W + 1; if (to < tq0) to = tq0;
;     const f32x4 hn = *(const f32x4*)(xq + (size_t)t * D) * smr[15 + tl];
;     const f32x4 ho = *(const f32x4*)(xq + (size_t)to * D) * smr[15 + tl - W + 1];
;     const int cnt = (s + 1 < W) ? (s + 1) : W;
;     const float ic = 1.f / (float)cnt;
;     Sm += hn;
;     const f32x4 p = Sm * ic - hn;
;     Sm -= ho;
;     u32x2 o; o.x = pack_bf16(p.x, p.y); o.y = pack_bf16(p.z, p.w);
;     *(u32x2*)(pb + (size_t)t * LDH + tid * 4) = o;
;   }
	v_fma_f32 v36, -v48, v170, v36
	v_fma_f32 v37, -v49, v170, v37
	v_fma_f32 v38, -v50, v170, v38
	v_fma_f32 v39, -v51, v170, v39
	v_cvt_pk_bf16_f32 v2, v12, v13
	v_cvt_pk_bf16_f32 v3, v22, v23
	global_store_dwordx2 v222, v[2:3], s[54:55]
	s_add_u32 s70, s2, 0x38000
	s_addc_u32 s71, s3, 0
	global_load_dwordx4 v[44:47], v0, s[70:71]
	s_add_u32 s14, s2, 0x37000
	s_addc_u32 s15, s3, 0
	global_load_dwordx4 v[48:51], v0, s[14:15]
	s_add_u32 s74, s12, 0x1a080
	s_addc_u32 s75, s13, 0
	s_waitcnt vmcnt(22)
	v_mul_f32_e32 v212, v52, v172
	v_mul_f32_e32 v213, v53, v172
	v_mul_f32_e32 v214, v54, v172
	v_mul_f32_e32 v215, v55, v172
	v_fmac_f32_e32 v36, v52, v172
	v_fmac_f32_e32 v37, v53, v172
	v_fmac_f32_e32 v38, v54, v172
	v_fmac_f32_e32 v39, v55, v172
	v_fma_f32 v12, v36, s59, -v212
	v_fma_f32 v13, v37, s59, -v213
	v_fma_f32 v22, v38, s59, -v214
	v_fma_f32 v23, v39, s59, -v215
	s_waitcnt vmcnt(21)
	v_fma_f32 v36, -v56, v171, v36
	v_fma_f32 v37, -v57, v171, v37
	v_fma_f32 v38, -v58, v171, v38
	v_fma_f32 v39, -v59, v171, v39
	v_cvt_pk_bf16_f32 v208, v12, v13
	v_cvt_pk_bf16_f32 v209, v22, v23
	global_store_dwordx2 v222, v[208:209], s[74:75]
	s_add_u32 s56, s2, 0x39000
	s_addc_u32 s57, s3, 0
	global_load_dwordx4 v[52:55], v0, s[56:57]
	s_add_u32 s70, s2, 0x38000
	s_addc_u32 s71, s3, 0
	global_load_dwordx4 v[56:59], v0, s[70:71]
	s_add_u32 s54, s12, 0x1a900
	s_addc_u32 s55, s13, 0
	s_waitcnt vmcnt(22)
	v_mul_f32_e32 v212, v60, v173
	v_mul_f32_e32 v213, v61, v173
	v_mul_f32_e32 v214, v62, v173
	v_mul_f32_e32 v215, v63, v173
	v_fmac_f32_e32 v36, v60, v173
	v_fmac_f32_e32 v37, v61, v173
	v_fmac_f32_e32 v38, v62, v173
	v_fmac_f32_e32 v39, v63, v173
	v_fma_f32 v12, v36, s59, -v212
	v_fma_f32 v13, v37, s59, -v213
	v_fma_f32 v22, v38, s59, -v214
	v_fma_f32 v23, v39, s59, -v215
	s_waitcnt vmcnt(21)
	v_fma_f32 v36, -v64, v172, v36
	v_fma_f32 v37, -v65, v172, v37
	v_fma_f32 v38, -v66, v172, v38
	v_fma_f32 v39, -v67, v172, v39
	v_cvt_pk_bf16_f32 v2, v12, v13
	v_cvt_pk_bf16_f32 v3, v22, v23
	global_store_dwordx2 v222, v[2:3], s[54:55]
	s_add_u32 s14, s2, 0x3a000
	s_addc_u32 s15, s3, 0
	global_load_dwordx4 v[60:63], v0, s[14:15]
	s_add_u32 s56, s2, 0x39000
	s_addc_u32 s57, s3, 0
	global_load_dwordx4 v[64:67], v0, s[56:57]
	s_add_u32 s74, s12, 0x1b180
	s_addc_u32 s75, s13, 0
	s_waitcnt vmcnt(22)
	v_mul_f32_e32 v212, v68, v174
	v_mul_f32_e32 v213, v69, v174
	v_mul_f32_e32 v214, v70, v174
	v_mul_f32_e32 v215, v71, v174
	v_fmac_f32_e32 v36, v68, v174
	v_fmac_f32_e32 v37, v69, v174
	v_fmac_f32_e32 v38, v70, v174
	v_fmac_f32_e32 v39, v71, v174
	v_fma_f32 v12, v36, s59, -v212
	v_fma_f32 v13, v37, s59, -v213
	v_fma_f32 v22, v38, s59, -v214
	v_fma_f32 v23, v39, s59, -v215
	s_waitcnt vmcnt(21)
	v_fma_f32 v36, -v72, v173, v36
	v_fma_f32 v37, -v73, v173, v37
	v_fma_f32 v38, -v74, v173, v38
	v_fma_f32 v39, -v75, v173, v39
	v_cvt_pk_bf16_f32 v208, v12, v13
	v_cvt_pk_bf16_f32 v209, v22, v23
	global_store_dwordx2 v222, v[208:209], s[74:75]
	s_add_u32 s70, s2, 0x3b000
	s_addc_u32 s71, s3, 0
	global_load_dwordx4 v[68:71], v0, s[70:71]
	s_add_u32 s14, s2, 0x3a000
	s_addc_u32 s15, s3, 0
	global_load_dwordx4 v[72:75], v0, s[14:15]
	s_add_u32 s54, s12, 0x1ba00
	s_addc_u32 s55, s13, 0
	s_waitcnt vmcnt(22)
	v_mul_f32_e32 v212, v76, v175
	v_mul_f32_e32 v213, v77, v175
	v_mul_f32_e32 v214, v78, v175
	v_mul_f32_e32 v215, v79, v175
	v_fmac_f32_e32 v36, v76, v175
	v_fmac_f32_e32 v37, v77, v175
	v_fmac_f32_e32 v38, v78, v175
	v_fmac_f32_e32 v39, v79, v175
	v_fma_f32 v12, v36, s59, -v212
	v_fma_f32 v13, v37, s59, -v213
	v_fma_f32 v22, v38, s59, -v214
	v_fma_f32 v23, v39, s59, -v215
	s_waitcnt vmcnt(21)
	v_fma_f32 v36, -v80, v174, v36
	v_fma_f32 v37, -v81, v174, v37
	v_fma_f32 v38, -v82, v174, v38
	v_fma_f32 v39, -v83, v174, v39
	v_cvt_pk_bf16_f32 v2, v12, v13
	v_cvt_pk_bf16_f32 v3, v22, v23
	global_store_dwordx2 v222, v[2:3], s[54:55]
	s_add_u32 s56, s2, 0x3c000
	s_addc_u32 s57, s3, 0
	global_load_dwordx4 v[76:79], v0, s[56:57]
	s_add_u32 s70, s2, 0x3b000
	s_addc_u32 s71, s3, 0
	global_load_dwordx4 v[80:83], v0, s[70:71]
	s_add_u32 s74, s12, 0x1c280
	s_addc_u32 s75, s13, 0
	s_waitcnt vmcnt(22)
	v_mul_f32_e32 v212, v84, v176
	v_mul_f32_e32 v213, v85, v176
	v_mul_f32_e32 v214, v86, v176
	v_mul_f32_e32 v215, v87, v176
	v_fmac_f32_e32 v36, v84, v176
	v_fmac_f32_e32 v37, v85, v176
	v_fmac_f32_e32 v38, v86, v176
	v_fmac_f32_e32 v39, v87, v176
	v_fma_f32 v12, v36, s59, -v212
	v_fma_f32 v13, v37, s59, -v213
	v_fma_f32 v22, v38, s59, -v214
	v_fma_f32 v23, v39, s59, -v215
	s_waitcnt vmcnt(21)
	v_fma_f32 v36, -v88, v175, v36
	v_fma_f32 v37, -v89, v175, v37
	v_fma_f32 v38, -v90, v175, v38
	v_fma_f32 v39, -v91, v175, v39
	v_cvt_pk_bf16_f32 v208, v12, v13
	v_cvt_pk_bf16_f32 v209, v22, v23
	global_store_dwordx2 v222, v[208:209], s[74:75]
	s_add_u32 s14, s2, 0x3d000
	s_addc_u32 s15, s3, 0
	global_load_dwordx4 v[84:87], v0, s[14:15]
	s_add_u32 s56, s2, 0x3c000
	s_addc_u32 s57, s3, 0
	global_load_dwordx4 v[88:91], v0, s[56:57]
	s_add_u32 s54, s12, 0x1cb00
	s_addc_u32 s55, s13, 0
	s_waitcnt vmcnt(22)
	v_mul_f32_e32 v212, v92, v177
	v_mul_f32_e32 v213, v93, v177
	v_mul_f32_e32 v214, v94, v177
	v_mul_f32_e32 v215, v95, v177
	v_fmac_f32_e32 v36, v92, v177
	v_fmac_f32_e32 v37, v93, v177
	v_fmac_f32_e32 v38, v94, v177
	v_fmac_f32_e32 v39, v95, v177
	v_fma_f32 v12, v36, s59, -v212
	v_fma_f32 v13, v37, s59, -v213
	v_fma_f32 v22, v38, s59, -v214
	v_fma_f32 v23, v39, s59, -v215
	s_waitcnt vmcnt(21)
; DI unsigned pack_bf16(float lo, float hi) { f32x2 v = {lo, hi}; bf16v2 b = __builtin_convertvector(v, bf16v2); return __builtin_bit_cast(unsigned, b); }
; template <int W>
; DI void pool_rows(const float* __restrict__ x, const float* smr, bf16_t* __restrict__ pb, int t0, int s0, int tid) {
;     ...
; #pragma unroll 8
;   for (int tl = 0; tl < 64; ++tl) {
;     const int t = t0 + tl, s = s0 + tl;
;     int to = t - W + 1; if (to < tq0) to = tq0;
;     const f32x4 hn = *(const f32x4*)(xq + (size_t)t * D) * smr[15 + tl];
;     const f32x4 ho = *(const f32x4*)(xq + (size_t)to * D) * smr[15 + tl - W + 1];
;     const int cnt = (s + 1 < W) ? (s + 1) : W;
;     const float ic = 1.f / (float)cnt;
;     Sm += hn;
;     const f32x4 p = Sm * ic - hn;
;     Sm -= ho;
;     u32x2 o; o.x = pack_bf16(p.x, p.y); o.y = pack_bf16(p.z, p.w);
;     *(u32x2*)(pb + (size_t)t * LDH + tid * 4) = o;
;   }
	v_fma_f32 v36, -v96, v176, v36
	v_fma_f32 v37, -v97, v176, v37
	v_fma_f32 v38, -v98, v176, v38
	v_fma_f32 v39, -v99, v176, v39
	v_cvt_pk_bf16_f32 v2, v12, v13
	v_cvt_pk_bf16_f32 v3, v22, v23
	global_store_dwordx2 v222, v[2:3], s[54:55]
	s_add_u32 s70, s2, 0x3e000
	s_addc_u32 s71, s3, 0
	global_load_dwordx4 v[92:95], v0, s[70:71]
	s_add_u32 s14, s2, 0x3d000
	s_addc_u32 s15, s3, 0
	global_load_dwordx4 v[96:99], v0, s[14:15]
	s_add_u32 s74, s12, 0x1d380
	s_addc_u32 s75, s13, 0
	s_waitcnt vmcnt(22)
	v_mul_f32_e32 v212, v100, v178
	v_mul_f32_e32 v213, v101, v178
	v_mul_f32_e32 v214, v102, v178
	v_mul_f32_e32 v215, v103, v178
	v_fmac_f32_e32 v36, v100, v178
	v_fmac_f32_e32 v37, v101, v178
	v_fmac_f32_e32 v38, v102, v178
	v_fmac_f32_e32 v39, v103, v178
	v_fma_f32 v12, v36, s59, -v212
	v_fma_f32 v13, v37, s59, -v213
	v_fma_f32 v22, v38, s59, -v214
	v_fma_f32 v23, v39, s59, -v215
	s_waitcnt vmcnt(21)
	v_fma_f32 v36, -v104, v177, v36
	v_fma_f32 v37, -v105, v177, v37
	v_fma_f32 v38, -v106, v177, v38
	v_fma_f32 v39, -v107, v177, v39
	v_cvt_pk_bf16_f32 v208, v12, v13
	v_cvt_pk_bf16_f32 v209, v22, v23
	global_store_dwordx2 v222, v[208:209], s[74:75]
	s_add_u32 s56, s2, 0x3f000
	s_addc_u32 s57, s3, 0
	global_load_dwordx4 v[100:103], v0, s[56:57]
	s_add_u32 s70, s2, 0x3e000
	s_addc_u32 s71, s3, 0
	global_load_dwordx4 v[104:107], v0, s[70:71]
	s_add_u32 s54, s12, 0x1dc00
	s_addc_u32 s55, s13, 0
	s_waitcnt vmcnt(22)
	v_mul_f32_e32 v212, v44, v179
	v_mul_f32_e32 v213, v45, v179
	v_mul_f32_e32 v214, v46, v179
	v_mul_f32_e32 v215, v47, v179
	v_fmac_f32_e32 v36, v44, v179
	v_fmac_f32_e32 v37, v45, v179
	v_fmac_f32_e32 v38, v46, v179
	v_fmac_f32_e32 v39, v47, v179
	v_fma_f32 v12, v36, s59, -v212
	v_fma_f32 v13, v37, s59, -v213
	v_fma_f32 v22, v38, s59, -v214
	v_fma_f32 v23, v39, s59, -v215
	s_waitcnt vmcnt(21)
	v_fma_f32 v36, -v48, v178, v36
	v_fma_f32 v37, -v49, v178, v37
	v_fma_f32 v38, -v50, v178, v38
	v_fma_f32 v39, -v51, v178, v39
	v_cvt_pk_bf16_f32 v2, v12, v13
	v_cvt_pk_bf16_f32 v3, v22, v23
	global_store_dwordx2 v222, v[2:3], s[54:55]
	s_add_u32 s74, s12, 0x1e480
	s_addc_u32 s75, s13, 0
	s_waitcnt vmcnt(20)
	v_mul_f32_e32 v212, v52, v180
	v_mul_f32_e32 v213, v53, v180
	v_mul_f32_e32 v214, v54, v180
	v_mul_f32_e32 v215, v55, v180
	v_fmac_f32_e32 v36, v52, v180
	v_fmac_f32_e32 v37, v53, v180
	v_fmac_f32_e32 v38, v54, v180
	v_fmac_f32_e32 v39, v55, v180
	v_fma_f32 v12, v36, s59, -v212
	v_fma_f32 v13, v37, s59, -v213
	v_fma_f32 v22, v38, s59, -v214
	v_fma_f32 v23, v39, s59, -v215
	s_waitcnt vmcnt(19)
	v_fma_f32 v36, -v56, v179, v36
	v_fma_f32 v37, -v57, v179, v37
	v_fma_f32 v38, -v58, v179, v38
	v_fma_f32 v39, -v59, v179, v39
	v_cvt_pk_bf16_f32 v208, v12, v13
	v_cvt_pk_bf16_f32 v209, v22, v23
	global_store_dwordx2 v222, v[208:209], s[74:75]
	s_add_u32 s54, s12, 0x1ed00
	s_addc_u32 s55, s13, 0
	s_waitcnt vmcnt(18)
	v_mul_f32_e32 v212, v60, v181
	v_mul_f32_e32 v213, v61, v181
	v_mul_f32_e32 v214, v62, v181
	v_mul_f32_e32 v215, v63, v181
	v_fmac_f32_e32 v36, v60, v181
	v_fmac_f32_e32 v37, v61, v181
	v_fmac_f32_e32 v38, v62, v181
	v_fmac_f32_e32 v39, v63, v181
	v_fma_f32 v12, v36, s59, -v212
	v_fma_f32 v13, v37, s59, -v213
	v_fma_f32 v22, v38, s59, -v214
	v_fma_f32 v23, v39, s59, -v215
	s_waitcnt vmcnt(17)
	v_fma_f32 v36, -v64, v180, v36
	v_fma_f32 v37, -v65, v180, v37
	v_fma_f32 v38, -v66, v180, v38
	v_fma_f32 v39, -v67, v180, v39
	v_cvt_pk_bf16_f32 v2, v12, v13
	v_cvt_pk_bf16_f32 v3, v22, v23
	global_store_dwordx2 v222, v[2:3], s[54:55]
	s_add_u32 s74, s12, 0x1f580
	s_addc_u32 s75, s13, 0
	s_waitcnt vmcnt(16)
	v_mul_f32_e32 v212, v68, v182
	v_mul_f32_e32 v213, v69, v182
	v_mul_f32_e32 v214, v70, v182
	v_mul_f32_e32 v215, v71, v182
	v_fmac_f32_e32 v36, v68, v182
	v_fmac_f32_e32 v37, v69, v182
	v_fmac_f32_e32 v38, v70, v182
	v_fmac_f32_e32 v39, v71, v182
	v_fma_f32 v12, v36, s59, -v212
	v_fma_f32 v13, v37, s59, -v213
	v_fma_f32 v22, v38, s59, -v214
	v_fma_f32 v23, v39, s59, -v215
	s_waitcnt vmcnt(15)
	v_fma_f32 v36, -v72, v181, v36
	v_fma_f32 v37, -v73, v181, v37
	v_fma_f32 v38, -v74, v181, v38
	v_fma_f32 v39, -v75, v181, v39
	v_cvt_pk_bf16_f32 v208, v12, v13
	v_cvt_pk_bf16_f32 v209, v22, v23
	global_store_dwordx2 v222, v[208:209], s[74:75]
	s_add_u32 s54, s12, 0x1fe00
	s_addc_u32 s55, s13, 0
	s_waitcnt vmcnt(14)
	v_mul_f32_e32 v212, v76, v183
	v_mul_f32_e32 v213, v77, v183
	v_mul_f32_e32 v214, v78, v183
	v_mul_f32_e32 v215, v79, v183
	v_fmac_f32_e32 v36, v76, v183
	v_fmac_f32_e32 v37, v77, v183
	v_fmac_f32_e32 v38, v78, v183
	v_fmac_f32_e32 v39, v79, v183
	v_fma_f32 v12, v36, s59, -v212
	v_fma_f32 v13, v37, s59, -v213
	v_fma_f32 v22, v38, s59, -v214
	v_fma_f32 v23, v39, s59, -v215
	s_waitcnt vmcnt(13)
	v_fma_f32 v36, -v80, v182, v36
	v_fma_f32 v37, -v81, v182, v37
	v_fma_f32 v38, -v82, v182, v38
	v_fma_f32 v39, -v83, v182, v39
	v_cvt_pk_bf16_f32 v2, v12, v13
	v_cvt_pk_bf16_f32 v3, v22, v23
	global_store_dwordx2 v222, v[2:3], s[54:55]
	s_add_u32 s74, s12, 0x20680
	s_addc_u32 s75, s13, 0
	s_waitcnt vmcnt(12)
	v_mul_f32_e32 v212, v84, v184
	v_mul_f32_e32 v213, v85, v184
	v_mul_f32_e32 v214, v86, v184
	v_mul_f32_e32 v215, v87, v184
	v_fmac_f32_e32 v36, v84, v184
	v_fmac_f32_e32 v37, v85, v184
	v_fmac_f32_e32 v38, v86, v184
	v_fmac_f32_e32 v39, v87, v184
	v_fma_f32 v12, v36, s59, -v212
	v_fma_f32 v13, v37, s59, -v213
	v_fma_f32 v22, v38, s59, -v214
	v_fma_f32 v23, v39, s59, -v215
	s_waitcnt vmcnt(11)
	v_fma_f32 v36, -v88, v183, v36
	v_fma_f32 v37, -v89, v183, v37
	v_fma_f32 v38, -v90, v183, v38
	v_fma_f32 v39, -v91, v183, v39
	v_cvt_pk_bf16_f32 v208, v12, v13
	v_cvt_pk_bf16_f32 v209, v22, v23
	global_store_dwordx2 v222, v[208:209], s[74:75]
	s_add_u32 s54, s12, 0x20f00
	s_addc_u32 s55, s13, 0
	s_waitcnt vmcnt(10)
; DI unsigned pack_bf16(float lo, float hi) { f32x2 v = {lo, hi}; bf16v2 b = __builtin_convertvector(v, bf16v2); return __builtin_bit_cast(unsigned, b); }
; template <int W>
; DI void pool_rows(const float* __restrict__ x, const float* smr, bf16_t* __restrict__ pb, int t0, int s0, int tid) {
;     ...
;   const float* xq = x + tid * 4;
;   f32x4 Sm = {0.f, 0.f, 0.f, 0.f};
; #pragma unroll
;   for (int i = 1; i < W; ++i) {
;     int t = t0 - i; if (t < tq0) t = tq0;
;     Sm += *(const f32x4*)(xq + (size_t)t * D) * smr[15 - i];
;   }
;     ...
;   for (int tl = 0; tl < 64; ++tl) {
;     const int t = t0 + tl, s = s0 + tl;
;     int to = t - W + 1; if (to < tq0) to = tq0;
;     const f32x4 hn = *(const f32x4*)(xq + (size_t)t * D) * smr[15 + tl];
;     const f32x4 ho = *(const f32x4*)(xq + (size_t)to * D) * smr[15 + tl - W + 1];
;     const int cnt = (s + 1 < W) ? (s + 1) : W;
;     const float ic = 1.f / (float)cnt;
;     Sm += hn;
;     const f32x4 p = Sm * ic - hn;
;     Sm -= ho;
;     u32x2 o; o.x = pack_bf16(p.x, p.y); o.y = pack_bf16(p.z, p.w);
;     *(u32x2*)(pb + (size_t)t * LDH + tid * 4) = o;
;   }
; DI void poolprep_phase(int vb, int nvb, const float* __restrict__ x, const float* __restrict__ ssq, bf16_t* __restrict__ pb, float* smf) {
;     ...
;       else if (wave == 1) pool_rows<4>(x, smf, pb, t0, s0, tid);
	v_mul_f32_e32 v212, v92, v185
	v_mul_f32_e32 v213, v93, v185
	v_mul_f32_e32 v214, v94, v185
	v_mul_f32_e32 v215, v95, v185
	v_fmac_f32_e32 v36, v92, v185
	v_fmac_f32_e32 v37, v93, v185
	v_fmac_f32_e32 v38, v94, v185
	v_fmac_f32_e32 v39, v95, v185
	v_fma_f32 v12, v36, s59, -v212
	v_fma_f32 v13, v37, s59, -v213
	v_fma_f32 v22, v38, s59, -v214
	v_fma_f32 v23, v39, s59, -v215
	s_waitcnt vmcnt(9)
	v_fma_f32 v36, -v96, v184, v36
	v_fma_f32 v37, -v97, v184, v37
	v_fma_f32 v38, -v98, v184, v38
	v_fma_f32 v39, -v99, v184, v39
	v_cvt_pk_bf16_f32 v2, v12, v13
	v_cvt_pk_bf16_f32 v3, v22, v23
	global_store_dwordx2 v222, v[2:3], s[54:55]
	s_add_u32 s74, s12, 0x21780
	s_addc_u32 s75, s13, 0
	s_waitcnt vmcnt(8)
	v_mul_f32_e32 v212, v100, v186
	v_mul_f32_e32 v213, v101, v186
	v_mul_f32_e32 v214, v102, v186
	v_mul_f32_e32 v215, v103, v186
	v_fmac_f32_e32 v36, v100, v186
	v_fmac_f32_e32 v37, v101, v186
	v_fmac_f32_e32 v38, v102, v186
	v_fmac_f32_e32 v39, v103, v186
	v_fma_f32 v12, v36, s59, -v212
	v_fma_f32 v13, v37, s59, -v213
	v_fma_f32 v22, v38, s59, -v214
	v_fma_f32 v23, v39, s59, -v215
	s_waitcnt vmcnt(7)
	v_fma_f32 v36, -v104, v185, v36
	v_fma_f32 v37, -v105, v185, v37
	v_fma_f32 v38, -v106, v185, v38
	v_fma_f32 v39, -v107, v185, v39
	v_cvt_pk_bf16_f32 v208, v12, v13
	v_cvt_pk_bf16_f32 v209, v22, v23
	global_store_dwordx2 v222, v[208:209], s[74:75]
	s_branch .Lpp_done
.Lpp_w4:
	s_mov_b32 s59, 0x3e800000
	s_cmp_eq_u32 s58, 0
	s_cselect_b32 s31, 0, 0xfffff000
	s_cselect_b32 s32, 0, -1
	s_add_u32 s14, s2, s31
	s_addc_u32 s15, s3, s32
	global_load_dwordx4 v[188:191], v0, s[14:15]
	s_cmp_eq_u32 s58, 0
	s_cselect_b32 s31, 0, 0xffffe000
	s_cselect_b32 s32, 0, -1
	s_add_u32 s56, s2, s31
	s_addc_u32 s57, s3, s32
	global_load_dwordx4 v[192:195], v0, s[56:57]
	s_cmp_eq_u32 s58, 0
	s_cselect_b32 s31, 0, 0xffffd000
	s_cselect_b32 s32, 0, -1
	s_add_u32 s70, s2, s31
	s_addc_u32 s71, s3, s32
	global_load_dwordx4 v[196:199], v0, s[70:71]
	s_mov_b32 s14, s2
	s_mov_b32 s15, s3
	global_load_dwordx4 v[44:47], v0, s[14:15]
	s_cmp_eq_u32 s58, 0
	s_cselect_b32 s31, 0, 0xffffd000
	s_cselect_b32 s32, 0, -1
	s_add_u32 s56, s2, s31
	s_addc_u32 s57, s3, s32
	global_load_dwordx4 v[48:51], v0, s[56:57]
	s_add_u32 s70, s2, 0x1000
	s_addc_u32 s71, s3, 0
	global_load_dwordx4 v[52:55], v0, s[70:71]
	s_cmp_eq_u32 s58, 0
	s_cselect_b32 s31, 0, 0xffffe000
	s_cselect_b32 s32, 0, -1
	s_add_u32 s14, s2, s31
	s_addc_u32 s15, s3, s32
	global_load_dwordx4 v[56:59], v0, s[14:15]
	s_add_u32 s56, s2, 0x2000
	s_addc_u32 s57, s3, 0
	global_load_dwordx4 v[60:63], v0, s[56:57]
	s_cmp_eq_u32 s58, 0
	s_cselect_b32 s31, 0, 0xfffff000
	s_cselect_b32 s32, 0, -1
	s_add_u32 s70, s2, s31
	s_addc_u32 s71, s3, s32
	global_load_dwordx4 v[64:67], v0, s[70:71]
	s_add_u32 s14, s2, 0x3000
	s_addc_u32 s15, s3, 0
	global_load_dwordx4 v[68:71], v0, s[14:15]
	s_mov_b32 s56, s2
	s_mov_b32 s57, s3
	global_load_dwordx4 v[72:75], v0, s[56:57]
	s_add_u32 s70, s2, 0x4000
	s_addc_u32 s71, s3, 0
	global_load_dwordx4 v[76:79], v0, s[70:71]
	s_add_u32 s14, s2, 0x1000
	s_addc_u32 s15, s3, 0
	global_load_dwordx4 v[80:83], v0, s[14:15]
	s_add_u32 s56, s2, 0x5000
	s_addc_u32 s57, s3, 0
	global_load_dwordx4 v[84:87], v0, s[56:57]
	s_add_u32 s70, s2, 0x2000
	s_addc_u32 s71, s3, 0
	global_load_dwordx4 v[88:91], v0, s[70:71]
	s_add_u32 s14, s2, 0x6000
	s_addc_u32 s15, s3, 0
	global_load_dwordx4 v[92:95], v0, s[14:15]
	s_add_u32 s56, s2, 0x3000
	s_addc_u32 s57, s3, 0
	global_load_dwordx4 v[96:99], v0, s[56:57]
	s_add_u32 s70, s2, 0x7000
	s_addc_u32 s71, s3, 0
	global_load_dwordx4 v[100:103], v0, s[70:71]
	s_add_u32 s14, s2, 0x4000
	s_addc_u32 s15, s3, 0
	global_load_dwordx4 v[104:107], v0, s[14:15]
	s_waitcnt lgkmcnt(0)
	s_waitcnt vmcnt(16)
	v_mul_f32_e32 v36, v188, v122
	v_mul_f32_e32 v37, v189, v122
	v_mul_f32_e32 v38, v190, v122
	v_mul_f32_e32 v39, v191, v122
	v_fmac_f32_e32 v36, v192, v121
	v_fmac_f32_e32 v37, v193, v121
	v_fmac_f32_e32 v38, v194, v121
	v_fmac_f32_e32 v39, v195, v121
	v_fmac_f32_e32 v36, v196, v120
	v_fmac_f32_e32 v37, v197, v120
	v_fmac_f32_e32 v38, v198, v120
	v_fmac_f32_e32 v39, v199, v120
	s_mov_b32 s32, 0x3f800000
	s_cmp_eq_u32 s58, 0
	s_cselect_b32 s32, s32, s59
	s_add_u32 s54, s12, 0x0
	s_addc_u32 s55, s13, 0
	s_waitcnt vmcnt(15)
	v_mul_f32_e32 v212, v44, v123
	v_mul_f32_e32 v213, v45, v123
	v_mul_f32_e32 v214, v46, v123
	v_mul_f32_e32 v215, v47, v123
	v_fmac_f32_e32 v36, v44, v123
	v_fmac_f32_e32 v37, v45, v123
	v_fmac_f32_e32 v38, v46, v123
	v_fmac_f32_e32 v39, v47, v123
	v_fma_f32 v12, v36, s32, -v212
	v_fma_f32 v13, v37, s32, -v213
	v_fma_f32 v22, v38, s32, -v214
	v_fma_f32 v23, v39, s32, -v215
	s_waitcnt vmcnt(14)
	v_fma_f32 v36, -v48, v120, v36
	v_fma_f32 v37, -v49, v120, v37
	v_fma_f32 v38, -v50, v120, v38
	v_fma_f32 v39, -v51, v120, v39
	v_cvt_pk_bf16_f32 v2, v12, v13
	v_cvt_pk_bf16_f32 v3, v22, v23
	global_store_dwordx2 v222, v[2:3], s[54:55]
	s_add_u32 s56, s2, 0x8000
	s_addc_u32 s57, s3, 0
	global_load_dwordx4 v[44:47], v0, s[56:57]
	s_add_u32 s70, s2, 0x5000
	s_addc_u32 s71, s3, 0
	global_load_dwordx4 v[48:51], v0, s[70:71]
	s_mov_b32 s32, 0x3f000000
	s_cmp_eq_u32 s58, 0
	s_cselect_b32 s32, s32, s59
	s_add_u32 s74, s12, 0x880
	s_addc_u32 s75, s13, 0
	s_waitcnt vmcnt(16)
	v_mul_f32_e32 v212, v52, v124
	v_mul_f32_e32 v213, v53, v124
	v_mul_f32_e32 v214, v54, v124
	v_mul_f32_e32 v215, v55, v124
	v_fmac_f32_e32 v36, v52, v124
	v_fmac_f32_e32 v37, v53, v124
	v_fmac_f32_e32 v38, v54, v124
	v_fmac_f32_e32 v39, v55, v124
	v_fma_f32 v12, v36, s32, -v212
	v_fma_f32 v13, v37, s32, -v213
	v_fma_f32 v22, v38, s32, -v214
	v_fma_f32 v23, v39, s32, -v215
	s_waitcnt vmcnt(15)
; DI unsigned pack_bf16(float lo, float hi) { f32x2 v = {lo, hi}; bf16v2 b = __builtin_convertvector(v, bf16v2); return __builtin_bit_cast(unsigned, b); }
; template <int W>
; DI void pool_rows(const float* __restrict__ x, const float* smr, bf16_t* __restrict__ pb, int t0, int s0, int tid) {
;     ...
;   for (int tl = 0; tl < 64; ++tl) {
;     const int t = t0 + tl, s = s0 + tl;
;     int to = t - W + 1; if (to < tq0) to = tq0;
;     const f32x4 hn = *(const f32x4*)(xq + (size_t)t * D) * smr[15 + tl];
;     const f32x4 ho = *(const f32x4*)(xq + (size_t)to * D) * smr[15 + tl - W + 1];
;     const int cnt = (s + 1 < W) ? (s + 1) : W;
;     const float ic = 1.f / (float)cnt;
;     Sm += hn;
;     const f32x4 p = Sm * ic - hn;
;     Sm -= ho;
;     u32x2 o; o.x = pack_bf16(p.x, p.y); o.y = pack_bf16(p.z, p.w);
;     *(u32x2*)(pb + (size_t)t * LDH + tid * 4) = o;
;   }
	v_fma_f32 v36, -v56, v121, v36
	v_fma_f32 v37, -v57, v121, v37
	v_fma_f32 v38, -v58, v121, v38
	v_fma_f32 v39, -v59, v121, v39
	v_cvt_pk_bf16_f32 v208, v12, v13
	v_cvt_pk_bf16_f32 v209, v22, v23
	global_store_dwordx2 v222, v[208:209], s[74:75]
	s_add_u32 s14, s2, 0x9000
	s_addc_u32 s15, s3, 0
	global_load_dwordx4 v[52:55], v0, s[14:15]
	s_add_u32 s56, s2, 0x6000
	s_addc_u32 s57, s3, 0
	global_load_dwordx4 v[56:59], v0, s[56:57]
	s_mov_b32 s32, 0x3eaaaaab
	s_cmp_eq_u32 s58, 0
	s_cselect_b32 s32, s32, s59
	s_add_u32 s54, s12, 0x1100
	s_addc_u32 s55, s13, 0
	s_waitcnt vmcnt(17)
	v_mul_f32_e32 v212, v60, v125
	v_mul_f32_e32 v213, v61, v125
	v_mul_f32_e32 v214, v62, v125
	v_mul_f32_e32 v215, v63, v125
	v_fmac_f32_e32 v36, v60, v125
	v_fmac_f32_e32 v37, v61, v125
	v_fmac_f32_e32 v38, v62, v125
	v_fmac_f32_e32 v39, v63, v125
	v_fma_f32 v12, v36, s32, -v212
	v_fma_f32 v13, v37, s32, -v213
	v_fma_f32 v22, v38, s32, -v214
	v_fma_f32 v23, v39, s32, -v215
	s_waitcnt vmcnt(16)
	v_fma_f32 v36, -v64, v122, v36
	v_fma_f32 v37, -v65, v122, v37
	v_fma_f32 v38, -v66, v122, v38
	v_fma_f32 v39, -v67, v122, v39
	v_cvt_pk_bf16_f32 v2, v12, v13
	v_cvt_pk_bf16_f32 v3, v22, v23
	global_store_dwordx2 v222, v[2:3], s[54:55]
	s_add_u32 s70, s2, 0xa000
	s_addc_u32 s71, s3, 0
	global_load_dwordx4 v[60:63], v0, s[70:71]
	s_add_u32 s14, s2, 0x7000
	s_addc_u32 s15, s3, 0
	global_load_dwordx4 v[64:67], v0, s[14:15]
	s_add_u32 s74, s12, 0x1980
	s_addc_u32 s75, s13, 0
	s_waitcnt vmcnt(18)
	v_mul_f32_e32 v212, v68, v126
	v_mul_f32_e32 v213, v69, v126
	v_mul_f32_e32 v214, v70, v126
	v_mul_f32_e32 v215, v71, v126
	v_fmac_f32_e32 v36, v68, v126
	v_fmac_f32_e32 v37, v69, v126
	v_fmac_f32_e32 v38, v70, v126
	v_fmac_f32_e32 v39, v71, v126
	v_fma_f32 v12, v36, s59, -v212
	v_fma_f32 v13, v37, s59, -v213
	v_fma_f32 v22, v38, s59, -v214
	v_fma_f32 v23, v39, s59, -v215
	s_waitcnt vmcnt(17)
	v_fma_f32 v36, -v72, v123, v36
	v_fma_f32 v37, -v73, v123, v37
	v_fma_f32 v38, -v74, v123, v38
	v_fma_f32 v39, -v75, v123, v39
	v_cvt_pk_bf16_f32 v208, v12, v13
	v_cvt_pk_bf16_f32 v209, v22, v23
	global_store_dwordx2 v222, v[208:209], s[74:75]
	s_add_u32 s56, s2, 0xb000
	s_addc_u32 s57, s3, 0
	global_load_dwordx4 v[68:71], v0, s[56:57]
	s_add_u32 s70, s2, 0x8000
	s_addc_u32 s71, s3, 0
	global_load_dwordx4 v[72:75], v0, s[70:71]
	s_add_u32 s54, s12, 0x2200
	s_addc_u32 s55, s13, 0
	s_waitcnt vmcnt(19)
	v_mul_f32_e32 v212, v76, v127
	v_mul_f32_e32 v213, v77, v127
	v_mul_f32_e32 v214, v78, v127
	v_mul_f32_e32 v215, v79, v127
	v_fmac_f32_e32 v36, v76, v127
	v_fmac_f32_e32 v37, v77, v127
	v_fmac_f32_e32 v38, v78, v127
	v_fmac_f32_e32 v39, v79, v127
	v_fma_f32 v12, v36, s59, -v212
	v_fma_f32 v13, v37, s59, -v213
	v_fma_f32 v22, v38, s59, -v214
	v_fma_f32 v23, v39, s59, -v215
	s_waitcnt vmcnt(18)
	v_fma_f32 v36, -v80, v124, v36
	v_fma_f32 v37, -v81, v124, v37
	v_fma_f32 v38, -v82, v124, v38
	v_fma_f32 v39, -v83, v124, v39
	v_cvt_pk_bf16_f32 v2, v12, v13
	v_cvt_pk_bf16_f32 v3, v22, v23
	global_store_dwordx2 v222, v[2:3], s[54:55]
	s_add_u32 s14, s2, 0xc000
	s_addc_u32 s15, s3, 0
	global_load_dwordx4 v[76:79], v0, s[14:15]
	s_add_u32 s56, s2, 0x9000
	s_addc_u32 s57, s3, 0
	global_load_dwordx4 v[80:83], v0, s[56:57]
	s_add_u32 s74, s12, 0x2a80
	s_addc_u32 s75, s13, 0
	s_waitcnt vmcnt(20)
	v_mul_f32_e32 v212, v84, v128
	v_mul_f32_e32 v213, v85, v128
	v_mul_f32_e32 v214, v86, v128
	v_mul_f32_e32 v215, v87, v128
	v_fmac_f32_e32 v36, v84, v128
	v_fmac_f32_e32 v37, v85, v128
	v_fmac_f32_e32 v38, v86, v128
	v_fmac_f32_e32 v39, v87, v128
	v_fma_f32 v12, v36, s59, -v212
	v_fma_f32 v13, v37, s59, -v213
	v_fma_f32 v22, v38, s59, -v214
	v_fma_f32 v23, v39, s59, -v215
	s_waitcnt vmcnt(19)
	v_fma_f32 v36, -v88, v125, v36
	v_fma_f32 v37, -v89, v125, v37
	v_fma_f32 v38, -v90, v125, v38
	v_fma_f32 v39, -v91, v125, v39
	v_cvt_pk_bf16_f32 v208, v12, v13
	v_cvt_pk_bf16_f32 v209, v22, v23
	global_store_dwordx2 v222, v[208:209], s[74:75]
	s_add_u32 s70, s2, 0xd000
	s_addc_u32 s71, s3, 0
	global_load_dwordx4 v[84:87], v0, s[70:71]
	s_add_u32 s14, s2, 0xa000
	s_addc_u32 s15, s3, 0
	global_load_dwordx4 v[88:91], v0, s[14:15]
	s_add_u32 s54, s12, 0x3300
	s_addc_u32 s55, s13, 0
	s_waitcnt vmcnt(21)
	v_mul_f32_e32 v212, v92, v129
	v_mul_f32_e32 v213, v93, v129
	v_mul_f32_e32 v214, v94, v129
	v_mul_f32_e32 v215, v95, v129
	v_fmac_f32_e32 v36, v92, v129
	v_fmac_f32_e32 v37, v93, v129
	v_fmac_f32_e32 v38, v94, v129
	v_fmac_f32_e32 v39, v95, v129
	v_fma_f32 v12, v36, s59, -v212
	v_fma_f32 v13, v37, s59, -v213
	v_fma_f32 v22, v38, s59, -v214
	v_fma_f32 v23, v39, s59, -v215
	s_waitcnt vmcnt(20)
	v_fma_f32 v36, -v96, v126, v36
	v_fma_f32 v37, -v97, v126, v37
	v_fma_f32 v38, -v98, v126, v38
	v_fma_f32 v39, -v99, v126, v39
	v_cvt_pk_bf16_f32 v2, v12, v13
	v_cvt_pk_bf16_f32 v3, v22, v23
	global_store_dwordx2 v222, v[2:3], s[54:55]
	s_add_u32 s56, s2, 0xe000
	s_addc_u32 s57, s3, 0
	global_load_dwordx4 v[92:95], v0, s[56:57]
	s_add_u32 s70, s2, 0xb000
	s_addc_u32 s71, s3, 0
	global_load_dwordx4 v[96:99], v0, s[70:71]
	s_add_u32 s74, s12, 0x3b80
	s_addc_u32 s75, s13, 0
	s_waitcnt vmcnt(22)
	v_mul_f32_e32 v212, v100, v130
	v_mul_f32_e32 v213, v101, v130
	v_mul_f32_e32 v214, v102, v130
	v_mul_f32_e32 v215, v103, v130
	v_fmac_f32_e32 v36, v100, v130
	v_fmac_f32_e32 v37, v101, v130
	v_fmac_f32_e32 v38, v102, v130
	v_fmac_f32_e32 v39, v103, v130
	v_fma_f32 v12, v36, s59, -v212
	v_fma_f32 v13, v37, s59, -v213
	v_fma_f32 v22, v38, s59, -v214
	v_fma_f32 v23, v39, s59, -v215
	s_waitcnt vmcnt(21)
; DI unsigned pack_bf16(float lo, float hi) { f32x2 v = {lo, hi}; bf16v2 b = __builtin_convertvector(v, bf16v2); return __builtin_bit_cast(unsigned, b); }
; template <int W>
; DI void pool_rows(const float* __restrict__ x, const float* smr, bf16_t* __restrict__ pb, int t0, int s0, int tid) {
;     ...
;   for (int tl = 0; tl < 64; ++tl) {
;     const int t = t0 + tl, s = s0 + tl;
;     int to = t - W + 1; if (to < tq0) to = tq0;
;     const f32x4 hn = *(const f32x4*)(xq + (size_t)t * D) * smr[15 + tl];
;     const f32x4 ho = *(const f32x4*)(xq + (size_t)to * D) * smr[15 + tl - W + 1];
;     const int cnt = (s + 1 < W) ? (s + 1) : W;
;     const float ic = 1.f / (float)cnt;
;     Sm += hn;
;     const f32x4 p = Sm * ic - hn;
;     Sm -= ho;
;     u32x2 o; o.x = pack_bf16(p.x, p.y); o.y = pack_bf16(p.z, p.w);
;     *(u32x2*)(pb + (size_t)t * LDH + tid * 4) = o;
;   }
	v_fma_f32 v36, -v104, v127, v36
	v_fma_f32 v37, -v105, v127, v37
	v_fma_f32 v38, -v106, v127, v38
	v_fma_f32 v39, -v107, v127, v39
	v_cvt_pk_bf16_f32 v208, v12, v13
	v_cvt_pk_bf16_f32 v209, v22, v23
	global_store_dwordx2 v222, v[208:209], s[74:75]
	s_add_u32 s14, s2, 0xf000
	s_addc_u32 s15, s3, 0
	global_load_dwordx4 v[100:103], v0, s[14:15]
	s_add_u32 s56, s2, 0xc000
	s_addc_u32 s57, s3, 0
	global_load_dwordx4 v[104:107], v0, s[56:57]
	s_add_u32 s54, s12, 0x4400
	s_addc_u32 s55, s13, 0
	s_waitcnt vmcnt(22)
	v_mul_f32_e32 v212, v44, v131
	v_mul_f32_e32 v213, v45, v131
	v_mul_f32_e32 v214, v46, v131
	v_mul_f32_e32 v215, v47, v131
	v_fmac_f32_e32 v36, v44, v131
	v_fmac_f32_e32 v37, v45, v131
	v_fmac_f32_e32 v38, v46, v131
	v_fmac_f32_e32 v39, v47, v131
	v_fma_f32 v12, v36, s59, -v212
	v_fma_f32 v13, v37, s59, -v213
	v_fma_f32 v22, v38, s59, -v214
	v_fma_f32 v23, v39, s59, -v215
	s_waitcnt vmcnt(21)
	v_fma_f32 v36, -v48, v128, v36
	v_fma_f32 v37, -v49, v128, v37
	v_fma_f32 v38, -v50, v128, v38
	v_fma_f32 v39, -v51, v128, v39
	v_cvt_pk_bf16_f32 v2, v12, v13
	v_cvt_pk_bf16_f32 v3, v22, v23
	global_store_dwordx2 v222, v[2:3], s[54:55]
	s_add_u32 s70, s2, 0x10000
	s_addc_u32 s71, s3, 0
	global_load_dwordx4 v[44:47], v0, s[70:71]
	s_add_u32 s14, s2, 0xd000
	s_addc_u32 s15, s3, 0
	global_load_dwordx4 v[48:51], v0, s[14:15]
	s_add_u32 s74, s12, 0x4c80
	s_addc_u32 s75, s13, 0
	s_waitcnt vmcnt(22)
	v_mul_f32_e32 v212, v52, v132
	v_mul_f32_e32 v213, v53, v132
	v_mul_f32_e32 v214, v54, v132
	v_mul_f32_e32 v215, v55, v132
	v_fmac_f32_e32 v36, v52, v132
	v_fmac_f32_e32 v37, v53, v132
	v_fmac_f32_e32 v38, v54, v132
	v_fmac_f32_e32 v39, v55, v132
	v_fma_f32 v12, v36, s59, -v212
	v_fma_f32 v13, v37, s59, -v213
	v_fma_f32 v22, v38, s59, -v214
	v_fma_f32 v23, v39, s59, -v215
	s_waitcnt vmcnt(21)
	v_fma_f32 v36, -v56, v129, v36
	v_fma_f32 v37, -v57, v129, v37
	v_fma_f32 v38, -v58, v129, v38
	v_fma_f32 v39, -v59, v129, v39
	v_cvt_pk_bf16_f32 v208, v12, v13
	v_cvt_pk_bf16_f32 v209, v22, v23
	global_store_dwordx2 v222, v[208:209], s[74:75]
	s_add_u32 s56, s2, 0x11000
	s_addc_u32 s57, s3, 0
	global_load_dwordx4 v[52:55], v0, s[56:57]
	s_add_u32 s70, s2, 0xe000
	s_addc_u32 s71, s3, 0
	global_load_dwordx4 v[56:59], v0, s[70:71]
	s_add_u32 s54, s12, 0x5500
	s_addc_u32 s55, s13, 0
	s_waitcnt vmcnt(22)
	v_mul_f32_e32 v212, v60, v133
	v_mul_f32_e32 v213, v61, v133
	v_mul_f32_e32 v214, v62, v133
	v_mul_f32_e32 v215, v63, v133
	v_fmac_f32_e32 v36, v60, v133
	v_fmac_f32_e32 v37, v61, v133
	v_fmac_f32_e32 v38, v62, v133
	v_fmac_f32_e32 v39, v63, v133
	v_fma_f32 v12, v36, s59, -v212
	v_fma_f32 v13, v37, s59, -v213
	v_fma_f32 v22, v38, s59, -v214
	v_fma_f32 v23, v39, s59, -v215
	s_waitcnt vmcnt(21)
	v_fma_f32 v36, -v64, v130, v36
	v_fma_f32 v37, -v65, v130, v37
	v_fma_f32 v38, -v66, v130, v38
	v_fma_f32 v39, -v67, v130, v39
	v_cvt_pk_bf16_f32 v2, v12, v13
	v_cvt_pk_bf16_f32 v3, v22, v23
	global_store_dwordx2 v222, v[2:3], s[54:55]
	s_add_u32 s14, s2, 0x12000
	s_addc_u32 s15, s3, 0
	global_load_dwordx4 v[60:63], v0, s[14:15]
	s_add_u32 s56, s2, 0xf000
	s_addc_u32 s57, s3, 0
	global_load_dwordx4 v[64:67], v0, s[56:57]
	s_add_u32 s74, s12, 0x5d80
	s_addc_u32 s75, s13, 0
	s_waitcnt vmcnt(22)
	v_mul_f32_e32 v212, v68, v134
	v_mul_f32_e32 v213, v69, v134
	v_mul_f32_e32 v214, v70, v134
	v_mul_f32_e32 v215, v71, v134
	v_fmac_f32_e32 v36, v68, v134
	v_fmac_f32_e32 v37, v69, v134
	v_fmac_f32_e32 v38, v70, v134
	v_fmac_f32_e32 v39, v71, v134
	v_fma_f32 v12, v36, s59, -v212
	v_fma_f32 v13, v37, s59, -v213
	v_fma_f32 v22, v38, s59, -v214
	v_fma_f32 v23, v39, s59, -v215
	s_waitcnt vmcnt(21)
	v_fma_f32 v36, -v72, v131, v36
	v_fma_f32 v37, -v73, v131, v37
	v_fma_f32 v38, -v74, v131, v38
	v_fma_f32 v39, -v75, v131, v39
	v_cvt_pk_bf16_f32 v208, v12, v13
	v_cvt_pk_bf16_f32 v209, v22, v23
	global_store_dwordx2 v222, v[208:209], s[74:75]
	s_add_u32 s70, s2, 0x13000
	s_addc_u32 s71, s3, 0
	global_load_dwordx4 v[68:71], v0, s[70:71]
	s_add_u32 s14, s2, 0x10000
	s_addc_u32 s15, s3, 0
	global_load_dwordx4 v[72:75], v0, s[14:15]
	s_add_u32 s54, s12, 0x6600
	s_addc_u32 s55, s13, 0
	s_waitcnt vmcnt(22)
	v_mul_f32_e32 v212, v76, v135
	v_mul_f32_e32 v213, v77, v135
	v_mul_f32_e32 v214, v78, v135
	v_mul_f32_e32 v215, v79, v135
	v_fmac_f32_e32 v36, v76, v135
	v_fmac_f32_e32 v37, v77, v135
	v_fmac_f32_e32 v38, v78, v135
	v_fmac_f32_e32 v39, v79, v135
	v_fma_f32 v12, v36, s59, -v212
	v_fma_f32 v13, v37, s59, -v213
	v_fma_f32 v22, v38, s59, -v214
	v_fma_f32 v23, v39, s59, -v215
	s_waitcnt vmcnt(21)
	v_fma_f32 v36, -v80, v132, v36
	v_fma_f32 v37, -v81, v132, v37
	v_fma_f32 v38, -v82, v132, v38
	v_fma_f32 v39, -v83, v132, v39
	v_cvt_pk_bf16_f32 v2, v12, v13
	v_cvt_pk_bf16_f32 v3, v22, v23
	global_store_dwordx2 v222, v[2:3], s[54:55]
	s_add_u32 s56, s2, 0x14000
	s_addc_u32 s57, s3, 0
	global_load_dwordx4 v[76:79], v0, s[56:57]
	s_add_u32 s70, s2, 0x11000
	s_addc_u32 s71, s3, 0
	global_load_dwordx4 v[80:83], v0, s[70:71]
	s_add_u32 s74, s12, 0x6e80
	s_addc_u32 s75, s13, 0
	s_waitcnt vmcnt(22)
	v_mul_f32_e32 v212, v84, v136
	v_mul_f32_e32 v213, v85, v136
	v_mul_f32_e32 v214, v86, v136
	v_mul_f32_e32 v215, v87, v136
	v_fmac_f32_e32 v36, v84, v136
	v_fmac_f32_e32 v37, v85, v136
	v_fmac_f32_e32 v38, v86, v136
	v_fmac_f32_e32 v39, v87, v136
	v_fma_f32 v12, v36, s59, -v212
	v_fma_f32 v13, v37, s59, -v213
	v_fma_f32 v22, v38, s59, -v214
	v_fma_f32 v23, v39, s59, -v215
	s_waitcnt vmcnt(21)
; DI unsigned pack_bf16(float lo, float hi) { f32x2 v = {lo, hi}; bf16v2 b = __builtin_convertvector(v, bf16v2); return __builtin_bit_cast(unsigned, b); }
; template <int W>
; DI void pool_rows(const float* __restrict__ x, const float* smr, bf16_t* __restrict__ pb, int t0, int s0, int tid) {
;     ...
;   for (int tl = 0; tl < 64; ++tl) {
;     const int t = t0 + tl, s = s0 + tl;
;     int to = t - W + 1; if (to < tq0) to = tq0;
;     const f32x4 hn = *(const f32x4*)(xq + (size_t)t * D) * smr[15 + tl];
;     const f32x4 ho = *(const f32x4*)(xq + (size_t)to * D) * smr[15 + tl - W + 1];
;     const int cnt = (s + 1 < W) ? (s + 1) : W;
;     const float ic = 1.f / (float)cnt;
;     Sm += hn;
;     const f32x4 p = Sm * ic - hn;
;     Sm -= ho;
;     u32x2 o; o.x = pack_bf16(p.x, p.y); o.y = pack_bf16(p.z, p.w);
;     *(u32x2*)(pb + (size_t)t * LDH + tid * 4) = o;
;   }
	v_fma_f32 v36, -v88, v133, v36
	v_fma_f32 v37, -v89, v133, v37
	v_fma_f32 v38, -v90, v133, v38
	v_fma_f32 v39, -v91, v133, v39
	v_cvt_pk_bf16_f32 v208, v12, v13
	v_cvt_pk_bf16_f32 v209, v22, v23
	global_store_dwordx2 v222, v[208:209], s[74:75]
	s_add_u32 s14, s2, 0x15000
	s_addc_u32 s15, s3, 0
	global_load_dwordx4 v[84:87], v0, s[14:15]
	s_add_u32 s56, s2, 0x12000
	s_addc_u32 s57, s3, 0
	global_load_dwordx4 v[88:91], v0, s[56:57]
	s_add_u32 s54, s12, 0x7700
	s_addc_u32 s55, s13, 0
	s_waitcnt vmcnt(22)
	v_mul_f32_e32 v212, v92, v137
	v_mul_f32_e32 v213, v93, v137
	v_mul_f32_e32 v214, v94, v137
	v_mul_f32_e32 v215, v95, v137
	v_fmac_f32_e32 v36, v92, v137
	v_fmac_f32_e32 v37, v93, v137
	v_fmac_f32_e32 v38, v94, v137
	v_fmac_f32_e32 v39, v95, v137
	v_fma_f32 v12, v36, s59, -v212
	v_fma_f32 v13, v37, s59, -v213
	v_fma_f32 v22, v38, s59, -v214
	v_fma_f32 v23, v39, s59, -v215
	s_waitcnt vmcnt(21)
	v_fma_f32 v36, -v96, v134, v36
	v_fma_f32 v37, -v97, v134, v37
	v_fma_f32 v38, -v98, v134, v38
	v_fma_f32 v39, -v99, v134, v39
	v_cvt_pk_bf16_f32 v2, v12, v13
	v_cvt_pk_bf16_f32 v3, v22, v23
	global_store_dwordx2 v222, v[2:3], s[54:55]
	s_add_u32 s70, s2, 0x16000
	s_addc_u32 s71, s3, 0
	global_load_dwordx4 v[92:95], v0, s[70:71]
	s_add_u32 s14, s2, 0x13000
	s_addc_u32 s15, s3, 0
	global_load_dwordx4 v[96:99], v0, s[14:15]
	s_add_u32 s74, s12, 0x7f80
	s_addc_u32 s75, s13, 0
	s_waitcnt vmcnt(22)
	v_mul_f32_e32 v212, v100, v138
	v_mul_f32_e32 v213, v101, v138
	v_mul_f32_e32 v214, v102, v138
	v_mul_f32_e32 v215, v103, v138
	v_fmac_f32_e32 v36, v100, v138
	v_fmac_f32_e32 v37, v101, v138
	v_fmac_f32_e32 v38, v102, v138
	v_fmac_f32_e32 v39, v103, v138
	v_fma_f32 v12, v36, s59, -v212
	v_fma_f32 v13, v37, s59, -v213
	v_fma_f32 v22, v38, s59, -v214
	v_fma_f32 v23, v39, s59, -v215
	s_waitcnt vmcnt(21)
	v_fma_f32 v36, -v104, v135, v36
	v_fma_f32 v37, -v105, v135, v37
	v_fma_f32 v38, -v106, v135, v38
	v_fma_f32 v39, -v107, v135, v39
	v_cvt_pk_bf16_f32 v208, v12, v13
	v_cvt_pk_bf16_f32 v209, v22, v23
	global_store_dwordx2 v222, v[208:209], s[74:75]
	s_add_u32 s56, s2, 0x17000
	s_addc_u32 s57, s3, 0
	global_load_dwordx4 v[100:103], v0, s[56:57]
	s_add_u32 s70, s2, 0x14000
	s_addc_u32 s71, s3, 0
	global_load_dwordx4 v[104:107], v0, s[70:71]
	s_add_u32 s54, s12, 0x8800
	s_addc_u32 s55, s13, 0
	s_waitcnt vmcnt(22)
	v_mul_f32_e32 v212, v44, v139
	v_mul_f32_e32 v213, v45, v139
	v_mul_f32_e32 v214, v46, v139
	v_mul_f32_e32 v215, v47, v139
	v_fmac_f32_e32 v36, v44, v139
	v_fmac_f32_e32 v37, v45, v139
	v_fmac_f32_e32 v38, v46, v139
	v_fmac_f32_e32 v39, v47, v139
	v_fma_f32 v12, v36, s59, -v212
	v_fma_f32 v13, v37, s59, -v213
	v_fma_f32 v22, v38, s59, -v214
	v_fma_f32 v23, v39, s59, -v215
	s_waitcnt vmcnt(21)
	v_fma_f32 v36, -v48, v136, v36
	v_fma_f32 v37, -v49, v136, v37
	v_fma_f32 v38, -v50, v136, v38
	v_fma_f32 v39, -v51, v136, v39
	v_cvt_pk_bf16_f32 v2, v12, v13
	v_cvt_pk_bf16_f32 v3, v22, v23
	global_store_dwordx2 v222, v[2:3], s[54:55]
	s_add_u32 s14, s2, 0x18000
	s_addc_u32 s15, s3, 0
	global_load_dwordx4 v[44:47], v0, s[14:15]
	s_add_u32 s56, s2, 0x15000
	s_addc_u32 s57, s3, 0
	global_load_dwordx4 v[48:51], v0, s[56:57]
	s_add_u32 s74, s12, 0x9080
	s_addc_u32 s75, s13, 0
	s_waitcnt vmcnt(22)
	v_mul_f32_e32 v212, v52, v140
	v_mul_f32_e32 v213, v53, v140
	v_mul_f32_e32 v214, v54, v140
	v_mul_f32_e32 v215, v55, v140
	v_fmac_f32_e32 v36, v52, v140
	v_fmac_f32_e32 v37, v53, v140
	v_fmac_f32_e32 v38, v54, v140
	v_fmac_f32_e32 v39, v55, v140
	v_fma_f32 v12, v36, s59, -v212
	v_fma_f32 v13, v37, s59, -v213
	v_fma_f32 v22, v38, s59, -v214
	v_fma_f32 v23, v39, s59, -v215
	s_waitcnt vmcnt(21)
	v_fma_f32 v36, -v56, v137, v36
	v_fma_f32 v37, -v57, v137, v37
	v_fma_f32 v38, -v58, v137, v38
	v_fma_f32 v39, -v59, v137, v39
	v_cvt_pk_bf16_f32 v208, v12, v13
	v_cvt_pk_bf16_f32 v209, v22, v23
	global_store_dwordx2 v222, v[208:209], s[74:75]
	s_add_u32 s70, s2, 0x19000
	s_addc_u32 s71, s3, 0
	global_load_dwordx4 v[52:55], v0, s[70:71]
	s_add_u32 s14, s2, 0x16000
	s_addc_u32 s15, s3, 0
	global_load_dwordx4 v[56:59], v0, s[14:15]
	s_add_u32 s54, s12, 0x9900
	s_addc_u32 s55, s13, 0
	s_waitcnt vmcnt(22)
	v_mul_f32_e32 v212, v60, v141
	v_mul_f32_e32 v213, v61, v141
	v_mul_f32_e32 v214, v62, v141
	v_mul_f32_e32 v215, v63, v141
	v_fmac_f32_e32 v36, v60, v141
	v_fmac_f32_e32 v37, v61, v141
	v_fmac_f32_e32 v38, v62, v141
	v_fmac_f32_e32 v39, v63, v141
	v_fma_f32 v12, v36, s59, -v212
	v_fma_f32 v13, v37, s59, -v213
	v_fma_f32 v22, v38, s59, -v214
	v_fma_f32 v23, v39, s59, -v215
	s_waitcnt vmcnt(21)
	v_fma_f32 v36, -v64, v138, v36
	v_fma_f32 v37, -v65, v138, v37
	v_fma_f32 v38, -v66, v138, v38
	v_fma_f32 v39, -v67, v138, v39
	v_cvt_pk_bf16_f32 v2, v12, v13
	v_cvt_pk_bf16_f32 v3, v22, v23
	global_store_dwordx2 v222, v[2:3], s[54:55]
	s_add_u32 s56, s2, 0x1a000
	s_addc_u32 s57, s3, 0
	global_load_dwordx4 v[60:63], v0, s[56:57]
	s_add_u32 s70, s2, 0x17000
	s_addc_u32 s71, s3, 0
	global_load_dwordx4 v[64:67], v0, s[70:71]
	s_add_u32 s74, s12, 0xa180
	s_addc_u32 s75, s13, 0
	s_waitcnt vmcnt(22)
	v_mul_f32_e32 v212, v68, v142
	v_mul_f32_e32 v213, v69, v142
	v_mul_f32_e32 v214, v70, v142
	v_mul_f32_e32 v215, v71, v142
	v_fmac_f32_e32 v36, v68, v142
	v_fmac_f32_e32 v37, v69, v142
	v_fmac_f32_e32 v38, v70, v142
	v_fmac_f32_e32 v39, v71, v142
	v_fma_f32 v12, v36, s59, -v212
	v_fma_f32 v13, v37, s59, -v213
	v_fma_f32 v22, v38, s59, -v214
	v_fma_f32 v23, v39, s59, -v215
	s_waitcnt vmcnt(21)
; DI unsigned pack_bf16(float lo, float hi) { f32x2 v = {lo, hi}; bf16v2 b = __builtin_convertvector(v, bf16v2); return __builtin_bit_cast(unsigned, b); }
; template <int W>
; DI void pool_rows(const float* __restrict__ x, const float* smr, bf16_t* __restrict__ pb, int t0, int s0, int tid) {
;     ...
;   for (int tl = 0; tl < 64; ++tl) {
;     const int t = t0 + tl, s = s0 + tl;
;     int to = t - W + 1; if (to < tq0) to = tq0;
;     const f32x4 hn = *(const f32x4*)(xq + (size_t)t * D) * smr[15 + tl];
;     const f32x4 ho = *(const f32x4*)(xq + (size_t)to * D) * smr[15 + tl - W + 1];
;     const int cnt = (s + 1 < W) ? (s + 1) : W;
;     const float ic = 1.f / (float)cnt;
;     Sm += hn;
;     const f32x4 p = Sm * ic - hn;
;     Sm -= ho;
;     u32x2 o; o.x = pack_bf16(p.x, p.y); o.y = pack_bf16(p.z, p.w);
;     *(u32x2*)(pb + (size_t)t * LDH + tid * 4) = o;
;   }
	v_fma_f32 v36, -v72, v139, v36
	v_fma_f32 v37, -v73, v139, v37
	v_fma_f32 v38, -v74, v139, v38
	v_fma_f32 v39, -v75, v139, v39
	v_cvt_pk_bf16_f32 v208, v12, v13
	v_cvt_pk_bf16_f32 v209, v22, v23
	global_store_dwordx2 v222, v[208:209], s[74:75]
	s_add_u32 s14, s2, 0x1b000
	s_addc_u32 s15, s3, 0
	global_load_dwordx4 v[68:71], v0, s[14:15]
	s_add_u32 s56, s2, 0x18000
	s_addc_u32 s57, s3, 0
	global_load_dwordx4 v[72:75], v0, s[56:57]
	s_add_u32 s54, s12, 0xaa00
	s_addc_u32 s55, s13, 0
	s_waitcnt vmcnt(22)
	v_mul_f32_e32 v212, v76, v143
	v_mul_f32_e32 v213, v77, v143
	v_mul_f32_e32 v214, v78, v143
	v_mul_f32_e32 v215, v79, v143
	v_fmac_f32_e32 v36, v76, v143
	v_fmac_f32_e32 v37, v77, v143
	v_fmac_f32_e32 v38, v78, v143
	v_fmac_f32_e32 v39, v79, v143
	v_fma_f32 v12, v36, s59, -v212
	v_fma_f32 v13, v37, s59, -v213
	v_fma_f32 v22, v38, s59, -v214
	v_fma_f32 v23, v39, s59, -v215
	s_waitcnt vmcnt(21)
	v_fma_f32 v36, -v80, v140, v36
	v_fma_f32 v37, -v81, v140, v37
	v_fma_f32 v38, -v82, v140, v38
	v_fma_f32 v39, -v83, v140, v39
	v_cvt_pk_bf16_f32 v2, v12, v13
	v_cvt_pk_bf16_f32 v3, v22, v23
	global_store_dwordx2 v222, v[2:3], s[54:55]
	s_add_u32 s70, s2, 0x1c000
	s_addc_u32 s71, s3, 0
	global_load_dwordx4 v[76:79], v0, s[70:71]
	s_add_u32 s14, s2, 0x19000
	s_addc_u32 s15, s3, 0
	global_load_dwordx4 v[80:83], v0, s[14:15]
	s_add_u32 s74, s12, 0xb280
	s_addc_u32 s75, s13, 0
	s_waitcnt vmcnt(22)
	v_mul_f32_e32 v212, v84, v144
	v_mul_f32_e32 v213, v85, v144
	v_mul_f32_e32 v214, v86, v144
	v_mul_f32_e32 v215, v87, v144
	v_fmac_f32_e32 v36, v84, v144
	v_fmac_f32_e32 v37, v85, v144
	v_fmac_f32_e32 v38, v86, v144
	v_fmac_f32_e32 v39, v87, v144
	v_fma_f32 v12, v36, s59, -v212
	v_fma_f32 v13, v37, s59, -v213
	v_fma_f32 v22, v38, s59, -v214
	v_fma_f32 v23, v39, s59, -v215
	s_waitcnt vmcnt(21)
	v_fma_f32 v36, -v88, v141, v36
	v_fma_f32 v37, -v89, v141, v37
	v_fma_f32 v38, -v90, v141, v38
	v_fma_f32 v39, -v91, v141, v39
	v_cvt_pk_bf16_f32 v208, v12, v13
	v_cvt_pk_bf16_f32 v209, v22, v23
	global_store_dwordx2 v222, v[208:209], s[74:75]
	s_add_u32 s56, s2, 0x1d000
	s_addc_u32 s57, s3, 0
	global_load_dwordx4 v[84:87], v0, s[56:57]
	s_add_u32 s70, s2, 0x1a000
	s_addc_u32 s71, s3, 0
	global_load_dwordx4 v[88:91], v0, s[70:71]
	s_add_u32 s54, s12, 0xbb00
	s_addc_u32 s55, s13, 0
	s_waitcnt vmcnt(22)
	v_mul_f32_e32 v212, v92, v145
	v_mul_f32_e32 v213, v93, v145
	v_mul_f32_e32 v214, v94, v145
	v_mul_f32_e32 v215, v95, v145
	v_fmac_f32_e32 v36, v92, v145
	v_fmac_f32_e32 v37, v93, v145
	v_fmac_f32_e32 v38, v94, v145
	v_fmac_f32_e32 v39, v95, v145
	v_fma_f32 v12, v36, s59, -v212
	v_fma_f32 v13, v37, s59, -v213
	v_fma_f32 v22, v38, s59, -v214
	v_fma_f32 v23, v39, s59, -v215
	s_waitcnt vmcnt(21)
	v_fma_f32 v36, -v96, v142, v36
	v_fma_f32 v37, -v97, v142, v37
	v_fma_f32 v38, -v98, v142, v38
	v_fma_f32 v39, -v99, v142, v39
	v_cvt_pk_bf16_f32 v2, v12, v13
	v_cvt_pk_bf16_f32 v3, v22, v23
	global_store_dwordx2 v222, v[2:3], s[54:55]
	s_add_u32 s14, s2, 0x1e000
	s_addc_u32 s15, s3, 0
	global_load_dwordx4 v[92:95], v0, s[14:15]
	s_add_u32 s56, s2, 0x1b000
	s_addc_u32 s57, s3, 0
	global_load_dwordx4 v[96:99], v0, s[56:57]
	s_add_u32 s74, s12, 0xc380
	s_addc_u32 s75, s13, 0
	s_waitcnt vmcnt(22)
	v_mul_f32_e32 v212, v100, v146
	v_mul_f32_e32 v213, v101, v146
	v_mul_f32_e32 v214, v102, v146
	v_mul_f32_e32 v215, v103, v146
	v_fmac_f32_e32 v36, v100, v146
	v_fmac_f32_e32 v37, v101, v146
	v_fmac_f32_e32 v38, v102, v146
	v_fmac_f32_e32 v39, v103, v146
	v_fma_f32 v12, v36, s59, -v212
	v_fma_f32 v13, v37, s59, -v213
	v_fma_f32 v22, v38, s59, -v214
	v_fma_f32 v23, v39, s59, -v215
	s_waitcnt vmcnt(21)
	v_fma_f32 v36, -v104, v143, v36
	v_fma_f32 v37, -v105, v143, v37
	v_fma_f32 v38, -v106, v143, v38
	v_fma_f32 v39, -v107, v143, v39
	v_cvt_pk_bf16_f32 v208, v12, v13
	v_cvt_pk_bf16_f32 v209, v22, v23
	global_store_dwordx2 v222, v[208:209], s[74:75]
	s_add_u32 s70, s2, 0x1f000
	s_addc_u32 s71, s3, 0
	global_load_dwordx4 v[100:103], v0, s[70:71]
	s_add_u32 s14, s2, 0x1c000
	s_addc_u32 s15, s3, 0
	global_load_dwordx4 v[104:107], v0, s[14:15]
	s_add_u32 s54, s12, 0xcc00
	s_addc_u32 s55, s13, 0
	s_waitcnt vmcnt(22)
	v_mul_f32_e32 v212, v44, v147
	v_mul_f32_e32 v213, v45, v147
	v_mul_f32_e32 v214, v46, v147
	v_mul_f32_e32 v215, v47, v147
	v_fmac_f32_e32 v36, v44, v147
	v_fmac_f32_e32 v37, v45, v147
	v_fmac_f32_e32 v38, v46, v147
	v_fmac_f32_e32 v39, v47, v147
	v_fma_f32 v12, v36, s59, -v212
	v_fma_f32 v13, v37, s59, -v213
	v_fma_f32 v22, v38, s59, -v214
	v_fma_f32 v23, v39, s59, -v215
	s_waitcnt vmcnt(21)
	v_fma_f32 v36, -v48, v144, v36
	v_fma_f32 v37, -v49, v144, v37
	v_fma_f32 v38, -v50, v144, v38
	v_fma_f32 v39, -v51, v144, v39
	v_cvt_pk_bf16_f32 v2, v12, v13
	v_cvt_pk_bf16_f32 v3, v22, v23
	global_store_dwordx2 v222, v[2:3], s[54:55]
	s_add_u32 s56, s2, 0x20000
	s_addc_u32 s57, s3, 0
	global_load_dwordx4 v[44:47], v0, s[56:57]
	s_add_u32 s70, s2, 0x1d000
	s_addc_u32 s71, s3, 0
	global_load_dwordx4 v[48:51], v0, s[70:71]
	s_add_u32 s74, s12, 0xd480
	s_addc_u32 s75, s13, 0
	s_waitcnt vmcnt(22)
	v_mul_f32_e32 v212, v52, v148
	v_mul_f32_e32 v213, v53, v148
	v_mul_f32_e32 v214, v54, v148
	v_mul_f32_e32 v215, v55, v148
	v_fmac_f32_e32 v36, v52, v148
	v_fmac_f32_e32 v37, v53, v148
	v_fmac_f32_e32 v38, v54, v148
	v_fmac_f32_e32 v39, v55, v148
	v_fma_f32 v12, v36, s59, -v212
	v_fma_f32 v13, v37, s59, -v213
	v_fma_f32 v22, v38, s59, -v214
	v_fma_f32 v23, v39, s59, -v215
	s_waitcnt vmcnt(21)
; DI unsigned pack_bf16(float lo, float hi) { f32x2 v = {lo, hi}; bf16v2 b = __builtin_convertvector(v, bf16v2); return __builtin_bit_cast(unsigned, b); }
; template <int W>
; DI void pool_rows(const float* __restrict__ x, const float* smr, bf16_t* __restrict__ pb, int t0, int s0, int tid) {
;     ...
;   for (int tl = 0; tl < 64; ++tl) {
;     const int t = t0 + tl, s = s0 + tl;
;     int to = t - W + 1; if (to < tq0) to = tq0;
;     const f32x4 hn = *(const f32x4*)(xq + (size_t)t * D) * smr[15 + tl];
;     const f32x4 ho = *(const f32x4*)(xq + (size_t)to * D) * smr[15 + tl - W + 1];
;     const int cnt = (s + 1 < W) ? (s + 1) : W;
;     const float ic = 1.f / (float)cnt;
;     Sm += hn;
;     const f32x4 p = Sm * ic - hn;
;     Sm -= ho;
;     u32x2 o; o.x = pack_bf16(p.x, p.y); o.y = pack_bf16(p.z, p.w);
;     *(u32x2*)(pb + (size_t)t * LDH + tid * 4) = o;
;   }
	v_fma_f32 v36, -v56, v145, v36
	v_fma_f32 v37, -v57, v145, v37
	v_fma_f32 v38, -v58, v145, v38
	v_fma_f32 v39, -v59, v145, v39
	v_cvt_pk_bf16_f32 v208, v12, v13
	v_cvt_pk_bf16_f32 v209, v22, v23
	global_store_dwordx2 v222, v[208:209], s[74:75]
	s_add_u32 s14, s2, 0x21000
	s_addc_u32 s15, s3, 0
	global_load_dwordx4 v[52:55], v0, s[14:15]
	s_add_u32 s56, s2, 0x1e000
	s_addc_u32 s57, s3, 0
	global_load_dwordx4 v[56:59], v0, s[56:57]
	s_add_u32 s54, s12, 0xdd00
	s_addc_u32 s55, s13, 0
	s_waitcnt vmcnt(22)
	v_mul_f32_e32 v212, v60, v149
	v_mul_f32_e32 v213, v61, v149
	v_mul_f32_e32 v214, v62, v149
	v_mul_f32_e32 v215, v63, v149
	v_fmac_f32_e32 v36, v60, v149
	v_fmac_f32_e32 v37, v61, v149
	v_fmac_f32_e32 v38, v62, v149
	v_fmac_f32_e32 v39, v63, v149
	v_fma_f32 v12, v36, s59, -v212
	v_fma_f32 v13, v37, s59, -v213
	v_fma_f32 v22, v38, s59, -v214
	v_fma_f32 v23, v39, s59, -v215
	s_waitcnt vmcnt(21)
	v_fma_f32 v36, -v64, v146, v36
	v_fma_f32 v37, -v65, v146, v37
	v_fma_f32 v38, -v66, v146, v38
	v_fma_f32 v39, -v67, v146, v39
	v_cvt_pk_bf16_f32 v2, v12, v13
	v_cvt_pk_bf16_f32 v3, v22, v23
	global_store_dwordx2 v222, v[2:3], s[54:55]
	s_add_u32 s70, s2, 0x22000
	s_addc_u32 s71, s3, 0
	global_load_dwordx4 v[60:63], v0, s[70:71]
	s_add_u32 s14, s2, 0x1f000
	s_addc_u32 s15, s3, 0
	global_load_dwordx4 v[64:67], v0, s[14:15]
	s_add_u32 s74, s12, 0xe580
	s_addc_u32 s75, s13, 0
	s_waitcnt vmcnt(22)
	v_mul_f32_e32 v212, v68, v150
	v_mul_f32_e32 v213, v69, v150
	v_mul_f32_e32 v214, v70, v150
	v_mul_f32_e32 v215, v71, v150
	v_fmac_f32_e32 v36, v68, v150
	v_fmac_f32_e32 v37, v69, v150
	v_fmac_f32_e32 v38, v70, v150
	v_fmac_f32_e32 v39, v71, v150
	v_fma_f32 v12, v36, s59, -v212
	v_fma_f32 v13, v37, s59, -v213
	v_fma_f32 v22, v38, s59, -v214
	v_fma_f32 v23, v39, s59, -v215
	s_waitcnt vmcnt(21)
	v_fma_f32 v36, -v72, v147, v36
	v_fma_f32 v37, -v73, v147, v37
	v_fma_f32 v38, -v74, v147, v38
	v_fma_f32 v39, -v75, v147, v39
	v_cvt_pk_bf16_f32 v208, v12, v13
	v_cvt_pk_bf16_f32 v209, v22, v23
	global_store_dwordx2 v222, v[208:209], s[74:75]
	s_add_u32 s56, s2, 0x23000
	s_addc_u32 s57, s3, 0
	global_load_dwordx4 v[68:71], v0, s[56:57]
	s_add_u32 s70, s2, 0x20000
	s_addc_u32 s71, s3, 0
	global_load_dwordx4 v[72:75], v0, s[70:71]
	s_add_u32 s54, s12, 0xee00
	s_addc_u32 s55, s13, 0
	s_waitcnt vmcnt(22)
	v_mul_f32_e32 v212, v76, v151
	v_mul_f32_e32 v213, v77, v151
	v_mul_f32_e32 v214, v78, v151
	v_mul_f32_e32 v215, v79, v151
	v_fmac_f32_e32 v36, v76, v151
	v_fmac_f32_e32 v37, v77, v151
	v_fmac_f32_e32 v38, v78, v151
	v_fmac_f32_e32 v39, v79, v151
	v_fma_f32 v12, v36, s59, -v212
	v_fma_f32 v13, v37, s59, -v213
	v_fma_f32 v22, v38, s59, -v214
	v_fma_f32 v23, v39, s59, -v215
	s_waitcnt vmcnt(21)
	v_fma_f32 v36, -v80, v148, v36
	v_fma_f32 v37, -v81, v148, v37
	v_fma_f32 v38, -v82, v148, v38
	v_fma_f32 v39, -v83, v148, v39
	v_cvt_pk_bf16_f32 v2, v12, v13
	v_cvt_pk_bf16_f32 v3, v22, v23
	global_store_dwordx2 v222, v[2:3], s[54:55]
	s_add_u32 s14, s2, 0x24000
	s_addc_u32 s15, s3, 0
	global_load_dwordx4 v[76:79], v0, s[14:15]
	s_add_u32 s56, s2, 0x21000
	s_addc_u32 s57, s3, 0
	global_load_dwordx4 v[80:83], v0, s[56:57]
	s_add_u32 s74, s12, 0xf680
	s_addc_u32 s75, s13, 0
	s_waitcnt vmcnt(22)
	v_mul_f32_e32 v212, v84, v152
	v_mul_f32_e32 v213, v85, v152
	v_mul_f32_e32 v214, v86, v152
	v_mul_f32_e32 v215, v87, v152
	v_fmac_f32_e32 v36, v84, v152
	v_fmac_f32_e32 v37, v85, v152
	v_fmac_f32_e32 v38, v86, v152
	v_fmac_f32_e32 v39, v87, v152
	v_fma_f32 v12, v36, s59, -v212
	v_fma_f32 v13, v37, s59, -v213
	v_fma_f32 v22, v38, s59, -v214
	v_fma_f32 v23, v39, s59, -v215
	s_waitcnt vmcnt(21)
	v_fma_f32 v36, -v88, v149, v36
	v_fma_f32 v37, -v89, v149, v37
	v_fma_f32 v38, -v90, v149, v38
	v_fma_f32 v39, -v91, v149, v39
	v_cvt_pk_bf16_f32 v208, v12, v13
	v_cvt_pk_bf16_f32 v209, v22, v23
	global_store_dwordx2 v222, v[208:209], s[74:75]
	s_add_u32 s70, s2, 0x25000
	s_addc_u32 s71, s3, 0
	global_load_dwordx4 v[84:87], v0, s[70:71]
	s_add_u32 s14, s2, 0x22000
	s_addc_u32 s15, s3, 0
	global_load_dwordx4 v[88:91], v0, s[14:15]
	s_add_u32 s54, s12, 0xff00
	s_addc_u32 s55, s13, 0
	s_waitcnt vmcnt(22)
	v_mul_f32_e32 v212, v92, v153
	v_mul_f32_e32 v213, v93, v153
	v_mul_f32_e32 v214, v94, v153
	v_mul_f32_e32 v215, v95, v153
	v_fmac_f32_e32 v36, v92, v153
	v_fmac_f32_e32 v37, v93, v153
	v_fmac_f32_e32 v38, v94, v153
	v_fmac_f32_e32 v39, v95, v153
	v_fma_f32 v12, v36, s59, -v212
	v_fma_f32 v13, v37, s59, -v213
	v_fma_f32 v22, v38, s59, -v214
	v_fma_f32 v23, v39, s59, -v215
	s_waitcnt vmcnt(21)
	v_fma_f32 v36, -v96, v150, v36
	v_fma_f32 v37, -v97, v150, v37
	v_fma_f32 v38, -v98, v150, v38
	v_fma_f32 v39, -v99, v150, v39
	v_cvt_pk_bf16_f32 v2, v12, v13
	v_cvt_pk_bf16_f32 v3, v22, v23
	global_store_dwordx2 v222, v[2:3], s[54:55]
	s_add_u32 s56, s2, 0x26000
	s_addc_u32 s57, s3, 0
	global_load_dwordx4 v[92:95], v0, s[56:57]
	s_add_u32 s70, s2, 0x23000
	s_addc_u32 s71, s3, 0
	global_load_dwordx4 v[96:99], v0, s[70:71]
	s_add_u32 s74, s12, 0x10780
	s_addc_u32 s75, s13, 0
	s_waitcnt vmcnt(22)
	v_mul_f32_e32 v212, v100, v154
	v_mul_f32_e32 v213, v101, v154
	v_mul_f32_e32 v214, v102, v154
	v_mul_f32_e32 v215, v103, v154
	v_fmac_f32_e32 v36, v100, v154
	v_fmac_f32_e32 v37, v101, v154
	v_fmac_f32_e32 v38, v102, v154
	v_fmac_f32_e32 v39, v103, v154
	v_fma_f32 v12, v36, s59, -v212
	v_fma_f32 v13, v37, s59, -v213
	v_fma_f32 v22, v38, s59, -v214
	v_fma_f32 v23, v39, s59, -v215
	s_waitcnt vmcnt(21)
; DI unsigned pack_bf16(float lo, float hi) { f32x2 v = {lo, hi}; bf16v2 b = __builtin_convertvector(v, bf16v2); return __builtin_bit_cast(unsigned, b); }
; template <int W>
; DI void pool_rows(const float* __restrict__ x, const float* smr, bf16_t* __restrict__ pb, int t0, int s0, int tid) {
;     ...
;   for (int tl = 0; tl < 64; ++tl) {
;     const int t = t0 + tl, s = s0 + tl;
;     int to = t - W + 1; if (to < tq0) to = tq0;
;     const f32x4 hn = *(const f32x4*)(xq + (size_t)t * D) * smr[15 + tl];
;     const f32x4 ho = *(const f32x4*)(xq + (size_t)to * D) * smr[15 + tl - W + 1];
;     const int cnt = (s + 1 < W) ? (s + 1) : W;
;     const float ic = 1.f / (float)cnt;
;     Sm += hn;
;     const f32x4 p = Sm * ic - hn;
;     Sm -= ho;
;     u32x2 o; o.x = pack_bf16(p.x, p.y); o.y = pack_bf16(p.z, p.w);
;     *(u32x2*)(pb + (size_t)t * LDH + tid * 4) = o;
;   }
	v_fma_f32 v36, -v104, v151, v36
	v_fma_f32 v37, -v105, v151, v37
	v_fma_f32 v38, -v106, v151, v38
	v_fma_f32 v39, -v107, v151, v39
	v_cvt_pk_bf16_f32 v208, v12, v13
	v_cvt_pk_bf16_f32 v209, v22, v23
	global_store_dwordx2 v222, v[208:209], s[74:75]
	s_add_u32 s14, s2, 0x27000
	s_addc_u32 s15, s3, 0
	global_load_dwordx4 v[100:103], v0, s[14:15]
	s_add_u32 s56, s2, 0x24000
	s_addc_u32 s57, s3, 0
	global_load_dwordx4 v[104:107], v0, s[56:57]
	s_add_u32 s54, s12, 0x11000
	s_addc_u32 s55, s13, 0
	s_waitcnt vmcnt(22)
	v_mul_f32_e32 v212, v44, v155
	v_mul_f32_e32 v213, v45, v155
	v_mul_f32_e32 v214, v46, v155
	v_mul_f32_e32 v215, v47, v155
	v_fmac_f32_e32 v36, v44, v155
	v_fmac_f32_e32 v37, v45, v155
	v_fmac_f32_e32 v38, v46, v155
	v_fmac_f32_e32 v39, v47, v155
	v_fma_f32 v12, v36, s59, -v212
	v_fma_f32 v13, v37, s59, -v213
	v_fma_f32 v22, v38, s59, -v214
	v_fma_f32 v23, v39, s59, -v215
	s_waitcnt vmcnt(21)
	v_fma_f32 v36, -v48, v152, v36
	v_fma_f32 v37, -v49, v152, v37
	v_fma_f32 v38, -v50, v152, v38
	v_fma_f32 v39, -v51, v152, v39
	v_cvt_pk_bf16_f32 v2, v12, v13
	v_cvt_pk_bf16_f32 v3, v22, v23
	global_store_dwordx2 v222, v[2:3], s[54:55]
	s_add_u32 s70, s2, 0x28000
	s_addc_u32 s71, s3, 0
	global_load_dwordx4 v[44:47], v0, s[70:71]
	s_add_u32 s14, s2, 0x25000
	s_addc_u32 s15, s3, 0
	global_load_dwordx4 v[48:51], v0, s[14:15]
	s_add_u32 s74, s12, 0x11880
	s_addc_u32 s75, s13, 0
	s_waitcnt vmcnt(22)
	v_mul_f32_e32 v212, v52, v156
	v_mul_f32_e32 v213, v53, v156
	v_mul_f32_e32 v214, v54, v156
	v_mul_f32_e32 v215, v55, v156
	v_fmac_f32_e32 v36, v52, v156
	v_fmac_f32_e32 v37, v53, v156
	v_fmac_f32_e32 v38, v54, v156
	v_fmac_f32_e32 v39, v55, v156
	v_fma_f32 v12, v36, s59, -v212
	v_fma_f32 v13, v37, s59, -v213
	v_fma_f32 v22, v38, s59, -v214
	v_fma_f32 v23, v39, s59, -v215
	s_waitcnt vmcnt(21)
	v_fma_f32 v36, -v56, v153, v36
	v_fma_f32 v37, -v57, v153, v37
	v_fma_f32 v38, -v58, v153, v38
	v_fma_f32 v39, -v59, v153, v39
	v_cvt_pk_bf16_f32 v208, v12, v13
	v_cvt_pk_bf16_f32 v209, v22, v23
	global_store_dwordx2 v222, v[208:209], s[74:75]
	s_add_u32 s56, s2, 0x29000
	s_addc_u32 s57, s3, 0
	global_load_dwordx4 v[52:55], v0, s[56:57]
	s_add_u32 s70, s2, 0x26000
	s_addc_u32 s71, s3, 0
	global_load_dwordx4 v[56:59], v0, s[70:71]
	s_add_u32 s54, s12, 0x12100
	s_addc_u32 s55, s13, 0
	s_waitcnt vmcnt(22)
	v_mul_f32_e32 v212, v60, v157
	v_mul_f32_e32 v213, v61, v157
	v_mul_f32_e32 v214, v62, v157
	v_mul_f32_e32 v215, v63, v157
	v_fmac_f32_e32 v36, v60, v157
	v_fmac_f32_e32 v37, v61, v157
	v_fmac_f32_e32 v38, v62, v157
	v_fmac_f32_e32 v39, v63, v157
	v_fma_f32 v12, v36, s59, -v212
	v_fma_f32 v13, v37, s59, -v213
	v_fma_f32 v22, v38, s59, -v214
	v_fma_f32 v23, v39, s59, -v215
	s_waitcnt vmcnt(21)
	v_fma_f32 v36, -v64, v154, v36
	v_fma_f32 v37, -v65, v154, v37
	v_fma_f32 v38, -v66, v154, v38
	v_fma_f32 v39, -v67, v154, v39
	v_cvt_pk_bf16_f32 v2, v12, v13
	v_cvt_pk_bf16_f32 v3, v22, v23
	global_store_dwordx2 v222, v[2:3], s[54:55]
	s_add_u32 s14, s2, 0x2a000
	s_addc_u32 s15, s3, 0
	global_load_dwordx4 v[60:63], v0, s[14:15]
	s_add_u32 s56, s2, 0x27000
	s_addc_u32 s57, s3, 0
	global_load_dwordx4 v[64:67], v0, s[56:57]
	s_add_u32 s74, s12, 0x12980
	s_addc_u32 s75, s13, 0
	s_waitcnt vmcnt(22)
	v_mul_f32_e32 v212, v68, v158
	v_mul_f32_e32 v213, v69, v158
	v_mul_f32_e32 v214, v70, v158
	v_mul_f32_e32 v215, v71, v158
	v_fmac_f32_e32 v36, v68, v158
	v_fmac_f32_e32 v37, v69, v158
	v_fmac_f32_e32 v38, v70, v158
	v_fmac_f32_e32 v39, v71, v158
	v_fma_f32 v12, v36, s59, -v212
	v_fma_f32 v13, v37, s59, -v213
	v_fma_f32 v22, v38, s59, -v214
	v_fma_f32 v23, v39, s59, -v215
	s_waitcnt vmcnt(21)
	v_fma_f32 v36, -v72, v155, v36
	v_fma_f32 v37, -v73, v155, v37
	v_fma_f32 v38, -v74, v155, v38
	v_fma_f32 v39, -v75, v155, v39
	v_cvt_pk_bf16_f32 v208, v12, v13
	v_cvt_pk_bf16_f32 v209, v22, v23
	global_store_dwordx2 v222, v[208:209], s[74:75]
	s_add_u32 s70, s2, 0x2b000
	s_addc_u32 s71, s3, 0
	global_load_dwordx4 v[68:71], v0, s[70:71]
	s_add_u32 s14, s2, 0x28000
	s_addc_u32 s15, s3, 0
	global_load_dwordx4 v[72:75], v0, s[14:15]
	s_add_u32 s54, s12, 0x13200
	s_addc_u32 s55, s13, 0
	s_waitcnt vmcnt(22)
	v_mul_f32_e32 v212, v76, v159
	v_mul_f32_e32 v213, v77, v159
	v_mul_f32_e32 v214, v78, v159
	v_mul_f32_e32 v215, v79, v159
	v_fmac_f32_e32 v36, v76, v159
	v_fmac_f32_e32 v37, v77, v159
	v_fmac_f32_e32 v38, v78, v159
	v_fmac_f32_e32 v39, v79, v159
	v_fma_f32 v12, v36, s59, -v212
	v_fma_f32 v13, v37, s59, -v213
	v_fma_f32 v22, v38, s59, -v214
	v_fma_f32 v23, v39, s59, -v215
	s_waitcnt vmcnt(21)
	v_fma_f32 v36, -v80, v156, v36
	v_fma_f32 v37, -v81, v156, v37
	v_fma_f32 v38, -v82, v156, v38
	v_fma_f32 v39, -v83, v156, v39
	v_cvt_pk_bf16_f32 v2, v12, v13
	v_cvt_pk_bf16_f32 v3, v22, v23
	global_store_dwordx2 v222, v[2:3], s[54:55]
	s_add_u32 s56, s2, 0x2c000
	s_addc_u32 s57, s3, 0
	global_load_dwordx4 v[76:79], v0, s[56:57]
	s_add_u32 s70, s2, 0x29000
	s_addc_u32 s71, s3, 0
	global_load_dwordx4 v[80:83], v0, s[70:71]
	s_add_u32 s74, s12, 0x13a80
	s_addc_u32 s75, s13, 0
	s_waitcnt vmcnt(22)
	v_mul_f32_e32 v212, v84, v160
	v_mul_f32_e32 v213, v85, v160
	v_mul_f32_e32 v214, v86, v160
	v_mul_f32_e32 v215, v87, v160
	v_fmac_f32_e32 v36, v84, v160
	v_fmac_f32_e32 v37, v85, v160
	v_fmac_f32_e32 v38, v86, v160
	v_fmac_f32_e32 v39, v87, v160
	v_fma_f32 v12, v36, s59, -v212
	v_fma_f32 v13, v37, s59, -v213
	v_fma_f32 v22, v38, s59, -v214
	v_fma_f32 v23, v39, s59, -v215
	s_waitcnt vmcnt(21)
; DI unsigned pack_bf16(float lo, float hi) { f32x2 v = {lo, hi}; bf16v2 b = __builtin_convertvector(v, bf16v2); return __builtin_bit_cast(unsigned, b); }
; template <int W>
; DI void pool_rows(const float* __restrict__ x, const float* smr, bf16_t* __restrict__ pb, int t0, int s0, int tid) {
;     ...
;   for (int tl = 0; tl < 64; ++tl) {
;     const int t = t0 + tl, s = s0 + tl;
;     int to = t - W + 1; if (to < tq0) to = tq0;
;     const f32x4 hn = *(const f32x4*)(xq + (size_t)t * D) * smr[15 + tl];
;     const f32x4 ho = *(const f32x4*)(xq + (size_t)to * D) * smr[15 + tl - W + 1];
;     const int cnt = (s + 1 < W) ? (s + 1) : W;
;     const float ic = 1.f / (float)cnt;
;     Sm += hn;
;     const f32x4 p = Sm * ic - hn;
;     Sm -= ho;
;     u32x2 o; o.x = pack_bf16(p.x, p.y); o.y = pack_bf16(p.z, p.w);
;     *(u32x2*)(pb + (size_t)t * LDH + tid * 4) = o;
;   }
	v_fma_f32 v36, -v88, v157, v36
	v_fma_f32 v37, -v89, v157, v37
	v_fma_f32 v38, -v90, v157, v38
	v_fma_f32 v39, -v91, v157, v39
	v_cvt_pk_bf16_f32 v208, v12, v13
	v_cvt_pk_bf16_f32 v209, v22, v23
	global_store_dwordx2 v222, v[208:209], s[74:75]
	s_add_u32 s14, s2, 0x2d000
	s_addc_u32 s15, s3, 0
	global_load_dwordx4 v[84:87], v0, s[14:15]
	s_add_u32 s56, s2, 0x2a000
	s_addc_u32 s57, s3, 0
	global_load_dwordx4 v[88:91], v0, s[56:57]
	s_add_u32 s54, s12, 0x14300
	s_addc_u32 s55, s13, 0
	s_waitcnt vmcnt(22)
	v_mul_f32_e32 v212, v92, v161
	v_mul_f32_e32 v213, v93, v161
	v_mul_f32_e32 v214, v94, v161
	v_mul_f32_e32 v215, v95, v161
	v_fmac_f32_e32 v36, v92, v161
	v_fmac_f32_e32 v37, v93, v161
	v_fmac_f32_e32 v38, v94, v161
	v_fmac_f32_e32 v39, v95, v161
	v_fma_f32 v12, v36, s59, -v212
	v_fma_f32 v13, v37, s59, -v213
	v_fma_f32 v22, v38, s59, -v214
	v_fma_f32 v23, v39, s59, -v215
	s_waitcnt vmcnt(21)
	v_fma_f32 v36, -v96, v158, v36
	v_fma_f32 v37, -v97, v158, v37
	v_fma_f32 v38, -v98, v158, v38
	v_fma_f32 v39, -v99, v158, v39
	v_cvt_pk_bf16_f32 v2, v12, v13
	v_cvt_pk_bf16_f32 v3, v22, v23
	global_store_dwordx2 v222, v[2:3], s[54:55]
	s_add_u32 s70, s2, 0x2e000
	s_addc_u32 s71, s3, 0
	global_load_dwordx4 v[92:95], v0, s[70:71]
	s_add_u32 s14, s2, 0x2b000
	s_addc_u32 s15, s3, 0
	global_load_dwordx4 v[96:99], v0, s[14:15]
	s_add_u32 s74, s12, 0x14b80
	s_addc_u32 s75, s13, 0
	s_waitcnt vmcnt(22)
	v_mul_f32_e32 v212, v100, v162
	v_mul_f32_e32 v213, v101, v162
	v_mul_f32_e32 v214, v102, v162
	v_mul_f32_e32 v215, v103, v162
	v_fmac_f32_e32 v36, v100, v162
	v_fmac_f32_e32 v37, v101, v162
	v_fmac_f32_e32 v38, v102, v162
	v_fmac_f32_e32 v39, v103, v162
	v_fma_f32 v12, v36, s59, -v212
	v_fma_f32 v13, v37, s59, -v213
	v_fma_f32 v22, v38, s59, -v214
	v_fma_f32 v23, v39, s59, -v215
	s_waitcnt vmcnt(21)
	v_fma_f32 v36, -v104, v159, v36
	v_fma_f32 v37, -v105, v159, v37
	v_fma_f32 v38, -v106, v159, v38
	v_fma_f32 v39, -v107, v159, v39
	v_cvt_pk_bf16_f32 v208, v12, v13
	v_cvt_pk_bf16_f32 v209, v22, v23
	global_store_dwordx2 v222, v[208:209], s[74:75]
	s_add_u32 s56, s2, 0x2f000
	s_addc_u32 s57, s3, 0
	global_load_dwordx4 v[100:103], v0, s[56:57]
	s_add_u32 s70, s2, 0x2c000
	s_addc_u32 s71, s3, 0
	global_load_dwordx4 v[104:107], v0, s[70:71]
	s_add_u32 s54, s12, 0x15400
	s_addc_u32 s55, s13, 0
	s_waitcnt vmcnt(22)
	v_mul_f32_e32 v212, v44, v163
	v_mul_f32_e32 v213, v45, v163
	v_mul_f32_e32 v214, v46, v163
	v_mul_f32_e32 v215, v47, v163
	v_fmac_f32_e32 v36, v44, v163
	v_fmac_f32_e32 v37, v45, v163
	v_fmac_f32_e32 v38, v46, v163
	v_fmac_f32_e32 v39, v47, v163
	v_fma_f32 v12, v36, s59, -v212
	v_fma_f32 v13, v37, s59, -v213
	v_fma_f32 v22, v38, s59, -v214
	v_fma_f32 v23, v39, s59, -v215
	s_waitcnt vmcnt(21)
	v_fma_f32 v36, -v48, v160, v36
	v_fma_f32 v37, -v49, v160, v37
	v_fma_f32 v38, -v50, v160, v38
	v_fma_f32 v39, -v51, v160, v39
	v_cvt_pk_bf16_f32 v2, v12, v13
	v_cvt_pk_bf16_f32 v3, v22, v23
	global_store_dwordx2 v222, v[2:3], s[54:55]
	s_add_u32 s14, s2, 0x30000
	s_addc_u32 s15, s3, 0
	global_load_dwordx4 v[44:47], v0, s[14:15]
	s_add_u32 s56, s2, 0x2d000
	s_addc_u32 s57, s3, 0
	global_load_dwordx4 v[48:51], v0, s[56:57]
	s_add_u32 s74, s12, 0x15c80
	s_addc_u32 s75, s13, 0
	s_waitcnt vmcnt(22)
	v_mul_f32_e32 v212, v52, v164
	v_mul_f32_e32 v213, v53, v164
	v_mul_f32_e32 v214, v54, v164
	v_mul_f32_e32 v215, v55, v164
	v_fmac_f32_e32 v36, v52, v164
	v_fmac_f32_e32 v37, v53, v164
	v_fmac_f32_e32 v38, v54, v164
	v_fmac_f32_e32 v39, v55, v164
	v_fma_f32 v12, v36, s59, -v212
	v_fma_f32 v13, v37, s59, -v213
	v_fma_f32 v22, v38, s59, -v214
	v_fma_f32 v23, v39, s59, -v215
	s_waitcnt vmcnt(21)
	v_fma_f32 v36, -v56, v161, v36
	v_fma_f32 v37, -v57, v161, v37
	v_fma_f32 v38, -v58, v161, v38
	v_fma_f32 v39, -v59, v161, v39
	v_cvt_pk_bf16_f32 v208, v12, v13
	v_cvt_pk_bf16_f32 v209, v22, v23
	global_store_dwordx2 v222, v[208:209], s[74:75]
	s_add_u32 s70, s2, 0x31000
	s_addc_u32 s71, s3, 0
	global_load_dwordx4 v[52:55], v0, s[70:71]
	s_add_u32 s14, s2, 0x2e000
	s_addc_u32 s15, s3, 0
	global_load_dwordx4 v[56:59], v0, s[14:15]
	s_add_u32 s54, s12, 0x16500
	s_addc_u32 s55, s13, 0
	s_waitcnt vmcnt(22)
	v_mul_f32_e32 v212, v60, v165
	v_mul_f32_e32 v213, v61, v165
	v_mul_f32_e32 v214, v62, v165
	v_mul_f32_e32 v215, v63, v165
	v_fmac_f32_e32 v36, v60, v165
	v_fmac_f32_e32 v37, v61, v165
	v_fmac_f32_e32 v38, v62, v165
	v_fmac_f32_e32 v39, v63, v165
	v_fma_f32 v12, v36, s59, -v212
	v_fma_f32 v13, v37, s59, -v213
	v_fma_f32 v22, v38, s59, -v214
	v_fma_f32 v23, v39, s59, -v215
	s_waitcnt vmcnt(21)
	v_fma_f32 v36, -v64, v162, v36
	v_fma_f32 v37, -v65, v162, v37
	v_fma_f32 v38, -v66, v162, v38
	v_fma_f32 v39, -v67, v162, v39
	v_cvt_pk_bf16_f32 v2, v12, v13
	v_cvt_pk_bf16_f32 v3, v22, v23
	global_store_dwordx2 v222, v[2:3], s[54:55]
	s_add_u32 s56, s2, 0x32000
	s_addc_u32 s57, s3, 0
	global_load_dwordx4 v[60:63], v0, s[56:57]
	s_add_u32 s70, s2, 0x2f000
	s_addc_u32 s71, s3, 0
	global_load_dwordx4 v[64:67], v0, s[70:71]
	s_add_u32 s74, s12, 0x16d80
	s_addc_u32 s75, s13, 0
	s_waitcnt vmcnt(22)
	v_mul_f32_e32 v212, v68, v166
	v_mul_f32_e32 v213, v69, v166
	v_mul_f32_e32 v214, v70, v166
	v_mul_f32_e32 v215, v71, v166
	v_fmac_f32_e32 v36, v68, v166
	v_fmac_f32_e32 v37, v69, v166
	v_fmac_f32_e32 v38, v70, v166
	v_fmac_f32_e32 v39, v71, v166
	v_fma_f32 v12, v36, s59, -v212
	v_fma_f32 v13, v37, s59, -v213
	v_fma_f32 v22, v38, s59, -v214
	v_fma_f32 v23, v39, s59, -v215
	s_waitcnt vmcnt(21)
; DI unsigned pack_bf16(float lo, float hi) { f32x2 v = {lo, hi}; bf16v2 b = __builtin_convertvector(v, bf16v2); return __builtin_bit_cast(unsigned, b); }
; template <int W>
; DI void pool_rows(const float* __restrict__ x, const float* smr, bf16_t* __restrict__ pb, int t0, int s0, int tid) {
;     ...
;   for (int tl = 0; tl < 64; ++tl) {
;     const int t = t0 + tl, s = s0 + tl;
;     int to = t - W + 1; if (to < tq0) to = tq0;
;     const f32x4 hn = *(const f32x4*)(xq + (size_t)t * D) * smr[15 + tl];
;     const f32x4 ho = *(const f32x4*)(xq + (size_t)to * D) * smr[15 + tl - W + 1];
;     const int cnt = (s + 1 < W) ? (s + 1) : W;
;     const float ic = 1.f / (float)cnt;
;     Sm += hn;
;     const f32x4 p = Sm * ic - hn;
;     Sm -= ho;
;     u32x2 o; o.x = pack_bf16(p.x, p.y); o.y = pack_bf16(p.z, p.w);
;     *(u32x2*)(pb + (size_t)t * LDH + tid * 4) = o;
;   }
	v_fma_f32 v36, -v72, v163, v36
	v_fma_f32 v37, -v73, v163, v37
	v_fma_f32 v38, -v74, v163, v38
	v_fma_f32 v39, -v75, v163, v39
	v_cvt_pk_bf16_f32 v208, v12, v13
	v_cvt_pk_bf16_f32 v209, v22, v23
	global_store_dwordx2 v222, v[208:209], s[74:75]
	s_add_u32 s14, s2, 0x33000
	s_addc_u32 s15, s3, 0
	global_load_dwordx4 v[68:71], v0, s[14:15]
	s_add_u32 s56, s2, 0x30000
	s_addc_u32 s57, s3, 0
	global_load_dwordx4 v[72:75], v0, s[56:57]
	s_add_u32 s54, s12, 0x17600
	s_addc_u32 s55, s13, 0
	s_waitcnt vmcnt(22)
	v_mul_f32_e32 v212, v76, v167
	v_mul_f32_e32 v213, v77, v167
	v_mul_f32_e32 v214, v78, v167
	v_mul_f32_e32 v215, v79, v167
	v_fmac_f32_e32 v36, v76, v167
	v_fmac_f32_e32 v37, v77, v167
	v_fmac_f32_e32 v38, v78, v167
	v_fmac_f32_e32 v39, v79, v167
	v_fma_f32 v12, v36, s59, -v212
	v_fma_f32 v13, v37, s59, -v213
	v_fma_f32 v22, v38, s59, -v214
	v_fma_f32 v23, v39, s59, -v215
	s_waitcnt vmcnt(21)
	v_fma_f32 v36, -v80, v164, v36
	v_fma_f32 v37, -v81, v164, v37
	v_fma_f32 v38, -v82, v164, v38
	v_fma_f32 v39, -v83, v164, v39
	v_cvt_pk_bf16_f32 v2, v12, v13
	v_cvt_pk_bf16_f32 v3, v22, v23
	global_store_dwordx2 v222, v[2:3], s[54:55]
	s_add_u32 s70, s2, 0x34000
	s_addc_u32 s71, s3, 0
	global_load_dwordx4 v[76:79], v0, s[70:71]
	s_add_u32 s14, s2, 0x31000
	s_addc_u32 s15, s3, 0
	global_load_dwordx4 v[80:83], v0, s[14:15]
	s_add_u32 s74, s12, 0x17e80
	s_addc_u32 s75, s13, 0
	s_waitcnt vmcnt(22)
	v_mul_f32_e32 v212, v84, v168
	v_mul_f32_e32 v213, v85, v168
	v_mul_f32_e32 v214, v86, v168
	v_mul_f32_e32 v215, v87, v168
	v_fmac_f32_e32 v36, v84, v168
	v_fmac_f32_e32 v37, v85, v168
	v_fmac_f32_e32 v38, v86, v168
	v_fmac_f32_e32 v39, v87, v168
	v_fma_f32 v12, v36, s59, -v212
	v_fma_f32 v13, v37, s59, -v213
	v_fma_f32 v22, v38, s59, -v214
	v_fma_f32 v23, v39, s59, -v215
	s_waitcnt vmcnt(21)
	v_fma_f32 v36, -v88, v165, v36
	v_fma_f32 v37, -v89, v165, v37
	v_fma_f32 v38, -v90, v165, v38
	v_fma_f32 v39, -v91, v165, v39
	v_cvt_pk_bf16_f32 v208, v12, v13
	v_cvt_pk_bf16_f32 v209, v22, v23
	global_store_dwordx2 v222, v[208:209], s[74:75]
	s_add_u32 s56, s2, 0x35000
	s_addc_u32 s57, s3, 0
	global_load_dwordx4 v[84:87], v0, s[56:57]
	s_add_u32 s70, s2, 0x32000
	s_addc_u32 s71, s3, 0
	global_load_dwordx4 v[88:91], v0, s[70:71]
	s_add_u32 s54, s12, 0x18700
	s_addc_u32 s55, s13, 0
	s_waitcnt vmcnt(22)
	v_mul_f32_e32 v212, v92, v169
	v_mul_f32_e32 v213, v93, v169
	v_mul_f32_e32 v214, v94, v169
	v_mul_f32_e32 v215, v95, v169
	v_fmac_f32_e32 v36, v92, v169
	v_fmac_f32_e32 v37, v93, v169
	v_fmac_f32_e32 v38, v94, v169
	v_fmac_f32_e32 v39, v95, v169
	v_fma_f32 v12, v36, s59, -v212
	v_fma_f32 v13, v37, s59, -v213
	v_fma_f32 v22, v38, s59, -v214
	v_fma_f32 v23, v39, s59, -v215
	s_waitcnt vmcnt(21)
	v_fma_f32 v36, -v96, v166, v36
	v_fma_f32 v37, -v97, v166, v37
	v_fma_f32 v38, -v98, v166, v38
	v_fma_f32 v39, -v99, v166, v39
	v_cvt_pk_bf16_f32 v2, v12, v13
	v_cvt_pk_bf16_f32 v3, v22, v23
	global_store_dwordx2 v222, v[2:3], s[54:55]
	s_add_u32 s14, s2, 0x36000
	s_addc_u32 s15, s3, 0
	global_load_dwordx4 v[92:95], v0, s[14:15]
	s_add_u32 s56, s2, 0x33000
	s_addc_u32 s57, s3, 0
	global_load_dwordx4 v[96:99], v0, s[56:57]
	s_add_u32 s74, s12, 0x18f80
	s_addc_u32 s75, s13, 0
	s_waitcnt vmcnt(22)
	v_mul_f32_e32 v212, v100, v170
	v_mul_f32_e32 v213, v101, v170
	v_mul_f32_e32 v214, v102, v170
	v_mul_f32_e32 v215, v103, v170
	v_fmac_f32_e32 v36, v100, v170
	v_fmac_f32_e32 v37, v101, v170
	v_fmac_f32_e32 v38, v102, v170
	v_fmac_f32_e32 v39, v103, v170
	v_fma_f32 v12, v36, s59, -v212
	v_fma_f32 v13, v37, s59, -v213
	v_fma_f32 v22, v38, s59, -v214
	v_fma_f32 v23, v39, s59, -v215
	s_waitcnt vmcnt(21)
	v_fma_f32 v36, -v104, v167, v36
	v_fma_f32 v37, -v105, v167, v37
	v_fma_f32 v38, -v106, v167, v38
	v_fma_f32 v39, -v107, v167, v39
	v_cvt_pk_bf16_f32 v208, v12, v13
	v_cvt_pk_bf16_f32 v209, v22, v23
	global_store_dwordx2 v222, v[208:209], s[74:75]
	s_add_u32 s70, s2, 0x37000
	s_addc_u32 s71, s3, 0
	global_load_dwordx4 v[100:103], v0, s[70:71]
	s_add_u32 s14, s2, 0x34000
	s_addc_u32 s15, s3, 0
	global_load_dwordx4 v[104:107], v0, s[14:15]
	s_add_u32 s54, s12, 0x19800
	s_addc_u32 s55, s13, 0
	s_waitcnt vmcnt(22)
	v_mul_f32_e32 v212, v44, v171
	v_mul_f32_e32 v213, v45, v171
	v_mul_f32_e32 v214, v46, v171
	v_mul_f32_e32 v215, v47, v171
	v_fmac_f32_e32 v36, v44, v171
	v_fmac_f32_e32 v37, v45, v171
	v_fmac_f32_e32 v38, v46, v171
	v_fmac_f32_e32 v39, v47, v171
	v_fma_f32 v12, v36, s59, -v212
	v_fma_f32 v13, v37, s59, -v213
	v_fma_f32 v22, v38, s59, -v214
	v_fma_f32 v23, v39, s59, -v215
	s_waitcnt vmcnt(21)
	v_fma_f32 v36, -v48, v168, v36
	v_fma_f32 v37, -v49, v168, v37
	v_fma_f32 v38, -v50, v168, v38
	v_fma_f32 v39, -v51, v168, v39
	v_cvt_pk_bf16_f32 v2, v12, v13
	v_cvt_pk_bf16_f32 v3, v22, v23
	global_store_dwordx2 v222, v[2:3], s[54:55]
	s_add_u32 s56, s2, 0x38000
	s_addc_u32 s57, s3, 0
	global_load_dwordx4 v[44:47], v0, s[56:57]
	s_add_u32 s70, s2, 0x35000
	s_addc_u32 s71, s3, 0
	global_load_dwordx4 v[48:51], v0, s[70:71]
	s_add_u32 s74, s12, 0x1a080
	s_addc_u32 s75, s13, 0
	s_waitcnt vmcnt(22)
	v_mul_f32_e32 v212, v52, v172
	v_mul_f32_e32 v213, v53, v172
	v_mul_f32_e32 v214, v54, v172
	v_mul_f32_e32 v215, v55, v172
	v_fmac_f32_e32 v36, v52, v172
	v_fmac_f32_e32 v37, v53, v172
	v_fmac_f32_e32 v38, v54, v172
	v_fmac_f32_e32 v39, v55, v172
	v_fma_f32 v12, v36, s59, -v212
	v_fma_f32 v13, v37, s59, -v213
	v_fma_f32 v22, v38, s59, -v214
	v_fma_f32 v23, v39, s59, -v215
	s_waitcnt vmcnt(21)
; DI unsigned pack_bf16(float lo, float hi) { f32x2 v = {lo, hi}; bf16v2 b = __builtin_convertvector(v, bf16v2); return __builtin_bit_cast(unsigned, b); }
; template <int W>
; DI void pool_rows(const float* __restrict__ x, const float* smr, bf16_t* __restrict__ pb, int t0, int s0, int tid) {
;     ...
;   for (int tl = 0; tl < 64; ++tl) {
;     const int t = t0 + tl, s = s0 + tl;
;     int to = t - W + 1; if (to < tq0) to = tq0;
;     const f32x4 hn = *(const f32x4*)(xq + (size_t)t * D) * smr[15 + tl];
;     const f32x4 ho = *(const f32x4*)(xq + (size_t)to * D) * smr[15 + tl - W + 1];
;     const int cnt = (s + 1 < W) ? (s + 1) : W;
;     const float ic = 1.f / (float)cnt;
;     Sm += hn;
;     const f32x4 p = Sm * ic - hn;
;     Sm -= ho;
;     u32x2 o; o.x = pack_bf16(p.x, p.y); o.y = pack_bf16(p.z, p.w);
;     *(u32x2*)(pb + (size_t)t * LDH + tid * 4) = o;
;   }
	v_fma_f32 v36, -v56, v169, v36
	v_fma_f32 v37, -v57, v169, v37
	v_fma_f32 v38, -v58, v169, v38
	v_fma_f32 v39, -v59, v169, v39
	v_cvt_pk_bf16_f32 v208, v12, v13
	v_cvt_pk_bf16_f32 v209, v22, v23
	global_store_dwordx2 v222, v[208:209], s[74:75]
	s_add_u32 s14, s2, 0x39000
	s_addc_u32 s15, s3, 0
	global_load_dwordx4 v[52:55], v0, s[14:15]
	s_add_u32 s56, s2, 0x36000
	s_addc_u32 s57, s3, 0
	global_load_dwordx4 v[56:59], v0, s[56:57]
	s_add_u32 s54, s12, 0x1a900
	s_addc_u32 s55, s13, 0
	s_waitcnt vmcnt(22)
	v_mul_f32_e32 v212, v60, v173
	v_mul_f32_e32 v213, v61, v173
	v_mul_f32_e32 v214, v62, v173
	v_mul_f32_e32 v215, v63, v173
	v_fmac_f32_e32 v36, v60, v173
	v_fmac_f32_e32 v37, v61, v173
	v_fmac_f32_e32 v38, v62, v173
	v_fmac_f32_e32 v39, v63, v173
	v_fma_f32 v12, v36, s59, -v212
	v_fma_f32 v13, v37, s59, -v213
	v_fma_f32 v22, v38, s59, -v214
	v_fma_f32 v23, v39, s59, -v215
	s_waitcnt vmcnt(21)
	v_fma_f32 v36, -v64, v170, v36
	v_fma_f32 v37, -v65, v170, v37
	v_fma_f32 v38, -v66, v170, v38
	v_fma_f32 v39, -v67, v170, v39
	v_cvt_pk_bf16_f32 v2, v12, v13
	v_cvt_pk_bf16_f32 v3, v22, v23
	global_store_dwordx2 v222, v[2:3], s[54:55]
	s_add_u32 s70, s2, 0x3a000
	s_addc_u32 s71, s3, 0
	global_load_dwordx4 v[60:63], v0, s[70:71]
	s_add_u32 s14, s2, 0x37000
	s_addc_u32 s15, s3, 0
	global_load_dwordx4 v[64:67], v0, s[14:15]
	s_add_u32 s74, s12, 0x1b180
	s_addc_u32 s75, s13, 0
	s_waitcnt vmcnt(22)
	v_mul_f32_e32 v212, v68, v174
	v_mul_f32_e32 v213, v69, v174
	v_mul_f32_e32 v214, v70, v174
	v_mul_f32_e32 v215, v71, v174
	v_fmac_f32_e32 v36, v68, v174
	v_fmac_f32_e32 v37, v69, v174
	v_fmac_f32_e32 v38, v70, v174
	v_fmac_f32_e32 v39, v71, v174
	v_fma_f32 v12, v36, s59, -v212
	v_fma_f32 v13, v37, s59, -v213
	v_fma_f32 v22, v38, s59, -v214
	v_fma_f32 v23, v39, s59, -v215
	s_waitcnt vmcnt(21)
	v_fma_f32 v36, -v72, v171, v36
	v_fma_f32 v37, -v73, v171, v37
	v_fma_f32 v38, -v74, v171, v38
	v_fma_f32 v39, -v75, v171, v39
	v_cvt_pk_bf16_f32 v208, v12, v13
	v_cvt_pk_bf16_f32 v209, v22, v23
	global_store_dwordx2 v222, v[208:209], s[74:75]
	s_add_u32 s56, s2, 0x3b000
	s_addc_u32 s57, s3, 0
	global_load_dwordx4 v[68:71], v0, s[56:57]
	s_add_u32 s70, s2, 0x38000
	s_addc_u32 s71, s3, 0
	global_load_dwordx4 v[72:75], v0, s[70:71]
	s_add_u32 s54, s12, 0x1ba00
	s_addc_u32 s55, s13, 0
	s_waitcnt vmcnt(22)
	v_mul_f32_e32 v212, v76, v175
	v_mul_f32_e32 v213, v77, v175
	v_mul_f32_e32 v214, v78, v175
	v_mul_f32_e32 v215, v79, v175
	v_fmac_f32_e32 v36, v76, v175
	v_fmac_f32_e32 v37, v77, v175
	v_fmac_f32_e32 v38, v78, v175
	v_fmac_f32_e32 v39, v79, v175
	v_fma_f32 v12, v36, s59, -v212
	v_fma_f32 v13, v37, s59, -v213
	v_fma_f32 v22, v38, s59, -v214
	v_fma_f32 v23, v39, s59, -v215
	s_waitcnt vmcnt(21)
	v_fma_f32 v36, -v80, v172, v36
	v_fma_f32 v37, -v81, v172, v37
	v_fma_f32 v38, -v82, v172, v38
	v_fma_f32 v39, -v83, v172, v39
	v_cvt_pk_bf16_f32 v2, v12, v13
	v_cvt_pk_bf16_f32 v3, v22, v23
	global_store_dwordx2 v222, v[2:3], s[54:55]
	s_add_u32 s14, s2, 0x3c000
	s_addc_u32 s15, s3, 0
	global_load_dwordx4 v[76:79], v0, s[14:15]
	s_add_u32 s56, s2, 0x39000
	s_addc_u32 s57, s3, 0
	global_load_dwordx4 v[80:83], v0, s[56:57]
	s_add_u32 s74, s12, 0x1c280
	s_addc_u32 s75, s13, 0
	s_waitcnt vmcnt(22)
	v_mul_f32_e32 v212, v84, v176
	v_mul_f32_e32 v213, v85, v176
	v_mul_f32_e32 v214, v86, v176
	v_mul_f32_e32 v215, v87, v176
	v_fmac_f32_e32 v36, v84, v176
	v_fmac_f32_e32 v37, v85, v176
	v_fmac_f32_e32 v38, v86, v176
	v_fmac_f32_e32 v39, v87, v176
	v_fma_f32 v12, v36, s59, -v212
	v_fma_f32 v13, v37, s59, -v213
	v_fma_f32 v22, v38, s59, -v214
	v_fma_f32 v23, v39, s59, -v215
	s_waitcnt vmcnt(21)
	v_fma_f32 v36, -v88, v173, v36
	v_fma_f32 v37, -v89, v173, v37
	v_fma_f32 v38, -v90, v173, v38
	v_fma_f32 v39, -v91, v173, v39
	v_cvt_pk_bf16_f32 v208, v12, v13
	v_cvt_pk_bf16_f32 v209, v22, v23
	global_store_dwordx2 v222, v[208:209], s[74:75]
	s_add_u32 s70, s2, 0x3d000
	s_addc_u32 s71, s3, 0
	global_load_dwordx4 v[84:87], v0, s[70:71]
	s_add_u32 s14, s2, 0x3a000
	s_addc_u32 s15, s3, 0
	global_load_dwordx4 v[88:91], v0, s[14:15]
	s_add_u32 s54, s12, 0x1cb00
	s_addc_u32 s55, s13, 0
	s_waitcnt vmcnt(22)
	v_mul_f32_e32 v212, v92, v177
	v_mul_f32_e32 v213, v93, v177
	v_mul_f32_e32 v214, v94, v177
	v_mul_f32_e32 v215, v95, v177
	v_fmac_f32_e32 v36, v92, v177
	v_fmac_f32_e32 v37, v93, v177
	v_fmac_f32_e32 v38, v94, v177
	v_fmac_f32_e32 v39, v95, v177
	v_fma_f32 v12, v36, s59, -v212
	v_fma_f32 v13, v37, s59, -v213
	v_fma_f32 v22, v38, s59, -v214
	v_fma_f32 v23, v39, s59, -v215
	s_waitcnt vmcnt(21)
	v_fma_f32 v36, -v96, v174, v36
	v_fma_f32 v37, -v97, v174, v37
	v_fma_f32 v38, -v98, v174, v38
	v_fma_f32 v39, -v99, v174, v39
	v_cvt_pk_bf16_f32 v2, v12, v13
	v_cvt_pk_bf16_f32 v3, v22, v23
	global_store_dwordx2 v222, v[2:3], s[54:55]
	s_add_u32 s56, s2, 0x3e000
	s_addc_u32 s57, s3, 0
	global_load_dwordx4 v[92:95], v0, s[56:57]
	s_add_u32 s70, s2, 0x3b000
	s_addc_u32 s71, s3, 0
	global_load_dwordx4 v[96:99], v0, s[70:71]
	s_add_u32 s74, s12, 0x1d380
	s_addc_u32 s75, s13, 0
	s_waitcnt vmcnt(22)
	v_mul_f32_e32 v212, v100, v178
	v_mul_f32_e32 v213, v101, v178
	v_mul_f32_e32 v214, v102, v178
	v_mul_f32_e32 v215, v103, v178
	v_fmac_f32_e32 v36, v100, v178
	v_fmac_f32_e32 v37, v101, v178
	v_fmac_f32_e32 v38, v102, v178
	v_fmac_f32_e32 v39, v103, v178
	v_fma_f32 v12, v36, s59, -v212
	v_fma_f32 v13, v37, s59, -v213
	v_fma_f32 v22, v38, s59, -v214
	v_fma_f32 v23, v39, s59, -v215
	s_waitcnt vmcnt(21)
; DI unsigned pack_bf16(float lo, float hi) { f32x2 v = {lo, hi}; bf16v2 b = __builtin_convertvector(v, bf16v2); return __builtin_bit_cast(unsigned, b); }
; template <int W>
; DI void pool_rows(const float* __restrict__ x, const float* smr, bf16_t* __restrict__ pb, int t0, int s0, int tid) {
;     ...
;   for (int tl = 0; tl < 64; ++tl) {
;     const int t = t0 + tl, s = s0 + tl;
;     int to = t - W + 1; if (to < tq0) to = tq0;
;     const f32x4 hn = *(const f32x4*)(xq + (size_t)t * D) * smr[15 + tl];
;     const f32x4 ho = *(const f32x4*)(xq + (size_t)to * D) * smr[15 + tl - W + 1];
;     const int cnt = (s + 1 < W) ? (s + 1) : W;
;     const float ic = 1.f / (float)cnt;
;     Sm += hn;
;     const f32x4 p = Sm * ic - hn;
;     Sm -= ho;
;     u32x2 o; o.x = pack_bf16(p.x, p.y); o.y = pack_bf16(p.z, p.w);
;     *(u32x2*)(pb + (size_t)t * LDH + tid * 4) = o;
;   }
	v_fma_f32 v36, -v104, v175, v36
	v_fma_f32 v37, -v105, v175, v37
	v_fma_f32 v38, -v106, v175, v38
	v_fma_f32 v39, -v107, v175, v39
	v_cvt_pk_bf16_f32 v208, v12, v13
	v_cvt_pk_bf16_f32 v209, v22, v23
	global_store_dwordx2 v222, v[208:209], s[74:75]
	s_add_u32 s14, s2, 0x3f000
	s_addc_u32 s15, s3, 0
	global_load_dwordx4 v[100:103], v0, s[14:15]
	s_add_u32 s56, s2, 0x3c000
	s_addc_u32 s57, s3, 0
	global_load_dwordx4 v[104:107], v0, s[56:57]
	s_add_u32 s54, s12, 0x1dc00
	s_addc_u32 s55, s13, 0
	s_waitcnt vmcnt(22)
	v_mul_f32_e32 v212, v44, v179
	v_mul_f32_e32 v213, v45, v179
	v_mul_f32_e32 v214, v46, v179
	v_mul_f32_e32 v215, v47, v179
	v_fmac_f32_e32 v36, v44, v179
	v_fmac_f32_e32 v37, v45, v179
	v_fmac_f32_e32 v38, v46, v179
	v_fmac_f32_e32 v39, v47, v179
	v_fma_f32 v12, v36, s59, -v212
	v_fma_f32 v13, v37, s59, -v213
	v_fma_f32 v22, v38, s59, -v214
	v_fma_f32 v23, v39, s59, -v215
	s_waitcnt vmcnt(21)
	v_fma_f32 v36, -v48, v176, v36
	v_fma_f32 v37, -v49, v176, v37
	v_fma_f32 v38, -v50, v176, v38
	v_fma_f32 v39, -v51, v176, v39
	v_cvt_pk_bf16_f32 v2, v12, v13
	v_cvt_pk_bf16_f32 v3, v22, v23
	global_store_dwordx2 v222, v[2:3], s[54:55]
	s_add_u32 s74, s12, 0x1e480
	s_addc_u32 s75, s13, 0
	s_waitcnt vmcnt(20)
	v_mul_f32_e32 v212, v52, v180
	v_mul_f32_e32 v213, v53, v180
	v_mul_f32_e32 v214, v54, v180
	v_mul_f32_e32 v215, v55, v180
	v_fmac_f32_e32 v36, v52, v180
	v_fmac_f32_e32 v37, v53, v180
	v_fmac_f32_e32 v38, v54, v180
	v_fmac_f32_e32 v39, v55, v180
	v_fma_f32 v12, v36, s59, -v212
	v_fma_f32 v13, v37, s59, -v213
	v_fma_f32 v22, v38, s59, -v214
	v_fma_f32 v23, v39, s59, -v215
	s_waitcnt vmcnt(19)
	v_fma_f32 v36, -v56, v177, v36
	v_fma_f32 v37, -v57, v177, v37
	v_fma_f32 v38, -v58, v177, v38
	v_fma_f32 v39, -v59, v177, v39
	v_cvt_pk_bf16_f32 v208, v12, v13
	v_cvt_pk_bf16_f32 v209, v22, v23
	global_store_dwordx2 v222, v[208:209], s[74:75]
	s_add_u32 s54, s12, 0x1ed00
	s_addc_u32 s55, s13, 0
	s_waitcnt vmcnt(18)
	v_mul_f32_e32 v212, v60, v181
	v_mul_f32_e32 v213, v61, v181
	v_mul_f32_e32 v214, v62, v181
	v_mul_f32_e32 v215, v63, v181
	v_fmac_f32_e32 v36, v60, v181
	v_fmac_f32_e32 v37, v61, v181
	v_fmac_f32_e32 v38, v62, v181
	v_fmac_f32_e32 v39, v63, v181
	v_fma_f32 v12, v36, s59, -v212
	v_fma_f32 v13, v37, s59, -v213
	v_fma_f32 v22, v38, s59, -v214
	v_fma_f32 v23, v39, s59, -v215
	s_waitcnt vmcnt(17)
	v_fma_f32 v36, -v64, v178, v36
	v_fma_f32 v37, -v65, v178, v37
	v_fma_f32 v38, -v66, v178, v38
	v_fma_f32 v39, -v67, v178, v39
	v_cvt_pk_bf16_f32 v2, v12, v13
	v_cvt_pk_bf16_f32 v3, v22, v23
	global_store_dwordx2 v222, v[2:3], s[54:55]
	s_add_u32 s74, s12, 0x1f580
	s_addc_u32 s75, s13, 0
	s_waitcnt vmcnt(16)
	v_mul_f32_e32 v212, v68, v182
	v_mul_f32_e32 v213, v69, v182
	v_mul_f32_e32 v214, v70, v182
	v_mul_f32_e32 v215, v71, v182
	v_fmac_f32_e32 v36, v68, v182
	v_fmac_f32_e32 v37, v69, v182
	v_fmac_f32_e32 v38, v70, v182
	v_fmac_f32_e32 v39, v71, v182
	v_fma_f32 v12, v36, s59, -v212
	v_fma_f32 v13, v37, s59, -v213
	v_fma_f32 v22, v38, s59, -v214
	v_fma_f32 v23, v39, s59, -v215
	s_waitcnt vmcnt(15)
	v_fma_f32 v36, -v72, v179, v36
	v_fma_f32 v37, -v73, v179, v37
	v_fma_f32 v38, -v74, v179, v38
	v_fma_f32 v39, -v75, v179, v39
	v_cvt_pk_bf16_f32 v208, v12, v13
	v_cvt_pk_bf16_f32 v209, v22, v23
	global_store_dwordx2 v222, v[208:209], s[74:75]
	s_add_u32 s54, s12, 0x1fe00
	s_addc_u32 s55, s13, 0
	s_waitcnt vmcnt(14)
	v_mul_f32_e32 v212, v76, v183
	v_mul_f32_e32 v213, v77, v183
	v_mul_f32_e32 v214, v78, v183
	v_mul_f32_e32 v215, v79, v183
	v_fmac_f32_e32 v36, v76, v183
	v_fmac_f32_e32 v37, v77, v183
	v_fmac_f32_e32 v38, v78, v183
	v_fmac_f32_e32 v39, v79, v183
	v_fma_f32 v12, v36, s59, -v212
	v_fma_f32 v13, v37, s59, -v213
	v_fma_f32 v22, v38, s59, -v214
	v_fma_f32 v23, v39, s59, -v215
	s_waitcnt vmcnt(13)
	v_fma_f32 v36, -v80, v180, v36
	v_fma_f32 v37, -v81, v180, v37
	v_fma_f32 v38, -v82, v180, v38
	v_fma_f32 v39, -v83, v180, v39
	v_cvt_pk_bf16_f32 v2, v12, v13
	v_cvt_pk_bf16_f32 v3, v22, v23
	global_store_dwordx2 v222, v[2:3], s[54:55]
	s_add_u32 s74, s12, 0x20680
	s_addc_u32 s75, s13, 0
	s_waitcnt vmcnt(12)
	v_mul_f32_e32 v212, v84, v184
	v_mul_f32_e32 v213, v85, v184
	v_mul_f32_e32 v214, v86, v184
	v_mul_f32_e32 v215, v87, v184
	v_fmac_f32_e32 v36, v84, v184
	v_fmac_f32_e32 v37, v85, v184
	v_fmac_f32_e32 v38, v86, v184
	v_fmac_f32_e32 v39, v87, v184
	v_fma_f32 v12, v36, s59, -v212
	v_fma_f32 v13, v37, s59, -v213
	v_fma_f32 v22, v38, s59, -v214
	v_fma_f32 v23, v39, s59, -v215
	s_waitcnt vmcnt(11)
	v_fma_f32 v36, -v88, v181, v36
	v_fma_f32 v37, -v89, v181, v37
	v_fma_f32 v38, -v90, v181, v38
	v_fma_f32 v39, -v91, v181, v39
	v_cvt_pk_bf16_f32 v208, v12, v13
	v_cvt_pk_bf16_f32 v209, v22, v23
	global_store_dwordx2 v222, v[208:209], s[74:75]
	s_add_u32 s54, s12, 0x20f00
	s_addc_u32 s55, s13, 0
	s_waitcnt vmcnt(10)
	v_mul_f32_e32 v212, v92, v185
	v_mul_f32_e32 v213, v93, v185
	v_mul_f32_e32 v214, v94, v185
	v_mul_f32_e32 v215, v95, v185
	v_fmac_f32_e32 v36, v92, v185
	v_fmac_f32_e32 v37, v93, v185
	v_fmac_f32_e32 v38, v94, v185
	v_fmac_f32_e32 v39, v95, v185
	v_fma_f32 v12, v36, s59, -v212
	v_fma_f32 v13, v37, s59, -v213
	v_fma_f32 v22, v38, s59, -v214
	v_fma_f32 v23, v39, s59, -v215
	s_waitcnt vmcnt(9)
	v_fma_f32 v36, -v96, v182, v36
	v_fma_f32 v37, -v97, v182, v37
	v_fma_f32 v38, -v98, v182, v38
	v_fma_f32 v39, -v99, v182, v39
	v_cvt_pk_bf16_f32 v2, v12, v13
	v_cvt_pk_bf16_f32 v3, v22, v23
	global_store_dwordx2 v222, v[2:3], s[54:55]
	s_add_u32 s74, s12, 0x21780
	s_addc_u32 s75, s13, 0
	s_waitcnt vmcnt(8)
	v_mul_f32_e32 v212, v100, v186
	v_mul_f32_e32 v213, v101, v186
	v_mul_f32_e32 v214, v102, v186
	v_mul_f32_e32 v215, v103, v186
	v_fmac_f32_e32 v36, v100, v186
	v_fmac_f32_e32 v37, v101, v186
	v_fmac_f32_e32 v38, v102, v186
	v_fmac_f32_e32 v39, v103, v186
	v_fma_f32 v12, v36, s59, -v212
	v_fma_f32 v13, v37, s59, -v213
	v_fma_f32 v22, v38, s59, -v214
	v_fma_f32 v23, v39, s59, -v215
	s_waitcnt vmcnt(7)
	v_fma_f32 v36, -v104, v183, v36
	v_fma_f32 v37, -v105, v183, v37
	v_fma_f32 v38, -v106, v183, v38
	v_fma_f32 v39, -v107, v183, v39
	v_cvt_pk_bf16_f32 v208, v12, v13
	v_cvt_pk_bf16_f32 v209, v22, v23
	global_store_dwordx2 v222, v[208:209], s[74:75]
	s_branch .Lpp_done
; DI unsigned pack_bf16(float lo, float hi) { f32x2 v = {lo, hi}; bf16v2 b = __builtin_convertvector(v, bf16v2); return __builtin_bit_cast(unsigned, b); }
; template <int W>
; DI void pool_rows(const float* __restrict__ x, const float* smr, bf16_t* __restrict__ pb, int t0, int s0, int tid) {
;     ...
;   const float* xq = x + tid * 4;
;   f32x4 Sm = {0.f, 0.f, 0.f, 0.f};
; #pragma unroll
;   for (int i = 1; i < W; ++i) {
;     int t = t0 - i; if (t < tq0) t = tq0;
;     Sm += *(const f32x4*)(xq + (size_t)t * D) * smr[15 - i];
;   }
; #pragma unroll 8
;   for (int tl = 0; tl < 64; ++tl) {
;     const int t = t0 + tl, s = s0 + tl;
;     int to = t - W + 1; if (to < tq0) to = tq0;
;     const f32x4 hn = *(const f32x4*)(xq + (size_t)t * D) * smr[15 + tl];
;     const f32x4 ho = *(const f32x4*)(xq + (size_t)to * D) * smr[15 + tl - W + 1];
;     const int cnt = (s + 1 < W) ? (s + 1) : W;
;     const float ic = 1.f / (float)cnt;
;     Sm += hn;
;     const f32x4 p = Sm * ic - hn;
;     Sm -= ho;
;     u32x2 o; o.x = pack_bf16(p.x, p.y); o.y = pack_bf16(p.z, p.w);
;     *(u32x2*)(pb + (size_t)t * LDH + tid * 4) = o;
;   }
.Lpp_w8:
	s_mov_b32 s59, 0x3e000000
	s_cmp_eq_u32 s58, 0
	s_cselect_b32 s31, 0, 0xfffff000
	s_cselect_b32 s32, 0, -1
	s_add_u32 s14, s2, s31
	s_addc_u32 s15, s3, s32
	global_load_dwordx4 v[188:191], v0, s[14:15]
	s_cmp_eq_u32 s58, 0
	s_cselect_b32 s31, 0, 0xffffe000
	s_cselect_b32 s32, 0, -1
	s_add_u32 s56, s2, s31
	s_addc_u32 s57, s3, s32
	global_load_dwordx4 v[192:195], v0, s[56:57]
	s_cmp_eq_u32 s58, 0
	s_cselect_b32 s31, 0, 0xffffd000
	s_cselect_b32 s32, 0, -1
	s_add_u32 s70, s2, s31
	s_addc_u32 s71, s3, s32
	global_load_dwordx4 v[196:199], v0, s[70:71]
	s_cmp_eq_u32 s58, 0
	s_cselect_b32 s31, 0, 0xffffc000
	s_cselect_b32 s32, 0, -1
	s_add_u32 s14, s2, s31
	s_addc_u32 s15, s3, s32
	global_load_dwordx4 v[200:203], v0, s[14:15]
	s_cmp_eq_u32 s58, 0
	s_cselect_b32 s31, 0, 0xffffb000
	s_cselect_b32 s32, 0, -1
	s_add_u32 s56, s2, s31
	s_addc_u32 s57, s3, s32
	global_load_dwordx4 v[204:207], v0, s[56:57]
	s_cmp_eq_u32 s58, 0
	s_cselect_b32 s31, 0, 0xffffa000
	s_cselect_b32 s32, 0, -1
	s_add_u32 s70, s2, s31
	s_addc_u32 s71, s3, s32
	global_load_dwordx4 v[224:227], v0, s[70:71]
	s_cmp_eq_u32 s58, 0
	s_cselect_b32 s31, 0, 0xffff9000
	s_cselect_b32 s32, 0, -1
	s_add_u32 s14, s2, s31
	s_addc_u32 s15, s3, s32
	global_load_dwordx4 v[228:231], v0, s[14:15]
	s_mov_b32 s56, s2
	s_mov_b32 s57, s3
	global_load_dwordx4 v[44:47], v0, s[56:57]
	s_cmp_eq_u32 s58, 0
	s_cselect_b32 s31, 0, 0xffff9000
	s_cselect_b32 s32, 0, -1
	s_add_u32 s70, s2, s31
	s_addc_u32 s71, s3, s32
	global_load_dwordx4 v[48:51], v0, s[70:71]
	s_add_u32 s14, s2, 0x1000
	s_addc_u32 s15, s3, 0
	global_load_dwordx4 v[52:55], v0, s[14:15]
	s_cmp_eq_u32 s58, 0
	s_cselect_b32 s31, 0, 0xffffa000
	s_cselect_b32 s32, 0, -1
	s_add_u32 s56, s2, s31
	s_addc_u32 s57, s3, s32
	global_load_dwordx4 v[56:59], v0, s[56:57]
	s_add_u32 s70, s2, 0x2000
	s_addc_u32 s71, s3, 0
	global_load_dwordx4 v[60:63], v0, s[70:71]
	s_cmp_eq_u32 s58, 0
	s_cselect_b32 s31, 0, 0xffffb000
	s_cselect_b32 s32, 0, -1
	s_add_u32 s14, s2, s31
	s_addc_u32 s15, s3, s32
	global_load_dwordx4 v[64:67], v0, s[14:15]
	s_add_u32 s56, s2, 0x3000
	s_addc_u32 s57, s3, 0
	global_load_dwordx4 v[68:71], v0, s[56:57]
	s_cmp_eq_u32 s58, 0
	s_cselect_b32 s31, 0, 0xffffc000
	s_cselect_b32 s32, 0, -1
	s_add_u32 s70, s2, s31
	s_addc_u32 s71, s3, s32
	global_load_dwordx4 v[72:75], v0, s[70:71]
	s_add_u32 s14, s2, 0x4000
	s_addc_u32 s15, s3, 0
	global_load_dwordx4 v[76:79], v0, s[14:15]
	s_cmp_eq_u32 s58, 0
	s_cselect_b32 s31, 0, 0xffffd000
	s_cselect_b32 s32, 0, -1
	s_add_u32 s56, s2, s31
	s_addc_u32 s57, s3, s32
	global_load_dwordx4 v[80:83], v0, s[56:57]
	s_add_u32 s70, s2, 0x5000
	s_addc_u32 s71, s3, 0
	global_load_dwordx4 v[84:87], v0, s[70:71]
	s_cmp_eq_u32 s58, 0
	s_cselect_b32 s31, 0, 0xffffe000
	s_cselect_b32 s32, 0, -1
	s_add_u32 s14, s2, s31
	s_addc_u32 s15, s3, s32
	global_load_dwordx4 v[88:91], v0, s[14:15]
	s_add_u32 s56, s2, 0x6000
	s_addc_u32 s57, s3, 0
	global_load_dwordx4 v[92:95], v0, s[56:57]
	s_cmp_eq_u32 s58, 0
	s_cselect_b32 s31, 0, 0xfffff000
	s_cselect_b32 s32, 0, -1
	s_add_u32 s70, s2, s31
	s_addc_u32 s71, s3, s32
	global_load_dwordx4 v[96:99], v0, s[70:71]
	s_add_u32 s14, s2, 0x7000
	s_addc_u32 s15, s3, 0
	global_load_dwordx4 v[100:103], v0, s[14:15]
	s_mov_b32 s56, s2
	s_mov_b32 s57, s3
	global_load_dwordx4 v[104:107], v0, s[56:57]
	s_waitcnt lgkmcnt(0)
	s_waitcnt vmcnt(16)
	v_mul_f32_e32 v36, v188, v122
	v_mul_f32_e32 v37, v189, v122
	v_mul_f32_e32 v38, v190, v122
	v_mul_f32_e32 v39, v191, v122
	v_fmac_f32_e32 v36, v192, v121
	v_fmac_f32_e32 v37, v193, v121
	v_fmac_f32_e32 v38, v194, v121
	v_fmac_f32_e32 v39, v195, v121
	v_fmac_f32_e32 v36, v196, v120
	v_fmac_f32_e32 v37, v197, v120
	v_fmac_f32_e32 v38, v198, v120
	v_fmac_f32_e32 v39, v199, v120
	v_fmac_f32_e32 v36, v200, v119
	v_fmac_f32_e32 v37, v201, v119
	v_fmac_f32_e32 v38, v202, v119
	v_fmac_f32_e32 v39, v203, v119
	v_fmac_f32_e32 v36, v204, v118
	v_fmac_f32_e32 v37, v205, v118
	v_fmac_f32_e32 v38, v206, v118
	v_fmac_f32_e32 v39, v207, v118
	v_fmac_f32_e32 v36, v224, v117
	v_fmac_f32_e32 v37, v225, v117
	v_fmac_f32_e32 v38, v226, v117
	v_fmac_f32_e32 v39, v227, v117
	v_fmac_f32_e32 v36, v228, v116
	v_fmac_f32_e32 v37, v229, v116
	v_fmac_f32_e32 v38, v230, v116
	v_fmac_f32_e32 v39, v231, v116
	s_mov_b32 s32, 0x3f800000
	s_cmp_eq_u32 s58, 0
	s_cselect_b32 s32, s32, s59
	s_add_u32 s54, s12, 0x0
	s_addc_u32 s55, s13, 0
	s_waitcnt vmcnt(15)
	v_mul_f32_e32 v212, v44, v123
	v_mul_f32_e32 v213, v45, v123
	v_mul_f32_e32 v214, v46, v123
	v_mul_f32_e32 v215, v47, v123
	v_fmac_f32_e32 v36, v44, v123
	v_fmac_f32_e32 v37, v45, v123
	v_fmac_f32_e32 v38, v46, v123
	v_fmac_f32_e32 v39, v47, v123
	v_fma_f32 v12, v36, s32, -v212
	v_fma_f32 v13, v37, s32, -v213
	v_fma_f32 v22, v38, s32, -v214
	v_fma_f32 v23, v39, s32, -v215
	s_waitcnt vmcnt(14)
	v_fma_f32 v36, -v48, v116, v36
	v_fma_f32 v37, -v49, v116, v37
	v_fma_f32 v38, -v50, v116, v38
	v_fma_f32 v39, -v51, v116, v39
	v_cvt_pk_bf16_f32 v2, v12, v13
	v_cvt_pk_bf16_f32 v3, v22, v23
	global_store_dwordx2 v222, v[2:3], s[54:55]
	s_add_u32 s70, s2, 0x8000
	s_addc_u32 s71, s3, 0
	global_load_dwordx4 v[44:47], v0, s[70:71]
	s_add_u32 s14, s2, 0x1000
	s_addc_u32 s15, s3, 0
	global_load_dwordx4 v[48:51], v0, s[14:15]
	s_mov_b32 s32, 0x3f000000
	s_cmp_eq_u32 s58, 0
	s_cselect_b32 s32, s32, s59
	s_add_u32 s74, s12, 0x880
	s_addc_u32 s75, s13, 0
	s_waitcnt vmcnt(16)
	v_mul_f32_e32 v212, v52, v124
	v_mul_f32_e32 v213, v53, v124
	v_mul_f32_e32 v214, v54, v124
	v_mul_f32_e32 v215, v55, v124
	v_fmac_f32_e32 v36, v52, v124
	v_fmac_f32_e32 v37, v53, v124
	v_fmac_f32_e32 v38, v54, v124
	v_fmac_f32_e32 v39, v55, v124
	v_fma_f32 v12, v36, s32, -v212
	v_fma_f32 v13, v37, s32, -v213
	v_fma_f32 v22, v38, s32, -v214
	v_fma_f32 v23, v39, s32, -v215
	s_waitcnt vmcnt(15)
; DI unsigned pack_bf16(float lo, float hi) { f32x2 v = {lo, hi}; bf16v2 b = __builtin_convertvector(v, bf16v2); return __builtin_bit_cast(unsigned, b); }
; template <int W>
; DI void pool_rows(const float* __restrict__ x, const float* smr, bf16_t* __restrict__ pb, int t0, int s0, int tid) {
;     ...
;   for (int tl = 0; tl < 64; ++tl) {
;     const int t = t0 + tl, s = s0 + tl;
;     int to = t - W + 1; if (to < tq0) to = tq0;
;     const f32x4 hn = *(const f32x4*)(xq + (size_t)t * D) * smr[15 + tl];
;     const f32x4 ho = *(const f32x4*)(xq + (size_t)to * D) * smr[15 + tl - W + 1];
;     const int cnt = (s + 1 < W) ? (s + 1) : W;
;     const float ic = 1.f / (float)cnt;
;     Sm += hn;
;     const f32x4 p = Sm * ic - hn;
;     Sm -= ho;
;     u32x2 o; o.x = pack_bf16(p.x, p.y); o.y = pack_bf16(p.z, p.w);
;     *(u32x2*)(pb + (size_t)t * LDH + tid * 4) = o;
;   }
	v_fma_f32 v36, -v56, v117, v36
	v_fma_f32 v37, -v57, v117, v37
	v_fma_f32 v38, -v58, v117, v38
	v_fma_f32 v39, -v59, v117, v39
	v_cvt_pk_bf16_f32 v208, v12, v13
	v_cvt_pk_bf16_f32 v209, v22, v23
	global_store_dwordx2 v222, v[208:209], s[74:75]
	s_add_u32 s56, s2, 0x9000
	s_addc_u32 s57, s3, 0
	global_load_dwordx4 v[52:55], v0, s[56:57]
	s_add_u32 s70, s2, 0x2000
	s_addc_u32 s71, s3, 0
	global_load_dwordx4 v[56:59], v0, s[70:71]
	s_mov_b32 s32, 0x3eaaaaab
	s_cmp_eq_u32 s58, 0
	s_cselect_b32 s32, s32, s59
	s_add_u32 s54, s12, 0x1100
	s_addc_u32 s55, s13, 0
	s_waitcnt vmcnt(17)
	v_mul_f32_e32 v212, v60, v125
	v_mul_f32_e32 v213, v61, v125
	v_mul_f32_e32 v214, v62, v125
	v_mul_f32_e32 v215, v63, v125
	v_fmac_f32_e32 v36, v60, v125
	v_fmac_f32_e32 v37, v61, v125
	v_fmac_f32_e32 v38, v62, v125
	v_fmac_f32_e32 v39, v63, v125
	v_fma_f32 v12, v36, s32, -v212
	v_fma_f32 v13, v37, s32, -v213
	v_fma_f32 v22, v38, s32, -v214
	v_fma_f32 v23, v39, s32, -v215
	s_waitcnt vmcnt(16)
	v_fma_f32 v36, -v64, v118, v36
	v_fma_f32 v37, -v65, v118, v37
	v_fma_f32 v38, -v66, v118, v38
	v_fma_f32 v39, -v67, v118, v39
	v_cvt_pk_bf16_f32 v2, v12, v13
	v_cvt_pk_bf16_f32 v3, v22, v23
	global_store_dwordx2 v222, v[2:3], s[54:55]
	s_add_u32 s14, s2, 0xa000
	s_addc_u32 s15, s3, 0
	global_load_dwordx4 v[60:63], v0, s[14:15]
	s_add_u32 s56, s2, 0x3000
	s_addc_u32 s57, s3, 0
	global_load_dwordx4 v[64:67], v0, s[56:57]
	s_mov_b32 s32, 0x3e800000
	s_cmp_eq_u32 s58, 0
	s_cselect_b32 s32, s32, s59
	s_add_u32 s74, s12, 0x1980
	s_addc_u32 s75, s13, 0
	s_waitcnt vmcnt(18)
	v_mul_f32_e32 v212, v68, v126
	v_mul_f32_e32 v213, v69, v126
	v_mul_f32_e32 v214, v70, v126
	v_mul_f32_e32 v215, v71, v126
	v_fmac_f32_e32 v36, v68, v126
	v_fmac_f32_e32 v37, v69, v126
	v_fmac_f32_e32 v38, v70, v126
	v_fmac_f32_e32 v39, v71, v126
	v_fma_f32 v12, v36, s32, -v212
	v_fma_f32 v13, v37, s32, -v213
	v_fma_f32 v22, v38, s32, -v214
	v_fma_f32 v23, v39, s32, -v215
	s_waitcnt vmcnt(17)
	v_fma_f32 v36, -v72, v119, v36
	v_fma_f32 v37, -v73, v119, v37
	v_fma_f32 v38, -v74, v119, v38
	v_fma_f32 v39, -v75, v119, v39
	v_cvt_pk_bf16_f32 v208, v12, v13
	v_cvt_pk_bf16_f32 v209, v22, v23
	global_store_dwordx2 v222, v[208:209], s[74:75]
	s_add_u32 s70, s2, 0xb000
	s_addc_u32 s71, s3, 0
	global_load_dwordx4 v[68:71], v0, s[70:71]
	s_add_u32 s14, s2, 0x4000
	s_addc_u32 s15, s3, 0
	global_load_dwordx4 v[72:75], v0, s[14:15]
	s_mov_b32 s32, 0x3e4ccccd
	s_cmp_eq_u32 s58, 0
	s_cselect_b32 s32, s32, s59
	s_add_u32 s54, s12, 0x2200
	s_addc_u32 s55, s13, 0
	s_waitcnt vmcnt(19)
	v_mul_f32_e32 v212, v76, v127
	v_mul_f32_e32 v213, v77, v127
	v_mul_f32_e32 v214, v78, v127
	v_mul_f32_e32 v215, v79, v127
	v_fmac_f32_e32 v36, v76, v127
	v_fmac_f32_e32 v37, v77, v127
	v_fmac_f32_e32 v38, v78, v127
	v_fmac_f32_e32 v39, v79, v127
	v_fma_f32 v12, v36, s32, -v212
	v_fma_f32 v13, v37, s32, -v213
	v_fma_f32 v22, v38, s32, -v214
	v_fma_f32 v23, v39, s32, -v215
	s_waitcnt vmcnt(18)
	v_fma_f32 v36, -v80, v120, v36
	v_fma_f32 v37, -v81, v120, v37
	v_fma_f32 v38, -v82, v120, v38
	v_fma_f32 v39, -v83, v120, v39
	v_cvt_pk_bf16_f32 v2, v12, v13
	v_cvt_pk_bf16_f32 v3, v22, v23
	global_store_dwordx2 v222, v[2:3], s[54:55]
	s_add_u32 s56, s2, 0xc000
	s_addc_u32 s57, s3, 0
	global_load_dwordx4 v[76:79], v0, s[56:57]
	s_add_u32 s70, s2, 0x5000
	s_addc_u32 s71, s3, 0
	global_load_dwordx4 v[80:83], v0, s[70:71]
	s_mov_b32 s32, 0x3e2aaaab
	s_cmp_eq_u32 s58, 0
	s_cselect_b32 s32, s32, s59
	s_add_u32 s74, s12, 0x2a80
	s_addc_u32 s75, s13, 0
	s_waitcnt vmcnt(20)
	v_mul_f32_e32 v212, v84, v128
	v_mul_f32_e32 v213, v85, v128
	v_mul_f32_e32 v214, v86, v128
	v_mul_f32_e32 v215, v87, v128
	v_fmac_f32_e32 v36, v84, v128
	v_fmac_f32_e32 v37, v85, v128
	v_fmac_f32_e32 v38, v86, v128
	v_fmac_f32_e32 v39, v87, v128
	v_fma_f32 v12, v36, s32, -v212
	v_fma_f32 v13, v37, s32, -v213
	v_fma_f32 v22, v38, s32, -v214
	v_fma_f32 v23, v39, s32, -v215
	s_waitcnt vmcnt(19)
	v_fma_f32 v36, -v88, v121, v36
	v_fma_f32 v37, -v89, v121, v37
	v_fma_f32 v38, -v90, v121, v38
	v_fma_f32 v39, -v91, v121, v39
	v_cvt_pk_bf16_f32 v208, v12, v13
	v_cvt_pk_bf16_f32 v209, v22, v23
	global_store_dwordx2 v222, v[208:209], s[74:75]
	s_add_u32 s14, s2, 0xd000
	s_addc_u32 s15, s3, 0
	global_load_dwordx4 v[84:87], v0, s[14:15]
	s_add_u32 s56, s2, 0x6000
	s_addc_u32 s57, s3, 0
	global_load_dwordx4 v[88:91], v0, s[56:57]
	s_mov_b32 s32, 0x3e124925
	s_cmp_eq_u32 s58, 0
	s_cselect_b32 s32, s32, s59
	s_add_u32 s54, s12, 0x3300
	s_addc_u32 s55, s13, 0
	s_waitcnt vmcnt(21)
	v_mul_f32_e32 v212, v92, v129
	v_mul_f32_e32 v213, v93, v129
	v_mul_f32_e32 v214, v94, v129
	v_mul_f32_e32 v215, v95, v129
	v_fmac_f32_e32 v36, v92, v129
	v_fmac_f32_e32 v37, v93, v129
	v_fmac_f32_e32 v38, v94, v129
	v_fmac_f32_e32 v39, v95, v129
	v_fma_f32 v12, v36, s32, -v212
	v_fma_f32 v13, v37, s32, -v213
	v_fma_f32 v22, v38, s32, -v214
	v_fma_f32 v23, v39, s32, -v215
	s_waitcnt vmcnt(20)
	v_fma_f32 v36, -v96, v122, v36
	v_fma_f32 v37, -v97, v122, v37
	v_fma_f32 v38, -v98, v122, v38
	v_fma_f32 v39, -v99, v122, v39
	v_cvt_pk_bf16_f32 v2, v12, v13
	v_cvt_pk_bf16_f32 v3, v22, v23
	global_store_dwordx2 v222, v[2:3], s[54:55]
	s_add_u32 s70, s2, 0xe000
	s_addc_u32 s71, s3, 0
	global_load_dwordx4 v[92:95], v0, s[70:71]
	s_add_u32 s14, s2, 0x7000
	s_addc_u32 s15, s3, 0
	global_load_dwordx4 v[96:99], v0, s[14:15]
	s_add_u32 s74, s12, 0x3b80
	s_addc_u32 s75, s13, 0
	s_waitcnt vmcnt(22)
	v_mul_f32_e32 v212, v100, v130
	v_mul_f32_e32 v213, v101, v130
	v_mul_f32_e32 v214, v102, v130
	v_mul_f32_e32 v215, v103, v130
	v_fmac_f32_e32 v36, v100, v130
	v_fmac_f32_e32 v37, v101, v130
	v_fmac_f32_e32 v38, v102, v130
	v_fmac_f32_e32 v39, v103, v130
	v_fma_f32 v12, v36, s59, -v212
	v_fma_f32 v13, v37, s59, -v213
	v_fma_f32 v22, v38, s59, -v214
	v_fma_f32 v23, v39, s59, -v215
	s_waitcnt vmcnt(21)
; DI unsigned pack_bf16(float lo, float hi) { f32x2 v = {lo, hi}; bf16v2 b = __builtin_convertvector(v, bf16v2); return __builtin_bit_cast(unsigned, b); }
; template <int W>
; DI void pool_rows(const float* __restrict__ x, const float* smr, bf16_t* __restrict__ pb, int t0, int s0, int tid) {
;     ...
;   for (int tl = 0; tl < 64; ++tl) {
;     const int t = t0 + tl, s = s0 + tl;
;     int to = t - W + 1; if (to < tq0) to = tq0;
;     const f32x4 hn = *(const f32x4*)(xq + (size_t)t * D) * smr[15 + tl];
;     const f32x4 ho = *(const f32x4*)(xq + (size_t)to * D) * smr[15 + tl - W + 1];
;     const int cnt = (s + 1 < W) ? (s + 1) : W;
;     const float ic = 1.f / (float)cnt;
;     Sm += hn;
;     const f32x4 p = Sm * ic - hn;
;     Sm -= ho;
;     u32x2 o; o.x = pack_bf16(p.x, p.y); o.y = pack_bf16(p.z, p.w);
;     *(u32x2*)(pb + (size_t)t * LDH + tid * 4) = o;
;   }
	v_fma_f32 v36, -v104, v123, v36
	v_fma_f32 v37, -v105, v123, v37
	v_fma_f32 v38, -v106, v123, v38
	v_fma_f32 v39, -v107, v123, v39
	v_cvt_pk_bf16_f32 v208, v12, v13
	v_cvt_pk_bf16_f32 v209, v22, v23
	global_store_dwordx2 v222, v[208:209], s[74:75]
	s_add_u32 s56, s2, 0xf000
	s_addc_u32 s57, s3, 0
	global_load_dwordx4 v[100:103], v0, s[56:57]
	s_add_u32 s70, s2, 0x8000
	s_addc_u32 s71, s3, 0
	global_load_dwordx4 v[104:107], v0, s[70:71]
	s_add_u32 s54, s12, 0x4400
	s_addc_u32 s55, s13, 0
	s_waitcnt vmcnt(22)
	v_mul_f32_e32 v212, v44, v131
	v_mul_f32_e32 v213, v45, v131
	v_mul_f32_e32 v214, v46, v131
	v_mul_f32_e32 v215, v47, v131
	v_fmac_f32_e32 v36, v44, v131
	v_fmac_f32_e32 v37, v45, v131
	v_fmac_f32_e32 v38, v46, v131
	v_fmac_f32_e32 v39, v47, v131
	v_fma_f32 v12, v36, s59, -v212
	v_fma_f32 v13, v37, s59, -v213
	v_fma_f32 v22, v38, s59, -v214
	v_fma_f32 v23, v39, s59, -v215
	s_waitcnt vmcnt(21)
	v_fma_f32 v36, -v48, v124, v36
	v_fma_f32 v37, -v49, v124, v37
	v_fma_f32 v38, -v50, v124, v38
	v_fma_f32 v39, -v51, v124, v39
	v_cvt_pk_bf16_f32 v2, v12, v13
	v_cvt_pk_bf16_f32 v3, v22, v23
	global_store_dwordx2 v222, v[2:3], s[54:55]
	s_add_u32 s14, s2, 0x10000
	s_addc_u32 s15, s3, 0
	global_load_dwordx4 v[44:47], v0, s[14:15]
	s_add_u32 s56, s2, 0x9000
	s_addc_u32 s57, s3, 0
	global_load_dwordx4 v[48:51], v0, s[56:57]
	s_add_u32 s74, s12, 0x4c80
	s_addc_u32 s75, s13, 0
	s_waitcnt vmcnt(22)
	v_mul_f32_e32 v212, v52, v132
	v_mul_f32_e32 v213, v53, v132
	v_mul_f32_e32 v214, v54, v132
	v_mul_f32_e32 v215, v55, v132
	v_fmac_f32_e32 v36, v52, v132
	v_fmac_f32_e32 v37, v53, v132
	v_fmac_f32_e32 v38, v54, v132
	v_fmac_f32_e32 v39, v55, v132
	v_fma_f32 v12, v36, s59, -v212
	v_fma_f32 v13, v37, s59, -v213
	v_fma_f32 v22, v38, s59, -v214
	v_fma_f32 v23, v39, s59, -v215
	s_waitcnt vmcnt(21)
	v_fma_f32 v36, -v56, v125, v36
	v_fma_f32 v37, -v57, v125, v37
	v_fma_f32 v38, -v58, v125, v38
	v_fma_f32 v39, -v59, v125, v39
	v_cvt_pk_bf16_f32 v208, v12, v13
	v_cvt_pk_bf16_f32 v209, v22, v23
	global_store_dwordx2 v222, v[208:209], s[74:75]
	s_add_u32 s70, s2, 0x11000
	s_addc_u32 s71, s3, 0
	global_load_dwordx4 v[52:55], v0, s[70:71]
	s_add_u32 s14, s2, 0xa000
	s_addc_u32 s15, s3, 0
	global_load_dwordx4 v[56:59], v0, s[14:15]
	s_add_u32 s54, s12, 0x5500
	s_addc_u32 s55, s13, 0
	s_waitcnt vmcnt(22)
	v_mul_f32_e32 v212, v60, v133
	v_mul_f32_e32 v213, v61, v133
	v_mul_f32_e32 v214, v62, v133
	v_mul_f32_e32 v215, v63, v133
	v_fmac_f32_e32 v36, v60, v133
	v_fmac_f32_e32 v37, v61, v133
	v_fmac_f32_e32 v38, v62, v133
	v_fmac_f32_e32 v39, v63, v133
	v_fma_f32 v12, v36, s59, -v212
	v_fma_f32 v13, v37, s59, -v213
	v_fma_f32 v22, v38, s59, -v214
	v_fma_f32 v23, v39, s59, -v215
	s_waitcnt vmcnt(21)
	v_fma_f32 v36, -v64, v126, v36
	v_fma_f32 v37, -v65, v126, v37
	v_fma_f32 v38, -v66, v126, v38
	v_fma_f32 v39, -v67, v126, v39
	v_cvt_pk_bf16_f32 v2, v12, v13
	v_cvt_pk_bf16_f32 v3, v22, v23
	global_store_dwordx2 v222, v[2:3], s[54:55]
	s_add_u32 s56, s2, 0x12000
	s_addc_u32 s57, s3, 0
	global_load_dwordx4 v[60:63], v0, s[56:57]
	s_add_u32 s70, s2, 0xb000
	s_addc_u32 s71, s3, 0
	global_load_dwordx4 v[64:67], v0, s[70:71]
	s_add_u32 s74, s12, 0x5d80
	s_addc_u32 s75, s13, 0
	s_waitcnt vmcnt(22)
	v_mul_f32_e32 v212, v68, v134
	v_mul_f32_e32 v213, v69, v134
	v_mul_f32_e32 v214, v70, v134
	v_mul_f32_e32 v215, v71, v134
	v_fmac_f32_e32 v36, v68, v134
	v_fmac_f32_e32 v37, v69, v134
	v_fmac_f32_e32 v38, v70, v134
	v_fmac_f32_e32 v39, v71, v134
	v_fma_f32 v12, v36, s59, -v212
	v_fma_f32 v13, v37, s59, -v213
	v_fma_f32 v22, v38, s59, -v214
	v_fma_f32 v23, v39, s59, -v215
	s_waitcnt vmcnt(21)
	v_fma_f32 v36, -v72, v127, v36
	v_fma_f32 v37, -v73, v127, v37
	v_fma_f32 v38, -v74, v127, v38
	v_fma_f32 v39, -v75, v127, v39
	v_cvt_pk_bf16_f32 v208, v12, v13
	v_cvt_pk_bf16_f32 v209, v22, v23
	global_store_dwordx2 v222, v[208:209], s[74:75]
	s_add_u32 s14, s2, 0x13000
	s_addc_u32 s15, s3, 0
	global_load_dwordx4 v[68:71], v0, s[14:15]
	s_add_u32 s56, s2, 0xc000
	s_addc_u32 s57, s3, 0
	global_load_dwordx4 v[72:75], v0, s[56:57]
	s_add_u32 s54, s12, 0x6600
	s_addc_u32 s55, s13, 0
	s_waitcnt vmcnt(22)
	v_mul_f32_e32 v212, v76, v135
	v_mul_f32_e32 v213, v77, v135
	v_mul_f32_e32 v214, v78, v135
	v_mul_f32_e32 v215, v79, v135
	v_fmac_f32_e32 v36, v76, v135
	v_fmac_f32_e32 v37, v77, v135
	v_fmac_f32_e32 v38, v78, v135
	v_fmac_f32_e32 v39, v79, v135
	v_fma_f32 v12, v36, s59, -v212
	v_fma_f32 v13, v37, s59, -v213
	v_fma_f32 v22, v38, s59, -v214
	v_fma_f32 v23, v39, s59, -v215
	s_waitcnt vmcnt(21)
	v_fma_f32 v36, -v80, v128, v36
	v_fma_f32 v37, -v81, v128, v37
	v_fma_f32 v38, -v82, v128, v38
	v_fma_f32 v39, -v83, v128, v39
	v_cvt_pk_bf16_f32 v2, v12, v13
	v_cvt_pk_bf16_f32 v3, v22, v23
	global_store_dwordx2 v222, v[2:3], s[54:55]
	s_add_u32 s70, s2, 0x14000
	s_addc_u32 s71, s3, 0
	global_load_dwordx4 v[76:79], v0, s[70:71]
	s_add_u32 s14, s2, 0xd000
	s_addc_u32 s15, s3, 0
	global_load_dwordx4 v[80:83], v0, s[14:15]
	s_add_u32 s74, s12, 0x6e80
	s_addc_u32 s75, s13, 0
	s_waitcnt vmcnt(22)
	v_mul_f32_e32 v212, v84, v136
	v_mul_f32_e32 v213, v85, v136
	v_mul_f32_e32 v214, v86, v136
	v_mul_f32_e32 v215, v87, v136
	v_fmac_f32_e32 v36, v84, v136
	v_fmac_f32_e32 v37, v85, v136
	v_fmac_f32_e32 v38, v86, v136
	v_fmac_f32_e32 v39, v87, v136
	v_fma_f32 v12, v36, s59, -v212
	v_fma_f32 v13, v37, s59, -v213
	v_fma_f32 v22, v38, s59, -v214
	v_fma_f32 v23, v39, s59, -v215
	s_waitcnt vmcnt(21)
; DI unsigned pack_bf16(float lo, float hi) { f32x2 v = {lo, hi}; bf16v2 b = __builtin_convertvector(v, bf16v2); return __builtin_bit_cast(unsigned, b); }
; template <int W>
; DI void pool_rows(const float* __restrict__ x, const float* smr, bf16_t* __restrict__ pb, int t0, int s0, int tid) {
;     ...
;   for (int tl = 0; tl < 64; ++tl) {
;     const int t = t0 + tl, s = s0 + tl;
;     int to = t - W + 1; if (to < tq0) to = tq0;
;     const f32x4 hn = *(const f32x4*)(xq + (size_t)t * D) * smr[15 + tl];
;     const f32x4 ho = *(const f32x4*)(xq + (size_t)to * D) * smr[15 + tl - W + 1];
;     const int cnt = (s + 1 < W) ? (s + 1) : W;
;     const float ic = 1.f / (float)cnt;
;     Sm += hn;
;     const f32x4 p = Sm * ic - hn;
;     Sm -= ho;
;     u32x2 o; o.x = pack_bf16(p.x, p.y); o.y = pack_bf16(p.z, p.w);
;     *(u32x2*)(pb + (size_t)t * LDH + tid * 4) = o;
;   }
	v_fma_f32 v36, -v88, v129, v36
	v_fma_f32 v37, -v89, v129, v37
	v_fma_f32 v38, -v90, v129, v38
	v_fma_f32 v39, -v91, v129, v39
	v_cvt_pk_bf16_f32 v208, v12, v13
	v_cvt_pk_bf16_f32 v209, v22, v23
	global_store_dwordx2 v222, v[208:209], s[74:75]
	s_add_u32 s56, s2, 0x15000
	s_addc_u32 s57, s3, 0
	global_load_dwordx4 v[84:87], v0, s[56:57]
	s_add_u32 s70, s2, 0xe000
	s_addc_u32 s71, s3, 0
	global_load_dwordx4 v[88:91], v0, s[70:71]
	s_add_u32 s54, s12, 0x7700
	s_addc_u32 s55, s13, 0
	s_waitcnt vmcnt(22)
	v_mul_f32_e32 v212, v92, v137
	v_mul_f32_e32 v213, v93, v137
	v_mul_f32_e32 v214, v94, v137
	v_mul_f32_e32 v215, v95, v137
	v_fmac_f32_e32 v36, v92, v137
	v_fmac_f32_e32 v37, v93, v137
	v_fmac_f32_e32 v38, v94, v137
	v_fmac_f32_e32 v39, v95, v137
	v_fma_f32 v12, v36, s59, -v212
	v_fma_f32 v13, v37, s59, -v213
	v_fma_f32 v22, v38, s59, -v214
	v_fma_f32 v23, v39, s59, -v215
	s_waitcnt vmcnt(21)
	v_fma_f32 v36, -v96, v130, v36
	v_fma_f32 v37, -v97, v130, v37
	v_fma_f32 v38, -v98, v130, v38
	v_fma_f32 v39, -v99, v130, v39
	v_cvt_pk_bf16_f32 v2, v12, v13
	v_cvt_pk_bf16_f32 v3, v22, v23
	global_store_dwordx2 v222, v[2:3], s[54:55]
	s_add_u32 s14, s2, 0x16000
	s_addc_u32 s15, s3, 0
	global_load_dwordx4 v[92:95], v0, s[14:15]
	s_add_u32 s56, s2, 0xf000
	s_addc_u32 s57, s3, 0
	global_load_dwordx4 v[96:99], v0, s[56:57]
	s_add_u32 s74, s12, 0x7f80
	s_addc_u32 s75, s13, 0
	s_waitcnt vmcnt(22)
	v_mul_f32_e32 v212, v100, v138
	v_mul_f32_e32 v213, v101, v138
	v_mul_f32_e32 v214, v102, v138
	v_mul_f32_e32 v215, v103, v138
	v_fmac_f32_e32 v36, v100, v138
	v_fmac_f32_e32 v37, v101, v138
	v_fmac_f32_e32 v38, v102, v138
	v_fmac_f32_e32 v39, v103, v138
	v_fma_f32 v12, v36, s59, -v212
	v_fma_f32 v13, v37, s59, -v213
	v_fma_f32 v22, v38, s59, -v214
	v_fma_f32 v23, v39, s59, -v215
	s_waitcnt vmcnt(21)
	v_fma_f32 v36, -v104, v131, v36
	v_fma_f32 v37, -v105, v131, v37
	v_fma_f32 v38, -v106, v131, v38
	v_fma_f32 v39, -v107, v131, v39
	v_cvt_pk_bf16_f32 v208, v12, v13
	v_cvt_pk_bf16_f32 v209, v22, v23
	global_store_dwordx2 v222, v[208:209], s[74:75]
	s_add_u32 s70, s2, 0x17000
	s_addc_u32 s71, s3, 0
	global_load_dwordx4 v[100:103], v0, s[70:71]
	s_add_u32 s14, s2, 0x10000
	s_addc_u32 s15, s3, 0
	global_load_dwordx4 v[104:107], v0, s[14:15]
	s_add_u32 s54, s12, 0x8800
	s_addc_u32 s55, s13, 0
	s_waitcnt vmcnt(22)
	v_mul_f32_e32 v212, v44, v139
	v_mul_f32_e32 v213, v45, v139
	v_mul_f32_e32 v214, v46, v139
	v_mul_f32_e32 v215, v47, v139
	v_fmac_f32_e32 v36, v44, v139
	v_fmac_f32_e32 v37, v45, v139
	v_fmac_f32_e32 v38, v46, v139
	v_fmac_f32_e32 v39, v47, v139
	v_fma_f32 v12, v36, s59, -v212
	v_fma_f32 v13, v37, s59, -v213
	v_fma_f32 v22, v38, s59, -v214
	v_fma_f32 v23, v39, s59, -v215
	s_waitcnt vmcnt(21)
	v_fma_f32 v36, -v48, v132, v36
	v_fma_f32 v37, -v49, v132, v37
	v_fma_f32 v38, -v50, v132, v38
	v_fma_f32 v39, -v51, v132, v39
	v_cvt_pk_bf16_f32 v2, v12, v13
	v_cvt_pk_bf16_f32 v3, v22, v23
	global_store_dwordx2 v222, v[2:3], s[54:55]
	s_add_u32 s56, s2, 0x18000
	s_addc_u32 s57, s3, 0
	global_load_dwordx4 v[44:47], v0, s[56:57]
	s_add_u32 s70, s2, 0x11000
	s_addc_u32 s71, s3, 0
	global_load_dwordx4 v[48:51], v0, s[70:71]
	s_add_u32 s74, s12, 0x9080
	s_addc_u32 s75, s13, 0
	s_waitcnt vmcnt(22)
	v_mul_f32_e32 v212, v52, v140
	v_mul_f32_e32 v213, v53, v140
	v_mul_f32_e32 v214, v54, v140
	v_mul_f32_e32 v215, v55, v140
	v_fmac_f32_e32 v36, v52, v140
	v_fmac_f32_e32 v37, v53, v140
	v_fmac_f32_e32 v38, v54, v140
	v_fmac_f32_e32 v39, v55, v140
	v_fma_f32 v12, v36, s59, -v212
	v_fma_f32 v13, v37, s59, -v213
	v_fma_f32 v22, v38, s59, -v214
	v_fma_f32 v23, v39, s59, -v215
	s_waitcnt vmcnt(21)
	v_fma_f32 v36, -v56, v133, v36
	v_fma_f32 v37, -v57, v133, v37
	v_fma_f32 v38, -v58, v133, v38
	v_fma_f32 v39, -v59, v133, v39
	v_cvt_pk_bf16_f32 v208, v12, v13
	v_cvt_pk_bf16_f32 v209, v22, v23
	global_store_dwordx2 v222, v[208:209], s[74:75]
	s_add_u32 s14, s2, 0x19000
	s_addc_u32 s15, s3, 0
	global_load_dwordx4 v[52:55], v0, s[14:15]
	s_add_u32 s56, s2, 0x12000
	s_addc_u32 s57, s3, 0
	global_load_dwordx4 v[56:59], v0, s[56:57]
	s_add_u32 s54, s12, 0x9900
	s_addc_u32 s55, s13, 0
	s_waitcnt vmcnt(22)
	v_mul_f32_e32 v212, v60, v141
	v_mul_f32_e32 v213, v61, v141
	v_mul_f32_e32 v214, v62, v141
	v_mul_f32_e32 v215, v63, v141
	v_fmac_f32_e32 v36, v60, v141
	v_fmac_f32_e32 v37, v61, v141
	v_fmac_f32_e32 v38, v62, v141
	v_fmac_f32_e32 v39, v63, v141
	v_fma_f32 v12, v36, s59, -v212
	v_fma_f32 v13, v37, s59, -v213
	v_fma_f32 v22, v38, s59, -v214
	v_fma_f32 v23, v39, s59, -v215
	s_waitcnt vmcnt(21)
	v_fma_f32 v36, -v64, v134, v36
	v_fma_f32 v37, -v65, v134, v37
	v_fma_f32 v38, -v66, v134, v38
	v_fma_f32 v39, -v67, v134, v39
	v_cvt_pk_bf16_f32 v2, v12, v13
	v_cvt_pk_bf16_f32 v3, v22, v23
	global_store_dwordx2 v222, v[2:3], s[54:55]
	s_add_u32 s70, s2, 0x1a000
	s_addc_u32 s71, s3, 0
	global_load_dwordx4 v[60:63], v0, s[70:71]
	s_add_u32 s14, s2, 0x13000
	s_addc_u32 s15, s3, 0
	global_load_dwordx4 v[64:67], v0, s[14:15]
	s_add_u32 s74, s12, 0xa180
	s_addc_u32 s75, s13, 0
	s_waitcnt vmcnt(22)
	v_mul_f32_e32 v212, v68, v142
	v_mul_f32_e32 v213, v69, v142
	v_mul_f32_e32 v214, v70, v142
	v_mul_f32_e32 v215, v71, v142
	v_fmac_f32_e32 v36, v68, v142
	v_fmac_f32_e32 v37, v69, v142
	v_fmac_f32_e32 v38, v70, v142
	v_fmac_f32_e32 v39, v71, v142
	v_fma_f32 v12, v36, s59, -v212
	v_fma_f32 v13, v37, s59, -v213
	v_fma_f32 v22, v38, s59, -v214
	v_fma_f32 v23, v39, s59, -v215
	s_waitcnt vmcnt(21)
; DI unsigned pack_bf16(float lo, float hi) { f32x2 v = {lo, hi}; bf16v2 b = __builtin_convertvector(v, bf16v2); return __builtin_bit_cast(unsigned, b); }
; template <int W>
; DI void pool_rows(const float* __restrict__ x, const float* smr, bf16_t* __restrict__ pb, int t0, int s0, int tid) {
;     ...
;   for (int tl = 0; tl < 64; ++tl) {
;     const int t = t0 + tl, s = s0 + tl;
;     int to = t - W + 1; if (to < tq0) to = tq0;
;     const f32x4 hn = *(const f32x4*)(xq + (size_t)t * D) * smr[15 + tl];
;     const f32x4 ho = *(const f32x4*)(xq + (size_t)to * D) * smr[15 + tl - W + 1];
;     const int cnt = (s + 1 < W) ? (s + 1) : W;
;     const float ic = 1.f / (float)cnt;
;     Sm += hn;
;     const f32x4 p = Sm * ic - hn;
;     Sm -= ho;
;     u32x2 o; o.x = pack_bf16(p.x, p.y); o.y = pack_bf16(p.z, p.w);
;     *(u32x2*)(pb + (size_t)t * LDH + tid * 4) = o;
;   }
	v_fma_f32 v36, -v72, v135, v36
	v_fma_f32 v37, -v73, v135, v37
	v_fma_f32 v38, -v74, v135, v38
	v_fma_f32 v39, -v75, v135, v39
	v_cvt_pk_bf16_f32 v208, v12, v13
	v_cvt_pk_bf16_f32 v209, v22, v23
	global_store_dwordx2 v222, v[208:209], s[74:75]
	s_add_u32 s56, s2, 0x1b000
	s_addc_u32 s57, s3, 0
	global_load_dwordx4 v[68:71], v0, s[56:57]
	s_add_u32 s70, s2, 0x14000
	s_addc_u32 s71, s3, 0
	global_load_dwordx4 v[72:75], v0, s[70:71]
	s_add_u32 s54, s12, 0xaa00
	s_addc_u32 s55, s13, 0
	s_waitcnt vmcnt(22)
	v_mul_f32_e32 v212, v76, v143
	v_mul_f32_e32 v213, v77, v143
	v_mul_f32_e32 v214, v78, v143
	v_mul_f32_e32 v215, v79, v143
	v_fmac_f32_e32 v36, v76, v143
	v_fmac_f32_e32 v37, v77, v143
	v_fmac_f32_e32 v38, v78, v143
	v_fmac_f32_e32 v39, v79, v143
	v_fma_f32 v12, v36, s59, -v212
	v_fma_f32 v13, v37, s59, -v213
	v_fma_f32 v22, v38, s59, -v214
	v_fma_f32 v23, v39, s59, -v215
	s_waitcnt vmcnt(21)
	v_fma_f32 v36, -v80, v136, v36
	v_fma_f32 v37, -v81, v136, v37
	v_fma_f32 v38, -v82, v136, v38
	v_fma_f32 v39, -v83, v136, v39
	v_cvt_pk_bf16_f32 v2, v12, v13
	v_cvt_pk_bf16_f32 v3, v22, v23
	global_store_dwordx2 v222, v[2:3], s[54:55]
	s_add_u32 s14, s2, 0x1c000
	s_addc_u32 s15, s3, 0
	global_load_dwordx4 v[76:79], v0, s[14:15]
	s_add_u32 s56, s2, 0x15000
	s_addc_u32 s57, s3, 0
	global_load_dwordx4 v[80:83], v0, s[56:57]
	s_add_u32 s74, s12, 0xb280
	s_addc_u32 s75, s13, 0
	s_waitcnt vmcnt(22)
	v_mul_f32_e32 v212, v84, v144
	v_mul_f32_e32 v213, v85, v144
	v_mul_f32_e32 v214, v86, v144
	v_mul_f32_e32 v215, v87, v144
	v_fmac_f32_e32 v36, v84, v144
	v_fmac_f32_e32 v37, v85, v144
	v_fmac_f32_e32 v38, v86, v144
	v_fmac_f32_e32 v39, v87, v144
	v_fma_f32 v12, v36, s59, -v212
	v_fma_f32 v13, v37, s59, -v213
	v_fma_f32 v22, v38, s59, -v214
	v_fma_f32 v23, v39, s59, -v215
	s_waitcnt vmcnt(21)
	v_fma_f32 v36, -v88, v137, v36
	v_fma_f32 v37, -v89, v137, v37
	v_fma_f32 v38, -v90, v137, v38
	v_fma_f32 v39, -v91, v137, v39
	v_cvt_pk_bf16_f32 v208, v12, v13
	v_cvt_pk_bf16_f32 v209, v22, v23
	global_store_dwordx2 v222, v[208:209], s[74:75]
	s_add_u32 s70, s2, 0x1d000
	s_addc_u32 s71, s3, 0
	global_load_dwordx4 v[84:87], v0, s[70:71]
	s_add_u32 s14, s2, 0x16000
	s_addc_u32 s15, s3, 0
	global_load_dwordx4 v[88:91], v0, s[14:15]
	s_add_u32 s54, s12, 0xbb00
	s_addc_u32 s55, s13, 0
	s_waitcnt vmcnt(22)
	v_mul_f32_e32 v212, v92, v145
	v_mul_f32_e32 v213, v93, v145
	v_mul_f32_e32 v214, v94, v145
	v_mul_f32_e32 v215, v95, v145
	v_fmac_f32_e32 v36, v92, v145
	v_fmac_f32_e32 v37, v93, v145
	v_fmac_f32_e32 v38, v94, v145
	v_fmac_f32_e32 v39, v95, v145
	v_fma_f32 v12, v36, s59, -v212
	v_fma_f32 v13, v37, s59, -v213
	v_fma_f32 v22, v38, s59, -v214
	v_fma_f32 v23, v39, s59, -v215
	s_waitcnt vmcnt(21)
	v_fma_f32 v36, -v96, v138, v36
	v_fma_f32 v37, -v97, v138, v37
	v_fma_f32 v38, -v98, v138, v38
	v_fma_f32 v39, -v99, v138, v39
	v_cvt_pk_bf16_f32 v2, v12, v13
	v_cvt_pk_bf16_f32 v3, v22, v23
	global_store_dwordx2 v222, v[2:3], s[54:55]
	s_add_u32 s56, s2, 0x1e000
	s_addc_u32 s57, s3, 0
	global_load_dwordx4 v[92:95], v0, s[56:57]
	s_add_u32 s70, s2, 0x17000
	s_addc_u32 s71, s3, 0
	global_load_dwordx4 v[96:99], v0, s[70:71]
	s_add_u32 s74, s12, 0xc380
	s_addc_u32 s75, s13, 0
	s_waitcnt vmcnt(22)
	v_mul_f32_e32 v212, v100, v146
	v_mul_f32_e32 v213, v101, v146
	v_mul_f32_e32 v214, v102, v146
	v_mul_f32_e32 v215, v103, v146
	v_fmac_f32_e32 v36, v100, v146
	v_fmac_f32_e32 v37, v101, v146
	v_fmac_f32_e32 v38, v102, v146
	v_fmac_f32_e32 v39, v103, v146
	v_fma_f32 v12, v36, s59, -v212
	v_fma_f32 v13, v37, s59, -v213
	v_fma_f32 v22, v38, s59, -v214
	v_fma_f32 v23, v39, s59, -v215
	s_waitcnt vmcnt(21)
	v_fma_f32 v36, -v104, v139, v36
	v_fma_f32 v37, -v105, v139, v37
	v_fma_f32 v38, -v106, v139, v38
	v_fma_f32 v39, -v107, v139, v39
	v_cvt_pk_bf16_f32 v208, v12, v13
	v_cvt_pk_bf16_f32 v209, v22, v23
	global_store_dwordx2 v222, v[208:209], s[74:75]
	s_add_u32 s14, s2, 0x1f000
	s_addc_u32 s15, s3, 0
	global_load_dwordx4 v[100:103], v0, s[14:15]
	s_add_u32 s56, s2, 0x18000
	s_addc_u32 s57, s3, 0
	global_load_dwordx4 v[104:107], v0, s[56:57]
	s_add_u32 s54, s12, 0xcc00
	s_addc_u32 s55, s13, 0
	s_waitcnt vmcnt(22)
	v_mul_f32_e32 v212, v44, v147
	v_mul_f32_e32 v213, v45, v147
	v_mul_f32_e32 v214, v46, v147
	v_mul_f32_e32 v215, v47, v147
	v_fmac_f32_e32 v36, v44, v147
	v_fmac_f32_e32 v37, v45, v147
	v_fmac_f32_e32 v38, v46, v147
	v_fmac_f32_e32 v39, v47, v147
	v_fma_f32 v12, v36, s59, -v212
	v_fma_f32 v13, v37, s59, -v213
	v_fma_f32 v22, v38, s59, -v214
	v_fma_f32 v23, v39, s59, -v215
	s_waitcnt vmcnt(21)
	v_fma_f32 v36, -v48, v140, v36
	v_fma_f32 v37, -v49, v140, v37
	v_fma_f32 v38, -v50, v140, v38
	v_fma_f32 v39, -v51, v140, v39
	v_cvt_pk_bf16_f32 v2, v12, v13
	v_cvt_pk_bf16_f32 v3, v22, v23
	global_store_dwordx2 v222, v[2:3], s[54:55]
	s_add_u32 s70, s2, 0x20000
	s_addc_u32 s71, s3, 0
	global_load_dwordx4 v[44:47], v0, s[70:71]
	s_add_u32 s14, s2, 0x19000
	s_addc_u32 s15, s3, 0
	global_load_dwordx4 v[48:51], v0, s[14:15]
	s_add_u32 s74, s12, 0xd480
	s_addc_u32 s75, s13, 0
	s_waitcnt vmcnt(22)
	v_mul_f32_e32 v212, v52, v148
	v_mul_f32_e32 v213, v53, v148
	v_mul_f32_e32 v214, v54, v148
	v_mul_f32_e32 v215, v55, v148
	v_fmac_f32_e32 v36, v52, v148
	v_fmac_f32_e32 v37, v53, v148
	v_fmac_f32_e32 v38, v54, v148
	v_fmac_f32_e32 v39, v55, v148
	v_fma_f32 v12, v36, s59, -v212
	v_fma_f32 v13, v37, s59, -v213
	v_fma_f32 v22, v38, s59, -v214
	v_fma_f32 v23, v39, s59, -v215
	s_waitcnt vmcnt(21)
; DI unsigned pack_bf16(float lo, float hi) { f32x2 v = {lo, hi}; bf16v2 b = __builtin_convertvector(v, bf16v2); return __builtin_bit_cast(unsigned, b); }
; template <int W>
; DI void pool_rows(const float* __restrict__ x, const float* smr, bf16_t* __restrict__ pb, int t0, int s0, int tid) {
;     ...
;   for (int tl = 0; tl < 64; ++tl) {
;     const int t = t0 + tl, s = s0 + tl;
;     int to = t - W + 1; if (to < tq0) to = tq0;
;     const f32x4 hn = *(const f32x4*)(xq + (size_t)t * D) * smr[15 + tl];
;     const f32x4 ho = *(const f32x4*)(xq + (size_t)to * D) * smr[15 + tl - W + 1];
;     const int cnt = (s + 1 < W) ? (s + 1) : W;
;     const float ic = 1.f / (float)cnt;
;     Sm += hn;
;     const f32x4 p = Sm * ic - hn;
;     Sm -= ho;
;     u32x2 o; o.x = pack_bf16(p.x, p.y); o.y = pack_bf16(p.z, p.w);
;     *(u32x2*)(pb + (size_t)t * LDH + tid * 4) = o;
;   }
	v_fma_f32 v36, -v56, v141, v36
	v_fma_f32 v37, -v57, v141, v37
	v_fma_f32 v38, -v58, v141, v38
	v_fma_f32 v39, -v59, v141, v39
	v_cvt_pk_bf16_f32 v208, v12, v13
	v_cvt_pk_bf16_f32 v209, v22, v23
	global_store_dwordx2 v222, v[208:209], s[74:75]
	s_add_u32 s56, s2, 0x21000
	s_addc_u32 s57, s3, 0
	global_load_dwordx4 v[52:55], v0, s[56:57]
	s_add_u32 s70, s2, 0x1a000
	s_addc_u32 s71, s3, 0
	global_load_dwordx4 v[56:59], v0, s[70:71]
	s_add_u32 s54, s12, 0xdd00
	s_addc_u32 s55, s13, 0
	s_waitcnt vmcnt(22)
	v_mul_f32_e32 v212, v60, v149
	v_mul_f32_e32 v213, v61, v149
	v_mul_f32_e32 v214, v62, v149
	v_mul_f32_e32 v215, v63, v149
	v_fmac_f32_e32 v36, v60, v149
	v_fmac_f32_e32 v37, v61, v149
	v_fmac_f32_e32 v38, v62, v149
	v_fmac_f32_e32 v39, v63, v149
	v_fma_f32 v12, v36, s59, -v212
	v_fma_f32 v13, v37, s59, -v213
	v_fma_f32 v22, v38, s59, -v214
	v_fma_f32 v23, v39, s59, -v215
	s_waitcnt vmcnt(21)
	v_fma_f32 v36, -v64, v142, v36
	v_fma_f32 v37, -v65, v142, v37
	v_fma_f32 v38, -v66, v142, v38
	v_fma_f32 v39, -v67, v142, v39
	v_cvt_pk_bf16_f32 v2, v12, v13
	v_cvt_pk_bf16_f32 v3, v22, v23
	global_store_dwordx2 v222, v[2:3], s[54:55]
	s_add_u32 s14, s2, 0x22000
	s_addc_u32 s15, s3, 0
	global_load_dwordx4 v[60:63], v0, s[14:15]
	s_add_u32 s56, s2, 0x1b000
	s_addc_u32 s57, s3, 0
	global_load_dwordx4 v[64:67], v0, s[56:57]
	s_add_u32 s74, s12, 0xe580
	s_addc_u32 s75, s13, 0
	s_waitcnt vmcnt(22)
	v_mul_f32_e32 v212, v68, v150
	v_mul_f32_e32 v213, v69, v150
	v_mul_f32_e32 v214, v70, v150
	v_mul_f32_e32 v215, v71, v150
	v_fmac_f32_e32 v36, v68, v150
	v_fmac_f32_e32 v37, v69, v150
	v_fmac_f32_e32 v38, v70, v150
	v_fmac_f32_e32 v39, v71, v150
	v_fma_f32 v12, v36, s59, -v212
	v_fma_f32 v13, v37, s59, -v213
	v_fma_f32 v22, v38, s59, -v214
	v_fma_f32 v23, v39, s59, -v215
	s_waitcnt vmcnt(21)
	v_fma_f32 v36, -v72, v143, v36
	v_fma_f32 v37, -v73, v143, v37
	v_fma_f32 v38, -v74, v143, v38
	v_fma_f32 v39, -v75, v143, v39
	v_cvt_pk_bf16_f32 v208, v12, v13
	v_cvt_pk_bf16_f32 v209, v22, v23
	global_store_dwordx2 v222, v[208:209], s[74:75]
	s_add_u32 s70, s2, 0x23000
	s_addc_u32 s71, s3, 0
	global_load_dwordx4 v[68:71], v0, s[70:71]
	s_add_u32 s14, s2, 0x1c000
	s_addc_u32 s15, s3, 0
	global_load_dwordx4 v[72:75], v0, s[14:15]
	s_add_u32 s54, s12, 0xee00
	s_addc_u32 s55, s13, 0
	s_waitcnt vmcnt(22)
	v_mul_f32_e32 v212, v76, v151
	v_mul_f32_e32 v213, v77, v151
	v_mul_f32_e32 v214, v78, v151
	v_mul_f32_e32 v215, v79, v151
	v_fmac_f32_e32 v36, v76, v151
	v_fmac_f32_e32 v37, v77, v151
	v_fmac_f32_e32 v38, v78, v151
	v_fmac_f32_e32 v39, v79, v151
	v_fma_f32 v12, v36, s59, -v212
	v_fma_f32 v13, v37, s59, -v213
	v_fma_f32 v22, v38, s59, -v214
	v_fma_f32 v23, v39, s59, -v215
	s_waitcnt vmcnt(21)
	v_fma_f32 v36, -v80, v144, v36
	v_fma_f32 v37, -v81, v144, v37
	v_fma_f32 v38, -v82, v144, v38
	v_fma_f32 v39, -v83, v144, v39
	v_cvt_pk_bf16_f32 v2, v12, v13
	v_cvt_pk_bf16_f32 v3, v22, v23
	global_store_dwordx2 v222, v[2:3], s[54:55]
	s_add_u32 s56, s2, 0x24000
	s_addc_u32 s57, s3, 0
	global_load_dwordx4 v[76:79], v0, s[56:57]
	s_add_u32 s70, s2, 0x1d000
	s_addc_u32 s71, s3, 0
	global_load_dwordx4 v[80:83], v0, s[70:71]
	s_add_u32 s74, s12, 0xf680
	s_addc_u32 s75, s13, 0
	s_waitcnt vmcnt(22)
	v_mul_f32_e32 v212, v84, v152
	v_mul_f32_e32 v213, v85, v152
	v_mul_f32_e32 v214, v86, v152
	v_mul_f32_e32 v215, v87, v152
	v_fmac_f32_e32 v36, v84, v152
	v_fmac_f32_e32 v37, v85, v152
	v_fmac_f32_e32 v38, v86, v152
	v_fmac_f32_e32 v39, v87, v152
	v_fma_f32 v12, v36, s59, -v212
	v_fma_f32 v13, v37, s59, -v213
	v_fma_f32 v22, v38, s59, -v214
	v_fma_f32 v23, v39, s59, -v215
	s_waitcnt vmcnt(21)
	v_fma_f32 v36, -v88, v145, v36
	v_fma_f32 v37, -v89, v145, v37
	v_fma_f32 v38, -v90, v145, v38
	v_fma_f32 v39, -v91, v145, v39
	v_cvt_pk_bf16_f32 v208, v12, v13
	v_cvt_pk_bf16_f32 v209, v22, v23
	global_store_dwordx2 v222, v[208:209], s[74:75]
	s_add_u32 s14, s2, 0x25000
	s_addc_u32 s15, s3, 0
	global_load_dwordx4 v[84:87], v0, s[14:15]
	s_add_u32 s56, s2, 0x1e000
	s_addc_u32 s57, s3, 0
	global_load_dwordx4 v[88:91], v0, s[56:57]
	s_add_u32 s54, s12, 0xff00
	s_addc_u32 s55, s13, 0
	s_waitcnt vmcnt(22)
	v_mul_f32_e32 v212, v92, v153
	v_mul_f32_e32 v213, v93, v153
	v_mul_f32_e32 v214, v94, v153
	v_mul_f32_e32 v215, v95, v153
	v_fmac_f32_e32 v36, v92, v153
	v_fmac_f32_e32 v37, v93, v153
	v_fmac_f32_e32 v38, v94, v153
	v_fmac_f32_e32 v39, v95, v153
	v_fma_f32 v12, v36, s59, -v212
	v_fma_f32 v13, v37, s59, -v213
	v_fma_f32 v22, v38, s59, -v214
	v_fma_f32 v23, v39, s59, -v215
	s_waitcnt vmcnt(21)
	v_fma_f32 v36, -v96, v146, v36
	v_fma_f32 v37, -v97, v146, v37
	v_fma_f32 v38, -v98, v146, v38
	v_fma_f32 v39, -v99, v146, v39
	v_cvt_pk_bf16_f32 v2, v12, v13
	v_cvt_pk_bf16_f32 v3, v22, v23
	global_store_dwordx2 v222, v[2:3], s[54:55]
	s_add_u32 s70, s2, 0x26000
	s_addc_u32 s71, s3, 0
	global_load_dwordx4 v[92:95], v0, s[70:71]
	s_add_u32 s14, s2, 0x1f000
	s_addc_u32 s15, s3, 0
	global_load_dwordx4 v[96:99], v0, s[14:15]
	s_add_u32 s74, s12, 0x10780
	s_addc_u32 s75, s13, 0
	s_waitcnt vmcnt(22)
	v_mul_f32_e32 v212, v100, v154
	v_mul_f32_e32 v213, v101, v154
	v_mul_f32_e32 v214, v102, v154
	v_mul_f32_e32 v215, v103, v154
	v_fmac_f32_e32 v36, v100, v154
	v_fmac_f32_e32 v37, v101, v154
	v_fmac_f32_e32 v38, v102, v154
	v_fmac_f32_e32 v39, v103, v154
	v_fma_f32 v12, v36, s59, -v212
	v_fma_f32 v13, v37, s59, -v213
	v_fma_f32 v22, v38, s59, -v214
	v_fma_f32 v23, v39, s59, -v215
	s_waitcnt vmcnt(21)
; DI unsigned pack_bf16(float lo, float hi) { f32x2 v = {lo, hi}; bf16v2 b = __builtin_convertvector(v, bf16v2); return __builtin_bit_cast(unsigned, b); }
; template <int W>
; DI void pool_rows(const float* __restrict__ x, const float* smr, bf16_t* __restrict__ pb, int t0, int s0, int tid) {
;     ...
;   for (int tl = 0; tl < 64; ++tl) {
;     const int t = t0 + tl, s = s0 + tl;
;     int to = t - W + 1; if (to < tq0) to = tq0;
;     const f32x4 hn = *(const f32x4*)(xq + (size_t)t * D) * smr[15 + tl];
;     const f32x4 ho = *(const f32x4*)(xq + (size_t)to * D) * smr[15 + tl - W + 1];
;     const int cnt = (s + 1 < W) ? (s + 1) : W;
;     const float ic = 1.f / (float)cnt;
;     Sm += hn;
;     const f32x4 p = Sm * ic - hn;
;     Sm -= ho;
;     u32x2 o; o.x = pack_bf16(p.x, p.y); o.y = pack_bf16(p.z, p.w);
;     *(u32x2*)(pb + (size_t)t * LDH + tid * 4) = o;
;   }
	v_fma_f32 v36, -v104, v147, v36
	v_fma_f32 v37, -v105, v147, v37
	v_fma_f32 v38, -v106, v147, v38
	v_fma_f32 v39, -v107, v147, v39
	v_cvt_pk_bf16_f32 v208, v12, v13
	v_cvt_pk_bf16_f32 v209, v22, v23
	global_store_dwordx2 v222, v[208:209], s[74:75]
	s_add_u32 s56, s2, 0x27000
	s_addc_u32 s57, s3, 0
	global_load_dwordx4 v[100:103], v0, s[56:57]
	s_add_u32 s70, s2, 0x20000
	s_addc_u32 s71, s3, 0
	global_load_dwordx4 v[104:107], v0, s[70:71]
	s_add_u32 s54, s12, 0x11000
	s_addc_u32 s55, s13, 0
	s_waitcnt vmcnt(22)
	v_mul_f32_e32 v212, v44, v155
	v_mul_f32_e32 v213, v45, v155
	v_mul_f32_e32 v214, v46, v155
	v_mul_f32_e32 v215, v47, v155
	v_fmac_f32_e32 v36, v44, v155
	v_fmac_f32_e32 v37, v45, v155
	v_fmac_f32_e32 v38, v46, v155
	v_fmac_f32_e32 v39, v47, v155
	v_fma_f32 v12, v36, s59, -v212
	v_fma_f32 v13, v37, s59, -v213
	v_fma_f32 v22, v38, s59, -v214
	v_fma_f32 v23, v39, s59, -v215
	s_waitcnt vmcnt(21)
	v_fma_f32 v36, -v48, v148, v36
	v_fma_f32 v37, -v49, v148, v37
	v_fma_f32 v38, -v50, v148, v38
	v_fma_f32 v39, -v51, v148, v39
	v_cvt_pk_bf16_f32 v2, v12, v13
	v_cvt_pk_bf16_f32 v3, v22, v23
	global_store_dwordx2 v222, v[2:3], s[54:55]
	s_add_u32 s14, s2, 0x28000
	s_addc_u32 s15, s3, 0
	global_load_dwordx4 v[44:47], v0, s[14:15]
	s_add_u32 s56, s2, 0x21000
	s_addc_u32 s57, s3, 0
	global_load_dwordx4 v[48:51], v0, s[56:57]
	s_add_u32 s74, s12, 0x11880
	s_addc_u32 s75, s13, 0
	s_waitcnt vmcnt(22)
	v_mul_f32_e32 v212, v52, v156
	v_mul_f32_e32 v213, v53, v156
	v_mul_f32_e32 v214, v54, v156
	v_mul_f32_e32 v215, v55, v156
	v_fmac_f32_e32 v36, v52, v156
	v_fmac_f32_e32 v37, v53, v156
	v_fmac_f32_e32 v38, v54, v156
	v_fmac_f32_e32 v39, v55, v156
	v_fma_f32 v12, v36, s59, -v212
	v_fma_f32 v13, v37, s59, -v213
	v_fma_f32 v22, v38, s59, -v214
	v_fma_f32 v23, v39, s59, -v215
	s_waitcnt vmcnt(21)
	v_fma_f32 v36, -v56, v149, v36
	v_fma_f32 v37, -v57, v149, v37
	v_fma_f32 v38, -v58, v149, v38
	v_fma_f32 v39, -v59, v149, v39
	v_cvt_pk_bf16_f32 v208, v12, v13
	v_cvt_pk_bf16_f32 v209, v22, v23
	global_store_dwordx2 v222, v[208:209], s[74:75]
	s_add_u32 s70, s2, 0x29000
	s_addc_u32 s71, s3, 0
	global_load_dwordx4 v[52:55], v0, s[70:71]
	s_add_u32 s14, s2, 0x22000
	s_addc_u32 s15, s3, 0
	global_load_dwordx4 v[56:59], v0, s[14:15]
	s_add_u32 s54, s12, 0x12100
	s_addc_u32 s55, s13, 0
	s_waitcnt vmcnt(22)
	v_mul_f32_e32 v212, v60, v157
	v_mul_f32_e32 v213, v61, v157
	v_mul_f32_e32 v214, v62, v157
	v_mul_f32_e32 v215, v63, v157
	v_fmac_f32_e32 v36, v60, v157
	v_fmac_f32_e32 v37, v61, v157
	v_fmac_f32_e32 v38, v62, v157
	v_fmac_f32_e32 v39, v63, v157
	v_fma_f32 v12, v36, s59, -v212
	v_fma_f32 v13, v37, s59, -v213
	v_fma_f32 v22, v38, s59, -v214
	v_fma_f32 v23, v39, s59, -v215
	s_waitcnt vmcnt(21)
	v_fma_f32 v36, -v64, v150, v36
	v_fma_f32 v37, -v65, v150, v37
	v_fma_f32 v38, -v66, v150, v38
	v_fma_f32 v39, -v67, v150, v39
	v_cvt_pk_bf16_f32 v2, v12, v13
	v_cvt_pk_bf16_f32 v3, v22, v23
	global_store_dwordx2 v222, v[2:3], s[54:55]
	s_add_u32 s56, s2, 0x2a000
	s_addc_u32 s57, s3, 0
	global_load_dwordx4 v[60:63], v0, s[56:57]
	s_add_u32 s70, s2, 0x23000
	s_addc_u32 s71, s3, 0
	global_load_dwordx4 v[64:67], v0, s[70:71]
	s_add_u32 s74, s12, 0x12980
	s_addc_u32 s75, s13, 0
	s_waitcnt vmcnt(22)
	v_mul_f32_e32 v212, v68, v158
	v_mul_f32_e32 v213, v69, v158
	v_mul_f32_e32 v214, v70, v158
	v_mul_f32_e32 v215, v71, v158
	v_fmac_f32_e32 v36, v68, v158
	v_fmac_f32_e32 v37, v69, v158
	v_fmac_f32_e32 v38, v70, v158
	v_fmac_f32_e32 v39, v71, v158
	v_fma_f32 v12, v36, s59, -v212
	v_fma_f32 v13, v37, s59, -v213
	v_fma_f32 v22, v38, s59, -v214
	v_fma_f32 v23, v39, s59, -v215
	s_waitcnt vmcnt(21)
	v_fma_f32 v36, -v72, v151, v36
	v_fma_f32 v37, -v73, v151, v37
	v_fma_f32 v38, -v74, v151, v38
	v_fma_f32 v39, -v75, v151, v39
	v_cvt_pk_bf16_f32 v208, v12, v13
	v_cvt_pk_bf16_f32 v209, v22, v23
	global_store_dwordx2 v222, v[208:209], s[74:75]
	s_add_u32 s14, s2, 0x2b000
	s_addc_u32 s15, s3, 0
	global_load_dwordx4 v[68:71], v0, s[14:15]
	s_add_u32 s56, s2, 0x24000
	s_addc_u32 s57, s3, 0
	global_load_dwordx4 v[72:75], v0, s[56:57]
	s_add_u32 s54, s12, 0x13200
	s_addc_u32 s55, s13, 0
	s_waitcnt vmcnt(22)
	v_mul_f32_e32 v212, v76, v159
	v_mul_f32_e32 v213, v77, v159
	v_mul_f32_e32 v214, v78, v159
	v_mul_f32_e32 v215, v79, v159
	v_fmac_f32_e32 v36, v76, v159
	v_fmac_f32_e32 v37, v77, v159
	v_fmac_f32_e32 v38, v78, v159
	v_fmac_f32_e32 v39, v79, v159
	v_fma_f32 v12, v36, s59, -v212
	v_fma_f32 v13, v37, s59, -v213
	v_fma_f32 v22, v38, s59, -v214
	v_fma_f32 v23, v39, s59, -v215
	s_waitcnt vmcnt(21)
	v_fma_f32 v36, -v80, v152, v36
	v_fma_f32 v37, -v81, v152, v37
	v_fma_f32 v38, -v82, v152, v38
	v_fma_f32 v39, -v83, v152, v39
	v_cvt_pk_bf16_f32 v2, v12, v13
	v_cvt_pk_bf16_f32 v3, v22, v23
	global_store_dwordx2 v222, v[2:3], s[54:55]
	s_add_u32 s70, s2, 0x2c000
	s_addc_u32 s71, s3, 0
	global_load_dwordx4 v[76:79], v0, s[70:71]
	s_add_u32 s14, s2, 0x25000
	s_addc_u32 s15, s3, 0
	global_load_dwordx4 v[80:83], v0, s[14:15]
	s_add_u32 s74, s12, 0x13a80
	s_addc_u32 s75, s13, 0
	s_waitcnt vmcnt(22)
	v_mul_f32_e32 v212, v84, v160
	v_mul_f32_e32 v213, v85, v160
	v_mul_f32_e32 v214, v86, v160
	v_mul_f32_e32 v215, v87, v160
	v_fmac_f32_e32 v36, v84, v160
	v_fmac_f32_e32 v37, v85, v160
	v_fmac_f32_e32 v38, v86, v160
	v_fmac_f32_e32 v39, v87, v160
	v_fma_f32 v12, v36, s59, -v212
	v_fma_f32 v13, v37, s59, -v213
	v_fma_f32 v22, v38, s59, -v214
	v_fma_f32 v23, v39, s59, -v215
	s_waitcnt vmcnt(21)
; DI unsigned pack_bf16(float lo, float hi) { f32x2 v = {lo, hi}; bf16v2 b = __builtin_convertvector(v, bf16v2); return __builtin_bit_cast(unsigned, b); }
; template <int W>
; DI void pool_rows(const float* __restrict__ x, const float* smr, bf16_t* __restrict__ pb, int t0, int s0, int tid) {
;     ...
;   for (int tl = 0; tl < 64; ++tl) {
;     const int t = t0 + tl, s = s0 + tl;
;     int to = t - W + 1; if (to < tq0) to = tq0;
;     const f32x4 hn = *(const f32x4*)(xq + (size_t)t * D) * smr[15 + tl];
;     const f32x4 ho = *(const f32x4*)(xq + (size_t)to * D) * smr[15 + tl - W + 1];
;     const int cnt = (s + 1 < W) ? (s + 1) : W;
;     const float ic = 1.f / (float)cnt;
;     Sm += hn;
;     const f32x4 p = Sm * ic - hn;
;     Sm -= ho;
;     u32x2 o; o.x = pack_bf16(p.x, p.y); o.y = pack_bf16(p.z, p.w);
;     *(u32x2*)(pb + (size_t)t * LDH + tid * 4) = o;
;   }
	v_fma_f32 v36, -v88, v153, v36
	v_fma_f32 v37, -v89, v153, v37
	v_fma_f32 v38, -v90, v153, v38
	v_fma_f32 v39, -v91, v153, v39
	v_cvt_pk_bf16_f32 v208, v12, v13
	v_cvt_pk_bf16_f32 v209, v22, v23
	global_store_dwordx2 v222, v[208:209], s[74:75]
	s_add_u32 s56, s2, 0x2d000
	s_addc_u32 s57, s3, 0
	global_load_dwordx4 v[84:87], v0, s[56:57]
	s_add_u32 s70, s2, 0x26000
	s_addc_u32 s71, s3, 0
	global_load_dwordx4 v[88:91], v0, s[70:71]
	s_add_u32 s54, s12, 0x14300
	s_addc_u32 s55, s13, 0
	s_waitcnt vmcnt(22)
	v_mul_f32_e32 v212, v92, v161
	v_mul_f32_e32 v213, v93, v161
	v_mul_f32_e32 v214, v94, v161
	v_mul_f32_e32 v215, v95, v161
	v_fmac_f32_e32 v36, v92, v161
	v_fmac_f32_e32 v37, v93, v161
	v_fmac_f32_e32 v38, v94, v161
	v_fmac_f32_e32 v39, v95, v161
	v_fma_f32 v12, v36, s59, -v212
	v_fma_f32 v13, v37, s59, -v213
	v_fma_f32 v22, v38, s59, -v214
	v_fma_f32 v23, v39, s59, -v215
	s_waitcnt vmcnt(21)
	v_fma_f32 v36, -v96, v154, v36
	v_fma_f32 v37, -v97, v154, v37
	v_fma_f32 v38, -v98, v154, v38
	v_fma_f32 v39, -v99, v154, v39
	v_cvt_pk_bf16_f32 v2, v12, v13
	v_cvt_pk_bf16_f32 v3, v22, v23
	global_store_dwordx2 v222, v[2:3], s[54:55]
	s_add_u32 s14, s2, 0x2e000
	s_addc_u32 s15, s3, 0
	global_load_dwordx4 v[92:95], v0, s[14:15]
	s_add_u32 s56, s2, 0x27000
	s_addc_u32 s57, s3, 0
	global_load_dwordx4 v[96:99], v0, s[56:57]
	s_add_u32 s74, s12, 0x14b80
	s_addc_u32 s75, s13, 0
	s_waitcnt vmcnt(22)
	v_mul_f32_e32 v212, v100, v162
	v_mul_f32_e32 v213, v101, v162
	v_mul_f32_e32 v214, v102, v162
	v_mul_f32_e32 v215, v103, v162
	v_fmac_f32_e32 v36, v100, v162
	v_fmac_f32_e32 v37, v101, v162
	v_fmac_f32_e32 v38, v102, v162
	v_fmac_f32_e32 v39, v103, v162
	v_fma_f32 v12, v36, s59, -v212
	v_fma_f32 v13, v37, s59, -v213
	v_fma_f32 v22, v38, s59, -v214
	v_fma_f32 v23, v39, s59, -v215
	s_waitcnt vmcnt(21)
	v_fma_f32 v36, -v104, v155, v36
	v_fma_f32 v37, -v105, v155, v37
	v_fma_f32 v38, -v106, v155, v38
	v_fma_f32 v39, -v107, v155, v39
	v_cvt_pk_bf16_f32 v208, v12, v13
	v_cvt_pk_bf16_f32 v209, v22, v23
	global_store_dwordx2 v222, v[208:209], s[74:75]
	s_add_u32 s70, s2, 0x2f000
	s_addc_u32 s71, s3, 0
	global_load_dwordx4 v[100:103], v0, s[70:71]
	s_add_u32 s14, s2, 0x28000
	s_addc_u32 s15, s3, 0
	global_load_dwordx4 v[104:107], v0, s[14:15]
	s_add_u32 s54, s12, 0x15400
	s_addc_u32 s55, s13, 0
	s_waitcnt vmcnt(22)
	v_mul_f32_e32 v212, v44, v163
	v_mul_f32_e32 v213, v45, v163
	v_mul_f32_e32 v214, v46, v163
	v_mul_f32_e32 v215, v47, v163
	v_fmac_f32_e32 v36, v44, v163
	v_fmac_f32_e32 v37, v45, v163
	v_fmac_f32_e32 v38, v46, v163
	v_fmac_f32_e32 v39, v47, v163
	v_fma_f32 v12, v36, s59, -v212
	v_fma_f32 v13, v37, s59, -v213
	v_fma_f32 v22, v38, s59, -v214
	v_fma_f32 v23, v39, s59, -v215
	s_waitcnt vmcnt(21)
	v_fma_f32 v36, -v48, v156, v36
	v_fma_f32 v37, -v49, v156, v37
	v_fma_f32 v38, -v50, v156, v38
	v_fma_f32 v39, -v51, v156, v39
	v_cvt_pk_bf16_f32 v2, v12, v13
	v_cvt_pk_bf16_f32 v3, v22, v23
	global_store_dwordx2 v222, v[2:3], s[54:55]
	s_add_u32 s56, s2, 0x30000
	s_addc_u32 s57, s3, 0
	global_load_dwordx4 v[44:47], v0, s[56:57]
	s_add_u32 s70, s2, 0x29000
	s_addc_u32 s71, s3, 0
	global_load_dwordx4 v[48:51], v0, s[70:71]
	s_add_u32 s74, s12, 0x15c80
	s_addc_u32 s75, s13, 0
	s_waitcnt vmcnt(22)
	v_mul_f32_e32 v212, v52, v164
	v_mul_f32_e32 v213, v53, v164
	v_mul_f32_e32 v214, v54, v164
	v_mul_f32_e32 v215, v55, v164
	v_fmac_f32_e32 v36, v52, v164
	v_fmac_f32_e32 v37, v53, v164
	v_fmac_f32_e32 v38, v54, v164
	v_fmac_f32_e32 v39, v55, v164
	v_fma_f32 v12, v36, s59, -v212
	v_fma_f32 v13, v37, s59, -v213
	v_fma_f32 v22, v38, s59, -v214
	v_fma_f32 v23, v39, s59, -v215
	s_waitcnt vmcnt(21)
	v_fma_f32 v36, -v56, v157, v36
	v_fma_f32 v37, -v57, v157, v37
	v_fma_f32 v38, -v58, v157, v38
	v_fma_f32 v39, -v59, v157, v39
	v_cvt_pk_bf16_f32 v208, v12, v13
	v_cvt_pk_bf16_f32 v209, v22, v23
	global_store_dwordx2 v222, v[208:209], s[74:75]
	s_add_u32 s14, s2, 0x31000
	s_addc_u32 s15, s3, 0
	global_load_dwordx4 v[52:55], v0, s[14:15]
	s_add_u32 s56, s2, 0x2a000
	s_addc_u32 s57, s3, 0
	global_load_dwordx4 v[56:59], v0, s[56:57]
	s_add_u32 s54, s12, 0x16500
	s_addc_u32 s55, s13, 0
	s_waitcnt vmcnt(22)
	v_mul_f32_e32 v212, v60, v165
	v_mul_f32_e32 v213, v61, v165
	v_mul_f32_e32 v214, v62, v165
	v_mul_f32_e32 v215, v63, v165
	v_fmac_f32_e32 v36, v60, v165
	v_fmac_f32_e32 v37, v61, v165
	v_fmac_f32_e32 v38, v62, v165
	v_fmac_f32_e32 v39, v63, v165
	v_fma_f32 v12, v36, s59, -v212
	v_fma_f32 v13, v37, s59, -v213
	v_fma_f32 v22, v38, s59, -v214
	v_fma_f32 v23, v39, s59, -v215
	s_waitcnt vmcnt(21)
	v_fma_f32 v36, -v64, v158, v36
	v_fma_f32 v37, -v65, v158, v37
	v_fma_f32 v38, -v66, v158, v38
	v_fma_f32 v39, -v67, v158, v39
	v_cvt_pk_bf16_f32 v2, v12, v13
	v_cvt_pk_bf16_f32 v3, v22, v23
	global_store_dwordx2 v222, v[2:3], s[54:55]
	s_add_u32 s70, s2, 0x32000
	s_addc_u32 s71, s3, 0
	global_load_dwordx4 v[60:63], v0, s[70:71]
	s_add_u32 s14, s2, 0x2b000
	s_addc_u32 s15, s3, 0
	global_load_dwordx4 v[64:67], v0, s[14:15]
	s_add_u32 s74, s12, 0x16d80
	s_addc_u32 s75, s13, 0
	s_waitcnt vmcnt(22)
	v_mul_f32_e32 v212, v68, v166
	v_mul_f32_e32 v213, v69, v166
	v_mul_f32_e32 v214, v70, v166
	v_mul_f32_e32 v215, v71, v166
	v_fmac_f32_e32 v36, v68, v166
	v_fmac_f32_e32 v37, v69, v166
	v_fmac_f32_e32 v38, v70, v166
	v_fmac_f32_e32 v39, v71, v166
	v_fma_f32 v12, v36, s59, -v212
	v_fma_f32 v13, v37, s59, -v213
	v_fma_f32 v22, v38, s59, -v214
	v_fma_f32 v23, v39, s59, -v215
	s_waitcnt vmcnt(21)
; DI unsigned pack_bf16(float lo, float hi) { f32x2 v = {lo, hi}; bf16v2 b = __builtin_convertvector(v, bf16v2); return __builtin_bit_cast(unsigned, b); }
; template <int W>
; DI void pool_rows(const float* __restrict__ x, const float* smr, bf16_t* __restrict__ pb, int t0, int s0, int tid) {
;     ...
;   for (int tl = 0; tl < 64; ++tl) {
;     const int t = t0 + tl, s = s0 + tl;
;     int to = t - W + 1; if (to < tq0) to = tq0;
;     const f32x4 hn = *(const f32x4*)(xq + (size_t)t * D) * smr[15 + tl];
;     const f32x4 ho = *(const f32x4*)(xq + (size_t)to * D) * smr[15 + tl - W + 1];
;     const int cnt = (s + 1 < W) ? (s + 1) : W;
;     const float ic = 1.f / (float)cnt;
;     Sm += hn;
;     const f32x4 p = Sm * ic - hn;
;     Sm -= ho;
;     u32x2 o; o.x = pack_bf16(p.x, p.y); o.y = pack_bf16(p.z, p.w);
;     *(u32x2*)(pb + (size_t)t * LDH + tid * 4) = o;
;   }
	v_fma_f32 v36, -v72, v159, v36
	v_fma_f32 v37, -v73, v159, v37
	v_fma_f32 v38, -v74, v159, v38
	v_fma_f32 v39, -v75, v159, v39
	v_cvt_pk_bf16_f32 v208, v12, v13
	v_cvt_pk_bf16_f32 v209, v22, v23
	global_store_dwordx2 v222, v[208:209], s[74:75]
	s_add_u32 s56, s2, 0x33000
	s_addc_u32 s57, s3, 0
	global_load_dwordx4 v[68:71], v0, s[56:57]
	s_add_u32 s70, s2, 0x2c000
	s_addc_u32 s71, s3, 0
	global_load_dwordx4 v[72:75], v0, s[70:71]
	s_add_u32 s54, s12, 0x17600
	s_addc_u32 s55, s13, 0
	s_waitcnt vmcnt(22)
	v_mul_f32_e32 v212, v76, v167
	v_mul_f32_e32 v213, v77, v167
	v_mul_f32_e32 v214, v78, v167
	v_mul_f32_e32 v215, v79, v167
	v_fmac_f32_e32 v36, v76, v167
	v_fmac_f32_e32 v37, v77, v167
	v_fmac_f32_e32 v38, v78, v167
	v_fmac_f32_e32 v39, v79, v167
	v_fma_f32 v12, v36, s59, -v212
	v_fma_f32 v13, v37, s59, -v213
	v_fma_f32 v22, v38, s59, -v214
	v_fma_f32 v23, v39, s59, -v215
	s_waitcnt vmcnt(21)
	v_fma_f32 v36, -v80, v160, v36
	v_fma_f32 v37, -v81, v160, v37
	v_fma_f32 v38, -v82, v160, v38
	v_fma_f32 v39, -v83, v160, v39
	v_cvt_pk_bf16_f32 v2, v12, v13
	v_cvt_pk_bf16_f32 v3, v22, v23
	global_store_dwordx2 v222, v[2:3], s[54:55]
	s_add_u32 s14, s2, 0x34000
	s_addc_u32 s15, s3, 0
	global_load_dwordx4 v[76:79], v0, s[14:15]
	s_add_u32 s56, s2, 0x2d000
	s_addc_u32 s57, s3, 0
	global_load_dwordx4 v[80:83], v0, s[56:57]
	s_add_u32 s74, s12, 0x17e80
	s_addc_u32 s75, s13, 0
	s_waitcnt vmcnt(22)
	v_mul_f32_e32 v212, v84, v168
	v_mul_f32_e32 v213, v85, v168
	v_mul_f32_e32 v214, v86, v168
	v_mul_f32_e32 v215, v87, v168
	v_fmac_f32_e32 v36, v84, v168
	v_fmac_f32_e32 v37, v85, v168
	v_fmac_f32_e32 v38, v86, v168
	v_fmac_f32_e32 v39, v87, v168
	v_fma_f32 v12, v36, s59, -v212
	v_fma_f32 v13, v37, s59, -v213
	v_fma_f32 v22, v38, s59, -v214
	v_fma_f32 v23, v39, s59, -v215
	s_waitcnt vmcnt(21)
	v_fma_f32 v36, -v88, v161, v36
	v_fma_f32 v37, -v89, v161, v37
	v_fma_f32 v38, -v90, v161, v38
	v_fma_f32 v39, -v91, v161, v39
	v_cvt_pk_bf16_f32 v208, v12, v13
	v_cvt_pk_bf16_f32 v209, v22, v23
	global_store_dwordx2 v222, v[208:209], s[74:75]
	s_add_u32 s70, s2, 0x35000
	s_addc_u32 s71, s3, 0
	global_load_dwordx4 v[84:87], v0, s[70:71]
	s_add_u32 s14, s2, 0x2e000
	s_addc_u32 s15, s3, 0
	global_load_dwordx4 v[88:91], v0, s[14:15]
	s_add_u32 s54, s12, 0x18700
	s_addc_u32 s55, s13, 0
	s_waitcnt vmcnt(22)
	v_mul_f32_e32 v212, v92, v169
	v_mul_f32_e32 v213, v93, v169
	v_mul_f32_e32 v214, v94, v169
	v_mul_f32_e32 v215, v95, v169
	v_fmac_f32_e32 v36, v92, v169
	v_fmac_f32_e32 v37, v93, v169
	v_fmac_f32_e32 v38, v94, v169
	v_fmac_f32_e32 v39, v95, v169
	v_fma_f32 v12, v36, s59, -v212
	v_fma_f32 v13, v37, s59, -v213
	v_fma_f32 v22, v38, s59, -v214
	v_fma_f32 v23, v39, s59, -v215
	s_waitcnt vmcnt(21)
	v_fma_f32 v36, -v96, v162, v36
	v_fma_f32 v37, -v97, v162, v37
	v_fma_f32 v38, -v98, v162, v38
	v_fma_f32 v39, -v99, v162, v39
	v_cvt_pk_bf16_f32 v2, v12, v13
	v_cvt_pk_bf16_f32 v3, v22, v23
	global_store_dwordx2 v222, v[2:3], s[54:55]
	s_add_u32 s56, s2, 0x36000
	s_addc_u32 s57, s3, 0
	global_load_dwordx4 v[92:95], v0, s[56:57]
	s_add_u32 s70, s2, 0x2f000
	s_addc_u32 s71, s3, 0
	global_load_dwordx4 v[96:99], v0, s[70:71]
	s_add_u32 s74, s12, 0x18f80
	s_addc_u32 s75, s13, 0
	s_waitcnt vmcnt(22)
	v_mul_f32_e32 v212, v100, v170
	v_mul_f32_e32 v213, v101, v170
	v_mul_f32_e32 v214, v102, v170
	v_mul_f32_e32 v215, v103, v170
	v_fmac_f32_e32 v36, v100, v170
	v_fmac_f32_e32 v37, v101, v170
	v_fmac_f32_e32 v38, v102, v170
	v_fmac_f32_e32 v39, v103, v170
	v_fma_f32 v12, v36, s59, -v212
	v_fma_f32 v13, v37, s59, -v213
	v_fma_f32 v22, v38, s59, -v214
	v_fma_f32 v23, v39, s59, -v215
	s_waitcnt vmcnt(21)
	v_fma_f32 v36, -v104, v163, v36
	v_fma_f32 v37, -v105, v163, v37
	v_fma_f32 v38, -v106, v163, v38
	v_fma_f32 v39, -v107, v163, v39
	v_cvt_pk_bf16_f32 v208, v12, v13
	v_cvt_pk_bf16_f32 v209, v22, v23
	global_store_dwordx2 v222, v[208:209], s[74:75]
	s_add_u32 s14, s2, 0x37000
	s_addc_u32 s15, s3, 0
	global_load_dwordx4 v[100:103], v0, s[14:15]
	s_add_u32 s56, s2, 0x30000
	s_addc_u32 s57, s3, 0
	global_load_dwordx4 v[104:107], v0, s[56:57]
	s_add_u32 s54, s12, 0x19800
	s_addc_u32 s55, s13, 0
	s_waitcnt vmcnt(22)
	v_mul_f32_e32 v212, v44, v171
	v_mul_f32_e32 v213, v45, v171
	v_mul_f32_e32 v214, v46, v171
	v_mul_f32_e32 v215, v47, v171
	v_fmac_f32_e32 v36, v44, v171
	v_fmac_f32_e32 v37, v45, v171
	v_fmac_f32_e32 v38, v46, v171
	v_fmac_f32_e32 v39, v47, v171
	v_fma_f32 v12, v36, s59, -v212
	v_fma_f32 v13, v37, s59, -v213
	v_fma_f32 v22, v38, s59, -v214
	v_fma_f32 v23, v39, s59, -v215
	s_waitcnt vmcnt(21)
	v_fma_f32 v36, -v48, v164, v36
	v_fma_f32 v37, -v49, v164, v37
	v_fma_f32 v38, -v50, v164, v38
	v_fma_f32 v39, -v51, v164, v39
	v_cvt_pk_bf16_f32 v2, v12, v13
	v_cvt_pk_bf16_f32 v3, v22, v23
	global_store_dwordx2 v222, v[2:3], s[54:55]
	s_add_u32 s70, s2, 0x38000
	s_addc_u32 s71, s3, 0
	global_load_dwordx4 v[44:47], v0, s[70:71]
	s_add_u32 s14, s2, 0x31000
	s_addc_u32 s15, s3, 0
	global_load_dwordx4 v[48:51], v0, s[14:15]
	s_add_u32 s74, s12, 0x1a080
	s_addc_u32 s75, s13, 0
	s_waitcnt vmcnt(22)
	v_mul_f32_e32 v212, v52, v172
	v_mul_f32_e32 v213, v53, v172
	v_mul_f32_e32 v214, v54, v172
	v_mul_f32_e32 v215, v55, v172
	v_fmac_f32_e32 v36, v52, v172
	v_fmac_f32_e32 v37, v53, v172
	v_fmac_f32_e32 v38, v54, v172
	v_fmac_f32_e32 v39, v55, v172
	v_fma_f32 v12, v36, s59, -v212
	v_fma_f32 v13, v37, s59, -v213
	v_fma_f32 v22, v38, s59, -v214
	v_fma_f32 v23, v39, s59, -v215
	s_waitcnt vmcnt(21)
; DI unsigned pack_bf16(float lo, float hi) { f32x2 v = {lo, hi}; bf16v2 b = __builtin_convertvector(v, bf16v2); return __builtin_bit_cast(unsigned, b); }
; template <int W>
; DI void pool_rows(const float* __restrict__ x, const float* smr, bf16_t* __restrict__ pb, int t0, int s0, int tid) {
;     ...
;   for (int tl = 0; tl < 64; ++tl) {
;     const int t = t0 + tl, s = s0 + tl;
;     int to = t - W + 1; if (to < tq0) to = tq0;
;     const f32x4 hn = *(const f32x4*)(xq + (size_t)t * D) * smr[15 + tl];
;     const f32x4 ho = *(const f32x4*)(xq + (size_t)to * D) * smr[15 + tl - W + 1];
;     const int cnt = (s + 1 < W) ? (s + 1) : W;
;     const float ic = 1.f / (float)cnt;
;     Sm += hn;
;     const f32x4 p = Sm * ic - hn;
;     Sm -= ho;
;     u32x2 o; o.x = pack_bf16(p.x, p.y); o.y = pack_bf16(p.z, p.w);
;     *(u32x2*)(pb + (size_t)t * LDH + tid * 4) = o;
;   }
	v_fma_f32 v36, -v56, v165, v36
	v_fma_f32 v37, -v57, v165, v37
	v_fma_f32 v38, -v58, v165, v38
	v_fma_f32 v39, -v59, v165, v39
	v_cvt_pk_bf16_f32 v208, v12, v13
	v_cvt_pk_bf16_f32 v209, v22, v23
	global_store_dwordx2 v222, v[208:209], s[74:75]
	s_add_u32 s56, s2, 0x39000
	s_addc_u32 s57, s3, 0
	global_load_dwordx4 v[52:55], v0, s[56:57]
	s_add_u32 s70, s2, 0x32000
	s_addc_u32 s71, s3, 0
	global_load_dwordx4 v[56:59], v0, s[70:71]
	s_add_u32 s54, s12, 0x1a900
	s_addc_u32 s55, s13, 0
	s_waitcnt vmcnt(22)
	v_mul_f32_e32 v212, v60, v173
	v_mul_f32_e32 v213, v61, v173
	v_mul_f32_e32 v214, v62, v173
	v_mul_f32_e32 v215, v63, v173
	v_fmac_f32_e32 v36, v60, v173
	v_fmac_f32_e32 v37, v61, v173
	v_fmac_f32_e32 v38, v62, v173
	v_fmac_f32_e32 v39, v63, v173
	v_fma_f32 v12, v36, s59, -v212
	v_fma_f32 v13, v37, s59, -v213
	v_fma_f32 v22, v38, s59, -v214
	v_fma_f32 v23, v39, s59, -v215
	s_waitcnt vmcnt(21)
	v_fma_f32 v36, -v64, v166, v36
	v_fma_f32 v37, -v65, v166, v37
	v_fma_f32 v38, -v66, v166, v38
	v_fma_f32 v39, -v67, v166, v39
	v_cvt_pk_bf16_f32 v2, v12, v13
	v_cvt_pk_bf16_f32 v3, v22, v23
	global_store_dwordx2 v222, v[2:3], s[54:55]
	s_add_u32 s14, s2, 0x3a000
	s_addc_u32 s15, s3, 0
	global_load_dwordx4 v[60:63], v0, s[14:15]
	s_add_u32 s56, s2, 0x33000
	s_addc_u32 s57, s3, 0
	global_load_dwordx4 v[64:67], v0, s[56:57]
	s_add_u32 s74, s12, 0x1b180
	s_addc_u32 s75, s13, 0
	s_waitcnt vmcnt(22)
	v_mul_f32_e32 v212, v68, v174
	v_mul_f32_e32 v213, v69, v174
	v_mul_f32_e32 v214, v70, v174
	v_mul_f32_e32 v215, v71, v174
	v_fmac_f32_e32 v36, v68, v174
	v_fmac_f32_e32 v37, v69, v174
	v_fmac_f32_e32 v38, v70, v174
	v_fmac_f32_e32 v39, v71, v174
	v_fma_f32 v12, v36, s59, -v212
	v_fma_f32 v13, v37, s59, -v213
	v_fma_f32 v22, v38, s59, -v214
	v_fma_f32 v23, v39, s59, -v215
	s_waitcnt vmcnt(21)
	v_fma_f32 v36, -v72, v167, v36
	v_fma_f32 v37, -v73, v167, v37
	v_fma_f32 v38, -v74, v167, v38
	v_fma_f32 v39, -v75, v167, v39
	v_cvt_pk_bf16_f32 v208, v12, v13
	v_cvt_pk_bf16_f32 v209, v22, v23
	global_store_dwordx2 v222, v[208:209], s[74:75]
	s_add_u32 s70, s2, 0x3b000
	s_addc_u32 s71, s3, 0
	global_load_dwordx4 v[68:71], v0, s[70:71]
	s_add_u32 s14, s2, 0x34000
	s_addc_u32 s15, s3, 0
	global_load_dwordx4 v[72:75], v0, s[14:15]
	s_add_u32 s54, s12, 0x1ba00
	s_addc_u32 s55, s13, 0
	s_waitcnt vmcnt(22)
	v_mul_f32_e32 v212, v76, v175
	v_mul_f32_e32 v213, v77, v175
	v_mul_f32_e32 v214, v78, v175
	v_mul_f32_e32 v215, v79, v175
	v_fmac_f32_e32 v36, v76, v175
	v_fmac_f32_e32 v37, v77, v175
	v_fmac_f32_e32 v38, v78, v175
	v_fmac_f32_e32 v39, v79, v175
	v_fma_f32 v12, v36, s59, -v212
	v_fma_f32 v13, v37, s59, -v213
	v_fma_f32 v22, v38, s59, -v214
	v_fma_f32 v23, v39, s59, -v215
	s_waitcnt vmcnt(21)
	v_fma_f32 v36, -v80, v168, v36
	v_fma_f32 v37, -v81, v168, v37
	v_fma_f32 v38, -v82, v168, v38
	v_fma_f32 v39, -v83, v168, v39
	v_cvt_pk_bf16_f32 v2, v12, v13
	v_cvt_pk_bf16_f32 v3, v22, v23
	global_store_dwordx2 v222, v[2:3], s[54:55]
	s_add_u32 s56, s2, 0x3c000
	s_addc_u32 s57, s3, 0
	global_load_dwordx4 v[76:79], v0, s[56:57]
	s_add_u32 s70, s2, 0x35000
	s_addc_u32 s71, s3, 0
	global_load_dwordx4 v[80:83], v0, s[70:71]
	s_add_u32 s74, s12, 0x1c280
	s_addc_u32 s75, s13, 0
	s_waitcnt vmcnt(22)
	v_mul_f32_e32 v212, v84, v176
	v_mul_f32_e32 v213, v85, v176
	v_mul_f32_e32 v214, v86, v176
	v_mul_f32_e32 v215, v87, v176
	v_fmac_f32_e32 v36, v84, v176
	v_fmac_f32_e32 v37, v85, v176
	v_fmac_f32_e32 v38, v86, v176
	v_fmac_f32_e32 v39, v87, v176
	v_fma_f32 v12, v36, s59, -v212
	v_fma_f32 v13, v37, s59, -v213
	v_fma_f32 v22, v38, s59, -v214
	v_fma_f32 v23, v39, s59, -v215
	s_waitcnt vmcnt(21)
	v_fma_f32 v36, -v88, v169, v36
	v_fma_f32 v37, -v89, v169, v37
	v_fma_f32 v38, -v90, v169, v38
	v_fma_f32 v39, -v91, v169, v39
	v_cvt_pk_bf16_f32 v208, v12, v13
	v_cvt_pk_bf16_f32 v209, v22, v23
	global_store_dwordx2 v222, v[208:209], s[74:75]
	s_add_u32 s14, s2, 0x3d000
	s_addc_u32 s15, s3, 0
	global_load_dwordx4 v[84:87], v0, s[14:15]
	s_add_u32 s56, s2, 0x36000
	s_addc_u32 s57, s3, 0
	global_load_dwordx4 v[88:91], v0, s[56:57]
	s_add_u32 s54, s12, 0x1cb00
	s_addc_u32 s55, s13, 0
	s_waitcnt vmcnt(22)
	v_mul_f32_e32 v212, v92, v177
	v_mul_f32_e32 v213, v93, v177
	v_mul_f32_e32 v214, v94, v177
	v_mul_f32_e32 v215, v95, v177
	v_fmac_f32_e32 v36, v92, v177
	v_fmac_f32_e32 v37, v93, v177
	v_fmac_f32_e32 v38, v94, v177
	v_fmac_f32_e32 v39, v95, v177
	v_fma_f32 v12, v36, s59, -v212
	v_fma_f32 v13, v37, s59, -v213
	v_fma_f32 v22, v38, s59, -v214
	v_fma_f32 v23, v39, s59, -v215
	s_waitcnt vmcnt(21)
	v_fma_f32 v36, -v96, v170, v36
	v_fma_f32 v37, -v97, v170, v37
	v_fma_f32 v38, -v98, v170, v38
	v_fma_f32 v39, -v99, v170, v39
	v_cvt_pk_bf16_f32 v2, v12, v13
	v_cvt_pk_bf16_f32 v3, v22, v23
	global_store_dwordx2 v222, v[2:3], s[54:55]
	s_add_u32 s70, s2, 0x3e000
	s_addc_u32 s71, s3, 0
	global_load_dwordx4 v[92:95], v0, s[70:71]
	s_add_u32 s14, s2, 0x37000
	s_addc_u32 s15, s3, 0
	global_load_dwordx4 v[96:99], v0, s[14:15]
	s_add_u32 s74, s12, 0x1d380
	s_addc_u32 s75, s13, 0
	s_waitcnt vmcnt(22)
	v_mul_f32_e32 v212, v100, v178
	v_mul_f32_e32 v213, v101, v178
	v_mul_f32_e32 v214, v102, v178
	v_mul_f32_e32 v215, v103, v178
	v_fmac_f32_e32 v36, v100, v178
	v_fmac_f32_e32 v37, v101, v178
	v_fmac_f32_e32 v38, v102, v178
	v_fmac_f32_e32 v39, v103, v178
	v_fma_f32 v12, v36, s59, -v212
	v_fma_f32 v13, v37, s59, -v213
	v_fma_f32 v22, v38, s59, -v214
	v_fma_f32 v23, v39, s59, -v215
	s_waitcnt vmcnt(21)
; DI unsigned pack_bf16(float lo, float hi) { f32x2 v = {lo, hi}; bf16v2 b = __builtin_convertvector(v, bf16v2); return __builtin_bit_cast(unsigned, b); }
; DI void grid_bar(unsigned* ctr, unsigned target) {
;   asm volatile("s_waitcnt vmcnt(0)" ::: "memory");
;   __syncthreads();
;   if (threadIdx.x == 0) {
;     __builtin_amdgcn_fence(__ATOMIC_RELEASE, "agent");
;     asm volatile("s_waitcnt vmcnt(0)" ::: "memory");
;     (void)__hip_atomic_fetch_add(ctr, 1u, __ATOMIC_RELAXED, __HIP_MEMORY_SCOPE_AGENT);
;     while (__hip_atomic_load(ctr, __ATOMIC_RELAXED, __HIP_MEMORY_SCOPE_AGENT) < target) __builtin_amdgcn_s_sleep(1);
; template <int W>
; DI void pool_rows(const float* __restrict__ x, const float* smr, bf16_t* __restrict__ pb, int t0, int s0, int tid) {
;     ...
;   for (int tl = 0; tl < 64; ++tl) {
;     const int t = t0 + tl, s = s0 + tl;
;     int to = t - W + 1; if (to < tq0) to = tq0;
;     const f32x4 hn = *(const f32x4*)(xq + (size_t)t * D) * smr[15 + tl];
;     const f32x4 ho = *(const f32x4*)(xq + (size_t)to * D) * smr[15 + tl - W + 1];
;     const int cnt = (s + 1 < W) ? (s + 1) : W;
;     const float ic = 1.f / (float)cnt;
;     Sm += hn;
;     const f32x4 p = Sm * ic - hn;
;     Sm -= ho;
;     u32x2 o; o.x = pack_bf16(p.x, p.y); o.y = pack_bf16(p.z, p.w);
;     *(u32x2*)(pb + (size_t)t * LDH + tid * 4) = o;
;   }
	v_fma_f32 v36, -v104, v171, v36
	v_fma_f32 v37, -v105, v171, v37
	v_fma_f32 v38, -v106, v171, v38
	v_fma_f32 v39, -v107, v171, v39
	v_cvt_pk_bf16_f32 v208, v12, v13
	v_cvt_pk_bf16_f32 v209, v22, v23
	global_store_dwordx2 v222, v[208:209], s[74:75]
	s_add_u32 s56, s2, 0x3f000
	s_addc_u32 s57, s3, 0
	global_load_dwordx4 v[100:103], v0, s[56:57]
	s_add_u32 s70, s2, 0x38000
	s_addc_u32 s71, s3, 0
	global_load_dwordx4 v[104:107], v0, s[70:71]
	s_add_u32 s54, s12, 0x1dc00
	s_addc_u32 s55, s13, 0
	s_waitcnt vmcnt(22)
	v_mul_f32_e32 v212, v44, v179
	v_mul_f32_e32 v213, v45, v179
	v_mul_f32_e32 v214, v46, v179
	v_mul_f32_e32 v215, v47, v179
	v_fmac_f32_e32 v36, v44, v179
	v_fmac_f32_e32 v37, v45, v179
	v_fmac_f32_e32 v38, v46, v179
	v_fmac_f32_e32 v39, v47, v179
	v_fma_f32 v12, v36, s59, -v212
	v_fma_f32 v13, v37, s59, -v213
	v_fma_f32 v22, v38, s59, -v214
	v_fma_f32 v23, v39, s59, -v215
	s_waitcnt vmcnt(21)
	v_fma_f32 v36, -v48, v172, v36
	v_fma_f32 v37, -v49, v172, v37
	v_fma_f32 v38, -v50, v172, v38
	v_fma_f32 v39, -v51, v172, v39
	v_cvt_pk_bf16_f32 v2, v12, v13
	v_cvt_pk_bf16_f32 v3, v22, v23
	global_store_dwordx2 v222, v[2:3], s[54:55]
	s_add_u32 s74, s12, 0x1e480
	s_addc_u32 s75, s13, 0
	s_waitcnt vmcnt(20)
	v_mul_f32_e32 v212, v52, v180
	v_mul_f32_e32 v213, v53, v180
	v_mul_f32_e32 v214, v54, v180
	v_mul_f32_e32 v215, v55, v180
	v_fmac_f32_e32 v36, v52, v180
	v_fmac_f32_e32 v37, v53, v180
	v_fmac_f32_e32 v38, v54, v180
	v_fmac_f32_e32 v39, v55, v180
	v_fma_f32 v12, v36, s59, -v212
	v_fma_f32 v13, v37, s59, -v213
	v_fma_f32 v22, v38, s59, -v214
	v_fma_f32 v23, v39, s59, -v215
	s_waitcnt vmcnt(19)
	v_fma_f32 v36, -v56, v173, v36
	v_fma_f32 v37, -v57, v173, v37
	v_fma_f32 v38, -v58, v173, v38
	v_fma_f32 v39, -v59, v173, v39
	v_cvt_pk_bf16_f32 v208, v12, v13
	v_cvt_pk_bf16_f32 v209, v22, v23
	global_store_dwordx2 v222, v[208:209], s[74:75]
	s_add_u32 s54, s12, 0x1ed00
	s_addc_u32 s55, s13, 0
	s_waitcnt vmcnt(18)
	v_mul_f32_e32 v212, v60, v181
	v_mul_f32_e32 v213, v61, v181
	v_mul_f32_e32 v214, v62, v181
	v_mul_f32_e32 v215, v63, v181
	v_fmac_f32_e32 v36, v60, v181
	v_fmac_f32_e32 v37, v61, v181
	v_fmac_f32_e32 v38, v62, v181
	v_fmac_f32_e32 v39, v63, v181
	v_fma_f32 v12, v36, s59, -v212
	v_fma_f32 v13, v37, s59, -v213
	v_fma_f32 v22, v38, s59, -v214
	v_fma_f32 v23, v39, s59, -v215
	s_waitcnt vmcnt(17)
	v_fma_f32 v36, -v64, v174, v36
	v_fma_f32 v37, -v65, v174, v37
	v_fma_f32 v38, -v66, v174, v38
	v_fma_f32 v39, -v67, v174, v39
	v_cvt_pk_bf16_f32 v2, v12, v13
	v_cvt_pk_bf16_f32 v3, v22, v23
	global_store_dwordx2 v222, v[2:3], s[54:55]
	s_add_u32 s74, s12, 0x1f580
	s_addc_u32 s75, s13, 0
	s_waitcnt vmcnt(16)
	v_mul_f32_e32 v212, v68, v182
	v_mul_f32_e32 v213, v69, v182
	v_mul_f32_e32 v214, v70, v182
	v_mul_f32_e32 v215, v71, v182
	v_fmac_f32_e32 v36, v68, v182
	v_fmac_f32_e32 v37, v69, v182
	v_fmac_f32_e32 v38, v70, v182
	v_fmac_f32_e32 v39, v71, v182
	v_fma_f32 v12, v36, s59, -v212
	v_fma_f32 v13, v37, s59, -v213
	v_fma_f32 v22, v38, s59, -v214
	v_fma_f32 v23, v39, s59, -v215
	s_waitcnt vmcnt(15)
	v_fma_f32 v36, -v72, v175, v36
	v_fma_f32 v37, -v73, v175, v37
	v_fma_f32 v38, -v74, v175, v38
	v_fma_f32 v39, -v75, v175, v39
	v_cvt_pk_bf16_f32 v208, v12, v13
	v_cvt_pk_bf16_f32 v209, v22, v23
	global_store_dwordx2 v222, v[208:209], s[74:75]
	s_add_u32 s54, s12, 0x1fe00
	s_addc_u32 s55, s13, 0
	s_waitcnt vmcnt(14)
	v_mul_f32_e32 v212, v76, v183
	v_mul_f32_e32 v213, v77, v183
	v_mul_f32_e32 v214, v78, v183
	v_mul_f32_e32 v215, v79, v183
	v_fmac_f32_e32 v36, v76, v183
	v_fmac_f32_e32 v37, v77, v183
	v_fmac_f32_e32 v38, v78, v183
	v_fmac_f32_e32 v39, v79, v183
	v_fma_f32 v12, v36, s59, -v212
	v_fma_f32 v13, v37, s59, -v213
	v_fma_f32 v22, v38, s59, -v214
	v_fma_f32 v23, v39, s59, -v215
	s_waitcnt vmcnt(13)
	v_fma_f32 v36, -v80, v176, v36
	v_fma_f32 v37, -v81, v176, v37
	v_fma_f32 v38, -v82, v176, v38
	v_fma_f32 v39, -v83, v176, v39
	v_cvt_pk_bf16_f32 v2, v12, v13
	v_cvt_pk_bf16_f32 v3, v22, v23
	global_store_dwordx2 v222, v[2:3], s[54:55]
	s_add_u32 s74, s12, 0x20680
	s_addc_u32 s75, s13, 0
	s_waitcnt vmcnt(12)
	v_mul_f32_e32 v212, v84, v184
	v_mul_f32_e32 v213, v85, v184
	v_mul_f32_e32 v214, v86, v184
	v_mul_f32_e32 v215, v87, v184
	v_fmac_f32_e32 v36, v84, v184
	v_fmac_f32_e32 v37, v85, v184
	v_fmac_f32_e32 v38, v86, v184
	v_fmac_f32_e32 v39, v87, v184
	v_fma_f32 v12, v36, s59, -v212
	v_fma_f32 v13, v37, s59, -v213
	v_fma_f32 v22, v38, s59, -v214
	v_fma_f32 v23, v39, s59, -v215
	s_waitcnt vmcnt(11)
	v_fma_f32 v36, -v88, v177, v36
	v_fma_f32 v37, -v89, v177, v37
	v_fma_f32 v38, -v90, v177, v38
	v_fma_f32 v39, -v91, v177, v39
	v_cvt_pk_bf16_f32 v208, v12, v13
	v_cvt_pk_bf16_f32 v209, v22, v23
	global_store_dwordx2 v222, v[208:209], s[74:75]
	s_add_u32 s54, s12, 0x20f00
	s_addc_u32 s55, s13, 0
	s_waitcnt vmcnt(10)
	v_mul_f32_e32 v212, v92, v185
	v_mul_f32_e32 v213, v93, v185
	v_mul_f32_e32 v214, v94, v185
	v_mul_f32_e32 v215, v95, v185
	v_fmac_f32_e32 v36, v92, v185
	v_fmac_f32_e32 v37, v93, v185
	v_fmac_f32_e32 v38, v94, v185
	v_fmac_f32_e32 v39, v95, v185
	v_fma_f32 v12, v36, s59, -v212
	v_fma_f32 v13, v37, s59, -v213
	v_fma_f32 v22, v38, s59, -v214
	v_fma_f32 v23, v39, s59, -v215
	s_waitcnt vmcnt(9)
	v_fma_f32 v36, -v96, v178, v36
	v_fma_f32 v37, -v97, v178, v37
	v_fma_f32 v38, -v98, v178, v38
	v_fma_f32 v39, -v99, v178, v39
	v_cvt_pk_bf16_f32 v2, v12, v13
	v_cvt_pk_bf16_f32 v3, v22, v23
	global_store_dwordx2 v222, v[2:3], s[54:55]
	s_add_u32 s74, s12, 0x21780
	s_addc_u32 s75, s13, 0
	s_waitcnt vmcnt(8)
	v_mul_f32_e32 v212, v100, v186
	v_mul_f32_e32 v213, v101, v186
	v_mul_f32_e32 v214, v102, v186
	v_mul_f32_e32 v215, v103, v186
	v_fmac_f32_e32 v36, v100, v186
	v_fmac_f32_e32 v37, v101, v186
	v_fmac_f32_e32 v38, v102, v186
	v_fmac_f32_e32 v39, v103, v186
	v_fma_f32 v12, v36, s59, -v212
	v_fma_f32 v13, v37, s59, -v213
	v_fma_f32 v22, v38, s59, -v214
	v_fma_f32 v23, v39, s59, -v215
	s_waitcnt vmcnt(7)
	v_fma_f32 v36, -v104, v179, v36
	v_fma_f32 v37, -v105, v179, v37
	v_fma_f32 v38, -v106, v179, v38
	v_fma_f32 v39, -v107, v179, v39
	v_cvt_pk_bf16_f32 v208, v12, v13
	v_cvt_pk_bf16_f32 v209, v22, v23
	global_store_dwordx2 v222, v[208:209], s[74:75]
.Lpp_done:
	s_branch .LBB0_1470
.LBB0_1496:
	s_waitcnt vmcnt(0)
	v_readlane_b32 s0, v254, 12
	v_readlane_b32 s1, v253, 38
	s_add_i32 s58, s1, s0
	s_barrier
	s_mov_b64 s[0:1], exec
	v_readlane_b32 s2, v254, 13
	v_readlane_b32 s3, v254, 14
	v_readlane_b32 s14, v253, 29
	s_and_b64 s[2:3], s[0:1], s[2:3]
	s_mov_b32 s92, 0x10000
	v_readlane_b32 s15, v253, 30
	s_mov_b64 exec, s[2:3]
	s_cbranch_execz .LBB0_1502
	s_mov_b64 s[2:3], exec
	buffer_wbl2 sc1
	s_waitcnt vmcnt(0)
	s_waitcnt vmcnt(0)
	v_mbcnt_lo_u32_b32 v0, s2, 0
	v_mbcnt_hi_u32_b32 v0, s3, v0
	v_cmp_eq_u32_e32 vcc, 0, v0
	s_and_saveexec_b64 s[6:7], vcc
	s_cbranch_execz .LBB0_1499
	s_bcnt1_i32_b64 s2, s[2:3]
	v_mov_b32_e32 v0, s2
	global_atomic_add v1, v0, s[14:15]
